# thread-invariant hoisting: FFT twiddle factors (w, w^2, w^4) for all radix-8 passes computed once per channel into persistent VGPRs instead of an LDS read plus 7 packed ops per sub-iteration
# speedup vs baseline: 1.0069x; 1.0069x over previous
; #define LAS __attribute__((address_space(3)))
; __device__ __forceinline__ int otid() { int t = threadIdx.x; asm volatile("" : "+v"(t)); return t; }
; __device__ __forceinline__ cf twc(cf ws, int k16) { if (k16 == 0) return ws; if (k16 == 4) return cf{ws.y, -ws.x}; return cmul(ws, cf{c16(k16), -s16(k16)}); }
; __device__ __forceinline__ void lds_barrier() { asm volatile("s_waitcnt lgkmcnt(0)\n\ts_barrier" ::: "memory"); }
; template <int LR> __device__ __forceinline__ void dif_reg(cf (&x)[1 << LR], cf w) {
;     constexpr int R = 1 << LR; cf ws = w;
; #pragma unroll
;     for (int s = 0; s < LR; ++s) { const int half = R >> (s + 1);
; #pragma unroll
;         for (int m0 = 0; m0 < R; m0 += 2 * half)
; #pragma unroll
;             for (int mm = 0; mm < half; ++mm) { const int ia = m0 + mm, ib = ia + half; const cf a = x[ia], b = x[ib];
;                 x[ia] = cf{a.x + b.x, a.y + b.y}; const cf d{a.x - b.x, a.y - b.y};
;                 x[ib] = cmul(d, twc(ws, (mm << s) * (16 / R))); }
;         ws = cmul(ws, ws); }
; }
; template <int LR, bool INV> __device__ __forceinline__ void fft_pass(ldsf2 buf, int base, int stride, int twi) {
;     constexpr int R = 1 << LR; cf x[R];
;     const v2f wv = ((ldsf2)((LAS unsigned char*)buf + 139264))[twi];
; #pragma unroll
;     for (int m = 0; m < R; ++m) { const v2f v = buf[base + m * stride]; x[m] = cf{v.x, v.y}; }
;     const cf w{wv.x, wv.y};
;     if (INV) dit_reg<LR>(x, w); else dif_reg<LR>(x, w);
; #pragma unroll
;     for (int m = 0; m < R; ++m) buf[base + m * stride] = mkv2(x[m].x, x[m].y);
; }
; __device__ __forceinline__ void wave_lds_fence() { asm volatile("s_waitcnt lgkmcnt(0)" ::: "memory"); }
; __device__ __forceinline__ void fft_fwd_abc(ldsf2 buf) {
;     const int tid = otid(); const int wv = tid >> 6, l = tid & 63;
; #pragma unroll 1
;     for (int u = 0; u < 2; ++u) { const int bf = tid + NT * u; fft_pass<3, false>(buf, bf + (bf >> 4), 1088, bf); }
;     lds_barrier();
; #pragma unroll 1
;     for (int u = 0; u < 2; ++u) { const int o = l + 64 * u, e0 = wv * 1024 + o; fft_pass<3, false>(buf, e0 + (e0 >> 4), 136, o * 8); }
;     wave_lds_fence();
; #pragma unroll 1
;     for (int u = 0; u < 2; ++u) { const int j = l + 64 * u, o = j & 15, e0 = wv * 1024 + (j >> 4) * 128 + o; fft_pass<3, false>(buf, e0 + (e0 >> 4), 17, o * 64); }
;     wave_lds_fence();
.LBB0_344:
	v_or_b32_e32 v5, s0, v3
	ds_read_b64 v[14:15], v4
	v_lshlrev_b32_e32 v6, 3, v5
	v_ashrrev_i32_e32 v5, 1, v5
	v_add3_u32 v5, v2, v6, v5
	ds_read2_b64 v[6:9], v5 offset1:17
	ds_read2_b64 v[10:13], v5 offset0:34 offset1:51
	ds_read2_b64 v[24:27], v5 offset0:68 offset1:85
	ds_read2_b64 v[28:31], v5 offset0:102 offset1:119
	s_waitcnt lgkmcnt(4)
	v_pk_add_f32 v[32:33], v[14:15], v[14:15] op_sel:[0,1] op_sel_hi:[1,0] neg_lo:[0,0] neg_hi:[0,1]
	v_pk_mul_f32 v[38:39], v[14:15], v[14:15] op_sel:[1,1] op_sel_hi:[1,0]
	v_pk_mul_f32 v[34:35], v[32:33], s[16:17] op_sel:[0,0] op_sel_hi:[1,0]
	v_pk_fma_f32 v[38:39], v[14:15], v[14:15], v[38:39] op_sel:[0,0,0] op_sel_hi:[0,1,1] neg_lo:[0,0,1] neg_hi:[0,0,0]
	v_pk_mul_f32 v[36:37], v[32:33], s[16:17] op_sel:[1,0] op_sel_hi:[0,0] neg_lo:[0,0] neg_hi:[1,0]
	s_nop 0
	v_pk_mul_f32 v[40:41], v[38:39], v[38:39] op_sel:[1,1] op_sel_hi:[1,0]
	s_nop 0
	v_pk_fma_f32 v[40:41], v[38:39], v[38:39], v[40:41] op_sel:[0,0,0] op_sel_hi:[0,1,1] neg_lo:[0,0,1] neg_hi:[0,0,0]
	s_waitcnt lgkmcnt(0)
	v_pk_add_f32 v[42:43], v[6:7], v[24:25] neg_lo:[0,1] neg_hi:[0,1]
	v_pk_add_f32 v[44:45], v[8:9], v[26:27] neg_lo:[0,1] neg_hi:[0,1]
	v_pk_add_f32 v[46:47], v[10:11], v[28:29] neg_lo:[0,1] neg_hi:[0,1]
	v_pk_add_f32 v[48:49], v[12:13], v[30:31] neg_lo:[0,1] neg_hi:[0,1]
	v_pk_add_f32 v[6:7], v[6:7], v[24:25]
	v_pk_add_f32 v[8:9], v[8:9], v[26:27]
	v_pk_add_f32 v[10:11], v[10:11], v[28:29]
	v_pk_add_f32 v[12:13], v[12:13], v[30:31]
	v_pk_mul_f32 v[24:25], v[42:43], v[14:15] op_sel:[1,1] op_sel_hi:[1,0]
	v_pk_mul_f32 v[26:27], v[44:45], v[34:35] op_sel:[1,1] op_sel_hi:[1,0]
	v_pk_mul_f32 v[28:29], v[46:47], v[14:15] op_sel:[1,0] op_sel_hi:[1,1]
	v_pk_mul_f32 v[30:31], v[48:49], v[36:37] op_sel:[1,1] op_sel_hi:[1,0]
	v_pk_fma_f32 v[24:25], v[42:43], v[14:15], v[24:25] op_sel:[0,0,0] op_sel_hi:[0,1,1] neg_lo:[0,0,1] neg_hi:[0,0,0]
	v_pk_fma_f32 v[26:27], v[44:45], v[34:35], v[26:27] op_sel:[0,0,0] op_sel_hi:[0,1,1] neg_lo:[0,0,1] neg_hi:[0,0,0]
	v_pk_fma_f32 v[28:29], v[46:47], v[14:15], v[28:29] op_sel:[0,1,0] op_sel_hi:[0,0,1] neg_lo:[0,0,0] neg_hi:[0,1,0]
	v_pk_fma_f32 v[30:31], v[48:49], v[36:37], v[30:31] op_sel:[0,0,0] op_sel_hi:[0,1,1] neg_lo:[0,0,1] neg_hi:[0,0,0]
	v_pk_add_f32 v[42:43], v[6:7], v[10:11] neg_lo:[0,1] neg_hi:[0,1]
	v_pk_add_f32 v[44:45], v[8:9], v[12:13] neg_lo:[0,1] neg_hi:[0,1]
	v_pk_add_f32 v[46:47], v[24:25], v[28:29] neg_lo:[0,1] neg_hi:[0,1]
	v_pk_add_f32 v[48:49], v[26:27], v[30:31] neg_lo:[0,1] neg_hi:[0,1]
	v_pk_add_f32 v[6:7], v[6:7], v[10:11]
	v_pk_add_f32 v[8:9], v[8:9], v[12:13]
	v_pk_add_f32 v[24:25], v[24:25], v[28:29]
	v_pk_add_f32 v[26:27], v[26:27], v[30:31]
	v_pk_mul_f32 v[10:11], v[42:43], v[38:39] op_sel:[1,1] op_sel_hi:[1,0]
	v_pk_mul_f32 v[12:13], v[44:45], v[38:39] op_sel:[1,0] op_sel_hi:[1,1]
	v_pk_mul_f32 v[28:29], v[46:47], v[38:39] op_sel:[1,1] op_sel_hi:[1,0]
	v_pk_mul_f32 v[30:31], v[48:49], v[38:39] op_sel:[1,0] op_sel_hi:[1,1]
	v_pk_fma_f32 v[10:11], v[42:43], v[38:39], v[10:11] op_sel:[0,0,0] op_sel_hi:[0,1,1] neg_lo:[0,0,1] neg_hi:[0,0,0]
	v_pk_fma_f32 v[12:13], v[44:45], v[38:39], v[12:13] op_sel:[0,1,0] op_sel_hi:[0,0,1] neg_lo:[0,0,0] neg_hi:[0,1,0]
	v_pk_fma_f32 v[28:29], v[46:47], v[38:39], v[28:29] op_sel:[0,0,0] op_sel_hi:[0,1,1] neg_lo:[0,0,1] neg_hi:[0,0,0]
	v_pk_fma_f32 v[30:31], v[48:49], v[38:39], v[30:31] op_sel:[0,1,0] op_sel_hi:[0,0,1] neg_lo:[0,0,0] neg_hi:[0,1,0]
	v_pk_add_f32 v[42:43], v[6:7], v[8:9] neg_lo:[0,1] neg_hi:[0,1]
	v_pk_add_f32 v[44:45], v[10:11], v[12:13] neg_lo:[0,1] neg_hi:[0,1]
	v_pk_add_f32 v[46:47], v[24:25], v[26:27] neg_lo:[0,1] neg_hi:[0,1]
	v_pk_add_f32 v[48:49], v[28:29], v[30:31] neg_lo:[0,1] neg_hi:[0,1]
	v_pk_add_f32 v[6:7], v[6:7], v[8:9]
	v_pk_add_f32 v[10:11], v[10:11], v[12:13]
	v_pk_add_f32 v[24:25], v[24:25], v[26:27]
	v_pk_add_f32 v[28:29], v[28:29], v[30:31]
	v_pk_mul_f32 v[8:9], v[42:43], v[40:41] op_sel:[1,1] op_sel_hi:[1,0]
	v_pk_mul_f32 v[12:13], v[44:45], v[40:41] op_sel:[1,1] op_sel_hi:[1,0]
	v_pk_mul_f32 v[26:27], v[46:47], v[40:41] op_sel:[1,1] op_sel_hi:[1,0]
	v_pk_mul_f32 v[30:31], v[48:49], v[40:41] op_sel:[1,1] op_sel_hi:[1,0]
	v_pk_fma_f32 v[8:9], v[42:43], v[40:41], v[8:9] op_sel:[0,0,0] op_sel_hi:[0,1,1] neg_lo:[0,0,1] neg_hi:[0,0,0]
	v_pk_fma_f32 v[12:13], v[44:45], v[40:41], v[12:13] op_sel:[0,0,0] op_sel_hi:[0,1,1] neg_lo:[0,0,1] neg_hi:[0,0,0]
	v_pk_fma_f32 v[26:27], v[46:47], v[40:41], v[26:27] op_sel:[0,0,0] op_sel_hi:[0,1,1] neg_lo:[0,0,1] neg_hi:[0,0,0]
	v_pk_fma_f32 v[30:31], v[48:49], v[40:41], v[30:31] op_sel:[0,0,0] op_sel_hi:[0,1,1] neg_lo:[0,0,1] neg_hi:[0,0,0]
	ds_write2_b64 v5, v[6:7], v[8:9] offset1:17
	ds_write2_b64 v5, v[10:11], v[12:13] offset0:34 offset1:51
	ds_write2_b64 v5, v[24:25], v[26:27] offset0:68 offset1:85
	ds_write2_b64 v5, v[28:29], v[30:31] offset0:102 offset1:119
	s_movk_i32 s0, 0x200
	s_and_b64 vcc, exec, s[10:11]
	s_mov_b64 s[10:11], 0
	s_cbranch_vccnz .LBB0_344
; __device__ __forceinline__ cf twc(cf ws, int k16) { if (k16 == 0) return ws; if (k16 == 4) return cf{ws.y, -ws.x}; return cmul(ws, cf{c16(k16), -s16(k16)}); }
; __device__ __forceinline__ void lds_barrier() { asm volatile("s_waitcnt lgkmcnt(0)\n\ts_barrier" ::: "memory"); }
; template <int LR> __device__ __forceinline__ void dif_reg(cf (&x)[1 << LR], cf w) {
;     constexpr int R = 1 << LR; cf ws = w;
; #pragma unroll
;     for (int s = 0; s < LR; ++s) { const int half = R >> (s + 1);
; #pragma unroll
;         for (int m0 = 0; m0 < R; m0 += 2 * half)
; #pragma unroll
;             for (int mm = 0; mm < half; ++mm) { const int ia = m0 + mm, ib = ia + half; const cf a = x[ia], b = x[ib];
;                 x[ia] = cf{a.x + b.x, a.y + b.y}; const cf d{a.x - b.x, a.y - b.y};
;                 x[ib] = cmul(d, twc(ws, (mm << s) * (16 / R))); }
;         ws = cmul(ws, ws); }
; }
; __device__ __forceinline__ void make_spec(ldsf2 buf, LAS unsigned* spec, const float* __restrict__ kfrow) {
;     ...
;     cf x[16];
; #pragma unroll
;     for (int m = 0; m < 16; ++m) { const v2f v = buf[tid * 17 + m]; x[m] = cf{v.x, v.y}; }
;     dif_reg<4>(x, cf{1.0f, 0.0f});
; #pragma unroll
;     for (int m = 0; m < 16; ++m) { h2_t hv; hv.x = (_Float16)x[m].x; hv.y = (_Float16)x[m].y; spec[tid * 17 + m] = __builtin_bit_cast(unsigned, hv); }
;     lds_barrier();
	s_waitcnt lgkmcnt(0)
	ds_read2_b64 v[2:5], v1 offset1:1
	ds_read2_b64 v[6:9], v1 offset0:2 offset1:3
	ds_read2_b64 v[10:13], v1 offset0:4 offset1:5
	ds_read2_b64 v[24:27], v1 offset0:6 offset1:7
	ds_read2_b64 v[28:31], v1 offset0:8 offset1:9
	ds_read2_b64 v[32:35], v1 offset0:10 offset1:11
	ds_read2_b64 v[36:39], v1 offset0:12 offset1:13
	ds_read2_b64 v[40:43], v1 offset0:14 offset1:15
	s_movk_i32 s0, 0x44
	v_mul_lo_u32 v0, v0, s0
	v_add_u32_e32 v0, 0, v0
	v_add_u32_e32 v70, 0x19800, v0
	s_waitcnt lgkmcnt(3)
	v_pk_add_f32 v[0:1], v[2:3], v[28:29]
	v_pk_add_f32 v[14:15], v[4:5], v[30:31]
	s_waitcnt lgkmcnt(2)
	v_pk_add_f32 v[44:45], v[6:7], v[32:33]
	v_pk_add_f32 v[46:47], v[8:9], v[34:35]
	s_waitcnt lgkmcnt(1)
	v_pk_add_f32 v[48:49], v[10:11], v[36:37]
	v_pk_add_f32 v[50:51], v[12:13], v[38:39]
	s_waitcnt lgkmcnt(0)
	v_pk_add_f32 v[52:53], v[24:25], v[40:41]
	v_pk_add_f32 v[54:55], v[26:27], v[42:43]
	v_pk_add_f32 v[56:57], v[0:1], v[48:49]
	v_pk_add_f32 v[58:59], v[14:15], v[50:51]
	v_pk_add_f32 v[60:61], v[44:45], v[52:53]
	v_pk_add_f32 v[62:63], v[46:47], v[54:55]
	v_pk_add_f32 v[64:65], v[56:57], v[60:61]
	v_pk_add_f32 v[66:67], v[58:59], v[62:63]
	v_pk_add_f32 v[56:57], v[56:57], v[60:61] neg_lo:[0,1] neg_hi:[0,1]
	v_pk_add_f32 v[68:69], v[64:65], v[66:67]
	v_pk_add_f32 v[64:65], v[64:65], v[66:67] neg_lo:[0,1] neg_hi:[0,1]
	v_cvt_pk_f16_f32 v71, v68, v69
	v_pk_mul_f32 v[66:67], v[64:65], 0 op_sel_hi:[1,0]
	v_pk_mul_f32 v[60:61], v[56:57], 0 op_sel_hi:[1,0]
	v_pk_add_f32 v[68:69], v[64:65], v[66:67] op_sel:[0,1] op_sel_hi:[1,0] neg_lo:[0,1] neg_hi:[0,1]
	v_pk_add_f32 v[64:65], v[64:65], v[66:67] op_sel:[0,1] op_sel_hi:[1,0]
	v_pk_add_f32 v[0:1], v[0:1], v[48:49] neg_lo:[0,1] neg_hi:[0,1]
	v_cvt_pk_f16_f32 v64, v68, v65
	ds_write2_b32 v70, v71, v64 offset1:1
	v_pk_add_f32 v[64:65], v[56:57], v[60:61] op_sel:[0,1] op_sel_hi:[1,0] neg_lo:[0,1] neg_hi:[0,1]
	v_pk_add_f32 v[56:57], v[56:57], v[60:61] op_sel:[0,1] op_sel_hi:[1,0]
	v_pk_mul_f32 v[48:49], v[0:1], 0 op_sel_hi:[1,0]
	v_mov_b32_e32 v65, v57
	v_pk_add_f32 v[56:57], v[58:59], v[62:63] neg_lo:[0,1] neg_hi:[0,1]
	s_mov_b32 s0, s87
	v_pk_fma_f32 v[58:59], v[56:57], 0, v[56:57] op_sel:[0,0,1] op_sel_hi:[1,0,0]
	v_pk_fma_f32 v[56:57], v[56:57], 0, v[56:57] op_sel:[0,0,1] op_sel_hi:[1,0,0] neg_lo:[0,0,1] neg_hi:[0,0,1]
	s_mov_b32 s1, s16
	v_mov_b32_e32 v59, v57
	v_pk_add_f32 v[56:57], v[64:65], v[58:59]
	s_mov_b32 s17, s87
	v_cvt_pk_f16_f32 v62, v56, v57
	v_pk_add_f32 v[56:57], v[64:65], v[58:59] neg_lo:[0,1] neg_hi:[0,1]
	s_mov_b32 s10, s5
	v_pk_mul_f32 v[58:59], v[56:57], 0 op_sel_hi:[1,0]
	s_mov_b32 s14, s13
	v_pk_add_f32 v[60:61], v[56:57], v[58:59] op_sel:[0,1] op_sel_hi:[1,0] neg_lo:[0,1] neg_hi:[0,1]
	v_pk_add_f32 v[56:57], v[56:57], v[58:59] op_sel:[0,1] op_sel_hi:[1,0]
	v_mov_b32_e32 v58, v51
	v_cvt_pk_f16_f32 v56, v60, v57
	ds_write2_b32 v70, v62, v56 offset0:2 offset1:3
	v_pk_add_f32 v[56:57], v[0:1], v[48:49] op_sel:[0,1] op_sel_hi:[1,0] neg_lo:[0,1] neg_hi:[0,1]
	v_pk_add_f32 v[0:1], v[0:1], v[48:49] op_sel:[0,1] op_sel_hi:[1,0]
	v_mov_b32_e32 v48, v54
	v_mov_b32_e32 v57, v1
	v_pk_add_f32 v[0:1], v[44:45], v[52:53] neg_lo:[0,1] neg_hi:[0,1]
	v_mov_b32_e32 v49, v51
	v_pk_fma_f32 v[44:45], v[0:1], 0, v[0:1] op_sel:[0,0,1] op_sel_hi:[1,0,0]
	v_pk_fma_f32 v[0:1], v[0:1], 0, v[0:1] op_sel:[0,0,1] op_sel_hi:[1,0,0] neg_lo:[0,0,1] neg_hi:[0,0,1]
	v_mov_b32_e32 v52, v50
	v_mov_b32_e32 v45, v1
	v_mov_b32_e32 v0, v46
	v_mov_b32_e32 v1, v15
	v_pk_add_f32 v[0:1], v[0:1], v[48:49] neg_lo:[0,1] neg_hi:[0,1]
	v_mov_b32_e32 v48, v14
	v_mov_b32_e32 v49, v46
	v_mov_b32_e32 v53, v54
	v_pk_add_f32 v[48:49], v[48:49], v[52:53] neg_lo:[0,1] neg_hi:[0,1]
	v_mov_b32_e32 v52, v15
	v_mov_b32_e32 v53, v47
	v_mov_b32_e32 v59, v55
	v_pk_mov_b32 v[14:15], v[46:47], v[14:15] op_sel:[1,0]
	v_pk_mov_b32 v[46:47], v[54:55], v[50:51] op_sel:[1,0]
	v_pk_add_f32 v[52:53], v[52:53], v[58:59] neg_lo:[0,1] neg_hi:[0,1]
	v_pk_add_f32 v[14:15], v[14:15], v[46:47] neg_lo:[0,1] neg_hi:[0,1]
	v_pk_mul_f32 v[46:47], v[52:53], s[16:17]
	v_pk_mul_f32 v[14:15], v[14:15], s[0:1]
	s_mov_b32 s15, s4
	v_pk_fma_f32 v[0:1], v[0:1], s[0:1], v[14:15] neg_lo:[0,0,1] neg_hi:[0,0,1]
	v_pk_fma_f32 v[14:15], v[48:49], s[16:17], v[46:47]
	v_pk_add_f32 v[46:47], v[56:57], v[44:45]
	v_pk_add_f32 v[48:49], v[14:15], v[0:1]
	v_pk_add_f32 v[44:45], v[56:57], v[44:45] neg_lo:[0,1] neg_hi:[0,1]
	v_pk_add_f32 v[50:51], v[46:47], v[48:49]
	v_pk_add_f32 v[46:47], v[46:47], v[48:49] neg_lo:[0,1] neg_hi:[0,1]
	v_cvt_pk_f16_f32 v52, v50, v51
	v_pk_mul_f32 v[48:49], v[46:47], 0 op_sel_hi:[1,0]
	s_mov_b32 s35, s5
	v_pk_add_f32 v[50:51], v[46:47], v[48:49] op_sel:[0,1] op_sel_hi:[1,0] neg_lo:[0,1] neg_hi:[0,1]
	v_pk_add_f32 v[46:47], v[46:47], v[48:49] op_sel:[0,1] op_sel_hi:[1,0]
	s_mov_b32 s48, 0
	v_cvt_pk_f16_f32 v46, v50, v47
	ds_write2_b32 v70, v52, v46 offset0:4 offset1:5
	v_pk_mul_f32 v[46:47], v[44:45], 0 op_sel_hi:[1,0]
	s_mov_b32 s49, s48
	v_pk_add_f32 v[48:49], v[44:45], v[46:47] op_sel:[0,1] op_sel_hi:[1,0] neg_lo:[0,1] neg_hi:[0,1]
	v_pk_add_f32 v[44:45], v[44:45], v[46:47] op_sel:[0,1] op_sel_hi:[1,0]
	s_mov_b32 s50, s48
	v_mov_b32_e32 v49, v45
	v_mov_b32_e32 v44, v14
	v_mov_b32_e32 v45, v1
	v_mov_b32_e32 v1, v15
	v_pk_add_f32 v[0:1], v[44:45], v[0:1] neg_lo:[0,1] neg_hi:[0,1]
	s_mov_b32 s51, s48
	v_pk_fma_f32 v[14:15], v[0:1], 0, v[0:1] op_sel:[0,0,1] op_sel_hi:[1,0,0]
	v_pk_fma_f32 v[0:1], v[0:1], 0, v[0:1] op_sel:[0,0,1] op_sel_hi:[1,0,0] neg_lo:[0,0,1] neg_hi:[0,0,1]
	s_mov_b32 s53, s48
	v_mov_b32_e32 v15, v1
	v_pk_add_f32 v[0:1], v[48:49], v[14:15]
	s_nop 0
	v_cvt_pk_f16_f32 v46, v0, v1
	v_pk_add_f32 v[0:1], v[48:49], v[14:15] neg_lo:[0,1] neg_hi:[0,1]
; __device__ __forceinline__ cf twc(cf ws, int k16) { if (k16 == 0) return ws; if (k16 == 4) return cf{ws.y, -ws.x}; return cmul(ws, cf{c16(k16), -s16(k16)}); }
; __device__ __forceinline__ void lds_barrier() { asm volatile("s_waitcnt lgkmcnt(0)\n\ts_barrier" ::: "memory"); }
; template <int LR> __device__ __forceinline__ void dif_reg(cf (&x)[1 << LR], cf w) {
;     constexpr int R = 1 << LR; cf ws = w;
; #pragma unroll
;     for (int s = 0; s < LR; ++s) { const int half = R >> (s + 1);
; #pragma unroll
;         for (int m0 = 0; m0 < R; m0 += 2 * half)
; #pragma unroll
;             for (int mm = 0; mm < half; ++mm) { const int ia = m0 + mm, ib = ia + half; const cf a = x[ia], b = x[ib];
;                 x[ia] = cf{a.x + b.x, a.y + b.y}; const cf d{a.x - b.x, a.y - b.y};
;                 x[ib] = cmul(d, twc(ws, (mm << s) * (16 / R))); }
;         ws = cmul(ws, ws); }
; }
; __device__ __forceinline__ void make_spec(ldsf2 buf, LAS unsigned* spec, const float* __restrict__ kfrow) {
;     ...
;     cf x[16];
; #pragma unroll
;     for (int m = 0; m < 16; ++m) { const v2f v = buf[tid * 17 + m]; x[m] = cf{v.x, v.y}; }
;     dif_reg<4>(x, cf{1.0f, 0.0f});
; #pragma unroll
;     for (int m = 0; m < 16; ++m) { h2_t hv; hv.x = (_Float16)x[m].x; hv.y = (_Float16)x[m].y; spec[tid * 17 + m] = __builtin_bit_cast(unsigned, hv); }
;     lds_barrier();
	s_nop 0
	v_pk_mul_f32 v[14:15], v[0:1], 0 op_sel_hi:[1,0]
	s_nop 0
	v_pk_add_f32 v[44:45], v[0:1], v[14:15] op_sel:[0,1] op_sel_hi:[1,0] neg_lo:[0,1] neg_hi:[0,1]
	v_pk_add_f32 v[0:1], v[0:1], v[14:15] op_sel:[0,1] op_sel_hi:[1,0]
	s_nop 0
	v_cvt_pk_f16_f32 v0, v44, v1
	ds_write2_b32 v70, v46, v0 offset0:6 offset1:7
	v_pk_add_f32 v[0:1], v[2:3], v[28:29] neg_lo:[0,1] neg_hi:[0,1]
	s_nop 0
	v_pk_mul_f32 v[2:3], v[0:1], 0 op_sel_hi:[1,0]
	s_nop 0
	v_pk_add_f32 v[14:15], v[0:1], v[2:3] op_sel:[0,1] op_sel_hi:[1,0] neg_lo:[0,1] neg_hi:[0,1]
	v_pk_add_f32 v[0:1], v[0:1], v[2:3] op_sel:[0,1] op_sel_hi:[1,0]
	v_pk_add_f32 v[2:3], v[4:5], v[30:31] neg_lo:[0,1] neg_hi:[0,1]
	v_pk_mov_b32 v[0:1], v[0:1], v[14:15] op_sel:[1,0]
	v_pk_mul_f32 v[4:5], v[2:3], s[4:5] op_sel_hi:[1,0]
	s_nop 0
	v_pk_fma_f32 v[14:15], v[2:3], s[10:11], v[4:5] op_sel:[0,0,1] op_sel_hi:[1,0,0]
	v_pk_fma_f32 v[2:3], v[2:3], s[10:11], v[4:5] op_sel:[0,0,1] op_sel_hi:[1,0,0] neg_lo:[1,0,0] neg_hi:[1,0,0]
	v_pk_add_f32 v[4:5], v[8:9], v[34:35] neg_lo:[0,1] neg_hi:[0,1]
	v_mov_b32_e32 v34, v40
	v_pk_mul_f32 v[8:9], v[4:5], s[10:11] op_sel_hi:[1,0]
	v_mov_b32_e32 v35, v32
	v_pk_fma_f32 v[28:29], v[4:5], s[4:5], v[8:9] op_sel:[0,0,1] op_sel_hi:[1,0,0]
	v_pk_fma_f32 v[4:5], v[4:5], s[4:5], v[8:9] op_sel:[0,0,1] op_sel_hi:[1,0,0] neg_lo:[1,0,0] neg_hi:[1,0,0]
	v_pk_add_f32 v[8:9], v[10:11], v[36:37] neg_lo:[0,1] neg_hi:[0,1]
	v_mov_b32_e32 v36, v41
	v_pk_mul_f32 v[10:11], v[8:9], 0 op_sel_hi:[1,0]
	v_mov_b32_e32 v37, v33
	v_pk_add_f32 v[30:31], v[10:11], v[8:9] op_sel:[1,0] op_sel_hi:[0,1]
	v_pk_add_f32 v[8:9], v[10:11], v[8:9] op_sel:[1,0] op_sel_hi:[0,1] neg_lo:[0,1] neg_hi:[0,1]
	v_pk_add_f32 v[10:11], v[12:13], v[38:39] neg_lo:[0,1] neg_hi:[0,1]
	v_mov_b32_e32 v9, v31
	v_pk_mul_f32 v[12:13], v[10:11], s[10:11] op_sel_hi:[1,0]
	v_pk_mov_b32 v[30:31], v[32:33], v[40:41] op_sel:[1,0]
	v_pk_fma_f32 v[10:11], v[10:11], s[14:15], v[12:13] op_sel:[0,0,1] op_sel_hi:[1,1,0] neg_lo:[0,0,1] neg_hi:[0,0,1]
	v_pk_mov_b32 v[12:13], v[6:7], v[24:25] op_sel:[1,0]
	v_mov_b32_e32 v33, v41
	v_pk_add_f32 v[12:13], v[12:13], v[30:31] neg_lo:[0,1] neg_hi:[0,1]
	v_mov_b32_e32 v30, v24
	v_mov_b32_e32 v31, v6
	v_pk_add_f32 v[30:31], v[30:31], v[34:35] neg_lo:[0,1] neg_hi:[0,1]
	v_mov_b32_e32 v34, v25
	v_mov_b32_e32 v35, v7
	v_mov_b32_e32 v7, v25
	v_pk_add_f32 v[34:35], v[34:35], v[36:37] neg_lo:[0,1] neg_hi:[0,1]
	v_pk_add_f32 v[6:7], v[6:7], v[32:33] neg_lo:[0,1] neg_hi:[0,1]
	v_pk_mul_f32 v[24:25], v[34:35], s[0:1]
	v_pk_mul_f32 v[6:7], v[6:7], s[16:17]
	v_mov_b32_e32 v3, v15
	v_pk_fma_f32 v[6:7], v[12:13], s[16:17], v[6:7] neg_lo:[0,0,1] neg_hi:[0,0,1]
	v_pk_fma_f32 v[12:13], v[30:31], s[0:1], v[24:25]
	v_pk_add_f32 v[24:25], v[26:27], v[42:43] neg_lo:[0,1] neg_hi:[0,1]
	v_mov_b32_e32 v28, v4
	v_pk_mul_f32 v[26:27], v[24:25], s[4:5] op_sel_hi:[1,0]
	v_pk_add_f32 v[30:31], v[2:3], v[10:11]
	v_pk_fma_f32 v[24:25], v[24:25], s[34:35], v[26:27] op_sel:[0,0,1] op_sel_hi:[1,1,0] neg_lo:[0,0,1] neg_hi:[0,0,1]
	v_pk_add_f32 v[26:27], v[0:1], v[8:9]
	v_pk_add_f32 v[32:33], v[12:13], v[6:7]
	v_pk_add_f32 v[34:35], v[28:29], v[24:25]
	v_pk_add_f32 v[36:37], v[26:27], v[32:33]
	v_pk_add_f32 v[38:39], v[30:31], v[34:35]
	v_pk_add_f32 v[26:27], v[26:27], v[32:33] neg_lo:[0,1] neg_hi:[0,1]
	v_pk_add_f32 v[40:41], v[36:37], v[38:39]
	v_pk_add_f32 v[36:37], v[36:37], v[38:39] neg_lo:[0,1] neg_hi:[0,1]
	v_pk_mov_b32 v[40:41], v[40:41], v[40:41] op_sel:[1,0]
	v_pk_mul_f32 v[38:39], v[36:37], 0 op_sel_hi:[1,0]
	v_cvt_pk_f16_f32 v3, v40, v41
	v_pk_add_f32 v[40:41], v[36:37], v[38:39] op_sel:[0,1] op_sel_hi:[1,0] neg_lo:[0,1] neg_hi:[0,1]
	v_pk_add_f32 v[36:37], v[36:37], v[38:39] op_sel:[0,1] op_sel_hi:[1,0]
	v_pk_mul_f32 v[32:33], v[26:27], 0 op_sel_hi:[1,0]
	v_pk_mov_b32 v[36:37], v[40:41], v[36:37] op_sel:[1,0]
	v_pk_add_f32 v[30:31], v[30:31], v[34:35] neg_lo:[0,1] neg_hi:[0,1]
	v_cvt_pk_f16_f32 v28, v36, v37
	v_pk_add_f32 v[36:37], v[26:27], v[32:33] op_sel:[0,1] op_sel_hi:[1,0] neg_lo:[0,1] neg_hi:[0,1]
	v_pk_add_f32 v[26:27], v[26:27], v[32:33] op_sel:[0,1] op_sel_hi:[1,0]
	v_pk_mul_f32 v[32:33], v[30:31], 0 op_sel_hi:[1,0]
	v_pk_mov_b32 v[26:27], v[36:37], v[26:27] op_sel:[1,0]
	v_pk_add_f32 v[34:35], v[32:33], v[30:31] op_sel:[1,0] op_sel_hi:[0,1]
	v_pk_add_f32 v[30:31], v[32:33], v[30:31] op_sel:[1,0] op_sel_hi:[0,1] neg_lo:[0,1] neg_hi:[0,1]
	v_mov_b32_e32 v35, v31
	v_pk_add_f32 v[30:31], v[26:27], v[34:35]
	v_pk_add_f32 v[26:27], v[26:27], v[34:35] neg_lo:[0,1] neg_hi:[0,1]
	ds_write2_b32 v70, v3, v28 offset0:8 offset1:9
	v_cvt_pk_f16_f32 v3, v30, v31
	v_pk_mul_f32 v[30:31], v[26:27], 0 op_sel_hi:[1,0]
	v_pk_add_f32 v[0:1], v[0:1], v[8:9] neg_lo:[0,1] neg_hi:[0,1]
	v_pk_add_f32 v[32:33], v[26:27], v[30:31] op_sel:[0,1] op_sel_hi:[1,0] neg_lo:[0,1] neg_hi:[0,1]
	v_pk_add_f32 v[26:27], v[26:27], v[30:31] op_sel:[0,1] op_sel_hi:[1,0]
	v_pk_mul_f32 v[8:9], v[0:1], 0 op_sel_hi:[1,0]
	v_cvt_pk_f16_f32 v26, v32, v27
	ds_write2_b32 v70, v3, v26 offset0:10 offset1:11
	v_pk_add_f32 v[26:27], v[0:1], v[8:9] op_sel:[0,1] op_sel_hi:[1,0] neg_lo:[0,1] neg_hi:[0,1]
	v_pk_add_f32 v[0:1], v[0:1], v[8:9] op_sel:[0,1] op_sel_hi:[1,0]
	v_pk_mov_b32 v[8:9], v[12:13], v[6:7] op_sel:[1,0]
	v_pk_mov_b32 v[6:7], v[6:7], v[12:13] op_sel:[1,0]
	v_mov_b32_e32 v3, v29
	v_pk_add_f32 v[6:7], v[8:9], v[6:7] neg_lo:[0,1] neg_hi:[0,1]
	v_pk_mov_b32 v[4:5], v[14:15], v[4:5] op_sel:[1,0]
	v_pk_fma_f32 v[8:9], v[6:7], 0, v[6:7] op_sel:[0,0,1] op_sel_hi:[1,0,0]
	v_pk_fma_f32 v[6:7], v[6:7], 0, v[6:7] op_sel:[0,0,1] op_sel_hi:[1,0,0] neg_lo:[0,0,1] neg_hi:[0,0,1]
	v_pk_mov_b32 v[0:1], v[26:27], v[0:1] op_sel:[1,0]
	v_mov_b32_e32 v9, v7
; __device__ __forceinline__ void make_spec(ldsf2 buf, LAS unsigned* spec, const float* __restrict__ kfrow) {
;     ...
;     for (int m = 0; m < 16; ++m) { h2_t hv; hv.x = (_Float16)x[m].x; hv.y = (_Float16)x[m].y; spec[tid * 17 + m] = __builtin_bit_cast(unsigned, hv); }
;     lds_barrier();
; }
; __device__ __forceinline__ void fft_conv(ldsf2 buf, const LAS unsigned* spec) {
;     fft_fwd_abc(buf);
;     { const int tid = otid(); cf x[16];
; #pragma unroll
;       for (int m = 0; m < 16; ++m) { const v2f v = buf[tid * 17 + m]; x[m] = cf{v.x, v.y}; }
;       dif_reg<4>(x, cf{1.0f, 0.0f});
; #pragma unroll
;       for (int m = 0; m < 16; ++m) { const h2_t hv = __builtin_bit_cast(h2_t, spec[tid * 17 + m]); x[m] = cmul(x[m], cf{(float)hv.x, (float)hv.y}); }
;       dit_reg<4>(x, cf{1.0f, 0.0f});
; #pragma unroll
;       for (int m = 0; m < 16; ++m) buf[tid * 17 + m] = mkv2(x[m].x, x[m].y); }
;     wave_lds_fence();
;     fft_inv_cba(buf);
; }
; __device__ __forceinline__ Raw8 load_raw8(const bf16_t* __restrict__ row, int n0) {
;     Raw8 r; r.body = ntld_u4(row + n0); r.eL = row[n0 > 0 ? n0 - 1 : 0]; r.eR = row[n0 + 8 < SEQ ? n0 + 8 : SEQ - 1]; return r; }
; __device__ __forceinline__ void sconv8(const Raw8& r, int n0, float w0, float w1, float w2, float b, float (&out)[8]) {
;     float a[10]; a[0] = n0 > 0 ? bf2f(r.eL) : 0.f; a[9] = n0 + 8 < SEQ ? bf2f(r.eR) : 0.f;
;     a[1] = __uint_as_float(r.body.x << 16); a[2] = __uint_as_float(r.body.x & 0xffff0000u); a[3] = __uint_as_float(r.body.y << 16); a[4] = __uint_as_float(r.body.y & 0xffff0000u);
;     a[5] = __uint_as_float(r.body.z << 16); a[6] = __uint_as_float(r.body.z & 0xffff0000u); a[7] = __uint_as_float(r.body.w << 16); a[8] = __uint_as_float(r.body.w & 0xffff0000u);
; #pragma unroll
;     for (int k = 0; k < 8; ++k) out[k] = w0 * a[k] + w1 * a[k + 1] + w2 * a[k + 2] + b;
; }
; __device__ void ph_hyena_fft(const Params& P, int j, const bf16_t* __restrict__ projAT, const float* __restrict__ kf, bf16_t* __restrict__ yaT, unsigned char* lds_raw) {
;     const int tid = otid();
;     ldsf2 buf = (ldsf2)lds_raw; LAS unsigned* spec1 = (LAS unsigned*)(lds_raw + 69632); LAS unsigned* spec2 = spec1 + 8704;
;     const float* cw = P.in[6] + (size_t)j * 3 * 3072; const float* cb = P.in[7] + (size_t)j * 3072; const float* skip = P.in[16] + (size_t)j * 2 * 1024;
;     const float invN = 1.0f / 8192.0f;
	v_mov_b32_e32 v6, v10
	v_mov_b32_e32 v7, v25
	v_pk_add_f32 v[2:3], v[2:3], v[6:7] neg_lo:[0,1] neg_hi:[0,1]
	v_pk_mov_b32 v[6:7], v[10:11], v[24:25] op_sel:[1,0]
	v_pk_mul_f32 v[2:3], v[2:3], s[16:17]
	v_pk_add_f32 v[4:5], v[4:5], v[6:7] neg_lo:[0,1] neg_hi:[0,1]
	s_lshl_b64 s[0:1], s[46:47], 2
	v_pk_fma_f32 v[6:7], v[4:5], s[16:17], v[2:3] neg_lo:[1,0,0] neg_hi:[1,0,0]
	v_pk_fma_f32 v[2:3], v[4:5], s[16:17], v[2:3]
	v_pk_mov_b32 v[10:11], v[6:7], v[6:7] op_sel:[1,0]
	v_pk_add_f32 v[4:5], v[0:1], v[8:9]
	v_pk_add_f32 v[6:7], v[2:3], v[6:7] op_sel:[0,1] op_sel_hi:[1,0]
	v_pk_add_f32 v[0:1], v[0:1], v[8:9] neg_lo:[0,1] neg_hi:[0,1]
	v_pk_add_f32 v[12:13], v[4:5], v[6:7]
	v_pk_add_f32 v[4:5], v[4:5], v[6:7] neg_lo:[0,1] neg_hi:[0,1]
	v_cvt_pk_f16_f32 v14, v12, v13
	v_pk_mul_f32 v[6:7], v[4:5], 0 op_sel_hi:[1,0]
	s_add_u32 s14, s38, s0
	v_pk_add_f32 v[12:13], v[4:5], v[6:7] op_sel:[0,1] op_sel_hi:[1,0] neg_lo:[0,1] neg_hi:[0,1]
	v_pk_add_f32 v[4:5], v[4:5], v[6:7] op_sel:[0,1] op_sel_hi:[1,0]
	s_addc_u32 s15, s39, s1
	v_cvt_pk_f16_f32 v4, v12, v5
	ds_write2_b32 v70, v14, v4 offset0:12 offset1:13
	v_pk_mul_f32 v[4:5], v[0:1], 0 op_sel_hi:[1,0]
	s_lshl_b64 s[10:11], s[46:47], 16
	v_pk_add_f32 v[6:7], v[0:1], v[4:5] op_sel:[0,1] op_sel_hi:[1,0] neg_lo:[0,1] neg_hi:[0,1]
	v_pk_add_f32 v[0:1], v[0:1], v[4:5] op_sel:[0,1] op_sel_hi:[1,0]
	s_add_u32 s26, s54, s0
	v_mov_b32_e32 v7, v1
	v_mov_b32_e32 v0, v2
	v_mov_b32_e32 v1, v11
	v_mov_b32_e32 v11, v3
	v_pk_add_f32 v[0:1], v[0:1], v[10:11] neg_lo:[0,1] neg_hi:[0,1]
	s_addc_u32 s27, s55, s1
	v_pk_fma_f32 v[2:3], v[0:1], 0, v[0:1] op_sel:[0,0,1] op_sel_hi:[1,0,0]
	v_pk_fma_f32 v[0:1], v[0:1], 0, v[0:1] op_sel:[0,0,1] op_sel_hi:[1,0,0] neg_lo:[0,0,1] neg_hi:[0,0,1]
	s_add_u32 s0, s56, s0
	v_mov_b32_e32 v3, v1
	v_pk_add_f32 v[0:1], v[6:7], v[2:3]
	s_addc_u32 s1, s57, s1
	v_cvt_pk_f16_f32 v8, v0, v1
	v_pk_add_f32 v[0:1], v[6:7], v[2:3] neg_lo:[0,1] neg_hi:[0,1]
	s_nop 0
	v_pk_mul_f32 v[2:3], v[0:1], 0 op_sel_hi:[1,0]
	s_nop 0
	v_pk_add_f32 v[4:5], v[0:1], v[2:3] op_sel:[0,1] op_sel_hi:[1,0] neg_lo:[0,1] neg_hi:[0,1]
	v_pk_add_f32 v[0:1], v[0:1], v[2:3] op_sel:[0,1] op_sel_hi:[1,0]
	s_nop 0
	v_cvt_pk_f16_f32 v0, v4, v1
	ds_write2_b32 v70, v8, v0 offset0:14 offset1:15
	s_waitcnt lgkmcnt(0)
	s_barrier
	v_mov_b32_e32 v0, 0x3000
	global_load_dword v25, v193, s[14:15]
	global_load_dword v24, v0, s[14:15]
	v_mov_b32_e32 v0, 0x6000
	global_load_dword v26, v0, s[14:15]
	v_mov_b32_e32 v0, 0x7000
	global_load_dword v28, v193, s[26:27]
	global_load_dword v30, v231, s[14:15]
	global_load_dword v32, v230, s[14:15]
	global_load_dword v34, v0, s[14:15]
	global_load_dword v36, v231, s[26:27]
	global_load_dword v39, v238, s[14:15]
	v_mov_b32_e32 v0, 0x5000
	global_load_dword v38, v0, s[14:15]
	v_mov_b32_e32 v0, 0x8000
	global_load_dword v40, v0, s[14:15]
	global_load_dword v42, v238, s[26:27]
	global_load_dword v44, v193, s[0:1]
	global_load_dword v46, v231, s[0:1]
	s_lshl_b64 s[0:1], s[6:7], 1
	v_readlane_b32 s14, v252, 36
	v_readlane_b32 s15, v252, 37
	s_add_u32 s47, s14, s0
	s_addc_u32 s58, s15, s1
	s_lshl_b64 s[6:7], s[30:31], 16
	s_add_u32 s59, s14, s6
	s_addc_u32 s60, s15, s7
	s_add_u32 s6, s14, s10
	s_addc_u32 s7, s15, s11
	s_add_u32 s61, s6, 0x8000000
	s_addc_u32 s52, s7, 0
	v_lshl_add_u64 v[0:1], v[18:19], 0, s[10:11]
	s_mov_b64 s[6:7], 0xc000000
	v_lshl_add_u64 v[48:49], v[0:1], 0, s[6:7]
	v_lshl_add_u64 v[50:51], v[20:21], 0, s[0:1]
	s_waitcnt vmcnt(13)
	v_mov_b32_e32 v58, v25
	v_mov_b32_e32 v59, v25
	s_waitcnt vmcnt(12)
	v_mov_b32_e32 v60, v24
	s_waitcnt vmcnt(10)
	v_mov_b32_e32 v29, v28
	v_mov_b32_e32 v27, v26
	s_waitcnt vmcnt(6)
	v_mov_b32_e32 v37, v36
	s_waitcnt vmcnt(5)
	v_mov_b32_e32 v52, v39
	v_mov_b32_e32 v53, v39
	s_waitcnt vmcnt(4)
	v_mov_b32_e32 v54, v38
	s_waitcnt vmcnt(3)
	v_mov_b32_e32 v41, v40
	s_waitcnt vmcnt(2)
	v_mov_b32_e32 v43, v42
	s_waitcnt vmcnt(0)
	v_mov_b32_e32 v47, v46
	v_mov_b32_e32 v55, v38
	v_mov_b32_e32 v45, v44
	v_mov_b32_e32 v35, v34
	v_mov_b32_e32 v31, v30
	v_mov_b32_e32 v33, v32
	v_mov_b32_e32 v56, v32
	v_mov_b32_e32 v57, v30
	v_mov_b32_e32 v61, v24
	v_and_b32_e32 v250, 15, v195
	v_lshlrev_b32_e32 v250, 9, v250
	v_add_u32_e32 v250, 0x22000, v250
	ds_read_b64 v[204:205], v250
	v_and_b32_e32 v251, 63, v195
	v_lshlrev_b32_e32 v251, 6, v251
	v_add_u32_e32 v251, 0x22000, v251
	ds_read_b64 v[214:215], v251
	ds_read_b64 v[220:221], v251 offset:4096
	v_lshlrev_b32_e32 v250, 3, v195
	v_add_u32_e32 v250, 0x22000, v250
	ds_read_b64 v[232:233], v250
	ds_read_b64 v[240:241], v250 offset:4096
	s_waitcnt lgkmcnt(0)
	v_pk_mul_f32 v[206:207], v[204:205], v[204:205] op_sel:[1,1] op_sel_hi:[1,0]
	v_pk_mul_f32 v[216:217], v[214:215], v[214:215] op_sel:[1,1] op_sel_hi:[1,0]
	v_pk_mul_f32 v[222:223], v[220:221], v[220:221] op_sel:[1,1] op_sel_hi:[1,0]
	v_pk_mul_f32 v[234:235], v[232:233], v[232:233] op_sel:[1,1] op_sel_hi:[1,0]
	v_pk_mul_f32 v[242:243], v[240:241], v[240:241] op_sel:[1,1] op_sel_hi:[1,0]
	v_pk_fma_f32 v[206:207], v[204:205], v[204:205], v[206:207] op_sel:[0,0,0] op_sel_hi:[0,1,1] neg_lo:[0,0,1] neg_hi:[0,0,0]
	v_pk_fma_f32 v[216:217], v[214:215], v[214:215], v[216:217] op_sel:[0,0,0] op_sel_hi:[0,1,1] neg_lo:[0,0,1] neg_hi:[0,0,0]
	v_pk_fma_f32 v[222:223], v[220:221], v[220:221], v[222:223] op_sel:[0,0,0] op_sel_hi:[0,1,1] neg_lo:[0,0,1] neg_hi:[0,0,0]
	v_pk_fma_f32 v[234:235], v[232:233], v[232:233], v[234:235] op_sel:[0,0,0] op_sel_hi:[0,1,1] neg_lo:[0,0,1] neg_hi:[0,0,0]
	v_pk_fma_f32 v[242:243], v[240:241], v[240:241], v[242:243] op_sel:[0,0,0] op_sel_hi:[0,1,1] neg_lo:[0,0,1] neg_hi:[0,0,0]
	v_pk_mul_f32 v[208:209], v[206:207], v[206:207] op_sel:[1,1] op_sel_hi:[1,0]
	v_pk_mul_f32 v[218:219], v[216:217], v[216:217] op_sel:[1,1] op_sel_hi:[1,0]
	v_pk_mul_f32 v[224:225], v[222:223], v[222:223] op_sel:[1,1] op_sel_hi:[1,0]
	v_pk_mul_f32 v[236:237], v[234:235], v[234:235] op_sel:[1,1] op_sel_hi:[1,0]
	v_pk_mul_f32 v[244:245], v[242:243], v[242:243] op_sel:[1,1] op_sel_hi:[1,0]
	v_pk_fma_f32 v[208:209], v[206:207], v[206:207], v[208:209] op_sel:[0,0,0] op_sel_hi:[0,1,1] neg_lo:[0,0,1] neg_hi:[0,0,0]
	v_pk_fma_f32 v[218:219], v[216:217], v[216:217], v[218:219] op_sel:[0,0,0] op_sel_hi:[0,1,1] neg_lo:[0,0,1] neg_hi:[0,0,0]
	v_pk_fma_f32 v[224:225], v[222:223], v[222:223], v[224:225] op_sel:[0,0,0] op_sel_hi:[0,1,1] neg_lo:[0,0,1] neg_hi:[0,0,0]
	v_pk_fma_f32 v[236:237], v[234:235], v[234:235], v[236:237] op_sel:[0,0,0] op_sel_hi:[0,1,1] neg_lo:[0,0,1] neg_hi:[0,0,0]
	v_pk_fma_f32 v[244:245], v[242:243], v[242:243], v[244:245] op_sel:[0,0,0] op_sel_hi:[0,1,1] neg_lo:[0,0,1] neg_hi:[0,0,0]
	v_pk_add_f32 v[250:251], v[204:205], v[204:205] op_sel:[0,1] op_sel_hi:[1,0] neg_lo:[0,0] neg_hi:[0,1]
	s_nop 0
	v_pk_mul_f32 v[210:211], v[250:251], s[16:17] op_sel:[0,0] op_sel_hi:[1,0]
	v_pk_mul_f32 v[212:213], v[250:251], s[16:17] op_sel:[1,0] op_sel_hi:[0,0] neg_lo:[0,0] neg_hi:[1,0]

; #define LAS __attribute__((address_space(3)))
; __device__ __forceinline__ int otid() { int t = threadIdx.x; asm volatile("" : "+v"(t)); return t; }
; __device__ __forceinline__ cf twc(cf ws, int k16) { if (k16 == 0) return ws; if (k16 == 4) return cf{ws.y, -ws.x}; return cmul(ws, cf{c16(k16), -s16(k16)}); }
; template <int LR> __device__ __forceinline__ void dif_reg(cf (&x)[1 << LR], cf w) {
;     constexpr int R = 1 << LR; cf ws = w;
; #pragma unroll
;     for (int s = 0; s < LR; ++s) { const int half = R >> (s + 1);
; #pragma unroll
;         for (int m0 = 0; m0 < R; m0 += 2 * half)
; #pragma unroll
;             for (int mm = 0; mm < half; ++mm) { const int ia = m0 + mm, ib = ia + half; const cf a = x[ia], b = x[ib];
;                 x[ia] = cf{a.x + b.x, a.y + b.y}; const cf d{a.x - b.x, a.y - b.y};
;                 x[ib] = cmul(d, twc(ws, (mm << s) * (16 / R))); }
;         ws = cmul(ws, ws); }
; }
; template <int LR, bool INV> __device__ __forceinline__ void fft_pass(ldsf2 buf, int base, int stride, int twi) {
;     constexpr int R = 1 << LR; cf x[R];
;     const v2f wv = ((ldsf2)((LAS unsigned char*)buf + 139264))[twi];
; #pragma unroll
;     for (int m = 0; m < R; ++m) { const v2f v = buf[base + m * stride]; x[m] = cf{v.x, v.y}; }
;     const cf w{wv.x, wv.y};
;     if (INV) dit_reg<LR>(x, w); else dif_reg<LR>(x, w);
; #pragma unroll
;     for (int m = 0; m < R; ++m) buf[base + m * stride] = mkv2(x[m].x, x[m].y);
; }
; __device__ __forceinline__ void wave_lds_fence() { asm volatile("s_waitcnt lgkmcnt(0)" ::: "memory"); }
; __device__ __forceinline__ void fft_fwd_abc(ldsf2 buf) {
;     const int tid = otid(); const int wv = tid >> 6, l = tid & 63;
; #pragma unroll 1
;     for (int u = 0; u < 2; ++u) { const int bf = tid + NT * u; fft_pass<3, false>(buf, bf + (bf >> 4), 1088, bf); }
.LBB0_347:
	v_add_u32_e32 v72, s0, v68
	v_ashrrev_i32_e32 v69, 4, v72
	v_lshl_add_u32 v72, v72, 3, 0
	v_add_u32_e32 v73, 0x22000, v72
	v_lshl_add_u32 v69, v69, 3, v72
	ds_read2st64_b64 v[72:75], v69 offset1:17
	ds_read2st64_b64 v[76:79], v69 offset0:68 offset1:85
	ds_read2st64_b64 v[80:83], v69 offset0:34 offset1:51
	ds_read2st64_b64 v[84:87], v69 offset0:102 offset1:119
	s_movk_i32 s0, 0x200
	v_add_u32_e32 v112, s0, v68
	v_ashrrev_i32_e32 v114, 4, v112
	v_lshl_add_u32 v112, v112, 3, 0
	v_add_u32_e32 v116, 0x22000, v112
	v_lshl_add_u32 v114, v114, 3, v112
	ds_read2st64_b64 v[120:123], v114 offset1:17
	ds_read2st64_b64 v[124:127], v114 offset0:68 offset1:85
	ds_read2st64_b64 v[128:131], v114 offset0:34 offset1:51
	ds_read2st64_b64 v[132:135], v114 offset0:102 offset1:119
	s_waitcnt lgkmcnt(4)
	v_pk_add_f32 v[90:91], v[232:233], v[232:233] op_sel:[0,1] op_sel_hi:[1,0] neg_lo:[0,0] neg_hi:[0,1]
	s_nop 0
	v_pk_mul_f32 v[92:93], v[90:91], s[16:17] op_sel:[0,0] op_sel_hi:[1,0]
	v_pk_mul_f32 v[94:95], v[90:91], s[16:17] op_sel:[1,0] op_sel_hi:[0,0] neg_lo:[0,0] neg_hi:[1,0]
	v_pk_add_f32 v[100:101], v[72:73], v[76:77] neg_lo:[0,1] neg_hi:[0,1]
	v_pk_add_f32 v[102:103], v[74:75], v[78:79] neg_lo:[0,1] neg_hi:[0,1]
	v_pk_add_f32 v[104:105], v[80:81], v[84:85] neg_lo:[0,1] neg_hi:[0,1]
	v_pk_add_f32 v[106:107], v[82:83], v[86:87] neg_lo:[0,1] neg_hi:[0,1]
	v_pk_add_f32 v[72:73], v[72:73], v[76:77]
	v_pk_add_f32 v[74:75], v[74:75], v[78:79]
	v_pk_add_f32 v[80:81], v[80:81], v[84:85]
	v_pk_add_f32 v[82:83], v[82:83], v[86:87]
	v_pk_mul_f32 v[76:77], v[100:101], v[232:233] op_sel:[1,1] op_sel_hi:[1,0]
	v_pk_mul_f32 v[78:79], v[102:103], v[92:93] op_sel:[1,1] op_sel_hi:[1,0]
	v_pk_mul_f32 v[84:85], v[104:105], v[232:233] op_sel:[1,0] op_sel_hi:[1,1]
	v_pk_mul_f32 v[86:87], v[106:107], v[94:95] op_sel:[1,1] op_sel_hi:[1,0]
	v_pk_fma_f32 v[76:77], v[100:101], v[232:233], v[76:77] op_sel:[0,0,0] op_sel_hi:[0,1,1] neg_lo:[0,0,1] neg_hi:[0,0,0]
	v_pk_fma_f32 v[78:79], v[102:103], v[92:93], v[78:79] op_sel:[0,0,0] op_sel_hi:[0,1,1] neg_lo:[0,0,1] neg_hi:[0,0,0]
	v_pk_fma_f32 v[84:85], v[104:105], v[232:233], v[84:85] op_sel:[0,1,0] op_sel_hi:[0,0,1] neg_lo:[0,0,0] neg_hi:[0,1,0]
	v_pk_fma_f32 v[86:87], v[106:107], v[94:95], v[86:87] op_sel:[0,0,0] op_sel_hi:[0,1,1] neg_lo:[0,0,1] neg_hi:[0,0,0]
	v_pk_add_f32 v[100:101], v[72:73], v[80:81] neg_lo:[0,1] neg_hi:[0,1]
	v_pk_add_f32 v[102:103], v[74:75], v[82:83] neg_lo:[0,1] neg_hi:[0,1]
	v_pk_add_f32 v[104:105], v[76:77], v[84:85] neg_lo:[0,1] neg_hi:[0,1]
	v_pk_add_f32 v[106:107], v[78:79], v[86:87] neg_lo:[0,1] neg_hi:[0,1]
	v_pk_add_f32 v[72:73], v[72:73], v[80:81]
	v_pk_add_f32 v[74:75], v[74:75], v[82:83]
	v_pk_add_f32 v[76:77], v[76:77], v[84:85]
	v_pk_add_f32 v[78:79], v[78:79], v[86:87]
	v_pk_mul_f32 v[80:81], v[100:101], v[234:235] op_sel:[1,1] op_sel_hi:[1,0]
	v_pk_mul_f32 v[82:83], v[102:103], v[234:235] op_sel:[1,0] op_sel_hi:[1,1]
	v_pk_mul_f32 v[84:85], v[104:105], v[234:235] op_sel:[1,1] op_sel_hi:[1,0]
	v_pk_mul_f32 v[86:87], v[106:107], v[234:235] op_sel:[1,0] op_sel_hi:[1,1]
	v_pk_fma_f32 v[80:81], v[100:101], v[234:235], v[80:81] op_sel:[0,0,0] op_sel_hi:[0,1,1] neg_lo:[0,0,1] neg_hi:[0,0,0]
	v_pk_fma_f32 v[82:83], v[102:103], v[234:235], v[82:83] op_sel:[0,1,0] op_sel_hi:[0,0,1] neg_lo:[0,0,0] neg_hi:[0,1,0]
	v_pk_fma_f32 v[84:85], v[104:105], v[234:235], v[84:85] op_sel:[0,0,0] op_sel_hi:[0,1,1] neg_lo:[0,0,1] neg_hi:[0,0,0]
	v_pk_fma_f32 v[86:87], v[106:107], v[234:235], v[86:87] op_sel:[0,1,0] op_sel_hi:[0,0,1] neg_lo:[0,0,0] neg_hi:[0,1,0]
	v_pk_add_f32 v[100:101], v[72:73], v[74:75] neg_lo:[0,1] neg_hi:[0,1]
	v_pk_add_f32 v[102:103], v[80:81], v[82:83] neg_lo:[0,1] neg_hi:[0,1]
	v_pk_add_f32 v[104:105], v[76:77], v[78:79] neg_lo:[0,1] neg_hi:[0,1]
	v_pk_add_f32 v[106:107], v[84:85], v[86:87] neg_lo:[0,1] neg_hi:[0,1]
	v_pk_add_f32 v[72:73], v[72:73], v[74:75]
	v_pk_add_f32 v[80:81], v[80:81], v[82:83]
	v_pk_add_f32 v[76:77], v[76:77], v[78:79]
	v_pk_add_f32 v[84:85], v[84:85], v[86:87]
	v_pk_mul_f32 v[74:75], v[100:101], v[236:237] op_sel:[1,1] op_sel_hi:[1,0]
	v_pk_mul_f32 v[82:83], v[102:103], v[236:237] op_sel:[1,1] op_sel_hi:[1,0]
	v_pk_mul_f32 v[78:79], v[104:105], v[236:237] op_sel:[1,1] op_sel_hi:[1,0]
	v_pk_mul_f32 v[86:87], v[106:107], v[236:237] op_sel:[1,1] op_sel_hi:[1,0]
	v_pk_fma_f32 v[74:75], v[100:101], v[236:237], v[74:75] op_sel:[0,0,0] op_sel_hi:[0,1,1] neg_lo:[0,0,1] neg_hi:[0,0,0]
	v_pk_fma_f32 v[82:83], v[102:103], v[236:237], v[82:83] op_sel:[0,0,0] op_sel_hi:[0,1,1] neg_lo:[0,0,1] neg_hi:[0,0,0]
	v_pk_fma_f32 v[78:79], v[104:105], v[236:237], v[78:79] op_sel:[0,0,0] op_sel_hi:[0,1,1] neg_lo:[0,0,1] neg_hi:[0,0,0]
	v_pk_fma_f32 v[86:87], v[106:107], v[236:237], v[86:87] op_sel:[0,0,0] op_sel_hi:[0,1,1] neg_lo:[0,0,1] neg_hi:[0,0,0]
	ds_write2st64_b64 v69, v[72:73], v[74:75] offset1:17
	ds_write2st64_b64 v69, v[80:81], v[82:83] offset0:34 offset1:51
	ds_write2st64_b64 v69, v[76:77], v[78:79] offset0:68 offset1:85
	ds_write2st64_b64 v69, v[84:85], v[86:87] offset0:102 offset1:119
	s_waitcnt lgkmcnt(4)
; #define LAS __attribute__((address_space(3)))
; __device__ __forceinline__ int otid() { int t = threadIdx.x; asm volatile("" : "+v"(t)); return t; }
; __device__ __forceinline__ cf twc(cf ws, int k16) { if (k16 == 0) return ws; if (k16 == 4) return cf{ws.y, -ws.x}; return cmul(ws, cf{c16(k16), -s16(k16)}); }
; __device__ __forceinline__ void lds_barrier() { asm volatile("s_waitcnt lgkmcnt(0)\n\ts_barrier" ::: "memory"); }
; template <int LR> __device__ __forceinline__ void dif_reg(cf (&x)[1 << LR], cf w) {
;     constexpr int R = 1 << LR; cf ws = w;
; #pragma unroll
;     for (int s = 0; s < LR; ++s) { const int half = R >> (s + 1);
; #pragma unroll
;         for (int m0 = 0; m0 < R; m0 += 2 * half)
; #pragma unroll
;             for (int mm = 0; mm < half; ++mm) { const int ia = m0 + mm, ib = ia + half; const cf a = x[ia], b = x[ib];
;                 x[ia] = cf{a.x + b.x, a.y + b.y}; const cf d{a.x - b.x, a.y - b.y};
;                 x[ib] = cmul(d, twc(ws, (mm << s) * (16 / R))); }
;         ws = cmul(ws, ws); }
; }
; template <int LR, bool INV> __device__ __forceinline__ void fft_pass(ldsf2 buf, int base, int stride, int twi) {
;     constexpr int R = 1 << LR; cf x[R];
;     const v2f wv = ((ldsf2)((LAS unsigned char*)buf + 139264))[twi];
; #pragma unroll
;     for (int m = 0; m < R; ++m) { const v2f v = buf[base + m * stride]; x[m] = cf{v.x, v.y}; }
;     const cf w{wv.x, wv.y};
;     if (INV) dit_reg<LR>(x, w); else dif_reg<LR>(x, w);
; #pragma unroll
;     for (int m = 0; m < R; ++m) buf[base + m * stride] = mkv2(x[m].x, x[m].y);
; }
; __device__ __forceinline__ void wave_lds_fence() { asm volatile("s_waitcnt lgkmcnt(0)" ::: "memory"); }
; __device__ __forceinline__ void fft_fwd_abc(ldsf2 buf) {
;     const int tid = otid(); const int wv = tid >> 6, l = tid & 63;
; #pragma unroll 1
;     for (int u = 0; u < 2; ++u) { const int bf = tid + NT * u; fft_pass<3, false>(buf, bf + (bf >> 4), 1088, bf); }
;     lds_barrier();
; #pragma unroll 1
;     for (int u = 0; u < 2; ++u) { const int o = l + 64 * u, e0 = wv * 1024 + o; fft_pass<3, false>(buf, e0 + (e0 >> 4), 136, o * 8); }
	v_pk_add_f32 v[148:149], v[240:241], v[240:241] op_sel:[0,1] op_sel_hi:[1,0] neg_lo:[0,0] neg_hi:[0,1]
	s_nop 0
	v_pk_mul_f32 v[150:151], v[148:149], s[16:17] op_sel:[0,0] op_sel_hi:[1,0]
	v_pk_mul_f32 v[152:153], v[148:149], s[16:17] op_sel:[1,0] op_sel_hi:[0,0] neg_lo:[0,0] neg_hi:[1,0]
	v_pk_add_f32 v[158:159], v[120:121], v[124:125] neg_lo:[0,1] neg_hi:[0,1]
	v_pk_add_f32 v[160:161], v[122:123], v[126:127] neg_lo:[0,1] neg_hi:[0,1]
	v_pk_add_f32 v[162:163], v[128:129], v[132:133] neg_lo:[0,1] neg_hi:[0,1]
	v_pk_add_f32 v[164:165], v[130:131], v[134:135] neg_lo:[0,1] neg_hi:[0,1]
	v_pk_add_f32 v[120:121], v[120:121], v[124:125]
	v_pk_add_f32 v[122:123], v[122:123], v[126:127]
	v_pk_add_f32 v[128:129], v[128:129], v[132:133]
	v_pk_add_f32 v[130:131], v[130:131], v[134:135]
	v_pk_mul_f32 v[124:125], v[158:159], v[240:241] op_sel:[1,1] op_sel_hi:[1,0]
	v_pk_mul_f32 v[126:127], v[160:161], v[150:151] op_sel:[1,1] op_sel_hi:[1,0]
	v_pk_mul_f32 v[132:133], v[162:163], v[240:241] op_sel:[1,0] op_sel_hi:[1,1]
	v_pk_mul_f32 v[134:135], v[164:165], v[152:153] op_sel:[1,1] op_sel_hi:[1,0]
	v_pk_fma_f32 v[124:125], v[158:159], v[240:241], v[124:125] op_sel:[0,0,0] op_sel_hi:[0,1,1] neg_lo:[0,0,1] neg_hi:[0,0,0]
	v_pk_fma_f32 v[126:127], v[160:161], v[150:151], v[126:127] op_sel:[0,0,0] op_sel_hi:[0,1,1] neg_lo:[0,0,1] neg_hi:[0,0,0]
	v_pk_fma_f32 v[132:133], v[162:163], v[240:241], v[132:133] op_sel:[0,1,0] op_sel_hi:[0,0,1] neg_lo:[0,0,0] neg_hi:[0,1,0]
	v_pk_fma_f32 v[134:135], v[164:165], v[152:153], v[134:135] op_sel:[0,0,0] op_sel_hi:[0,1,1] neg_lo:[0,0,1] neg_hi:[0,0,0]
	v_pk_add_f32 v[158:159], v[120:121], v[128:129] neg_lo:[0,1] neg_hi:[0,1]
	v_pk_add_f32 v[160:161], v[122:123], v[130:131] neg_lo:[0,1] neg_hi:[0,1]
	v_pk_add_f32 v[162:163], v[124:125], v[132:133] neg_lo:[0,1] neg_hi:[0,1]
	v_pk_add_f32 v[164:165], v[126:127], v[134:135] neg_lo:[0,1] neg_hi:[0,1]
	v_pk_add_f32 v[120:121], v[120:121], v[128:129]
	v_pk_add_f32 v[122:123], v[122:123], v[130:131]
	v_pk_add_f32 v[124:125], v[124:125], v[132:133]
	v_pk_add_f32 v[126:127], v[126:127], v[134:135]
	v_pk_mul_f32 v[128:129], v[158:159], v[242:243] op_sel:[1,1] op_sel_hi:[1,0]
	v_pk_mul_f32 v[130:131], v[160:161], v[242:243] op_sel:[1,0] op_sel_hi:[1,1]
	v_pk_mul_f32 v[132:133], v[162:163], v[242:243] op_sel:[1,1] op_sel_hi:[1,0]
	v_pk_mul_f32 v[134:135], v[164:165], v[242:243] op_sel:[1,0] op_sel_hi:[1,1]
	v_pk_fma_f32 v[128:129], v[158:159], v[242:243], v[128:129] op_sel:[0,0,0] op_sel_hi:[0,1,1] neg_lo:[0,0,1] neg_hi:[0,0,0]
	v_pk_fma_f32 v[130:131], v[160:161], v[242:243], v[130:131] op_sel:[0,1,0] op_sel_hi:[0,0,1] neg_lo:[0,0,0] neg_hi:[0,1,0]
	v_pk_fma_f32 v[132:133], v[162:163], v[242:243], v[132:133] op_sel:[0,0,0] op_sel_hi:[0,1,1] neg_lo:[0,0,1] neg_hi:[0,0,0]
	v_pk_fma_f32 v[134:135], v[164:165], v[242:243], v[134:135] op_sel:[0,1,0] op_sel_hi:[0,0,1] neg_lo:[0,0,0] neg_hi:[0,1,0]
	v_pk_add_f32 v[158:159], v[120:121], v[122:123] neg_lo:[0,1] neg_hi:[0,1]
	v_pk_add_f32 v[160:161], v[128:129], v[130:131] neg_lo:[0,1] neg_hi:[0,1]
	v_pk_add_f32 v[162:163], v[124:125], v[126:127] neg_lo:[0,1] neg_hi:[0,1]
	v_pk_add_f32 v[164:165], v[132:133], v[134:135] neg_lo:[0,1] neg_hi:[0,1]
	v_pk_add_f32 v[120:121], v[120:121], v[122:123]
	v_pk_add_f32 v[128:129], v[128:129], v[130:131]
	v_pk_add_f32 v[124:125], v[124:125], v[126:127]
	v_pk_add_f32 v[132:133], v[132:133], v[134:135]
	v_pk_mul_f32 v[122:123], v[158:159], v[244:245] op_sel:[1,1] op_sel_hi:[1,0]
	v_pk_mul_f32 v[130:131], v[160:161], v[244:245] op_sel:[1,1] op_sel_hi:[1,0]
	v_pk_mul_f32 v[126:127], v[162:163], v[244:245] op_sel:[1,1] op_sel_hi:[1,0]
	v_pk_mul_f32 v[134:135], v[164:165], v[244:245] op_sel:[1,1] op_sel_hi:[1,0]
	v_pk_fma_f32 v[122:123], v[158:159], v[244:245], v[122:123] op_sel:[0,0,0] op_sel_hi:[0,1,1] neg_lo:[0,0,1] neg_hi:[0,0,0]
	v_pk_fma_f32 v[130:131], v[160:161], v[244:245], v[130:131] op_sel:[0,0,0] op_sel_hi:[0,1,1] neg_lo:[0,0,1] neg_hi:[0,0,0]
	v_pk_fma_f32 v[126:127], v[162:163], v[244:245], v[126:127] op_sel:[0,0,0] op_sel_hi:[0,1,1] neg_lo:[0,0,1] neg_hi:[0,0,0]
	v_pk_fma_f32 v[134:135], v[164:165], v[244:245], v[134:135] op_sel:[0,0,0] op_sel_hi:[0,1,1] neg_lo:[0,0,1] neg_hi:[0,0,0]
	ds_write2st64_b64 v114, v[120:121], v[122:123] offset1:17
	ds_write2st64_b64 v114, v[128:129], v[130:131] offset0:34 offset1:51
	ds_write2st64_b64 v114, v[124:125], v[126:127] offset0:68 offset1:85
	ds_write2st64_b64 v114, v[132:133], v[134:135] offset0:102 offset1:119
	s_mov_b64 s[6:7], 0
	s_waitcnt lgkmcnt(0)
	s_barrier
	v_lshlrev_b32_e32 v72, 4, v68
	v_and_b32_e32 v69, 63, v68
	v_and_b32_e32 v72, 0xfffffc00, v72
	s_mov_b32 s0, 0
	s_mov_b64 s[6:7], -1
; #define LAS __attribute__((address_space(3)))
; __device__ __forceinline__ int otid() { int t = threadIdx.x; asm volatile("" : "+v"(t)); return t; }
; __device__ __forceinline__ cf twc(cf ws, int k16) { if (k16 == 0) return ws; if (k16 == 4) return cf{ws.y, -ws.x}; return cmul(ws, cf{c16(k16), -s16(k16)}); }
; __device__ __forceinline__ void lds_barrier() { asm volatile("s_waitcnt lgkmcnt(0)\n\ts_barrier" ::: "memory"); }
; template <int LR> __device__ __forceinline__ void dif_reg(cf (&x)[1 << LR], cf w) {
;     constexpr int R = 1 << LR; cf ws = w;
; #pragma unroll
;     for (int s = 0; s < LR; ++s) { const int half = R >> (s + 1);
; #pragma unroll
;         for (int m0 = 0; m0 < R; m0 += 2 * half)
; #pragma unroll
;             for (int mm = 0; mm < half; ++mm) { const int ia = m0 + mm, ib = ia + half; const cf a = x[ia], b = x[ib];
;                 x[ia] = cf{a.x + b.x, a.y + b.y}; const cf d{a.x - b.x, a.y - b.y};
;                 x[ib] = cmul(d, twc(ws, (mm << s) * (16 / R))); }
;         ws = cmul(ws, ws); }
; }
; template <int LR, bool INV> __device__ __forceinline__ void fft_pass(ldsf2 buf, int base, int stride, int twi) {
;     constexpr int R = 1 << LR; cf x[R];
;     const v2f wv = ((ldsf2)((LAS unsigned char*)buf + 139264))[twi];
; #pragma unroll
;     for (int m = 0; m < R; ++m) { const v2f v = buf[base + m * stride]; x[m] = cf{v.x, v.y}; }
;     const cf w{wv.x, wv.y};
;     if (INV) dit_reg<LR>(x, w); else dif_reg<LR>(x, w);
; #pragma unroll
;     for (int m = 0; m < R; ++m) buf[base + m * stride] = mkv2(x[m].x, x[m].y);
; }
; __device__ __forceinline__ void wave_lds_fence() { asm volatile("s_waitcnt lgkmcnt(0)" ::: "memory"); }
; __device__ __forceinline__ void fft_fwd_abc(ldsf2 buf) {
;     const int tid = otid(); const int wv = tid >> 6, l = tid & 63;
; #pragma unroll 1
;     for (int u = 0; u < 2; ++u) { const int bf = tid + NT * u; fft_pass<3, false>(buf, bf + (bf >> 4), 1088, bf); }
;     lds_barrier();
; #pragma unroll 1
;     for (int u = 0; u < 2; ++u) { const int o = l + 64 * u, e0 = wv * 1024 + o; fft_pass<3, false>(buf, e0 + (e0 >> 4), 136, o * 8); }
.LBB0_349:
	v_or_b32_e32 v74, s0, v69
	v_or_b32_e32 v73, v74, v72
	v_lshl_add_u32 v74, v74, 6, 0
	v_ashrrev_i32_e32 v75, 4, v73
	v_add_u32_e32 v74, 0x22000, v74
	v_lshlrev_b32_e32 v73, 3, v73
	v_lshlrev_b32_e32 v74, 3, v75
	v_add3_u32 v73, 0, v73, v74
	v_add_u32_e32 v113, 0x800, v73
	ds_read2_b64 v[74:77], v73 offset1:136
	v_add_u32_e32 v118, 0x1000, v73
	v_add_u32_e32 v119, 0x1800, v73
	ds_read2_b64 v[78:81], v113 offset0:16 offset1:152
	ds_read2_b64 v[82:85], v118 offset0:32 offset1:168
	ds_read2_b64 v[86:89], v119 offset0:48 offset1:184
	s_mov_b32 s0, 64
	v_or_b32_e32 v120, s0, v69
	v_or_b32_e32 v122, v120, v72
	v_lshl_add_u32 v120, v120, 6, 0
	v_ashrrev_i32_e32 v124, 4, v122
	v_add_u32_e32 v120, 0x22000, v120
	v_lshlrev_b32_e32 v122, 3, v122
	v_lshlrev_b32_e32 v120, 3, v124
	v_add3_u32 v122, 0, v122, v120
	v_add_u32_e32 v128, 0x800, v122
	ds_read2_b64 v[130:133], v122 offset1:136
	v_add_u32_e32 v134, 0x1000, v122
	v_add_u32_e32 v148, 0x1800, v122
	ds_read2_b64 v[150:153], v128 offset0:16 offset1:152
	ds_read2_b64 v[154:157], v134 offset0:32 offset1:168
	ds_read2_b64 v[158:161], v148 offset0:48 offset1:184
	s_waitcnt lgkmcnt(4)
	v_pk_add_f32 v[92:93], v[214:215], v[214:215] op_sel:[0,1] op_sel_hi:[1,0] neg_lo:[0,0] neg_hi:[0,1]
	s_nop 0
	v_pk_mul_f32 v[94:95], v[92:93], s[16:17] op_sel:[0,0] op_sel_hi:[1,0]
	v_pk_mul_f32 v[96:97], v[92:93], s[16:17] op_sel:[1,0] op_sel_hi:[0,0] neg_lo:[0,0] neg_hi:[1,0]
	v_pk_add_f32 v[102:103], v[74:75], v[82:83] neg_lo:[0,1] neg_hi:[0,1]
	v_pk_add_f32 v[104:105], v[76:77], v[84:85] neg_lo:[0,1] neg_hi:[0,1]
	v_pk_add_f32 v[106:107], v[78:79], v[86:87] neg_lo:[0,1] neg_hi:[0,1]
	v_pk_add_f32 v[108:109], v[80:81], v[88:89] neg_lo:[0,1] neg_hi:[0,1]
	v_pk_add_f32 v[74:75], v[74:75], v[82:83]
	v_pk_add_f32 v[76:77], v[76:77], v[84:85]
	v_pk_add_f32 v[78:79], v[78:79], v[86:87]
	v_pk_add_f32 v[80:81], v[80:81], v[88:89]
	v_pk_mul_f32 v[82:83], v[102:103], v[214:215] op_sel:[1,1] op_sel_hi:[1,0]
	v_pk_mul_f32 v[84:85], v[104:105], v[94:95] op_sel:[1,1] op_sel_hi:[1,0]
	v_pk_mul_f32 v[86:87], v[106:107], v[214:215] op_sel:[1,0] op_sel_hi:[1,1]
	v_pk_mul_f32 v[88:89], v[108:109], v[96:97] op_sel:[1,1] op_sel_hi:[1,0]
	v_pk_fma_f32 v[82:83], v[102:103], v[214:215], v[82:83] op_sel:[0,0,0] op_sel_hi:[0,1,1] neg_lo:[0,0,1] neg_hi:[0,0,0]
	v_pk_fma_f32 v[84:85], v[104:105], v[94:95], v[84:85] op_sel:[0,0,0] op_sel_hi:[0,1,1] neg_lo:[0,0,1] neg_hi:[0,0,0]
	v_pk_fma_f32 v[86:87], v[106:107], v[214:215], v[86:87] op_sel:[0,1,0] op_sel_hi:[0,0,1] neg_lo:[0,0,0] neg_hi:[0,1,0]
	v_pk_fma_f32 v[88:89], v[108:109], v[96:97], v[88:89] op_sel:[0,0,0] op_sel_hi:[0,1,1] neg_lo:[0,0,1] neg_hi:[0,0,0]
	v_pk_add_f32 v[102:103], v[74:75], v[78:79] neg_lo:[0,1] neg_hi:[0,1]
	v_pk_add_f32 v[104:105], v[76:77], v[80:81] neg_lo:[0,1] neg_hi:[0,1]
	v_pk_add_f32 v[106:107], v[82:83], v[86:87] neg_lo:[0,1] neg_hi:[0,1]
	v_pk_add_f32 v[108:109], v[84:85], v[88:89] neg_lo:[0,1] neg_hi:[0,1]
	v_pk_add_f32 v[74:75], v[74:75], v[78:79]
	v_pk_add_f32 v[76:77], v[76:77], v[80:81]
	v_pk_add_f32 v[82:83], v[82:83], v[86:87]
	v_pk_add_f32 v[84:85], v[84:85], v[88:89]
	v_pk_mul_f32 v[78:79], v[102:103], v[216:217] op_sel:[1,1] op_sel_hi:[1,0]
	v_pk_mul_f32 v[80:81], v[104:105], v[216:217] op_sel:[1,0] op_sel_hi:[1,1]
	v_pk_mul_f32 v[86:87], v[106:107], v[216:217] op_sel:[1,1] op_sel_hi:[1,0]
	v_pk_mul_f32 v[88:89], v[108:109], v[216:217] op_sel:[1,0] op_sel_hi:[1,1]
	v_pk_fma_f32 v[78:79], v[102:103], v[216:217], v[78:79] op_sel:[0,0,0] op_sel_hi:[0,1,1] neg_lo:[0,0,1] neg_hi:[0,0,0]
	v_pk_fma_f32 v[80:81], v[104:105], v[216:217], v[80:81] op_sel:[0,1,0] op_sel_hi:[0,0,1] neg_lo:[0,0,0] neg_hi:[0,1,0]
	v_pk_fma_f32 v[86:87], v[106:107], v[216:217], v[86:87] op_sel:[0,0,0] op_sel_hi:[0,1,1] neg_lo:[0,0,1] neg_hi:[0,0,0]
	v_pk_fma_f32 v[88:89], v[108:109], v[216:217], v[88:89] op_sel:[0,1,0] op_sel_hi:[0,0,1] neg_lo:[0,0,0] neg_hi:[0,1,0]
	v_pk_add_f32 v[102:103], v[74:75], v[76:77] neg_lo:[0,1] neg_hi:[0,1]
	v_pk_add_f32 v[104:105], v[78:79], v[80:81] neg_lo:[0,1] neg_hi:[0,1]
	v_pk_add_f32 v[106:107], v[82:83], v[84:85] neg_lo:[0,1] neg_hi:[0,1]
	v_pk_add_f32 v[108:109], v[86:87], v[88:89] neg_lo:[0,1] neg_hi:[0,1]
	v_pk_add_f32 v[74:75], v[74:75], v[76:77]
	v_pk_add_f32 v[78:79], v[78:79], v[80:81]
	v_pk_add_f32 v[82:83], v[82:83], v[84:85]
	v_pk_add_f32 v[86:87], v[86:87], v[88:89]
	v_pk_mul_f32 v[76:77], v[102:103], v[218:219] op_sel:[1,1] op_sel_hi:[1,0]
	v_pk_mul_f32 v[80:81], v[104:105], v[218:219] op_sel:[1,1] op_sel_hi:[1,0]
	v_pk_mul_f32 v[84:85], v[106:107], v[218:219] op_sel:[1,1] op_sel_hi:[1,0]
	v_pk_mul_f32 v[88:89], v[108:109], v[218:219] op_sel:[1,1] op_sel_hi:[1,0]
	v_pk_fma_f32 v[76:77], v[102:103], v[218:219], v[76:77] op_sel:[0,0,0] op_sel_hi:[0,1,1] neg_lo:[0,0,1] neg_hi:[0,0,0]
	v_pk_fma_f32 v[80:81], v[104:105], v[218:219], v[80:81] op_sel:[0,0,0] op_sel_hi:[0,1,1] neg_lo:[0,0,1] neg_hi:[0,0,0]
	v_pk_fma_f32 v[84:85], v[106:107], v[218:219], v[84:85] op_sel:[0,0,0] op_sel_hi:[0,1,1] neg_lo:[0,0,1] neg_hi:[0,0,0]
	v_pk_fma_f32 v[88:89], v[108:109], v[218:219], v[88:89] op_sel:[0,0,0] op_sel_hi:[0,1,1] neg_lo:[0,0,1] neg_hi:[0,0,0]
	ds_write2_b64 v73, v[74:75], v[76:77] offset1:136
	ds_write2_b64 v113, v[78:79], v[80:81] offset0:16 offset1:152
	ds_write2_b64 v118, v[82:83], v[84:85] offset0:32 offset1:168
	ds_write2_b64 v119, v[86:87], v[88:89] offset0:48 offset1:184
	s_waitcnt lgkmcnt(4)
; #define LAS __attribute__((address_space(3)))
; __device__ __forceinline__ int otid() { int t = threadIdx.x; asm volatile("" : "+v"(t)); return t; }
; __device__ __forceinline__ cf twc(cf ws, int k16) { if (k16 == 0) return ws; if (k16 == 4) return cf{ws.y, -ws.x}; return cmul(ws, cf{c16(k16), -s16(k16)}); }
; __device__ __forceinline__ void lds_barrier() { asm volatile("s_waitcnt lgkmcnt(0)\n\ts_barrier" ::: "memory"); }
; template <int LR> __device__ __forceinline__ void dif_reg(cf (&x)[1 << LR], cf w) {
;     constexpr int R = 1 << LR; cf ws = w;
; #pragma unroll
;     for (int s = 0; s < LR; ++s) { const int half = R >> (s + 1);
; #pragma unroll
;         for (int m0 = 0; m0 < R; m0 += 2 * half)
; #pragma unroll
;             for (int mm = 0; mm < half; ++mm) { const int ia = m0 + mm, ib = ia + half; const cf a = x[ia], b = x[ib];
;                 x[ia] = cf{a.x + b.x, a.y + b.y}; const cf d{a.x - b.x, a.y - b.y};
;                 x[ib] = cmul(d, twc(ws, (mm << s) * (16 / R))); }
;         ws = cmul(ws, ws); }
; }
; template <int LR, bool INV> __device__ __forceinline__ void fft_pass(ldsf2 buf, int base, int stride, int twi) {
;     constexpr int R = 1 << LR; cf x[R];
;     const v2f wv = ((ldsf2)((LAS unsigned char*)buf + 139264))[twi];
; #pragma unroll
;     for (int m = 0; m < R; ++m) { const v2f v = buf[base + m * stride]; x[m] = cf{v.x, v.y}; }
;     const cf w{wv.x, wv.y};
;     if (INV) dit_reg<LR>(x, w); else dif_reg<LR>(x, w);
; #pragma unroll
;     for (int m = 0; m < R; ++m) buf[base + m * stride] = mkv2(x[m].x, x[m].y);
; }
; __device__ __forceinline__ void wave_lds_fence() { asm volatile("s_waitcnt lgkmcnt(0)" ::: "memory"); }
; __device__ __forceinline__ void fft_fwd_abc(ldsf2 buf) {
;     const int tid = otid(); const int wv = tid >> 6, l = tid & 63;
; #pragma unroll 1
;     for (int u = 0; u < 2; ++u) { const int bf = tid + NT * u; fft_pass<3, false>(buf, bf + (bf >> 4), 1088, bf); }
;     lds_barrier();
; #pragma unroll 1
;     for (int u = 0; u < 2; ++u) { const int o = l + 64 * u, e0 = wv * 1024 + o; fft_pass<3, false>(buf, e0 + (e0 >> 4), 136, o * 8); }
;     wave_lds_fence();
; #pragma unroll 1
;     for (int u = 0; u < 2; ++u) { const int j = l + 64 * u, o = j & 15, e0 = wv * 1024 + (j >> 4) * 128 + o; fft_pass<3, false>(buf, e0 + (e0 >> 4), 17, o * 64); }
	v_pk_add_f32 v[162:163], v[220:221], v[220:221] op_sel:[0,1] op_sel_hi:[1,0] neg_lo:[0,0] neg_hi:[0,1]
	s_nop 0
	v_pk_mul_f32 v[164:165], v[162:163], s[16:17] op_sel:[0,0] op_sel_hi:[1,0]
	v_pk_mul_f32 v[166:167], v[162:163], s[16:17] op_sel:[1,0] op_sel_hi:[0,0] neg_lo:[0,0] neg_hi:[1,0]
	v_pk_add_f32 v[172:173], v[130:131], v[154:155] neg_lo:[0,1] neg_hi:[0,1]
	v_pk_add_f32 v[174:175], v[132:133], v[156:157] neg_lo:[0,1] neg_hi:[0,1]
	v_pk_add_f32 v[188:189], v[150:151], v[158:159] neg_lo:[0,1] neg_hi:[0,1]
	v_pk_add_f32 v[190:191], v[152:153], v[160:161] neg_lo:[0,1] neg_hi:[0,1]
	v_pk_add_f32 v[130:131], v[130:131], v[154:155]
	v_pk_add_f32 v[132:133], v[132:133], v[156:157]
	v_pk_add_f32 v[150:151], v[150:151], v[158:159]
	v_pk_add_f32 v[152:153], v[152:153], v[160:161]
	v_pk_mul_f32 v[154:155], v[172:173], v[220:221] op_sel:[1,1] op_sel_hi:[1,0]
	v_pk_mul_f32 v[156:157], v[174:175], v[164:165] op_sel:[1,1] op_sel_hi:[1,0]
	v_pk_mul_f32 v[158:159], v[188:189], v[220:221] op_sel:[1,0] op_sel_hi:[1,1]
	v_pk_mul_f32 v[160:161], v[190:191], v[166:167] op_sel:[1,1] op_sel_hi:[1,0]
	v_pk_fma_f32 v[154:155], v[172:173], v[220:221], v[154:155] op_sel:[0,0,0] op_sel_hi:[0,1,1] neg_lo:[0,0,1] neg_hi:[0,0,0]
	v_pk_fma_f32 v[156:157], v[174:175], v[164:165], v[156:157] op_sel:[0,0,0] op_sel_hi:[0,1,1] neg_lo:[0,0,1] neg_hi:[0,0,0]
	v_pk_fma_f32 v[158:159], v[188:189], v[220:221], v[158:159] op_sel:[0,1,0] op_sel_hi:[0,0,1] neg_lo:[0,0,0] neg_hi:[0,1,0]
	v_pk_fma_f32 v[160:161], v[190:191], v[166:167], v[160:161] op_sel:[0,0,0] op_sel_hi:[0,1,1] neg_lo:[0,0,1] neg_hi:[0,0,0]
	v_pk_add_f32 v[172:173], v[130:131], v[150:151] neg_lo:[0,1] neg_hi:[0,1]
	v_pk_add_f32 v[174:175], v[132:133], v[152:153] neg_lo:[0,1] neg_hi:[0,1]
	v_pk_add_f32 v[188:189], v[154:155], v[158:159] neg_lo:[0,1] neg_hi:[0,1]
	v_pk_add_f32 v[190:191], v[156:157], v[160:161] neg_lo:[0,1] neg_hi:[0,1]
	v_pk_add_f32 v[130:131], v[130:131], v[150:151]
	v_pk_add_f32 v[132:133], v[132:133], v[152:153]
	v_pk_add_f32 v[154:155], v[154:155], v[158:159]
	v_pk_add_f32 v[156:157], v[156:157], v[160:161]
	v_pk_mul_f32 v[150:151], v[172:173], v[222:223] op_sel:[1,1] op_sel_hi:[1,0]
	v_pk_mul_f32 v[152:153], v[174:175], v[222:223] op_sel:[1,0] op_sel_hi:[1,1]
	v_pk_mul_f32 v[158:159], v[188:189], v[222:223] op_sel:[1,1] op_sel_hi:[1,0]
	v_pk_mul_f32 v[160:161], v[190:191], v[222:223] op_sel:[1,0] op_sel_hi:[1,1]
	v_pk_fma_f32 v[150:151], v[172:173], v[222:223], v[150:151] op_sel:[0,0,0] op_sel_hi:[0,1,1] neg_lo:[0,0,1] neg_hi:[0,0,0]
	v_pk_fma_f32 v[152:153], v[174:175], v[222:223], v[152:153] op_sel:[0,1,0] op_sel_hi:[0,0,1] neg_lo:[0,0,0] neg_hi:[0,1,0]
	v_pk_fma_f32 v[158:159], v[188:189], v[222:223], v[158:159] op_sel:[0,0,0] op_sel_hi:[0,1,1] neg_lo:[0,0,1] neg_hi:[0,0,0]
	v_pk_fma_f32 v[160:161], v[190:191], v[222:223], v[160:161] op_sel:[0,1,0] op_sel_hi:[0,0,1] neg_lo:[0,0,0] neg_hi:[0,1,0]
	v_pk_add_f32 v[172:173], v[130:131], v[132:133] neg_lo:[0,1] neg_hi:[0,1]
	v_pk_add_f32 v[174:175], v[150:151], v[152:153] neg_lo:[0,1] neg_hi:[0,1]
	v_pk_add_f32 v[188:189], v[154:155], v[156:157] neg_lo:[0,1] neg_hi:[0,1]
	v_pk_add_f32 v[190:191], v[158:159], v[160:161] neg_lo:[0,1] neg_hi:[0,1]
	v_pk_add_f32 v[130:131], v[130:131], v[132:133]
	v_pk_add_f32 v[150:151], v[150:151], v[152:153]
	v_pk_add_f32 v[154:155], v[154:155], v[156:157]
	v_pk_add_f32 v[158:159], v[158:159], v[160:161]
	v_pk_mul_f32 v[132:133], v[172:173], v[224:225] op_sel:[1,1] op_sel_hi:[1,0]
	v_pk_mul_f32 v[152:153], v[174:175], v[224:225] op_sel:[1,1] op_sel_hi:[1,0]
	v_pk_mul_f32 v[156:157], v[188:189], v[224:225] op_sel:[1,1] op_sel_hi:[1,0]
	v_pk_mul_f32 v[160:161], v[190:191], v[224:225] op_sel:[1,1] op_sel_hi:[1,0]
	v_pk_fma_f32 v[132:133], v[172:173], v[224:225], v[132:133] op_sel:[0,0,0] op_sel_hi:[0,1,1] neg_lo:[0,0,1] neg_hi:[0,0,0]
	v_pk_fma_f32 v[152:153], v[174:175], v[224:225], v[152:153] op_sel:[0,0,0] op_sel_hi:[0,1,1] neg_lo:[0,0,1] neg_hi:[0,0,0]
	v_pk_fma_f32 v[156:157], v[188:189], v[224:225], v[156:157] op_sel:[0,0,0] op_sel_hi:[0,1,1] neg_lo:[0,0,1] neg_hi:[0,0,0]
	v_pk_fma_f32 v[160:161], v[190:191], v[224:225], v[160:161] op_sel:[0,0,0] op_sel_hi:[0,1,1] neg_lo:[0,0,1] neg_hi:[0,0,0]
	ds_write2_b64 v122, v[130:131], v[132:133] offset1:136
	ds_write2_b64 v128, v[150:151], v[152:153] offset0:16 offset1:152
	ds_write2_b64 v134, v[154:155], v[156:157] offset0:32 offset1:168
	ds_write2_b64 v148, v[158:159], v[160:161] offset0:48 offset1:184
	s_mov_b64 s[6:7], 0
	v_and_b32_e32 v68, 15, v68
	s_waitcnt lgkmcnt(0)
	v_lshlrev_b32_e32 v69, 3, v69
	v_lshlrev_b32_e32 v73, 9, v68
	v_and_or_b32 v69, v69, s90, v72
	v_add_u32_e32 v72, 0, v73
	v_lshl_add_u32 v68, v68, 3, 0
	s_mov_b32 s0, 0
	s_mov_b64 s[6:7], -1
	v_add_u32_e32 v72, 0x22000, v72
; #define LAS __attribute__((address_space(3)))
; __device__ __forceinline__ int otid() { int t = threadIdx.x; asm volatile("" : "+v"(t)); return t; }
; __device__ __forceinline__ cf twc(cf ws, int k16) { if (k16 == 0) return ws; if (k16 == 4) return cf{ws.y, -ws.x}; return cmul(ws, cf{c16(k16), -s16(k16)}); }
; __device__ __forceinline__ void lds_barrier() { asm volatile("s_waitcnt lgkmcnt(0)\n\ts_barrier" ::: "memory"); }
; template <int LR> __device__ __forceinline__ void dif_reg(cf (&x)[1 << LR], cf w) {
;     constexpr int R = 1 << LR; cf ws = w;
; #pragma unroll
;     for (int s = 0; s < LR; ++s) { const int half = R >> (s + 1);
; #pragma unroll
;         for (int m0 = 0; m0 < R; m0 += 2 * half)
; #pragma unroll
;             for (int mm = 0; mm < half; ++mm) { const int ia = m0 + mm, ib = ia + half; const cf a = x[ia], b = x[ib];
;                 x[ia] = cf{a.x + b.x, a.y + b.y}; const cf d{a.x - b.x, a.y - b.y};
;                 x[ib] = cmul(d, twc(ws, (mm << s) * (16 / R))); }
;         ws = cmul(ws, ws); }
; }
; template <int LR, bool INV> __device__ __forceinline__ void fft_pass(ldsf2 buf, int base, int stride, int twi) {
;     constexpr int R = 1 << LR; cf x[R];
;     const v2f wv = ((ldsf2)((LAS unsigned char*)buf + 139264))[twi];
; #pragma unroll
;     for (int m = 0; m < R; ++m) { const v2f v = buf[base + m * stride]; x[m] = cf{v.x, v.y}; }
;     const cf w{wv.x, wv.y};
;     if (INV) dit_reg<LR>(x, w); else dif_reg<LR>(x, w);
; #pragma unroll
;     for (int m = 0; m < R; ++m) buf[base + m * stride] = mkv2(x[m].x, x[m].y);
; }
; __device__ __forceinline__ void wave_lds_fence() { asm volatile("s_waitcnt lgkmcnt(0)" ::: "memory"); }
; __device__ __forceinline__ void fft_fwd_abc(ldsf2 buf) {
;     const int tid = otid(); const int wv = tid >> 6, l = tid & 63;
; #pragma unroll 1
;     for (int u = 0; u < 2; ++u) { const int bf = tid + NT * u; fft_pass<3, false>(buf, bf + (bf >> 4), 1088, bf); }
;     lds_barrier();
; #pragma unroll 1
;     for (int u = 0; u < 2; ++u) { const int o = l + 64 * u, e0 = wv * 1024 + o; fft_pass<3, false>(buf, e0 + (e0 >> 4), 136, o * 8); }
;     wave_lds_fence();
; #pragma unroll 1
;     for (int u = 0; u < 2; ++u) { const int j = l + 64 * u, o = j & 15, e0 = wv * 1024 + (j >> 4) * 128 + o; fft_pass<3, false>(buf, e0 + (e0 >> 4), 17, o * 64); }
.LBB0_351:
	v_or_b32_e32 v73, s0, v69
	v_lshlrev_b32_e32 v74, 3, v73
	v_ashrrev_i32_e32 v73, 1, v73
	v_add3_u32 v73, v68, v74, v73
	ds_read2_b64 v[74:77], v73 offset1:17
	ds_read2_b64 v[78:81], v73 offset0:34 offset1:51
	ds_read2_b64 v[82:85], v73 offset0:68 offset1:85
	ds_read2_b64 v[86:89], v73 offset0:102 offset1:119
	s_movk_i32 s0, 0x200
	v_or_b32_e32 v118, s0, v69
	v_lshlrev_b32_e32 v122, 3, v118
	v_ashrrev_i32_e32 v118, 1, v118
	v_add3_u32 v118, v68, v122, v118
	ds_read2_b64 v[124:127], v118 offset1:17
	ds_read2_b64 v[128:131], v118 offset0:34 offset1:51
	ds_read2_b64 v[132:135], v118 offset0:68 offset1:85
	ds_read2_b64 v[148:151], v118 offset0:102 offset1:119
	s_waitcnt lgkmcnt(4)
	v_pk_add_f32 v[102:103], v[74:75], v[82:83] neg_lo:[0,1] neg_hi:[0,1]
	v_pk_add_f32 v[104:105], v[76:77], v[84:85] neg_lo:[0,1] neg_hi:[0,1]
	v_pk_add_f32 v[106:107], v[78:79], v[86:87] neg_lo:[0,1] neg_hi:[0,1]
	v_pk_add_f32 v[108:109], v[80:81], v[88:89] neg_lo:[0,1] neg_hi:[0,1]
	v_pk_add_f32 v[74:75], v[74:75], v[82:83]
	v_pk_add_f32 v[76:77], v[76:77], v[84:85]
	v_pk_add_f32 v[78:79], v[78:79], v[86:87]
	v_pk_add_f32 v[80:81], v[80:81], v[88:89]
	v_pk_mul_f32 v[82:83], v[102:103], v[204:205] op_sel:[1,1] op_sel_hi:[1,0]
	v_pk_mul_f32 v[84:85], v[104:105], v[210:211] op_sel:[1,1] op_sel_hi:[1,0]
	v_pk_mul_f32 v[86:87], v[106:107], v[204:205] op_sel:[1,0] op_sel_hi:[1,1]
	v_pk_mul_f32 v[88:89], v[108:109], v[212:213] op_sel:[1,1] op_sel_hi:[1,0]
	v_pk_fma_f32 v[82:83], v[102:103], v[204:205], v[82:83] op_sel:[0,0,0] op_sel_hi:[0,1,1] neg_lo:[0,0,1] neg_hi:[0,0,0]
	v_pk_fma_f32 v[84:85], v[104:105], v[210:211], v[84:85] op_sel:[0,0,0] op_sel_hi:[0,1,1] neg_lo:[0,0,1] neg_hi:[0,0,0]
	v_pk_fma_f32 v[86:87], v[106:107], v[204:205], v[86:87] op_sel:[0,1,0] op_sel_hi:[0,0,1] neg_lo:[0,0,0] neg_hi:[0,1,0]
	v_pk_fma_f32 v[88:89], v[108:109], v[212:213], v[88:89] op_sel:[0,0,0] op_sel_hi:[0,1,1] neg_lo:[0,0,1] neg_hi:[0,0,0]
	v_pk_add_f32 v[102:103], v[74:75], v[78:79] neg_lo:[0,1] neg_hi:[0,1]
	v_pk_add_f32 v[104:105], v[76:77], v[80:81] neg_lo:[0,1] neg_hi:[0,1]
	v_pk_add_f32 v[106:107], v[82:83], v[86:87] neg_lo:[0,1] neg_hi:[0,1]
	v_pk_add_f32 v[108:109], v[84:85], v[88:89] neg_lo:[0,1] neg_hi:[0,1]
	v_pk_add_f32 v[74:75], v[74:75], v[78:79]
	v_pk_add_f32 v[76:77], v[76:77], v[80:81]
	v_pk_add_f32 v[82:83], v[82:83], v[86:87]
	v_pk_add_f32 v[84:85], v[84:85], v[88:89]
	v_pk_mul_f32 v[78:79], v[102:103], v[206:207] op_sel:[1,1] op_sel_hi:[1,0]
	v_pk_mul_f32 v[80:81], v[104:105], v[206:207] op_sel:[1,0] op_sel_hi:[1,1]
	v_pk_mul_f32 v[86:87], v[106:107], v[206:207] op_sel:[1,1] op_sel_hi:[1,0]
	v_pk_mul_f32 v[88:89], v[108:109], v[206:207] op_sel:[1,0] op_sel_hi:[1,1]
	v_pk_fma_f32 v[78:79], v[102:103], v[206:207], v[78:79] op_sel:[0,0,0] op_sel_hi:[0,1,1] neg_lo:[0,0,1] neg_hi:[0,0,0]
	v_pk_fma_f32 v[80:81], v[104:105], v[206:207], v[80:81] op_sel:[0,1,0] op_sel_hi:[0,0,1] neg_lo:[0,0,0] neg_hi:[0,1,0]
	v_pk_fma_f32 v[86:87], v[106:107], v[206:207], v[86:87] op_sel:[0,0,0] op_sel_hi:[0,1,1] neg_lo:[0,0,1] neg_hi:[0,0,0]
	v_pk_fma_f32 v[88:89], v[108:109], v[206:207], v[88:89] op_sel:[0,1,0] op_sel_hi:[0,0,1] neg_lo:[0,0,0] neg_hi:[0,1,0]
	v_pk_add_f32 v[102:103], v[74:75], v[76:77] neg_lo:[0,1] neg_hi:[0,1]
	v_pk_add_f32 v[104:105], v[78:79], v[80:81] neg_lo:[0,1] neg_hi:[0,1]
	v_pk_add_f32 v[106:107], v[82:83], v[84:85] neg_lo:[0,1] neg_hi:[0,1]
	v_pk_add_f32 v[108:109], v[86:87], v[88:89] neg_lo:[0,1] neg_hi:[0,1]
	v_pk_add_f32 v[74:75], v[74:75], v[76:77]
	v_pk_add_f32 v[78:79], v[78:79], v[80:81]
	v_pk_add_f32 v[82:83], v[82:83], v[84:85]
	v_pk_add_f32 v[86:87], v[86:87], v[88:89]
	v_pk_mul_f32 v[76:77], v[102:103], v[208:209] op_sel:[1,1] op_sel_hi:[1,0]
	v_pk_mul_f32 v[80:81], v[104:105], v[208:209] op_sel:[1,1] op_sel_hi:[1,0]
	v_pk_mul_f32 v[84:85], v[106:107], v[208:209] op_sel:[1,1] op_sel_hi:[1,0]
	v_pk_mul_f32 v[88:89], v[108:109], v[208:209] op_sel:[1,1] op_sel_hi:[1,0]
	v_pk_fma_f32 v[76:77], v[102:103], v[208:209], v[76:77] op_sel:[0,0,0] op_sel_hi:[0,1,1] neg_lo:[0,0,1] neg_hi:[0,0,0]
	v_pk_fma_f32 v[80:81], v[104:105], v[208:209], v[80:81] op_sel:[0,0,0] op_sel_hi:[0,1,1] neg_lo:[0,0,1] neg_hi:[0,0,0]
	v_pk_fma_f32 v[84:85], v[106:107], v[208:209], v[84:85] op_sel:[0,0,0] op_sel_hi:[0,1,1] neg_lo:[0,0,1] neg_hi:[0,0,0]
	v_pk_fma_f32 v[88:89], v[108:109], v[208:209], v[88:89] op_sel:[0,0,0] op_sel_hi:[0,1,1] neg_lo:[0,0,1] neg_hi:[0,0,0]
	ds_write2_b64 v73, v[74:75], v[76:77] offset1:17
	ds_write2_b64 v73, v[78:79], v[80:81] offset0:34 offset1:51
	ds_write2_b64 v73, v[82:83], v[84:85] offset0:68 offset1:85
	ds_write2_b64 v73, v[86:87], v[88:89] offset0:102 offset1:119
	s_waitcnt lgkmcnt(4)
; #define LAS __attribute__((address_space(3)))
; __device__ __forceinline__ int otid() { int t = threadIdx.x; asm volatile("" : "+v"(t)); return t; }
; __device__ __forceinline__ void lds_barrier() { asm volatile("s_waitcnt lgkmcnt(0)\n\ts_barrier" ::: "memory"); }
; template <int LR, bool INV> __device__ __forceinline__ void fft_pass(ldsf2 buf, int base, int stride, int twi) {
;     constexpr int R = 1 << LR; cf x[R];
;     const v2f wv = ((ldsf2)((LAS unsigned char*)buf + 139264))[twi];
; #pragma unroll
;     for (int m = 0; m < R; ++m) { const v2f v = buf[base + m * stride]; x[m] = cf{v.x, v.y}; }
;     const cf w{wv.x, wv.y};
;     if (INV) dit_reg<LR>(x, w); else dif_reg<LR>(x, w);
; #pragma unroll
;     for (int m = 0; m < R; ++m) buf[base + m * stride] = mkv2(x[m].x, x[m].y);
; }
; __device__ __forceinline__ void wave_lds_fence() { asm volatile("s_waitcnt lgkmcnt(0)" ::: "memory"); }
; __device__ __forceinline__ void fft_fwd_abc(ldsf2 buf) {
;     const int tid = otid(); const int wv = tid >> 6, l = tid & 63;
; #pragma unroll 1
;     for (int u = 0; u < 2; ++u) { const int bf = tid + NT * u; fft_pass<3, false>(buf, bf + (bf >> 4), 1088, bf); }
;     lds_barrier();
; #pragma unroll 1
;     for (int u = 0; u < 2; ++u) { const int o = l + 64 * u, e0 = wv * 1024 + o; fft_pass<3, false>(buf, e0 + (e0 >> 4), 136, o * 8); }
;     wave_lds_fence();
; #pragma unroll 1
;     for (int u = 0; u < 2; ++u) { const int j = l + 64 * u, o = j & 15, e0 = wv * 1024 + (j >> 4) * 128 + o; fft_pass<3, false>(buf, e0 + (e0 >> 4), 17, o * 64); }
; __device__ __forceinline__ void fft_conv(ldsf2 buf, const LAS unsigned* spec) {
;     fft_fwd_abc(buf);
;     { const int tid = otid(); cf x[16];
; #pragma unroll
;       for (int m = 0; m < 16; ++m) { const v2f v = buf[tid * 17 + m]; x[m] = cf{v.x, v.y}; }
;       dif_reg<4>(x, cf{1.0f, 0.0f});
; #pragma unroll
;       for (int m = 0; m < 16; ++m) { const h2_t hv = __builtin_bit_cast(h2_t, spec[tid * 17 + m]); x[m] = cmul(x[m], cf{(float)hv.x, (float)hv.y}); }
	v_pk_add_f32 v[162:163], v[124:125], v[132:133] neg_lo:[0,1] neg_hi:[0,1]
	v_pk_add_f32 v[164:165], v[126:127], v[134:135] neg_lo:[0,1] neg_hi:[0,1]
	v_pk_add_f32 v[166:167], v[128:129], v[148:149] neg_lo:[0,1] neg_hi:[0,1]
	v_pk_add_f32 v[168:169], v[130:131], v[150:151] neg_lo:[0,1] neg_hi:[0,1]
	v_pk_add_f32 v[124:125], v[124:125], v[132:133]
	v_pk_add_f32 v[126:127], v[126:127], v[134:135]
	v_pk_add_f32 v[128:129], v[128:129], v[148:149]
	v_pk_add_f32 v[130:131], v[130:131], v[150:151]
	v_pk_mul_f32 v[132:133], v[162:163], v[204:205] op_sel:[1,1] op_sel_hi:[1,0]
	v_pk_mul_f32 v[134:135], v[164:165], v[210:211] op_sel:[1,1] op_sel_hi:[1,0]
	v_pk_mul_f32 v[148:149], v[166:167], v[204:205] op_sel:[1,0] op_sel_hi:[1,1]
	v_pk_mul_f32 v[150:151], v[168:169], v[212:213] op_sel:[1,1] op_sel_hi:[1,0]
	v_pk_fma_f32 v[132:133], v[162:163], v[204:205], v[132:133] op_sel:[0,0,0] op_sel_hi:[0,1,1] neg_lo:[0,0,1] neg_hi:[0,0,0]
	v_pk_fma_f32 v[134:135], v[164:165], v[210:211], v[134:135] op_sel:[0,0,0] op_sel_hi:[0,1,1] neg_lo:[0,0,1] neg_hi:[0,0,0]
	v_pk_fma_f32 v[148:149], v[166:167], v[204:205], v[148:149] op_sel:[0,1,0] op_sel_hi:[0,0,1] neg_lo:[0,0,0] neg_hi:[0,1,0]
	v_pk_fma_f32 v[150:151], v[168:169], v[212:213], v[150:151] op_sel:[0,0,0] op_sel_hi:[0,1,1] neg_lo:[0,0,1] neg_hi:[0,0,0]
	v_pk_add_f32 v[162:163], v[124:125], v[128:129] neg_lo:[0,1] neg_hi:[0,1]
	v_pk_add_f32 v[164:165], v[126:127], v[130:131] neg_lo:[0,1] neg_hi:[0,1]
	v_pk_add_f32 v[166:167], v[132:133], v[148:149] neg_lo:[0,1] neg_hi:[0,1]
	v_pk_add_f32 v[168:169], v[134:135], v[150:151] neg_lo:[0,1] neg_hi:[0,1]
	v_pk_add_f32 v[124:125], v[124:125], v[128:129]
	v_pk_add_f32 v[126:127], v[126:127], v[130:131]
	v_pk_add_f32 v[132:133], v[132:133], v[148:149]
	v_pk_add_f32 v[134:135], v[134:135], v[150:151]
	v_pk_mul_f32 v[128:129], v[162:163], v[206:207] op_sel:[1,1] op_sel_hi:[1,0]
	v_pk_mul_f32 v[130:131], v[164:165], v[206:207] op_sel:[1,0] op_sel_hi:[1,1]
	v_pk_mul_f32 v[148:149], v[166:167], v[206:207] op_sel:[1,1] op_sel_hi:[1,0]
	v_pk_mul_f32 v[150:151], v[168:169], v[206:207] op_sel:[1,0] op_sel_hi:[1,1]
	v_pk_fma_f32 v[128:129], v[162:163], v[206:207], v[128:129] op_sel:[0,0,0] op_sel_hi:[0,1,1] neg_lo:[0,0,1] neg_hi:[0,0,0]
	v_pk_fma_f32 v[130:131], v[164:165], v[206:207], v[130:131] op_sel:[0,1,0] op_sel_hi:[0,0,1] neg_lo:[0,0,0] neg_hi:[0,1,0]
	v_pk_fma_f32 v[148:149], v[166:167], v[206:207], v[148:149] op_sel:[0,0,0] op_sel_hi:[0,1,1] neg_lo:[0,0,1] neg_hi:[0,0,0]
	v_pk_fma_f32 v[150:151], v[168:169], v[206:207], v[150:151] op_sel:[0,1,0] op_sel_hi:[0,0,1] neg_lo:[0,0,0] neg_hi:[0,1,0]
	v_pk_add_f32 v[162:163], v[124:125], v[126:127] neg_lo:[0,1] neg_hi:[0,1]
	v_pk_add_f32 v[164:165], v[128:129], v[130:131] neg_lo:[0,1] neg_hi:[0,1]
	v_pk_add_f32 v[166:167], v[132:133], v[134:135] neg_lo:[0,1] neg_hi:[0,1]
	v_pk_add_f32 v[168:169], v[148:149], v[150:151] neg_lo:[0,1] neg_hi:[0,1]
	v_pk_add_f32 v[124:125], v[124:125], v[126:127]
	v_pk_add_f32 v[128:129], v[128:129], v[130:131]
	v_pk_add_f32 v[132:133], v[132:133], v[134:135]
	v_pk_add_f32 v[148:149], v[148:149], v[150:151]
	v_pk_mul_f32 v[126:127], v[162:163], v[208:209] op_sel:[1,1] op_sel_hi:[1,0]
	v_pk_mul_f32 v[130:131], v[164:165], v[208:209] op_sel:[1,1] op_sel_hi:[1,0]
	v_pk_mul_f32 v[134:135], v[166:167], v[208:209] op_sel:[1,1] op_sel_hi:[1,0]
	v_pk_mul_f32 v[150:151], v[168:169], v[208:209] op_sel:[1,1] op_sel_hi:[1,0]
	v_pk_fma_f32 v[126:127], v[162:163], v[208:209], v[126:127] op_sel:[0,0,0] op_sel_hi:[0,1,1] neg_lo:[0,0,1] neg_hi:[0,0,0]
	v_pk_fma_f32 v[130:131], v[164:165], v[208:209], v[130:131] op_sel:[0,0,0] op_sel_hi:[0,1,1] neg_lo:[0,0,1] neg_hi:[0,0,0]
	v_pk_fma_f32 v[134:135], v[166:167], v[208:209], v[134:135] op_sel:[0,0,0] op_sel_hi:[0,1,1] neg_lo:[0,0,1] neg_hi:[0,0,0]
	v_pk_fma_f32 v[150:151], v[168:169], v[208:209], v[150:151] op_sel:[0,0,0] op_sel_hi:[0,1,1] neg_lo:[0,0,1] neg_hi:[0,0,0]
	ds_write2_b64 v118, v[124:125], v[126:127] offset1:17
	ds_write2_b64 v118, v[128:129], v[130:131] offset0:34 offset1:51
	ds_write2_b64 v118, v[132:133], v[134:135] offset0:68 offset1:85
	ds_write2_b64 v118, v[148:149], v[150:151] offset0:102 offset1:119
	s_mov_b64 s[6:7], 0
	v_mov_b32_e32 v158, v195
	s_movk_i32 s0, 0x88
	s_waitcnt lgkmcnt(0)
	s_mov_b32 s86, s63
	v_mul_lo_u32 v68, v158, s0
	v_add_u32_e32 v147, 0, v68
	ds_read2_b64 v[72:75], v147 offset1:1
	ds_read2_b64 v[76:79], v147 offset0:2 offset1:3
	ds_read2_b64 v[90:93], v147 offset0:4 offset1:5
	ds_read2_b64 v[94:97], v147 offset0:6 offset1:7
	ds_read2_b64 v[98:101], v147 offset0:8 offset1:9
	ds_read2_b64 v[102:105], v147 offset0:10 offset1:11
	ds_read2_b64 v[118:121], v147 offset0:12 offset1:13
	ds_read2_b64 v[126:129], v147 offset0:14 offset1:15
	s_mov_b32 s6, s63
	s_mov_b32 s7, s16
	s_mov_b32 s17, s5
	s_mov_b32 s0, s16
	s_mov_b32 s1, s4
	s_mov_b32 s0, s63
	s_mov_b32 s1, s5
	s_mov_b32 s0, s87
	s_mov_b32 s1, s4
	s_mov_b32 s1, s5
	s_mov_b32 s35, s4
	s_mov_b32 s12, s63
	s_movk_i32 s0, 0x44
	v_mul_lo_u32 v106, v158, s0
	v_add_u32_e32 v106, 0, v106
	v_add_u32_e32 v106, 0x11000, v106
	ds_read2_b32 v[156:157], v106 offset1:1
	ds_read2_b32 v[158:159], v106 offset0:2 offset1:3
	ds_read2_b32 v[160:161], v106 offset0:4 offset1:5
	ds_read2_b32 v[162:163], v106 offset0:6 offset1:7
	ds_read2_b32 v[164:165], v106 offset0:8 offset1:9
	ds_read2_b32 v[134:135], v106 offset0:10 offset1:11
	ds_read2_b32 v[130:131], v106 offset0:12 offset1:13
	ds_read2_b32 v[168:169], v106 offset0:14 offset1:15
	s_mov_b32 s0, s5
	s_mov_b64 s[6:7], -1
	s_mov_b32 s35, s13
	s_mov_b32 s0, s13
	s_waitcnt lgkmcnt(8)
; __device__ __forceinline__ int otid() { int t = threadIdx.x; asm volatile("" : "+v"(t)); return t; }
; __device__ __forceinline__ cf twc(cf ws, int k16) { if (k16 == 0) return ws; if (k16 == 4) return cf{ws.y, -ws.x}; return cmul(ws, cf{c16(k16), -s16(k16)}); }
; template <int LR> __device__ __forceinline__ void dif_reg(cf (&x)[1 << LR], cf w) {
;     constexpr int R = 1 << LR; cf ws = w;
; #pragma unroll
;     for (int s = 0; s < LR; ++s) { const int half = R >> (s + 1);
; #pragma unroll
;         for (int m0 = 0; m0 < R; m0 += 2 * half)
; #pragma unroll
;             for (int mm = 0; mm < half; ++mm) { const int ia = m0 + mm, ib = ia + half; const cf a = x[ia], b = x[ib];
;                 x[ia] = cf{a.x + b.x, a.y + b.y}; const cf d{a.x - b.x, a.y - b.y};
;                 x[ib] = cmul(d, twc(ws, (mm << s) * (16 / R))); }
;         ws = cmul(ws, ws); }
; }
; __device__ __forceinline__ void fft_conv(ldsf2 buf, const LAS unsigned* spec) {
;     ...
;     { const int tid = otid(); cf x[16];
; #pragma unroll
;       for (int m = 0; m < 16; ++m) { const v2f v = buf[tid * 17 + m]; x[m] = cf{v.x, v.y}; }
;       dif_reg<4>(x, cf{1.0f, 0.0f});
	v_pk_add_f32 v[80:81], v[72:73], v[98:99]
	v_pk_add_f32 v[82:83], v[74:75], v[100:101]
	v_pk_add_f32 v[84:85], v[76:77], v[102:103]
	v_pk_add_f32 v[86:87], v[78:79], v[104:105]
	v_pk_add_f32 v[72:73], v[72:73], v[98:99] neg_lo:[0,1] neg_hi:[0,1]
	v_pk_add_f32 v[74:75], v[74:75], v[100:101] neg_lo:[0,1] neg_hi:[0,1]
	v_pk_add_f32 v[76:77], v[76:77], v[102:103] neg_lo:[0,1] neg_hi:[0,1]
	v_pk_add_f32 v[78:79], v[78:79], v[104:105] neg_lo:[0,1] neg_hi:[0,1]
	v_pk_mul_f32 v[100:101], v[74:75], s[4:5] op_sel:[1,1] op_sel_hi:[1,0] neg_lo:[0,1] neg_hi:[0,0]
	v_pk_mul_f32 v[102:103], v[76:77], s[16:17] op_sel:[1,0] op_sel_hi:[1,0] neg_lo:[0,1] neg_hi:[0,0]
	v_pk_mul_f32 v[104:105], v[78:79], s[4:5] op_sel:[1,0] op_sel_hi:[1,1] neg_lo:[0,1] neg_hi:[0,0]
	v_pk_fma_f32 v[100:101], v[74:75], s[4:5], v[100:101] op_sel:[0,0,0] op_sel_hi:[0,1,1] neg_lo:[0,0,1] neg_hi:[0,1,0]
	v_pk_fma_f32 v[102:103], v[76:77], s[16:17], v[102:103] op_sel:[0,0,0] op_sel_hi:[0,0,1] neg_lo:[0,0,1] neg_hi:[0,1,0]
	v_pk_fma_f32 v[104:105], v[78:79], s[4:5], v[104:105] op_sel:[0,1,0] op_sel_hi:[0,0,1] neg_lo:[0,0,1] neg_hi:[0,1,0]
	v_pk_add_f32 v[88:89], v[90:91], v[118:119]
	v_pk_add_f32 v[108:109], v[92:93], v[120:121]
	v_pk_add_f32 v[110:111], v[94:95], v[126:127]
	v_pk_add_f32 v[112:113], v[96:97], v[128:129]
	v_pk_add_f32 v[90:91], v[90:91], v[118:119] op_sel:[1,1] op_sel_hi:[0,0] neg_lo:[0,1] neg_hi:[1,0]
	v_pk_add_f32 v[92:93], v[92:93], v[120:121] neg_lo:[0,1] neg_hi:[0,1]
	v_pk_add_f32 v[94:95], v[94:95], v[126:127] neg_lo:[0,1] neg_hi:[0,1]
	v_pk_add_f32 v[96:97], v[96:97], v[128:129] neg_lo:[0,1] neg_hi:[0,1]
	v_pk_mul_f32 v[120:121], v[92:93], s[4:5] op_sel:[1,0] op_sel_hi:[1,1] neg_lo:[0,1] neg_hi:[0,1]
	v_pk_mul_f32 v[126:127], v[94:95], s[16:17] op_sel:[1,0] op_sel_hi:[1,0] neg_lo:[0,1] neg_hi:[0,1]
	v_pk_mul_f32 v[128:129], v[96:97], s[4:5] op_sel:[1,1] op_sel_hi:[1,0] neg_lo:[0,1] neg_hi:[0,1]
	v_pk_fma_f32 v[120:121], v[92:93], s[4:5], v[120:121] op_sel:[0,1,0] op_sel_hi:[0,0,1] neg_lo:[0,1,1] neg_hi:[0,1,0]
	v_pk_fma_f32 v[126:127], v[94:95], s[16:17], v[126:127] op_sel:[0,0,0] op_sel_hi:[0,0,1] neg_lo:[0,1,1] neg_hi:[0,1,0]
	v_pk_fma_f32 v[128:129], v[96:97], s[4:5], v[128:129] op_sel:[0,0,0] op_sel_hi:[0,1,1] neg_lo:[0,1,1] neg_hi:[0,1,0]
	v_pk_add_f32 v[114:115], v[80:81], v[88:89]
	v_pk_add_f32 v[116:117], v[82:83], v[108:109]
	v_pk_add_f32 v[122:123], v[84:85], v[110:111]
	v_pk_add_f32 v[124:125], v[86:87], v[112:113]
	v_pk_add_f32 v[80:81], v[80:81], v[88:89] neg_lo:[0,1] neg_hi:[0,1]
	v_pk_add_f32 v[82:83], v[82:83], v[108:109] neg_lo:[0,1] neg_hi:[0,1]
	v_pk_add_f32 v[84:85], v[84:85], v[110:111] op_sel:[1,1] op_sel_hi:[0,0] neg_lo:[0,1] neg_hi:[1,0]
	v_pk_add_f32 v[86:87], v[86:87], v[112:113] neg_lo:[0,1] neg_hi:[0,1]
	v_pk_mul_f32 v[108:109], v[82:83], s[16:17] op_sel:[1,0] op_sel_hi:[1,0] neg_lo:[0,1] neg_hi:[0,0]
	v_pk_mul_f32 v[112:113], v[86:87], s[16:17] op_sel:[1,0] op_sel_hi:[1,0] neg_lo:[0,1] neg_hi:[0,1]
	v_pk_fma_f32 v[108:109], v[82:83], s[16:17], v[108:109] op_sel:[0,0,0] op_sel_hi:[0,0,1] neg_lo:[0,0,1] neg_hi:[0,1,0]
	v_pk_fma_f32 v[112:113], v[86:87], s[16:17], v[112:113] op_sel:[0,0,0] op_sel_hi:[0,0,1] neg_lo:[0,1,1] neg_hi:[0,1,0]
	v_pk_add_f32 v[132:133], v[72:73], v[90:91]
	v_pk_add_f32 v[148:149], v[100:101], v[120:121]
	v_pk_add_f32 v[150:151], v[102:103], v[126:127]
	v_pk_add_f32 v[152:153], v[104:105], v[128:129]
	v_pk_add_f32 v[72:73], v[72:73], v[90:91] neg_lo:[0,1] neg_hi:[0,1]
	v_pk_add_f32 v[100:101], v[100:101], v[120:121] neg_lo:[0,1] neg_hi:[0,1]
	v_pk_add_f32 v[102:103], v[102:103], v[126:127] op_sel:[1,1] op_sel_hi:[0,0] neg_lo:[0,1] neg_hi:[1,0]
	v_pk_add_f32 v[104:105], v[104:105], v[128:129] neg_lo:[0,1] neg_hi:[0,1]
	v_pk_mul_f32 v[120:121], v[100:101], s[16:17] op_sel:[1,0] op_sel_hi:[1,0] neg_lo:[0,1] neg_hi:[0,0]
	v_pk_mul_f32 v[128:129], v[104:105], s[16:17] op_sel:[1,0] op_sel_hi:[1,0] neg_lo:[0,1] neg_hi:[0,1]
	v_pk_fma_f32 v[120:121], v[100:101], s[16:17], v[120:121] op_sel:[0,0,0] op_sel_hi:[0,0,1] neg_lo:[0,0,1] neg_hi:[0,1,0]
	v_pk_fma_f32 v[128:129], v[104:105], s[16:17], v[128:129] op_sel:[0,0,0] op_sel_hi:[0,0,1] neg_lo:[0,1,1] neg_hi:[0,1,0]
	v_pk_add_f32 v[154:155], v[114:115], v[122:123]
	v_pk_add_f32 v[166:167], v[116:117], v[124:125]
	v_pk_add_f32 v[98:99], v[80:81], v[84:85]
	v_pk_add_f32 v[74:75], v[108:109], v[112:113]
	v_pk_add_f32 v[114:115], v[114:115], v[122:123] neg_lo:[0,1] neg_hi:[0,1]
	v_pk_add_f32 v[116:117], v[116:117], v[124:125] op_sel:[1,1] op_sel_hi:[0,0] neg_lo:[0,1] neg_hi:[1,0]
	v_pk_add_f32 v[80:81], v[80:81], v[84:85] neg_lo:[0,1] neg_hi:[0,1]
	v_pk_add_f32 v[108:109], v[108:109], v[112:113] op_sel:[1,1] op_sel_hi:[0,0] neg_lo:[0,1] neg_hi:[1,0]
	v_pk_add_f32 v[76:77], v[132:133], v[150:151]
	v_pk_add_f32 v[78:79], v[148:149], v[152:153]
	v_pk_add_f32 v[118:119], v[72:73], v[102:103]
	v_pk_add_f32 v[92:93], v[120:121], v[128:129]
	v_pk_add_f32 v[132:133], v[132:133], v[150:151] neg_lo:[0,1] neg_hi:[0,1]
	v_pk_add_f32 v[148:149], v[148:149], v[152:153] op_sel:[1,1] op_sel_hi:[0,0] neg_lo:[0,1] neg_hi:[1,0]
	v_pk_add_f32 v[72:73], v[72:73], v[102:103] neg_lo:[0,1] neg_hi:[0,1]
	v_pk_add_f32 v[120:121], v[120:121], v[128:129] op_sel:[1,1] op_sel_hi:[0,0] neg_lo:[0,1] neg_hi:[1,0]
	v_pk_add_f32 v[94:95], v[154:155], v[166:167]
	v_pk_add_f32 v[96:97], v[114:115], v[116:117]
	v_pk_add_f32 v[88:89], v[98:99], v[74:75]
	v_pk_add_f32 v[82:83], v[80:81], v[108:109]
	v_pk_add_f32 v[154:155], v[154:155], v[166:167] neg_lo:[0,1] neg_hi:[0,1]
	v_pk_add_f32 v[114:115], v[114:115], v[116:117] neg_lo:[0,1] neg_hi:[0,1]
	v_pk_add_f32 v[98:99], v[98:99], v[74:75] neg_lo:[0,1] neg_hi:[0,1]
	v_pk_add_f32 v[80:81], v[80:81], v[108:109] neg_lo:[0,1] neg_hi:[0,1]
	v_pk_add_f32 v[110:111], v[76:77], v[78:79]
	v_pk_add_f32 v[86:87], v[132:133], v[148:149]
	v_pk_add_f32 v[90:91], v[118:119], v[92:93]
	v_pk_add_f32 v[100:101], v[72:73], v[120:121]
	v_pk_add_f32 v[76:77], v[76:77], v[78:79] neg_lo:[0,1] neg_hi:[0,1]
	v_pk_add_f32 v[132:133], v[132:133], v[148:149] neg_lo:[0,1] neg_hi:[0,1]
	v_pk_add_f32 v[118:119], v[118:119], v[92:93] neg_lo:[0,1] neg_hi:[0,1]
	v_pk_add_f32 v[72:73], v[72:73], v[120:121] neg_lo:[0,1] neg_hi:[0,1]
	s_waitcnt lgkmcnt(0)
; #define LAS __attribute__((address_space(3)))
; __device__ __forceinline__ int otid() { int t = threadIdx.x; asm volatile("" : "+v"(t)); return t; }
; __device__ __forceinline__ void fft_conv(ldsf2 buf, const LAS unsigned* spec) {
;     fft_fwd_abc(buf);
;     { const int tid = otid(); cf x[16];
; #pragma unroll
;       for (int m = 0; m < 16; ++m) { const v2f v = buf[tid * 17 + m]; x[m] = cf{v.x, v.y}; }
;       dif_reg<4>(x, cf{1.0f, 0.0f});
; #pragma unroll
;       for (int m = 0; m < 16; ++m) { const h2_t hv = __builtin_bit_cast(h2_t, spec[tid * 17 + m]); x[m] = cmul(x[m], cf{(float)hv.x, (float)hv.y}); }
;       dit_reg<4>(x, cf{1.0f, 0.0f});
	v_cvt_f32_f16_e32 v126, v156
	v_cvt_f32_f16_e32 v122, v157
	v_cvt_f32_f16_e32 v84, v158
	v_cvt_f32_f16_e32 v150, v159
	v_cvt_f32_f16_sdwa v127, v156 dst_sel:DWORD dst_unused:UNUSED_PAD src0_sel:WORD_1
	v_cvt_f32_f16_sdwa v123, v157 dst_sel:DWORD dst_unused:UNUSED_PAD src0_sel:WORD_1
	v_cvt_f32_f16_sdwa v85, v158 dst_sel:DWORD dst_unused:UNUSED_PAD src0_sel:WORD_1
	v_cvt_f32_f16_sdwa v151, v159 dst_sel:DWORD dst_unused:UNUSED_PAD src0_sel:WORD_1
	v_pk_mul_f32 v[104:105], v[94:95], v[126:127] op_sel:[1,1] op_sel_hi:[1,0]
	v_pk_mul_f32 v[124:125], v[154:155], v[122:123] op_sel:[1,1] op_sel_hi:[1,0]
	v_pk_mul_f32 v[112:113], v[96:97], v[84:85] op_sel:[1,1] op_sel_hi:[1,0]
	v_pk_mul_f32 v[152:153], v[114:115], v[150:151] op_sel:[1,1] op_sel_hi:[1,0]
	v_pk_fma_f32 v[126:127], v[94:95], v[126:127], v[104:105] op_sel:[0,0,0] op_sel_hi:[0,1,1] neg_lo:[0,0,1] neg_hi:[0,0,0]
	v_pk_fma_f32 v[122:123], v[154:155], v[122:123], v[124:125] op_sel:[0,0,0] op_sel_hi:[0,1,1] neg_lo:[0,0,1] neg_hi:[0,0,0]
	v_pk_fma_f32 v[84:85], v[96:97], v[84:85], v[112:113] op_sel:[0,0,0] op_sel_hi:[0,1,1] neg_lo:[0,0,1] neg_hi:[0,0,0]
	v_pk_fma_f32 v[150:151], v[114:115], v[150:151], v[152:153] op_sel:[0,0,0] op_sel_hi:[0,1,1] neg_lo:[0,0,1] neg_hi:[0,0,0]
	v_cvt_f32_f16_e32 v102, v160
	v_cvt_f32_f16_e32 v166, v161
	v_cvt_f32_f16_e32 v74, v162
	v_cvt_f32_f16_e32 v78, v163
	v_cvt_f32_f16_sdwa v103, v160 dst_sel:DWORD dst_unused:UNUSED_PAD src0_sel:WORD_1
	v_cvt_f32_f16_sdwa v167, v161 dst_sel:DWORD dst_unused:UNUSED_PAD src0_sel:WORD_1
	v_cvt_f32_f16_sdwa v75, v162 dst_sel:DWORD dst_unused:UNUSED_PAD src0_sel:WORD_1
	v_cvt_f32_f16_sdwa v79, v163 dst_sel:DWORD dst_unused:UNUSED_PAD src0_sel:WORD_1
	v_pk_mul_f32 v[128:129], v[88:89], v[102:103] op_sel:[1,1] op_sel_hi:[1,0]
	v_pk_mul_f32 v[116:117], v[98:99], v[166:167] op_sel:[1,1] op_sel_hi:[1,0]
	v_pk_mul_f32 v[108:109], v[82:83], v[74:75] op_sel:[1,1] op_sel_hi:[1,0]
	v_pk_mul_f32 v[148:149], v[80:81], v[78:79] op_sel:[1,1] op_sel_hi:[1,0]
	v_pk_fma_f32 v[102:103], v[88:89], v[102:103], v[128:129] op_sel:[0,0,0] op_sel_hi:[0,1,1] neg_lo:[0,0,1] neg_hi:[0,0,0]
	v_pk_fma_f32 v[166:167], v[98:99], v[166:167], v[116:117] op_sel:[0,0,0] op_sel_hi:[0,1,1] neg_lo:[0,0,1] neg_hi:[0,0,0]
	v_pk_fma_f32 v[74:75], v[82:83], v[74:75], v[108:109] op_sel:[0,0,0] op_sel_hi:[0,1,1] neg_lo:[0,0,1] neg_hi:[0,0,0]
	v_pk_fma_f32 v[78:79], v[80:81], v[78:79], v[148:149] op_sel:[0,0,0] op_sel_hi:[0,1,1] neg_lo:[0,0,1] neg_hi:[0,0,0]
	v_cvt_f32_f16_e32 v92, v164
	v_cvt_f32_f16_e32 v104, v165
	v_cvt_f32_f16_e32 v124, v134
	v_cvt_f32_f16_e32 v112, v135
	v_cvt_f32_f16_sdwa v93, v164 dst_sel:DWORD dst_unused:UNUSED_PAD src0_sel:WORD_1
	v_cvt_f32_f16_sdwa v105, v165 dst_sel:DWORD dst_unused:UNUSED_PAD src0_sel:WORD_1
	v_cvt_f32_f16_sdwa v125, v134 dst_sel:DWORD dst_unused:UNUSED_PAD src0_sel:WORD_1
	v_cvt_f32_f16_sdwa v113, v135 dst_sel:DWORD dst_unused:UNUSED_PAD src0_sel:WORD_1
	v_pk_mul_f32 v[120:121], v[110:111], v[92:93] op_sel:[1,1] op_sel_hi:[1,0]
	v_pk_mul_f32 v[94:95], v[76:77], v[104:105] op_sel:[1,1] op_sel_hi:[1,0]
	v_pk_mul_f32 v[154:155], v[86:87], v[124:125] op_sel:[1,1] op_sel_hi:[1,0]
	v_pk_mul_f32 v[96:97], v[132:133], v[112:113] op_sel:[1,1] op_sel_hi:[1,0]
	v_pk_fma_f32 v[92:93], v[110:111], v[92:93], v[120:121] op_sel:[0,0,0] op_sel_hi:[0,1,1] neg_lo:[0,0,1] neg_hi:[0,0,0]
	v_pk_fma_f32 v[104:105], v[76:77], v[104:105], v[94:95] op_sel:[0,0,0] op_sel_hi:[0,1,1] neg_lo:[0,0,1] neg_hi:[0,0,0]
	v_pk_fma_f32 v[124:125], v[86:87], v[124:125], v[154:155] op_sel:[0,0,0] op_sel_hi:[0,1,1] neg_lo:[0,0,1] neg_hi:[0,0,0]
	v_pk_fma_f32 v[112:113], v[132:133], v[112:113], v[96:97] op_sel:[0,0,0] op_sel_hi:[0,1,1] neg_lo:[0,0,1] neg_hi:[0,0,0]
	v_cvt_f32_f16_e32 v152, v130
	v_cvt_f32_f16_e32 v128, v131
	v_cvt_f32_f16_e32 v116, v168
	v_cvt_f32_f16_e32 v108, v169
	v_cvt_f32_f16_sdwa v153, v130 dst_sel:DWORD dst_unused:UNUSED_PAD src0_sel:WORD_1
	v_cvt_f32_f16_sdwa v129, v131 dst_sel:DWORD dst_unused:UNUSED_PAD src0_sel:WORD_1
	v_cvt_f32_f16_sdwa v117, v168 dst_sel:DWORD dst_unused:UNUSED_PAD src0_sel:WORD_1
	v_cvt_f32_f16_sdwa v109, v169 dst_sel:DWORD dst_unused:UNUSED_PAD src0_sel:WORD_1
	v_pk_mul_f32 v[114:115], v[90:91], v[152:153] op_sel:[1,1] op_sel_hi:[1,0]
	v_pk_mul_f32 v[88:89], v[118:119], v[128:129] op_sel:[1,1] op_sel_hi:[1,0]
	v_pk_mul_f32 v[98:99], v[100:101], v[116:117] op_sel:[1,1] op_sel_hi:[1,0]
	v_pk_mul_f32 v[82:83], v[72:73], v[108:109] op_sel:[1,1] op_sel_hi:[1,0]
	v_pk_fma_f32 v[152:153], v[90:91], v[152:153], v[114:115] op_sel:[0,0,0] op_sel_hi:[0,1,1] neg_lo:[0,0,1] neg_hi:[0,0,0]
	v_pk_fma_f32 v[128:129], v[118:119], v[128:129], v[88:89] op_sel:[0,0,0] op_sel_hi:[0,1,1] neg_lo:[0,0,1] neg_hi:[0,0,0]
	v_pk_fma_f32 v[116:117], v[100:101], v[116:117], v[98:99] op_sel:[0,0,0] op_sel_hi:[0,1,1] neg_lo:[0,0,1] neg_hi:[0,0,0]
	v_pk_fma_f32 v[108:109], v[72:73], v[108:109], v[82:83] op_sel:[0,0,0] op_sel_hi:[0,1,1] neg_lo:[0,0,1] neg_hi:[0,0,0]
	v_pk_add_f32 v[148:149], v[126:127], v[122:123]
	v_pk_add_f32 v[80:81], v[84:85], v[150:151]
	v_pk_add_f32 v[120:121], v[102:103], v[166:167]
	v_pk_add_f32 v[110:111], v[74:75], v[78:79]
	v_pk_add_f32 v[126:127], v[126:127], v[122:123] neg_lo:[0,1] neg_hi:[0,1]
	v_pk_add_f32 v[84:85], v[84:85], v[150:151] neg_lo:[0,1] neg_hi:[0,1]
	v_pk_add_f32 v[102:103], v[102:103], v[166:167] neg_lo:[0,1] neg_hi:[0,1]
	v_pk_add_f32 v[74:75], v[74:75], v[78:79] neg_lo:[0,1] neg_hi:[0,1]
	v_pk_add_f32 v[94:95], v[92:93], v[104:105]
	v_pk_add_f32 v[76:77], v[124:125], v[112:113]
	v_pk_add_f32 v[154:155], v[152:153], v[128:129]
	v_pk_add_f32 v[86:87], v[116:117], v[108:109]
; __device__ __forceinline__ cf twc(cf ws, int k16) { if (k16 == 0) return ws; if (k16 == 4) return cf{ws.y, -ws.x}; return cmul(ws, cf{c16(k16), -s16(k16)}); }
; __device__ __forceinline__ void wave_lds_fence() { asm volatile("s_waitcnt lgkmcnt(0)" ::: "memory"); }
; template <int LR> __device__ __forceinline__ void dit_reg(cf (&x)[1 << LR], cf w) {
;     constexpr int R = 1 << LR; cf wsv[LR]; wsv[0] = w;
; #pragma unroll
;     for (int s = 1; s < LR; ++s) wsv[s] = cmul(wsv[s - 1], wsv[s - 1]);
; #pragma unroll
;     for (int s = LR - 1; s >= 0; --s) { const int half = R >> (s + 1);
; #pragma unroll
;         for (int m0 = 0; m0 < R; m0 += 2 * half)
; #pragma unroll
;             for (int mm = 0; mm < half; ++mm) { const int ia = m0 + mm, ib = ia + half; const cf a = x[ia];
;                 const cf b = cmulc(x[ib], twc(wsv[s], (mm << s) * (16 / R)));
;                 x[ia] = cf{a.x + b.x, a.y + b.y}; x[ib] = cf{a.x - b.x, a.y - b.y}; } }
; }
; __device__ __forceinline__ void fft_conv(ldsf2 buf, const LAS unsigned* spec) {
;     ...
;       dit_reg<4>(x, cf{1.0f, 0.0f});
; #pragma unroll
;       for (int m = 0; m < 16; ++m) buf[tid * 17 + m] = mkv2(x[m].x, x[m].y); }
;     wave_lds_fence();
	v_pk_add_f32 v[92:93], v[92:93], v[104:105] neg_lo:[0,1] neg_hi:[0,1]
	v_pk_add_f32 v[124:125], v[124:125], v[112:113] neg_lo:[0,1] neg_hi:[0,1]
	v_pk_add_f32 v[152:153], v[152:153], v[128:129] neg_lo:[0,1] neg_hi:[0,1]
	v_pk_add_f32 v[116:117], v[116:117], v[108:109] neg_lo:[0,1] neg_hi:[0,1]
	v_pk_add_f32 v[96:97], v[148:149], v[80:81]
	v_pk_add_f32 v[132:133], v[126:127], v[84:85] op_sel:[0,1] op_sel_hi:[1,0] neg_lo:[0,1] neg_hi:[0,0]
	v_pk_add_f32 v[114:115], v[120:121], v[110:111]
	v_pk_add_f32 v[90:91], v[102:103], v[74:75] op_sel:[0,1] op_sel_hi:[1,0] neg_lo:[0,1] neg_hi:[0,0]
	v_pk_add_f32 v[148:149], v[148:149], v[80:81] neg_lo:[0,1] neg_hi:[0,1]
	v_pk_add_f32 v[126:127], v[126:127], v[84:85] op_sel:[0,1] op_sel_hi:[1,0] neg_lo:[0,0] neg_hi:[0,1]
	v_pk_add_f32 v[120:121], v[120:121], v[110:111] neg_lo:[0,1] neg_hi:[0,1]
	v_pk_add_f32 v[102:103], v[102:103], v[74:75] op_sel:[0,1] op_sel_hi:[1,0] neg_lo:[0,0] neg_hi:[0,1]
	v_pk_add_f32 v[88:89], v[94:95], v[76:77]
	v_pk_add_f32 v[118:119], v[92:93], v[124:125] op_sel:[0,1] op_sel_hi:[1,0] neg_lo:[0,1] neg_hi:[0,0]
	v_pk_add_f32 v[98:99], v[154:155], v[86:87]
	v_pk_add_f32 v[100:101], v[152:153], v[116:117] op_sel:[0,1] op_sel_hi:[1,0] neg_lo:[0,1] neg_hi:[0,0]
	v_pk_add_f32 v[94:95], v[94:95], v[76:77] neg_lo:[0,1] neg_hi:[0,1]
	v_pk_add_f32 v[92:93], v[92:93], v[124:125] op_sel:[0,1] op_sel_hi:[1,0] neg_lo:[0,0] neg_hi:[0,1]
	v_pk_add_f32 v[154:155], v[154:155], v[86:87] neg_lo:[0,1] neg_hi:[0,1]
	v_pk_add_f32 v[152:153], v[152:153], v[116:117] op_sel:[0,1] op_sel_hi:[1,0] neg_lo:[0,0] neg_hi:[0,1]
	v_pk_add_f32 v[82:83], v[96:97], v[114:115]
	v_pk_mul_f32 v[72:73], v[90:91], s[16:17] op_sel:[1,0] op_sel_hi:[1,0] neg_lo:[0,1] neg_hi:[0,0]
	v_pk_add_f32 v[122:123], v[148:149], v[120:121] op_sel:[0,1] op_sel_hi:[1,0] neg_lo:[0,1] neg_hi:[0,0]
	v_pk_mul_f32 v[150:151], v[102:103], s[16:17] op_sel:[1,0] op_sel_hi:[1,0] neg_lo:[0,1] neg_hi:[0,1]
	v_pk_add_f32 v[96:97], v[96:97], v[114:115] neg_lo:[0,1] neg_hi:[0,1]
	v_pk_fma_f32 v[72:73], v[90:91], s[16:17], v[72:73] op_sel:[0,0,0] op_sel_hi:[0,0,1] neg_lo:[0,0,0] neg_hi:[0,0,0]
	v_pk_add_f32 v[148:149], v[148:149], v[120:121] op_sel:[0,1] op_sel_hi:[1,0] neg_lo:[0,0] neg_hi:[0,1]
	v_pk_fma_f32 v[150:151], v[102:103], s[16:17], v[150:151] op_sel:[0,0,0] op_sel_hi:[0,0,1] neg_lo:[0,1,0] neg_hi:[0,0,0]
	v_pk_add_f32 v[90:91], v[132:133], v[72:73] neg_lo:[0,1] neg_hi:[0,1]
	v_pk_add_f32 v[102:103], v[126:127], v[150:151] neg_lo:[0,1] neg_hi:[0,1]
	v_pk_add_f32 v[132:133], v[132:133], v[72:73]
	v_pk_add_f32 v[126:127], v[126:127], v[150:151]
	v_pk_add_f32 v[166:167], v[88:89], v[98:99]
	v_pk_mul_f32 v[78:79], v[100:101], s[16:17] op_sel:[1,0] op_sel_hi:[1,0] neg_lo:[0,1] neg_hi:[0,0]
	v_pk_add_f32 v[104:105], v[94:95], v[154:155] op_sel:[0,1] op_sel_hi:[1,0] neg_lo:[0,1] neg_hi:[0,0]
	v_pk_mul_f32 v[112:113], v[152:153], s[16:17] op_sel:[1,0] op_sel_hi:[1,0] neg_lo:[0,1] neg_hi:[0,1]
	v_pk_add_f32 v[88:89], v[88:89], v[98:99] neg_lo:[0,1] neg_hi:[0,1]
	v_pk_fma_f32 v[78:79], v[100:101], s[16:17], v[78:79] op_sel:[0,0,0] op_sel_hi:[0,0,1] neg_lo:[0,0,0] neg_hi:[0,0,0]
	v_pk_add_f32 v[94:95], v[94:95], v[154:155] op_sel:[0,1] op_sel_hi:[1,0] neg_lo:[0,0] neg_hi:[0,1]
	v_pk_fma_f32 v[112:113], v[152:153], s[16:17], v[112:113] op_sel:[0,0,0] op_sel_hi:[0,0,1] neg_lo:[0,1,0] neg_hi:[0,0,0]
	v_pk_add_f32 v[100:101], v[118:119], v[78:79] neg_lo:[0,1] neg_hi:[0,1]
	v_pk_add_f32 v[152:153], v[92:93], v[112:113] neg_lo:[0,1] neg_hi:[0,1]
	v_pk_add_f32 v[118:119], v[118:119], v[78:79]
	v_pk_add_f32 v[92:93], v[92:93], v[112:113]
	v_pk_add_f32 v[128:129], v[82:83], v[166:167]
	v_pk_mul_f32 v[108:109], v[118:119], s[4:5] op_sel:[1,1] op_sel_hi:[1,0] neg_lo:[0,1] neg_hi:[0,0]
	v_pk_mul_f32 v[80:81], v[104:105], s[16:17] op_sel:[1,0] op_sel_hi:[1,0] neg_lo:[0,1] neg_hi:[0,0]
	v_pk_mul_f32 v[84:85], v[92:93], s[4:5] op_sel:[1,0] op_sel_hi:[1,1] neg_lo:[0,1] neg_hi:[0,0]
	v_pk_add_f32 v[82:83], v[82:83], v[166:167] neg_lo:[0,1] neg_hi:[0,1]
	v_pk_fma_f32 v[108:109], v[118:119], s[4:5], v[108:109] op_sel:[0,0,0] op_sel_hi:[0,1,1] neg_lo:[0,0,0] neg_hi:[0,0,0]
	v_pk_fma_f32 v[80:81], v[104:105], s[16:17], v[80:81] op_sel:[0,0,0] op_sel_hi:[0,0,1] neg_lo:[0,0,0] neg_hi:[0,0,0]
	v_pk_fma_f32 v[84:85], v[92:93], s[4:5], v[84:85] op_sel:[0,1,0] op_sel_hi:[0,0,1] neg_lo:[0,0,0] neg_hi:[0,0,0]
	v_pk_add_f32 v[118:119], v[132:133], v[108:109] neg_lo:[0,1] neg_hi:[0,1]
	v_pk_add_f32 v[104:105], v[122:123], v[80:81] neg_lo:[0,1] neg_hi:[0,1]
	v_pk_add_f32 v[92:93], v[126:127], v[84:85] neg_lo:[0,1] neg_hi:[0,1]
	v_pk_add_f32 v[132:133], v[132:133], v[108:109]
	v_pk_add_f32 v[122:123], v[122:123], v[80:81]
	v_pk_add_f32 v[126:127], v[126:127], v[84:85]
	v_pk_add_f32 v[110:111], v[96:97], v[88:89] op_sel:[0,1] op_sel_hi:[1,0] neg_lo:[0,1] neg_hi:[0,0]
	v_pk_mul_f32 v[74:75], v[100:101], s[4:5] op_sel:[1,0] op_sel_hi:[1,1] neg_lo:[0,1] neg_hi:[0,1]
	v_pk_mul_f32 v[76:77], v[94:95], s[16:17] op_sel:[1,0] op_sel_hi:[1,0] neg_lo:[0,1] neg_hi:[0,1]
	v_pk_mul_f32 v[124:125], v[152:153], s[4:5] op_sel:[1,1] op_sel_hi:[1,0] neg_lo:[0,1] neg_hi:[0,1]
	v_pk_add_f32 v[96:97], v[96:97], v[88:89] op_sel:[0,1] op_sel_hi:[1,0] neg_lo:[0,0] neg_hi:[0,1]
	v_pk_fma_f32 v[74:75], v[100:101], s[4:5], v[74:75] op_sel:[0,1,0] op_sel_hi:[0,0,1] neg_lo:[0,1,0] neg_hi:[0,0,0]
	v_pk_fma_f32 v[76:77], v[94:95], s[16:17], v[76:77] op_sel:[0,0,0] op_sel_hi:[0,0,1] neg_lo:[0,1,0] neg_hi:[0,0,0]
	v_pk_fma_f32 v[124:125], v[152:153], s[4:5], v[124:125] op_sel:[0,0,0] op_sel_hi:[0,1,1] neg_lo:[0,1,0] neg_hi:[0,0,0]
	v_pk_add_f32 v[100:101], v[90:91], v[74:75] neg_lo:[0,1] neg_hi:[0,1]
	v_pk_add_f32 v[94:95], v[148:149], v[76:77] neg_lo:[0,1] neg_hi:[0,1]
	v_pk_add_f32 v[152:153], v[102:103], v[124:125] neg_lo:[0,1] neg_hi:[0,1]
	v_pk_add_f32 v[90:91], v[90:91], v[74:75]
	v_pk_add_f32 v[148:149], v[148:149], v[76:77]
	v_pk_add_f32 v[102:103], v[102:103], v[124:125]
	ds_write2_b64 v147, v[128:129], v[132:133] offset1:1
	ds_write2_b64 v147, v[122:123], v[126:127] offset0:2 offset1:3
	ds_write2_b64 v147, v[110:111], v[90:91] offset0:4 offset1:5
	ds_write2_b64 v147, v[148:149], v[102:103] offset0:6 offset1:7
	ds_write2_b64 v147, v[82:83], v[118:119] offset0:8 offset1:9
	ds_write2_b64 v147, v[104:105], v[92:93] offset0:10 offset1:11
	ds_write2_b64 v147, v[96:97], v[100:101] offset0:12 offset1:13
	ds_write2_b64 v147, v[94:95], v[152:153] offset0:14 offset1:15
	v_mov_b32_e32 v68, v195
	s_waitcnt lgkmcnt(0)
	s_mov_b32 s0, 0
	v_and_b32_e32 v73, 15, v68
	v_lshlrev_b32_e32 v72, 4, v68
	v_lshlrev_b32_e32 v75, 9, v73
	v_and_b32_e32 v72, 0xfffffc00, v72
	v_lshlrev_b32_e32 v74, 3, v68
	v_add_u32_e32 v75, 0, v75
	v_and_b32_e32 v69, 63, v68
	v_lshl_add_u32 v73, v73, 3, 0
	v_and_or_b32 v74, v74, s90, v72
	v_add_u32_e32 v75, 0x22000, v75
; #define LAS __attribute__((address_space(3)))
; __device__ __forceinline__ int otid() { int t = threadIdx.x; asm volatile("" : "+v"(t)); return t; }
; __device__ __forceinline__ cf twc(cf ws, int k16) { if (k16 == 0) return ws; if (k16 == 4) return cf{ws.y, -ws.x}; return cmul(ws, cf{c16(k16), -s16(k16)}); }
; template <int LR> __device__ __forceinline__ void dit_reg(cf (&x)[1 << LR], cf w) {
;     constexpr int R = 1 << LR; cf wsv[LR]; wsv[0] = w;
; #pragma unroll
;     for (int s = 1; s < LR; ++s) wsv[s] = cmul(wsv[s - 1], wsv[s - 1]);
; #pragma unroll
;     for (int s = LR - 1; s >= 0; --s) { const int half = R >> (s + 1);
; #pragma unroll
;         for (int m0 = 0; m0 < R; m0 += 2 * half)
; #pragma unroll
;             for (int mm = 0; mm < half; ++mm) { const int ia = m0 + mm, ib = ia + half; const cf a = x[ia];
;                 const cf b = cmulc(x[ib], twc(wsv[s], (mm << s) * (16 / R)));
;                 x[ia] = cf{a.x + b.x, a.y + b.y}; x[ib] = cf{a.x - b.x, a.y - b.y}; } }
; }
; __device__ __forceinline__ void lds_barrier() { asm volatile("s_waitcnt lgkmcnt(0)\n\ts_barrier" ::: "memory"); }
; template <int LR, bool INV> __device__ __forceinline__ void fft_pass(ldsf2 buf, int base, int stride, int twi) {
;     constexpr int R = 1 << LR; cf x[R];
;     const v2f wv = ((ldsf2)((LAS unsigned char*)buf + 139264))[twi];
; #pragma unroll
;     for (int m = 0; m < R; ++m) { const v2f v = buf[base + m * stride]; x[m] = cf{v.x, v.y}; }
;     const cf w{wv.x, wv.y};
;     if (INV) dit_reg<LR>(x, w); else dif_reg<LR>(x, w);
; #pragma unroll
;     for (int m = 0; m < R; ++m) buf[base + m * stride] = mkv2(x[m].x, x[m].y);
; }
; __device__ __forceinline__ void fft_inv_cba(ldsf2 buf) {
;     const int tid = otid(); const int wv = tid >> 6, l = tid & 63;
; #pragma unroll 1
;     for (int u = 0; u < 2; ++u) { const int j = l + 64 * u, o = j & 15, e0 = wv * 1024 + (j >> 4) * 128 + o; fft_pass<3, true>(buf, e0 + (e0 >> 4), 17, o * 64); }
.LBB0_353:
	v_or_b32_e32 v76, s0, v74
	v_lshlrev_b32_e32 v77, 3, v76
	v_ashrrev_i32_e32 v76, 1, v76
	v_add3_u32 v122, v73, v77, v76
	ds_read2_b64 v[76:79], v122 offset1:17
	ds_read2_b64 v[80:83], v122 offset0:34 offset1:51
	ds_read2_b64 v[84:87], v122 offset0:68 offset1:85
	ds_read2_b64 v[88:91], v122 offset0:102 offset1:119
	s_movk_i32 s0, 0x200
	v_or_b32_e32 v126, s0, v74
	v_lshlrev_b32_e32 v128, 3, v126
	v_ashrrev_i32_e32 v126, 1, v126
	v_add3_u32 v130, v73, v128, v126
	ds_read2_b64 v[132:135], v130 offset1:17
	ds_read2_b64 v[148:151], v130 offset0:34 offset1:51
	ds_read2_b64 v[152:155], v130 offset0:68 offset1:85
	ds_read2_b64 v[156:159], v130 offset0:102 offset1:119
	s_waitcnt lgkmcnt(4)
	v_pk_mul_f32 v[104:105], v[78:79], v[208:209] op_sel:[1,1] op_sel_hi:[1,0]
	v_pk_mul_f32 v[106:107], v[82:83], v[208:209] op_sel:[1,1] op_sel_hi:[1,0]
	v_pk_mul_f32 v[108:109], v[86:87], v[208:209] op_sel:[1,1] op_sel_hi:[1,0]
	v_pk_mul_f32 v[110:111], v[90:91], v[208:209] op_sel:[1,1] op_sel_hi:[1,0]
	v_pk_fma_f32 v[104:105], v[78:79], v[208:209], v[104:105] op_sel:[0,0,0] op_sel_hi:[0,1,1] neg_lo:[0,0,0] neg_hi:[0,1,0]
	v_pk_fma_f32 v[106:107], v[82:83], v[208:209], v[106:107] op_sel:[0,0,0] op_sel_hi:[0,1,1] neg_lo:[0,0,0] neg_hi:[0,1,0]
	v_pk_fma_f32 v[108:109], v[86:87], v[208:209], v[108:109] op_sel:[0,0,0] op_sel_hi:[0,1,1] neg_lo:[0,0,0] neg_hi:[0,1,0]
	v_pk_fma_f32 v[110:111], v[90:91], v[208:209], v[110:111] op_sel:[0,0,0] op_sel_hi:[0,1,1] neg_lo:[0,0,0] neg_hi:[0,1,0]
	v_pk_add_f32 v[78:79], v[76:77], v[104:105] neg_lo:[0,1] neg_hi:[0,1]
	v_pk_add_f32 v[82:83], v[80:81], v[106:107] neg_lo:[0,1] neg_hi:[0,1]
	v_pk_add_f32 v[86:87], v[84:85], v[108:109] neg_lo:[0,1] neg_hi:[0,1]
	v_pk_add_f32 v[90:91], v[88:89], v[110:111] neg_lo:[0,1] neg_hi:[0,1]
	v_pk_add_f32 v[76:77], v[76:77], v[104:105]
	v_pk_add_f32 v[80:81], v[80:81], v[106:107]
	v_pk_add_f32 v[84:85], v[84:85], v[108:109]
	v_pk_add_f32 v[88:89], v[88:89], v[110:111]
	v_pk_mul_f32 v[104:105], v[80:81], v[206:207] op_sel:[1,1] op_sel_hi:[1,0]
	v_pk_mul_f32 v[106:107], v[82:83], v[206:207] op_sel:[1,0] op_sel_hi:[1,1]
	v_pk_mul_f32 v[108:109], v[88:89], v[206:207] op_sel:[1,1] op_sel_hi:[1,0]
	v_pk_mul_f32 v[110:111], v[90:91], v[206:207] op_sel:[1,0] op_sel_hi:[1,1]
	v_pk_fma_f32 v[104:105], v[80:81], v[206:207], v[104:105] op_sel:[0,0,0] op_sel_hi:[0,1,1] neg_lo:[0,0,0] neg_hi:[0,1,0]
	v_pk_fma_f32 v[106:107], v[82:83], v[206:207], v[106:107] op_sel:[0,1,0] op_sel_hi:[0,0,1] neg_lo:[0,0,1] neg_hi:[0,0,0]
	v_pk_fma_f32 v[108:109], v[88:89], v[206:207], v[108:109] op_sel:[0,0,0] op_sel_hi:[0,1,1] neg_lo:[0,0,0] neg_hi:[0,1,0]
	v_pk_fma_f32 v[110:111], v[90:91], v[206:207], v[110:111] op_sel:[0,1,0] op_sel_hi:[0,0,1] neg_lo:[0,0,1] neg_hi:[0,0,0]
	v_pk_add_f32 v[80:81], v[76:77], v[104:105] neg_lo:[0,1] neg_hi:[0,1]
	v_pk_add_f32 v[82:83], v[78:79], v[106:107] neg_lo:[0,1] neg_hi:[0,1]
	v_pk_add_f32 v[88:89], v[84:85], v[108:109] neg_lo:[0,1] neg_hi:[0,1]
	v_pk_add_f32 v[90:91], v[86:87], v[110:111] neg_lo:[0,1] neg_hi:[0,1]
	v_pk_add_f32 v[76:77], v[76:77], v[104:105]
	v_pk_add_f32 v[78:79], v[78:79], v[106:107]
	v_pk_add_f32 v[84:85], v[84:85], v[108:109]
	v_pk_add_f32 v[86:87], v[86:87], v[110:111]
	v_pk_mul_f32 v[104:105], v[84:85], v[204:205] op_sel:[1,1] op_sel_hi:[1,0]
	v_pk_mul_f32 v[106:107], v[86:87], v[210:211] op_sel:[1,1] op_sel_hi:[1,0]
	v_pk_mul_f32 v[108:109], v[88:89], v[204:205] op_sel:[1,0] op_sel_hi:[1,1]
	v_pk_mul_f32 v[110:111], v[90:91], v[212:213] op_sel:[1,1] op_sel_hi:[1,0]
	v_pk_fma_f32 v[104:105], v[84:85], v[204:205], v[104:105] op_sel:[0,0,0] op_sel_hi:[0,1,1] neg_lo:[0,0,0] neg_hi:[0,1,0]
	v_pk_fma_f32 v[106:107], v[86:87], v[210:211], v[106:107] op_sel:[0,0,0] op_sel_hi:[0,1,1] neg_lo:[0,0,0] neg_hi:[0,1,0]
	v_pk_fma_f32 v[108:109], v[88:89], v[204:205], v[108:109] op_sel:[0,1,0] op_sel_hi:[0,0,1] neg_lo:[0,0,1] neg_hi:[0,0,0]
	v_pk_fma_f32 v[110:111], v[90:91], v[212:213], v[110:111] op_sel:[0,0,0] op_sel_hi:[0,1,1] neg_lo:[0,0,0] neg_hi:[0,1,0]
	v_pk_add_f32 v[84:85], v[76:77], v[104:105] neg_lo:[0,1] neg_hi:[0,1]
	v_pk_add_f32 v[86:87], v[78:79], v[106:107] neg_lo:[0,1] neg_hi:[0,1]
	v_pk_add_f32 v[88:89], v[80:81], v[108:109] neg_lo:[0,1] neg_hi:[0,1]
	v_pk_add_f32 v[90:91], v[82:83], v[110:111] neg_lo:[0,1] neg_hi:[0,1]
	v_pk_add_f32 v[76:77], v[76:77], v[104:105]
	v_pk_add_f32 v[78:79], v[78:79], v[106:107]
	v_pk_add_f32 v[80:81], v[80:81], v[108:109]
	v_pk_add_f32 v[82:83], v[82:83], v[110:111]
	ds_write2_b64 v122, v[76:77], v[78:79] offset1:17
	ds_write2_b64 v122, v[80:81], v[82:83] offset0:34 offset1:51
	ds_write2_b64 v122, v[84:85], v[86:87] offset0:68 offset1:85
	ds_write2_b64 v122, v[88:89], v[90:91] offset0:102 offset1:119
	s_waitcnt lgkmcnt(4)
; #define LAS __attribute__((address_space(3)))
; __device__ __forceinline__ cf twc(cf ws, int k16) { if (k16 == 0) return ws; if (k16 == 4) return cf{ws.y, -ws.x}; return cmul(ws, cf{c16(k16), -s16(k16)}); }
; __device__ __forceinline__ void wave_lds_fence() { asm volatile("s_waitcnt lgkmcnt(0)" ::: "memory"); }
; template <int LR> __device__ __forceinline__ void dit_reg(cf (&x)[1 << LR], cf w) {
;     constexpr int R = 1 << LR; cf wsv[LR]; wsv[0] = w;
; #pragma unroll
;     for (int s = 1; s < LR; ++s) wsv[s] = cmul(wsv[s - 1], wsv[s - 1]);
; #pragma unroll
;     for (int s = LR - 1; s >= 0; --s) { const int half = R >> (s + 1);
; #pragma unroll
;         for (int m0 = 0; m0 < R; m0 += 2 * half)
; #pragma unroll
;             for (int mm = 0; mm < half; ++mm) { const int ia = m0 + mm, ib = ia + half; const cf a = x[ia];
;                 const cf b = cmulc(x[ib], twc(wsv[s], (mm << s) * (16 / R)));
;                 x[ia] = cf{a.x + b.x, a.y + b.y}; x[ib] = cf{a.x - b.x, a.y - b.y}; } }
; }
; __device__ __forceinline__ void lds_barrier() { asm volatile("s_waitcnt lgkmcnt(0)\n\ts_barrier" ::: "memory"); }
; template <int LR, bool INV> __device__ __forceinline__ void fft_pass(ldsf2 buf, int base, int stride, int twi) {
;     constexpr int R = 1 << LR; cf x[R];
;     const v2f wv = ((ldsf2)((LAS unsigned char*)buf + 139264))[twi];
; #pragma unroll
;     for (int m = 0; m < R; ++m) { const v2f v = buf[base + m * stride]; x[m] = cf{v.x, v.y}; }
;     const cf w{wv.x, wv.y};
;     if (INV) dit_reg<LR>(x, w); else dif_reg<LR>(x, w);
; #pragma unroll
;     for (int m = 0; m < R; ++m) buf[base + m * stride] = mkv2(x[m].x, x[m].y);
; }
; __device__ __forceinline__ void fft_inv_cba(ldsf2 buf) {
;     ...
;     for (int u = 0; u < 2; ++u) { const int j = l + 64 * u, o = j & 15, e0 = wv * 1024 + (j >> 4) * 128 + o; fft_pass<3, true>(buf, e0 + (e0 >> 4), 17, o * 64); }
;     wave_lds_fence();
	v_pk_mul_f32 v[170:171], v[134:135], v[208:209] op_sel:[1,1] op_sel_hi:[1,0]
	v_pk_mul_f32 v[172:173], v[150:151], v[208:209] op_sel:[1,1] op_sel_hi:[1,0]
	v_pk_mul_f32 v[174:175], v[154:155], v[208:209] op_sel:[1,1] op_sel_hi:[1,0]
	v_pk_mul_f32 v[188:189], v[158:159], v[208:209] op_sel:[1,1] op_sel_hi:[1,0]
	v_pk_fma_f32 v[170:171], v[134:135], v[208:209], v[170:171] op_sel:[0,0,0] op_sel_hi:[0,1,1] neg_lo:[0,0,0] neg_hi:[0,1,0]
	v_pk_fma_f32 v[172:173], v[150:151], v[208:209], v[172:173] op_sel:[0,0,0] op_sel_hi:[0,1,1] neg_lo:[0,0,0] neg_hi:[0,1,0]
	v_pk_fma_f32 v[174:175], v[154:155], v[208:209], v[174:175] op_sel:[0,0,0] op_sel_hi:[0,1,1] neg_lo:[0,0,0] neg_hi:[0,1,0]
	v_pk_fma_f32 v[188:189], v[158:159], v[208:209], v[188:189] op_sel:[0,0,0] op_sel_hi:[0,1,1] neg_lo:[0,0,0] neg_hi:[0,1,0]
	v_pk_add_f32 v[134:135], v[132:133], v[170:171] neg_lo:[0,1] neg_hi:[0,1]
	v_pk_add_f32 v[150:151], v[148:149], v[172:173] neg_lo:[0,1] neg_hi:[0,1]
	v_pk_add_f32 v[154:155], v[152:153], v[174:175] neg_lo:[0,1] neg_hi:[0,1]
	v_pk_add_f32 v[158:159], v[156:157], v[188:189] neg_lo:[0,1] neg_hi:[0,1]
	v_pk_add_f32 v[132:133], v[132:133], v[170:171]
	v_pk_add_f32 v[148:149], v[148:149], v[172:173]
	v_pk_add_f32 v[152:153], v[152:153], v[174:175]
	v_pk_add_f32 v[156:157], v[156:157], v[188:189]
	v_pk_mul_f32 v[170:171], v[148:149], v[206:207] op_sel:[1,1] op_sel_hi:[1,0]
	v_pk_mul_f32 v[172:173], v[150:151], v[206:207] op_sel:[1,0] op_sel_hi:[1,1]
	v_pk_mul_f32 v[174:175], v[156:157], v[206:207] op_sel:[1,1] op_sel_hi:[1,0]
	v_pk_mul_f32 v[188:189], v[158:159], v[206:207] op_sel:[1,0] op_sel_hi:[1,1]
	v_pk_fma_f32 v[170:171], v[148:149], v[206:207], v[170:171] op_sel:[0,0,0] op_sel_hi:[0,1,1] neg_lo:[0,0,0] neg_hi:[0,1,0]
	v_pk_fma_f32 v[172:173], v[150:151], v[206:207], v[172:173] op_sel:[0,1,0] op_sel_hi:[0,0,1] neg_lo:[0,0,1] neg_hi:[0,0,0]
	v_pk_fma_f32 v[174:175], v[156:157], v[206:207], v[174:175] op_sel:[0,0,0] op_sel_hi:[0,1,1] neg_lo:[0,0,0] neg_hi:[0,1,0]
	v_pk_fma_f32 v[188:189], v[158:159], v[206:207], v[188:189] op_sel:[0,1,0] op_sel_hi:[0,0,1] neg_lo:[0,0,1] neg_hi:[0,0,0]
	v_pk_add_f32 v[148:149], v[132:133], v[170:171] neg_lo:[0,1] neg_hi:[0,1]
	v_pk_add_f32 v[150:151], v[134:135], v[172:173] neg_lo:[0,1] neg_hi:[0,1]
	v_pk_add_f32 v[156:157], v[152:153], v[174:175] neg_lo:[0,1] neg_hi:[0,1]
	v_pk_add_f32 v[158:159], v[154:155], v[188:189] neg_lo:[0,1] neg_hi:[0,1]
	v_pk_add_f32 v[132:133], v[132:133], v[170:171]
	v_pk_add_f32 v[134:135], v[134:135], v[172:173]
	v_pk_add_f32 v[152:153], v[152:153], v[174:175]
	v_pk_add_f32 v[154:155], v[154:155], v[188:189]
	v_pk_mul_f32 v[170:171], v[152:153], v[204:205] op_sel:[1,1] op_sel_hi:[1,0]
	v_pk_mul_f32 v[172:173], v[154:155], v[210:211] op_sel:[1,1] op_sel_hi:[1,0]
	v_pk_mul_f32 v[174:175], v[156:157], v[204:205] op_sel:[1,0] op_sel_hi:[1,1]
	v_pk_mul_f32 v[188:189], v[158:159], v[212:213] op_sel:[1,1] op_sel_hi:[1,0]
	v_pk_fma_f32 v[170:171], v[152:153], v[204:205], v[170:171] op_sel:[0,0,0] op_sel_hi:[0,1,1] neg_lo:[0,0,0] neg_hi:[0,1,0]
	v_pk_fma_f32 v[172:173], v[154:155], v[210:211], v[172:173] op_sel:[0,0,0] op_sel_hi:[0,1,1] neg_lo:[0,0,0] neg_hi:[0,1,0]
	v_pk_fma_f32 v[174:175], v[156:157], v[204:205], v[174:175] op_sel:[0,1,0] op_sel_hi:[0,0,1] neg_lo:[0,0,1] neg_hi:[0,0,0]
	v_pk_fma_f32 v[188:189], v[158:159], v[212:213], v[188:189] op_sel:[0,0,0] op_sel_hi:[0,1,1] neg_lo:[0,0,0] neg_hi:[0,1,0]
	v_pk_add_f32 v[152:153], v[132:133], v[170:171] neg_lo:[0,1] neg_hi:[0,1]
	v_pk_add_f32 v[154:155], v[134:135], v[172:173] neg_lo:[0,1] neg_hi:[0,1]
	v_pk_add_f32 v[156:157], v[148:149], v[174:175] neg_lo:[0,1] neg_hi:[0,1]
	v_pk_add_f32 v[158:159], v[150:151], v[188:189] neg_lo:[0,1] neg_hi:[0,1]
	v_pk_add_f32 v[132:133], v[132:133], v[170:171]
	v_pk_add_f32 v[134:135], v[134:135], v[172:173]
	v_pk_add_f32 v[148:149], v[148:149], v[174:175]
	v_pk_add_f32 v[150:151], v[150:151], v[188:189]
	ds_write2_b64 v130, v[132:133], v[134:135] offset1:17
	ds_write2_b64 v130, v[148:149], v[150:151] offset0:34 offset1:51
	ds_write2_b64 v130, v[152:153], v[154:155] offset0:68 offset1:85
	ds_write2_b64 v130, v[156:157], v[158:159] offset0:102 offset1:119
	s_mov_b64 s[6:7], 0
	s_waitcnt lgkmcnt(0)
	s_mov_b32 s0, 0
	s_mov_b64 s[6:7], -1
; #define LAS __attribute__((address_space(3)))
; __device__ __forceinline__ cf twc(cf ws, int k16) { if (k16 == 0) return ws; if (k16 == 4) return cf{ws.y, -ws.x}; return cmul(ws, cf{c16(k16), -s16(k16)}); }
; template <int LR> __device__ __forceinline__ void dit_reg(cf (&x)[1 << LR], cf w) {
;     constexpr int R = 1 << LR; cf wsv[LR]; wsv[0] = w;
; #pragma unroll
;     for (int s = 1; s < LR; ++s) wsv[s] = cmul(wsv[s - 1], wsv[s - 1]);
; #pragma unroll
;     for (int s = LR - 1; s >= 0; --s) { const int half = R >> (s + 1);
; #pragma unroll
;         for (int m0 = 0; m0 < R; m0 += 2 * half)
; #pragma unroll
;             for (int mm = 0; mm < half; ++mm) { const int ia = m0 + mm, ib = ia + half; const cf a = x[ia];
;                 const cf b = cmulc(x[ib], twc(wsv[s], (mm << s) * (16 / R)));
;                 x[ia] = cf{a.x + b.x, a.y + b.y}; x[ib] = cf{a.x - b.x, a.y - b.y}; } }
; }
; __device__ __forceinline__ void lds_barrier() { asm volatile("s_waitcnt lgkmcnt(0)\n\ts_barrier" ::: "memory"); }
; template <int LR, bool INV> __device__ __forceinline__ void fft_pass(ldsf2 buf, int base, int stride, int twi) {
;     constexpr int R = 1 << LR; cf x[R];
;     const v2f wv = ((ldsf2)((LAS unsigned char*)buf + 139264))[twi];
; #pragma unroll
;     for (int m = 0; m < R; ++m) { const v2f v = buf[base + m * stride]; x[m] = cf{v.x, v.y}; }
;     const cf w{wv.x, wv.y};
;     if (INV) dit_reg<LR>(x, w); else dif_reg<LR>(x, w);
; #pragma unroll
;     for (int m = 0; m < R; ++m) buf[base + m * stride] = mkv2(x[m].x, x[m].y);
; }
; __device__ __forceinline__ void fft_inv_cba(ldsf2 buf) {
;     ...
;     for (int u = 0; u < 2; ++u) { const int o = l + 64 * u, e0 = wv * 1024 + o; fft_pass<3, true>(buf, e0 + (e0 >> 4), 136, o * 8); }
.LBB0_355:
	v_or_b32_e32 v73, s0, v69
	v_or_b32_e32 v74, v73, v72
	v_lshl_add_u32 v73, v73, 6, 0
	v_add_u32_e32 v73, 0x22000, v73
	v_ashrrev_i32_e32 v75, 4, v74
	v_lshlrev_b32_e32 v73, 3, v74
	v_lshlrev_b32_e32 v74, 3, v75
	v_add3_u32 v73, 0, v73, v74
	v_add_u32_e32 v122, 0x1800, v73
	v_add_u32_e32 v121, 0x1000, v73
	ds_read2_b64 v[86:89], v122 offset0:48 offset1:184
	ds_read2_b64 v[82:85], v121 offset0:32 offset1:168
	v_add_u32_e32 v120, 0x800, v73
	ds_read2_b64 v[74:77], v73 offset1:136
	ds_read2_b64 v[78:81], v120 offset0:16 offset1:152
	s_mov_b32 s0, 64
	v_or_b32_e32 v124, s0, v69
	v_or_b32_e32 v126, v124, v72
	v_lshl_add_u32 v124, v124, 6, 0
	v_add_u32_e32 v124, 0x22000, v124
	v_ashrrev_i32_e32 v130, 4, v126
	v_lshlrev_b32_e32 v124, 3, v126
	v_lshlrev_b32_e32 v126, 3, v130
	v_add3_u32 v124, 0, v124, v126
	v_add_u32_e32 v132, 0x1800, v124
	v_add_u32_e32 v134, 0x1000, v124
	ds_read2_b64 v[148:151], v132 offset0:48 offset1:184
	ds_read2_b64 v[152:155], v134 offset0:32 offset1:168
	v_add_u32_e32 v156, 0x800, v124
	ds_read2_b64 v[158:161], v124 offset1:136
	ds_read2_b64 v[162:165], v156 offset0:16 offset1:152
	s_waitcnt lgkmcnt(4)
	v_pk_add_f32 v[92:93], v[214:215], v[214:215] op_sel:[0,1] op_sel_hi:[1,0] neg_lo:[0,0] neg_hi:[0,1]
	s_nop 0
	v_pk_mul_f32 v[94:95], v[92:93], s[16:17] op_sel:[0,0] op_sel_hi:[1,0]
	v_pk_mul_f32 v[96:97], v[92:93], s[16:17] op_sel:[1,0] op_sel_hi:[0,0] neg_lo:[0,0] neg_hi:[1,0]
	v_pk_mul_f32 v[102:103], v[76:77], v[218:219] op_sel:[1,1] op_sel_hi:[1,0]
	v_pk_mul_f32 v[104:105], v[80:81], v[218:219] op_sel:[1,1] op_sel_hi:[1,0]
	v_pk_mul_f32 v[106:107], v[84:85], v[218:219] op_sel:[1,1] op_sel_hi:[1,0]
	v_pk_mul_f32 v[108:109], v[88:89], v[218:219] op_sel:[1,1] op_sel_hi:[1,0]
	v_pk_fma_f32 v[102:103], v[76:77], v[218:219], v[102:103] op_sel:[0,0,0] op_sel_hi:[0,1,1] neg_lo:[0,0,0] neg_hi:[0,1,0]
	v_pk_fma_f32 v[104:105], v[80:81], v[218:219], v[104:105] op_sel:[0,0,0] op_sel_hi:[0,1,1] neg_lo:[0,0,0] neg_hi:[0,1,0]
	v_pk_fma_f32 v[106:107], v[84:85], v[218:219], v[106:107] op_sel:[0,0,0] op_sel_hi:[0,1,1] neg_lo:[0,0,0] neg_hi:[0,1,0]
	v_pk_fma_f32 v[108:109], v[88:89], v[218:219], v[108:109] op_sel:[0,0,0] op_sel_hi:[0,1,1] neg_lo:[0,0,0] neg_hi:[0,1,0]
	v_pk_add_f32 v[76:77], v[74:75], v[102:103] neg_lo:[0,1] neg_hi:[0,1]
	v_pk_add_f32 v[80:81], v[78:79], v[104:105] neg_lo:[0,1] neg_hi:[0,1]
	v_pk_add_f32 v[84:85], v[82:83], v[106:107] neg_lo:[0,1] neg_hi:[0,1]
	v_pk_add_f32 v[88:89], v[86:87], v[108:109] neg_lo:[0,1] neg_hi:[0,1]
	v_pk_add_f32 v[74:75], v[74:75], v[102:103]
	v_pk_add_f32 v[78:79], v[78:79], v[104:105]
	v_pk_add_f32 v[82:83], v[82:83], v[106:107]
	v_pk_add_f32 v[86:87], v[86:87], v[108:109]
	v_pk_mul_f32 v[102:103], v[78:79], v[216:217] op_sel:[1,1] op_sel_hi:[1,0]
	v_pk_mul_f32 v[104:105], v[80:81], v[216:217] op_sel:[1,0] op_sel_hi:[1,1]
	v_pk_mul_f32 v[106:107], v[86:87], v[216:217] op_sel:[1,1] op_sel_hi:[1,0]
	v_pk_mul_f32 v[108:109], v[88:89], v[216:217] op_sel:[1,0] op_sel_hi:[1,1]
	v_pk_fma_f32 v[102:103], v[78:79], v[216:217], v[102:103] op_sel:[0,0,0] op_sel_hi:[0,1,1] neg_lo:[0,0,0] neg_hi:[0,1,0]
	v_pk_fma_f32 v[104:105], v[80:81], v[216:217], v[104:105] op_sel:[0,1,0] op_sel_hi:[0,0,1] neg_lo:[0,0,1] neg_hi:[0,0,0]
	v_pk_fma_f32 v[106:107], v[86:87], v[216:217], v[106:107] op_sel:[0,0,0] op_sel_hi:[0,1,1] neg_lo:[0,0,0] neg_hi:[0,1,0]
	v_pk_fma_f32 v[108:109], v[88:89], v[216:217], v[108:109] op_sel:[0,1,0] op_sel_hi:[0,0,1] neg_lo:[0,0,1] neg_hi:[0,0,0]
	v_pk_add_f32 v[78:79], v[74:75], v[102:103] neg_lo:[0,1] neg_hi:[0,1]
	v_pk_add_f32 v[80:81], v[76:77], v[104:105] neg_lo:[0,1] neg_hi:[0,1]
	v_pk_add_f32 v[86:87], v[82:83], v[106:107] neg_lo:[0,1] neg_hi:[0,1]
	v_pk_add_f32 v[88:89], v[84:85], v[108:109] neg_lo:[0,1] neg_hi:[0,1]
	v_pk_add_f32 v[74:75], v[74:75], v[102:103]
	v_pk_add_f32 v[76:77], v[76:77], v[104:105]
	v_pk_add_f32 v[82:83], v[82:83], v[106:107]
	v_pk_add_f32 v[84:85], v[84:85], v[108:109]
	v_pk_mul_f32 v[102:103], v[82:83], v[214:215] op_sel:[1,1] op_sel_hi:[1,0]
	v_pk_mul_f32 v[104:105], v[84:85], v[94:95] op_sel:[1,1] op_sel_hi:[1,0]
	v_pk_mul_f32 v[106:107], v[86:87], v[214:215] op_sel:[1,0] op_sel_hi:[1,1]
	v_pk_mul_f32 v[108:109], v[88:89], v[96:97] op_sel:[1,1] op_sel_hi:[1,0]
	v_pk_fma_f32 v[102:103], v[82:83], v[214:215], v[102:103] op_sel:[0,0,0] op_sel_hi:[0,1,1] neg_lo:[0,0,0] neg_hi:[0,1,0]
	v_pk_fma_f32 v[104:105], v[84:85], v[94:95], v[104:105] op_sel:[0,0,0] op_sel_hi:[0,1,1] neg_lo:[0,0,0] neg_hi:[0,1,0]
	v_pk_fma_f32 v[106:107], v[86:87], v[214:215], v[106:107] op_sel:[0,1,0] op_sel_hi:[0,0,1] neg_lo:[0,0,1] neg_hi:[0,0,0]
	v_pk_fma_f32 v[108:109], v[88:89], v[96:97], v[108:109] op_sel:[0,0,0] op_sel_hi:[0,1,1] neg_lo:[0,0,0] neg_hi:[0,1,0]
	v_pk_add_f32 v[82:83], v[74:75], v[102:103] neg_lo:[0,1] neg_hi:[0,1]
	v_pk_add_f32 v[84:85], v[76:77], v[104:105] neg_lo:[0,1] neg_hi:[0,1]
	v_pk_add_f32 v[86:87], v[78:79], v[106:107] neg_lo:[0,1] neg_hi:[0,1]
	v_pk_add_f32 v[88:89], v[80:81], v[108:109] neg_lo:[0,1] neg_hi:[0,1]
	v_pk_add_f32 v[74:75], v[74:75], v[102:103]
	v_pk_add_f32 v[76:77], v[76:77], v[104:105]
	v_pk_add_f32 v[78:79], v[78:79], v[106:107]
	v_pk_add_f32 v[80:81], v[80:81], v[108:109]
	ds_write2_b64 v73, v[74:75], v[76:77] offset1:136
	ds_write2_b64 v120, v[78:79], v[80:81] offset0:16 offset1:152
	ds_write2_b64 v121, v[82:83], v[84:85] offset0:32 offset1:168
	ds_write2_b64 v122, v[86:87], v[88:89] offset0:48 offset1:184
	s_waitcnt lgkmcnt(4)
; #define LAS __attribute__((address_space(3)))
; __device__ __forceinline__ cf twc(cf ws, int k16) { if (k16 == 0) return ws; if (k16 == 4) return cf{ws.y, -ws.x}; return cmul(ws, cf{c16(k16), -s16(k16)}); }
; template <int LR> __device__ __forceinline__ void dit_reg(cf (&x)[1 << LR], cf w) {
;     constexpr int R = 1 << LR; cf wsv[LR]; wsv[0] = w;
; #pragma unroll
;     for (int s = 1; s < LR; ++s) wsv[s] = cmul(wsv[s - 1], wsv[s - 1]);
; #pragma unroll
;     for (int s = LR - 1; s >= 0; --s) { const int half = R >> (s + 1);
; #pragma unroll
;         for (int m0 = 0; m0 < R; m0 += 2 * half)
; #pragma unroll
;             for (int mm = 0; mm < half; ++mm) { const int ia = m0 + mm, ib = ia + half; const cf a = x[ia];
;                 const cf b = cmulc(x[ib], twc(wsv[s], (mm << s) * (16 / R)));
;                 x[ia] = cf{a.x + b.x, a.y + b.y}; x[ib] = cf{a.x - b.x, a.y - b.y}; } }
; }
; __device__ __forceinline__ void lds_barrier() { asm volatile("s_waitcnt lgkmcnt(0)\n\ts_barrier" ::: "memory"); }
; template <int LR, bool INV> __device__ __forceinline__ void fft_pass(ldsf2 buf, int base, int stride, int twi) {
;     constexpr int R = 1 << LR; cf x[R];
;     const v2f wv = ((ldsf2)((LAS unsigned char*)buf + 139264))[twi];
; #pragma unroll
;     for (int m = 0; m < R; ++m) { const v2f v = buf[base + m * stride]; x[m] = cf{v.x, v.y}; }
;     const cf w{wv.x, wv.y};
;     if (INV) dit_reg<LR>(x, w); else dif_reg<LR>(x, w);
; #pragma unroll
;     for (int m = 0; m < R; ++m) buf[base + m * stride] = mkv2(x[m].x, x[m].y);
; }
; __device__ __forceinline__ void fft_inv_cba(ldsf2 buf) {
;     ...
;     for (int u = 0; u < 2; ++u) { const int o = l + 64 * u, e0 = wv * 1024 + o; fft_pass<3, true>(buf, e0 + (e0 >> 4), 136, o * 8); }
;     lds_barrier();
	v_pk_add_f32 v[166:167], v[220:221], v[220:221] op_sel:[0,1] op_sel_hi:[1,0] neg_lo:[0,0] neg_hi:[0,1]
	s_nop 0
	v_pk_mul_f32 v[168:169], v[166:167], s[16:17] op_sel:[0,0] op_sel_hi:[1,0]
	v_pk_mul_f32 v[170:171], v[166:167], s[16:17] op_sel:[1,0] op_sel_hi:[0,0] neg_lo:[0,0] neg_hi:[1,0]
	v_pk_mul_f32 v[188:189], v[160:161], v[224:225] op_sel:[1,1] op_sel_hi:[1,0]
	v_pk_mul_f32 v[190:191], v[164:165], v[224:225] op_sel:[1,1] op_sel_hi:[1,0]
	v_pk_mul_f32 v[196:197], v[154:155], v[224:225] op_sel:[1,1] op_sel_hi:[1,0]
	v_pk_mul_f32 v[198:199], v[150:151], v[224:225] op_sel:[1,1] op_sel_hi:[1,0]
	v_pk_fma_f32 v[188:189], v[160:161], v[224:225], v[188:189] op_sel:[0,0,0] op_sel_hi:[0,1,1] neg_lo:[0,0,0] neg_hi:[0,1,0]
	v_pk_fma_f32 v[190:191], v[164:165], v[224:225], v[190:191] op_sel:[0,0,0] op_sel_hi:[0,1,1] neg_lo:[0,0,0] neg_hi:[0,1,0]
	v_pk_fma_f32 v[196:197], v[154:155], v[224:225], v[196:197] op_sel:[0,0,0] op_sel_hi:[0,1,1] neg_lo:[0,0,0] neg_hi:[0,1,0]
	v_pk_fma_f32 v[198:199], v[150:151], v[224:225], v[198:199] op_sel:[0,0,0] op_sel_hi:[0,1,1] neg_lo:[0,0,0] neg_hi:[0,1,0]
	v_pk_add_f32 v[160:161], v[158:159], v[188:189] neg_lo:[0,1] neg_hi:[0,1]
	v_pk_add_f32 v[164:165], v[162:163], v[190:191] neg_lo:[0,1] neg_hi:[0,1]
	v_pk_add_f32 v[154:155], v[152:153], v[196:197] neg_lo:[0,1] neg_hi:[0,1]
	v_pk_add_f32 v[150:151], v[148:149], v[198:199] neg_lo:[0,1] neg_hi:[0,1]
	v_pk_add_f32 v[158:159], v[158:159], v[188:189]
	v_pk_add_f32 v[162:163], v[162:163], v[190:191]
	v_pk_add_f32 v[152:153], v[152:153], v[196:197]
	v_pk_add_f32 v[148:149], v[148:149], v[198:199]
	v_pk_mul_f32 v[188:189], v[162:163], v[222:223] op_sel:[1,1] op_sel_hi:[1,0]
	v_pk_mul_f32 v[190:191], v[164:165], v[222:223] op_sel:[1,0] op_sel_hi:[1,1]
	v_pk_mul_f32 v[196:197], v[148:149], v[222:223] op_sel:[1,1] op_sel_hi:[1,0]
	v_pk_mul_f32 v[198:199], v[150:151], v[222:223] op_sel:[1,0] op_sel_hi:[1,1]
	v_pk_fma_f32 v[188:189], v[162:163], v[222:223], v[188:189] op_sel:[0,0,0] op_sel_hi:[0,1,1] neg_lo:[0,0,0] neg_hi:[0,1,0]
	v_pk_fma_f32 v[190:191], v[164:165], v[222:223], v[190:191] op_sel:[0,1,0] op_sel_hi:[0,0,1] neg_lo:[0,0,1] neg_hi:[0,0,0]
	v_pk_fma_f32 v[196:197], v[148:149], v[222:223], v[196:197] op_sel:[0,0,0] op_sel_hi:[0,1,1] neg_lo:[0,0,0] neg_hi:[0,1,0]
	v_pk_fma_f32 v[198:199], v[150:151], v[222:223], v[198:199] op_sel:[0,1,0] op_sel_hi:[0,0,1] neg_lo:[0,0,1] neg_hi:[0,0,0]
	v_pk_add_f32 v[162:163], v[158:159], v[188:189] neg_lo:[0,1] neg_hi:[0,1]
	v_pk_add_f32 v[164:165], v[160:161], v[190:191] neg_lo:[0,1] neg_hi:[0,1]
	v_pk_add_f32 v[148:149], v[152:153], v[196:197] neg_lo:[0,1] neg_hi:[0,1]
	v_pk_add_f32 v[150:151], v[154:155], v[198:199] neg_lo:[0,1] neg_hi:[0,1]
	v_pk_add_f32 v[158:159], v[158:159], v[188:189]
	v_pk_add_f32 v[160:161], v[160:161], v[190:191]
	v_pk_add_f32 v[152:153], v[152:153], v[196:197]
	v_pk_add_f32 v[154:155], v[154:155], v[198:199]
	v_pk_mul_f32 v[188:189], v[152:153], v[220:221] op_sel:[1,1] op_sel_hi:[1,0]
	v_pk_mul_f32 v[190:191], v[154:155], v[168:169] op_sel:[1,1] op_sel_hi:[1,0]
	v_pk_mul_f32 v[196:197], v[148:149], v[220:221] op_sel:[1,0] op_sel_hi:[1,1]
	v_pk_mul_f32 v[198:199], v[150:151], v[170:171] op_sel:[1,1] op_sel_hi:[1,0]
	v_pk_fma_f32 v[188:189], v[152:153], v[220:221], v[188:189] op_sel:[0,0,0] op_sel_hi:[0,1,1] neg_lo:[0,0,0] neg_hi:[0,1,0]
	v_pk_fma_f32 v[190:191], v[154:155], v[168:169], v[190:191] op_sel:[0,0,0] op_sel_hi:[0,1,1] neg_lo:[0,0,0] neg_hi:[0,1,0]
	v_pk_fma_f32 v[196:197], v[148:149], v[220:221], v[196:197] op_sel:[0,1,0] op_sel_hi:[0,0,1] neg_lo:[0,0,1] neg_hi:[0,0,0]
	v_pk_fma_f32 v[198:199], v[150:151], v[170:171], v[198:199] op_sel:[0,0,0] op_sel_hi:[0,1,1] neg_lo:[0,0,0] neg_hi:[0,1,0]
	v_pk_add_f32 v[152:153], v[158:159], v[188:189] neg_lo:[0,1] neg_hi:[0,1]
	v_pk_add_f32 v[154:155], v[160:161], v[190:191] neg_lo:[0,1] neg_hi:[0,1]
	v_pk_add_f32 v[148:149], v[162:163], v[196:197] neg_lo:[0,1] neg_hi:[0,1]
	v_pk_add_f32 v[150:151], v[164:165], v[198:199] neg_lo:[0,1] neg_hi:[0,1]
	v_pk_add_f32 v[158:159], v[158:159], v[188:189]
	v_pk_add_f32 v[160:161], v[160:161], v[190:191]
	v_pk_add_f32 v[162:163], v[162:163], v[196:197]
	v_pk_add_f32 v[164:165], v[164:165], v[198:199]
	ds_write2_b64 v124, v[158:159], v[160:161] offset1:136
	ds_write2_b64 v156, v[162:163], v[164:165] offset0:16 offset1:152
	ds_write2_b64 v134, v[152:153], v[154:155] offset0:32 offset1:168
	ds_write2_b64 v132, v[148:149], v[150:151] offset0:48 offset1:184
	s_mov_b64 s[6:7], 0
	s_waitcnt lgkmcnt(0)
	s_barrier
	s_mov_b32 s0, 0
	s_mov_b64 s[6:7], -1
; #define LAS __attribute__((address_space(3)))
; __device__ __forceinline__ cf twc(cf ws, int k16) { if (k16 == 0) return ws; if (k16 == 4) return cf{ws.y, -ws.x}; return cmul(ws, cf{c16(k16), -s16(k16)}); }
; template <int LR> __device__ __forceinline__ void dit_reg(cf (&x)[1 << LR], cf w) {
;     constexpr int R = 1 << LR; cf wsv[LR]; wsv[0] = w;
; #pragma unroll
;     for (int s = 1; s < LR; ++s) wsv[s] = cmul(wsv[s - 1], wsv[s - 1]);
; #pragma unroll
;     for (int s = LR - 1; s >= 0; --s) { const int half = R >> (s + 1);
; #pragma unroll
;         for (int m0 = 0; m0 < R; m0 += 2 * half)
; #pragma unroll
;             for (int mm = 0; mm < half; ++mm) { const int ia = m0 + mm, ib = ia + half; const cf a = x[ia];
;                 const cf b = cmulc(x[ib], twc(wsv[s], (mm << s) * (16 / R)));
;                 x[ia] = cf{a.x + b.x, a.y + b.y}; x[ib] = cf{a.x - b.x, a.y - b.y}; } }
; }
; __device__ __forceinline__ void lds_barrier() { asm volatile("s_waitcnt lgkmcnt(0)\n\ts_barrier" ::: "memory"); }
; template <int LR, bool INV> __device__ __forceinline__ void fft_pass(ldsf2 buf, int base, int stride, int twi) {
;     constexpr int R = 1 << LR; cf x[R];
;     const v2f wv = ((ldsf2)((LAS unsigned char*)buf + 139264))[twi];
; #pragma unroll
;     for (int m = 0; m < R; ++m) { const v2f v = buf[base + m * stride]; x[m] = cf{v.x, v.y}; }
;     const cf w{wv.x, wv.y};
;     if (INV) dit_reg<LR>(x, w); else dif_reg<LR>(x, w);
; #pragma unroll
;     for (int m = 0; m < R; ++m) buf[base + m * stride] = mkv2(x[m].x, x[m].y);
; }
.LBB0_357:
	v_add_u32_e32 v69, s0, v68
	v_ashrrev_i32_e32 v72, 4, v69
	v_lshl_add_u32 v69, v69, 3, 0
	v_add_u32_e32 v73, 0x22000, v69
	v_lshl_add_u32 v69, v72, 3, v69
	ds_read2st64_b64 v[72:75], v69 offset1:17
	ds_read2st64_b64 v[76:79], v69 offset0:34 offset1:51
	ds_read2st64_b64 v[80:83], v69 offset0:68 offset1:85
	ds_read2st64_b64 v[84:87], v69 offset0:102 offset1:119
	s_movk_i32 s0, 0x200
	v_add_u32_e32 v118, s0, v68
	v_ashrrev_i32_e32 v120, 4, v118
	v_lshl_add_u32 v118, v118, 3, 0
	v_add_u32_e32 v122, 0x22000, v118
	v_lshl_add_u32 v118, v120, 3, v118
	ds_read2st64_b64 v[126:129], v118 offset1:17
	ds_read2st64_b64 v[130:133], v118 offset0:34 offset1:51
	ds_read2st64_b64 v[148:151], v118 offset0:68 offset1:85
	ds_read2st64_b64 v[152:155], v118 offset0:102 offset1:119
	s_waitcnt lgkmcnt(4)
	v_pk_add_f32 v[90:91], v[232:233], v[232:233] op_sel:[0,1] op_sel_hi:[1,0] neg_lo:[0,0] neg_hi:[0,1]
	s_nop 0
	v_pk_mul_f32 v[92:93], v[90:91], s[16:17] op_sel:[0,0] op_sel_hi:[1,0]
	v_pk_mul_f32 v[94:95], v[90:91], s[16:17] op_sel:[1,0] op_sel_hi:[0,0] neg_lo:[0,0] neg_hi:[1,0]
	v_pk_mul_f32 v[100:101], v[74:75], v[236:237] op_sel:[1,1] op_sel_hi:[1,0]
	v_pk_mul_f32 v[102:103], v[78:79], v[236:237] op_sel:[1,1] op_sel_hi:[1,0]
	v_pk_mul_f32 v[104:105], v[82:83], v[236:237] op_sel:[1,1] op_sel_hi:[1,0]
	v_pk_mul_f32 v[106:107], v[86:87], v[236:237] op_sel:[1,1] op_sel_hi:[1,0]
	v_pk_fma_f32 v[100:101], v[74:75], v[236:237], v[100:101] op_sel:[0,0,0] op_sel_hi:[0,1,1] neg_lo:[0,0,0] neg_hi:[0,1,0]
	v_pk_fma_f32 v[102:103], v[78:79], v[236:237], v[102:103] op_sel:[0,0,0] op_sel_hi:[0,1,1] neg_lo:[0,0,0] neg_hi:[0,1,0]
	v_pk_fma_f32 v[104:105], v[82:83], v[236:237], v[104:105] op_sel:[0,0,0] op_sel_hi:[0,1,1] neg_lo:[0,0,0] neg_hi:[0,1,0]
	v_pk_fma_f32 v[106:107], v[86:87], v[236:237], v[106:107] op_sel:[0,0,0] op_sel_hi:[0,1,1] neg_lo:[0,0,0] neg_hi:[0,1,0]
	v_pk_add_f32 v[74:75], v[72:73], v[100:101] neg_lo:[0,1] neg_hi:[0,1]
	v_pk_add_f32 v[78:79], v[76:77], v[102:103] neg_lo:[0,1] neg_hi:[0,1]
	v_pk_add_f32 v[82:83], v[80:81], v[104:105] neg_lo:[0,1] neg_hi:[0,1]
	v_pk_add_f32 v[86:87], v[84:85], v[106:107] neg_lo:[0,1] neg_hi:[0,1]
	v_pk_add_f32 v[72:73], v[72:73], v[100:101]
	v_pk_add_f32 v[76:77], v[76:77], v[102:103]
	v_pk_add_f32 v[80:81], v[80:81], v[104:105]
	v_pk_add_f32 v[84:85], v[84:85], v[106:107]
	v_pk_mul_f32 v[100:101], v[76:77], v[234:235] op_sel:[1,1] op_sel_hi:[1,0]
	v_pk_mul_f32 v[102:103], v[78:79], v[234:235] op_sel:[1,0] op_sel_hi:[1,1]
	v_pk_mul_f32 v[104:105], v[84:85], v[234:235] op_sel:[1,1] op_sel_hi:[1,0]
	v_pk_mul_f32 v[106:107], v[86:87], v[234:235] op_sel:[1,0] op_sel_hi:[1,1]
	v_pk_fma_f32 v[100:101], v[76:77], v[234:235], v[100:101] op_sel:[0,0,0] op_sel_hi:[0,1,1] neg_lo:[0,0,0] neg_hi:[0,1,0]
	v_pk_fma_f32 v[102:103], v[78:79], v[234:235], v[102:103] op_sel:[0,1,0] op_sel_hi:[0,0,1] neg_lo:[0,0,1] neg_hi:[0,0,0]
	v_pk_fma_f32 v[104:105], v[84:85], v[234:235], v[104:105] op_sel:[0,0,0] op_sel_hi:[0,1,1] neg_lo:[0,0,0] neg_hi:[0,1,0]
	v_pk_fma_f32 v[106:107], v[86:87], v[234:235], v[106:107] op_sel:[0,1,0] op_sel_hi:[0,0,1] neg_lo:[0,0,1] neg_hi:[0,0,0]
	v_pk_add_f32 v[76:77], v[72:73], v[100:101] neg_lo:[0,1] neg_hi:[0,1]
	v_pk_add_f32 v[78:79], v[74:75], v[102:103] neg_lo:[0,1] neg_hi:[0,1]
	v_pk_add_f32 v[84:85], v[80:81], v[104:105] neg_lo:[0,1] neg_hi:[0,1]
	v_pk_add_f32 v[86:87], v[82:83], v[106:107] neg_lo:[0,1] neg_hi:[0,1]
	v_pk_add_f32 v[72:73], v[72:73], v[100:101]
	v_pk_add_f32 v[74:75], v[74:75], v[102:103]
	v_pk_add_f32 v[80:81], v[80:81], v[104:105]
	v_pk_add_f32 v[82:83], v[82:83], v[106:107]
	v_pk_mul_f32 v[100:101], v[80:81], v[232:233] op_sel:[1,1] op_sel_hi:[1,0]
	v_pk_mul_f32 v[102:103], v[82:83], v[92:93] op_sel:[1,1] op_sel_hi:[1,0]
	v_pk_mul_f32 v[104:105], v[84:85], v[232:233] op_sel:[1,0] op_sel_hi:[1,1]
	v_pk_mul_f32 v[106:107], v[86:87], v[94:95] op_sel:[1,1] op_sel_hi:[1,0]
	v_pk_fma_f32 v[100:101], v[80:81], v[232:233], v[100:101] op_sel:[0,0,0] op_sel_hi:[0,1,1] neg_lo:[0,0,0] neg_hi:[0,1,0]
	v_pk_fma_f32 v[102:103], v[82:83], v[92:93], v[102:103] op_sel:[0,0,0] op_sel_hi:[0,1,1] neg_lo:[0,0,0] neg_hi:[0,1,0]
	v_pk_fma_f32 v[104:105], v[84:85], v[232:233], v[104:105] op_sel:[0,1,0] op_sel_hi:[0,0,1] neg_lo:[0,0,1] neg_hi:[0,0,0]
	v_pk_fma_f32 v[106:107], v[86:87], v[94:95], v[106:107] op_sel:[0,0,0] op_sel_hi:[0,1,1] neg_lo:[0,0,0] neg_hi:[0,1,0]
	v_pk_add_f32 v[80:81], v[72:73], v[100:101] neg_lo:[0,1] neg_hi:[0,1]
	v_pk_add_f32 v[82:83], v[74:75], v[102:103] neg_lo:[0,1] neg_hi:[0,1]
	v_pk_add_f32 v[84:85], v[76:77], v[104:105] neg_lo:[0,1] neg_hi:[0,1]
	v_pk_add_f32 v[86:87], v[78:79], v[106:107] neg_lo:[0,1] neg_hi:[0,1]
	v_pk_add_f32 v[72:73], v[72:73], v[100:101]
	v_pk_add_f32 v[74:75], v[74:75], v[102:103]
	v_pk_add_f32 v[76:77], v[76:77], v[104:105]
	v_pk_add_f32 v[78:79], v[78:79], v[106:107]
	ds_write2st64_b64 v69, v[72:73], v[74:75] offset1:17
	ds_write2st64_b64 v69, v[76:77], v[78:79] offset0:34 offset1:51
	ds_write2st64_b64 v69, v[80:81], v[82:83] offset0:68 offset1:85
	ds_write2st64_b64 v69, v[84:85], v[86:87] offset0:102 offset1:119
	s_waitcnt lgkmcnt(4)
; #define LAS __attribute__((address_space(3)))
; __device__ __forceinline__ float bf2f(bf16_t b) { return __uint_as_float(((unsigned)b) << 16); }
; template <int LR, bool INV> __device__ __forceinline__ void fft_pass(ldsf2 buf, int base, int stride, int twi) {
;     constexpr int R = 1 << LR; cf x[R];
;     const v2f wv = ((ldsf2)((LAS unsigned char*)buf + 139264))[twi];
; #pragma unroll
;     for (int m = 0; m < R; ++m) { const v2f v = buf[base + m * stride]; x[m] = cf{v.x, v.y}; }
;     const cf w{wv.x, wv.y};
;     if (INV) dit_reg<LR>(x, w); else dif_reg<LR>(x, w);
; #pragma unroll
;     for (int m = 0; m < R; ++m) buf[base + m * stride] = mkv2(x[m].x, x[m].y);
; }
; __device__ __forceinline__ void sconv8(const Raw8& r, int n0, float w0, float w1, float w2, float b, float (&out)[8]) {
;     float a[10]; a[0] = n0 > 0 ? bf2f(r.eL) : 0.f; a[9] = n0 + 8 < SEQ ? bf2f(r.eR) : 0.f;
;     a[1] = __uint_as_float(r.body.x << 16); a[2] = __uint_as_float(r.body.x & 0xffff0000u); a[3] = __uint_as_float(r.body.y << 16); a[4] = __uint_as_float(r.body.y & 0xffff0000u);
;     a[5] = __uint_as_float(r.body.z << 16); a[6] = __uint_as_float(r.body.z & 0xffff0000u); a[7] = __uint_as_float(r.body.w << 16); a[8] = __uint_as_float(r.body.w & 0xffff0000u);
; #pragma unroll
;     for (int k = 0; k < 8; ++k) out[k] = w0 * a[k] + w1 * a[k + 1] + w2 * a[k + 2] + b;
; }
	v_pk_add_f32 v[134:135], v[240:241], v[240:241] op_sel:[0,1] op_sel_hi:[1,0] neg_lo:[0,0] neg_hi:[0,1]
	s_nop 0
	v_pk_mul_f32 v[156:157], v[134:135], s[16:17] op_sel:[0,0] op_sel_hi:[1,0]
	v_pk_mul_f32 v[158:159], v[134:135], s[16:17] op_sel:[1,0] op_sel_hi:[0,0] neg_lo:[0,0] neg_hi:[1,0]
	v_pk_mul_f32 v[164:165], v[128:129], v[244:245] op_sel:[1,1] op_sel_hi:[1,0]
	v_pk_mul_f32 v[166:167], v[132:133], v[244:245] op_sel:[1,1] op_sel_hi:[1,0]
	v_pk_mul_f32 v[168:169], v[150:151], v[244:245] op_sel:[1,1] op_sel_hi:[1,0]
	v_pk_mul_f32 v[170:171], v[154:155], v[244:245] op_sel:[1,1] op_sel_hi:[1,0]
	v_pk_fma_f32 v[164:165], v[128:129], v[244:245], v[164:165] op_sel:[0,0,0] op_sel_hi:[0,1,1] neg_lo:[0,0,0] neg_hi:[0,1,0]
	v_pk_fma_f32 v[166:167], v[132:133], v[244:245], v[166:167] op_sel:[0,0,0] op_sel_hi:[0,1,1] neg_lo:[0,0,0] neg_hi:[0,1,0]
	v_pk_fma_f32 v[168:169], v[150:151], v[244:245], v[168:169] op_sel:[0,0,0] op_sel_hi:[0,1,1] neg_lo:[0,0,0] neg_hi:[0,1,0]
	v_pk_fma_f32 v[170:171], v[154:155], v[244:245], v[170:171] op_sel:[0,0,0] op_sel_hi:[0,1,1] neg_lo:[0,0,0] neg_hi:[0,1,0]
	v_pk_add_f32 v[128:129], v[126:127], v[164:165] neg_lo:[0,1] neg_hi:[0,1]
	v_pk_add_f32 v[132:133], v[130:131], v[166:167] neg_lo:[0,1] neg_hi:[0,1]
	v_pk_add_f32 v[150:151], v[148:149], v[168:169] neg_lo:[0,1] neg_hi:[0,1]
	v_pk_add_f32 v[154:155], v[152:153], v[170:171] neg_lo:[0,1] neg_hi:[0,1]
	v_pk_add_f32 v[126:127], v[126:127], v[164:165]
	v_pk_add_f32 v[130:131], v[130:131], v[166:167]
	v_pk_add_f32 v[148:149], v[148:149], v[168:169]
	v_pk_add_f32 v[152:153], v[152:153], v[170:171]
	v_pk_mul_f32 v[164:165], v[130:131], v[242:243] op_sel:[1,1] op_sel_hi:[1,0]
	v_pk_mul_f32 v[166:167], v[132:133], v[242:243] op_sel:[1,0] op_sel_hi:[1,1]
	v_pk_mul_f32 v[168:169], v[152:153], v[242:243] op_sel:[1,1] op_sel_hi:[1,0]
	v_pk_mul_f32 v[170:171], v[154:155], v[242:243] op_sel:[1,0] op_sel_hi:[1,1]
	v_pk_fma_f32 v[164:165], v[130:131], v[242:243], v[164:165] op_sel:[0,0,0] op_sel_hi:[0,1,1] neg_lo:[0,0,0] neg_hi:[0,1,0]
	v_pk_fma_f32 v[166:167], v[132:133], v[242:243], v[166:167] op_sel:[0,1,0] op_sel_hi:[0,0,1] neg_lo:[0,0,1] neg_hi:[0,0,0]
	v_pk_fma_f32 v[168:169], v[152:153], v[242:243], v[168:169] op_sel:[0,0,0] op_sel_hi:[0,1,1] neg_lo:[0,0,0] neg_hi:[0,1,0]
	v_pk_fma_f32 v[170:171], v[154:155], v[242:243], v[170:171] op_sel:[0,1,0] op_sel_hi:[0,0,1] neg_lo:[0,0,1] neg_hi:[0,0,0]
	v_pk_add_f32 v[130:131], v[126:127], v[164:165] neg_lo:[0,1] neg_hi:[0,1]
	v_pk_add_f32 v[132:133], v[128:129], v[166:167] neg_lo:[0,1] neg_hi:[0,1]
	v_pk_add_f32 v[152:153], v[148:149], v[168:169] neg_lo:[0,1] neg_hi:[0,1]
	v_pk_add_f32 v[154:155], v[150:151], v[170:171] neg_lo:[0,1] neg_hi:[0,1]
	v_pk_add_f32 v[126:127], v[126:127], v[164:165]
	v_pk_add_f32 v[128:129], v[128:129], v[166:167]
	v_pk_add_f32 v[148:149], v[148:149], v[168:169]
	v_pk_add_f32 v[150:151], v[150:151], v[170:171]
	v_pk_mul_f32 v[164:165], v[148:149], v[240:241] op_sel:[1,1] op_sel_hi:[1,0]
	v_pk_mul_f32 v[166:167], v[150:151], v[156:157] op_sel:[1,1] op_sel_hi:[1,0]
	v_pk_mul_f32 v[168:169], v[152:153], v[240:241] op_sel:[1,0] op_sel_hi:[1,1]
	v_pk_mul_f32 v[170:171], v[154:155], v[158:159] op_sel:[1,1] op_sel_hi:[1,0]
	v_pk_fma_f32 v[164:165], v[148:149], v[240:241], v[164:165] op_sel:[0,0,0] op_sel_hi:[0,1,1] neg_lo:[0,0,0] neg_hi:[0,1,0]
	v_pk_fma_f32 v[166:167], v[150:151], v[156:157], v[166:167] op_sel:[0,0,0] op_sel_hi:[0,1,1] neg_lo:[0,0,0] neg_hi:[0,1,0]
	v_pk_fma_f32 v[168:169], v[152:153], v[240:241], v[168:169] op_sel:[0,1,0] op_sel_hi:[0,0,1] neg_lo:[0,0,1] neg_hi:[0,0,0]
	v_pk_fma_f32 v[170:171], v[154:155], v[158:159], v[170:171] op_sel:[0,0,0] op_sel_hi:[0,1,1] neg_lo:[0,0,0] neg_hi:[0,1,0]
	v_pk_add_f32 v[148:149], v[126:127], v[164:165] neg_lo:[0,1] neg_hi:[0,1]
	v_pk_add_f32 v[150:151], v[128:129], v[166:167] neg_lo:[0,1] neg_hi:[0,1]
	v_pk_add_f32 v[152:153], v[130:131], v[168:169] neg_lo:[0,1] neg_hi:[0,1]
	v_pk_add_f32 v[154:155], v[132:133], v[170:171] neg_lo:[0,1] neg_hi:[0,1]
	v_pk_add_f32 v[126:127], v[126:127], v[164:165]
	v_pk_add_f32 v[128:129], v[128:129], v[166:167]
	v_pk_add_f32 v[130:131], v[130:131], v[168:169]
	v_pk_add_f32 v[132:133], v[132:133], v[170:171]
	ds_write2st64_b64 v118, v[126:127], v[128:129] offset1:17
	ds_write2st64_b64 v118, v[130:131], v[132:133] offset0:34 offset1:51
	ds_write2st64_b64 v118, v[148:149], v[150:151] offset0:68 offset1:85
	ds_write2st64_b64 v118, v[152:153], v[154:155] offset0:102 offset1:119
	s_mov_b64 s[6:7], 0
	s_waitcnt vmcnt(5)
	v_lshlrev_b32_e32 v68, 16, v143
	v_cndmask_b32_e64 v69, 0, v68, s[42:43]
	s_waitcnt vmcnt(3)
	v_lshlrev_b32_e32 v68, 16, v144
	v_lshlrev_b32_e32 v75, 16, v5
	v_cndmask_b32_e64 v73, 0, v68, s[44:45]
	v_lshlrev_b32_e32 v74, 16, v4
	v_and_b32_e32 v76, 0xffff0000, v4
	v_mov_b32_e32 v68, v75
	v_and_b32_e32 v77, 0xffff0000, v5
	v_mov_b32_e32 v80, v74
	v_mov_b32_e32 v81, v76
	v_pk_mul_f32 v[68:69], v[56:57], v[68:69]
	v_lshlrev_b32_e32 v79, 16, v6
	v_pk_fma_f32 v[68:69], v[56:57], v[80:81], v[68:69] op_sel:[0,0,1] op_sel_hi:[1,1,0]
	v_pk_mul_f32 v[80:81], v[32:33], v[76:77]
	v_and_b32_e32 v5, 0xffff0000, v7
	v_mov_b32_e32 v78, v75
	v_pk_fma_f32 v[74:75], v[30:31], v[74:75], v[80:81]
	v_and_b32_e32 v81, 16, v7
	v_and_b32_e32 v80, 0xffff0000, v6
	v_lshlrev_b32_e32 v7, 16, v7
	v_pk_fma_f32 v[68:69], v[34:35], v[76:77], v[68:69]
	v_mov_b32_e32 v6, v80
	v_mov_b32_e32 v4, v80
	v_pk_mov_b32 v[76:77], v[76:77], v[80:81] op_sel:[1,0]
	v_mov_b32_e32 v80, v79
	v_mov_b32_e32 v81, v7
	v_pk_mul_f32 v[80:81], v[32:33], v[80:81]
	v_pk_fma_f32 v[74:75], v[34:35], v[78:79], v[74:75]
	v_pk_fma_f32 v[76:77], v[30:31], v[76:77], v[80:81]
	v_mov_b32_e32 v78, v5
	v_pk_fma_f32 v[80:81], v[34:35], v[4:5], v[76:77]
	v_pk_mul_f32 v[4:5], v[56:57], v[78:79]
	v_mov_b32_e32 v72, v7
	v_pk_fma_f32 v[4:5], v[56:57], v[6:7], v[4:5] op_sel:[0,0,1] op_sel_hi:[1,1,0]
	s_waitcnt vmcnt(1)
; __device__ __forceinline__ uint4 ntld_u4(const void* p) { const ntu4_t v = __builtin_nontemporal_load((const ntu4_t*)p); return make_uint4(v.x, v.y, v.z, v.w); }
; __device__ __forceinline__ void lds_barrier() { asm volatile("s_waitcnt lgkmcnt(0)\n\ts_barrier" ::: "memory"); }
; __device__ void ph_hyena_fft(const Params& P, int j, const bf16_t* __restrict__ projAT, const float* __restrict__ kf, bf16_t* __restrict__ yaT, unsigned char* lds_raw) {
;     ...
;             { const Raw8 r0 = load_raw8(vrow + o0, n0), r1 = load_raw8(vrow + o1, n0); sconv8(r0, n0, wv0, wv1, wv2, bv, va); sconv8(r1, n0, wv0, wv1, wv2, bv, vb); }
; #pragma unroll
;             for (int k = 0; k < 8; ++k) { buf[ph0 + k] = mkv2(va[k], vb[k]); buf[ph0 + 4352 + k] = mkv2(0.f, 0.f); }
;             const Raw8 xa0 = load_raw8(x1row + o0, n0), xa1 = load_raw8(x1row + o1, n0);
;             lds_barrier();
;             fft_conv(buf, spec1);
;             { float xa[8], xb[8]; sconv8(xa0, n0, wa0, wa1, wa2, ba, xa); sconv8(xa1, n0, wa0, wa1, wa2, ba, xb);
; #pragma unroll
;               for (int k = 0; k < 8; ++k) { const v2f y = buf[ph0 + k]; va[k] = xa[k] * (y.x * invN + sk0 * va[k]); vb[k] = xb[k] * (y.y * invN + sk0 * vb[k]);
;                   buf[ph0 + k] = mkv2(va[k], vb[k]); buf[ph0 + 4352 + k] = mkv2(0.f, 0.f); } }
;             const Raw8 xb0 = load_raw8(x2row + o0, n0), xb1 = load_raw8(x2row + o1, n0);
;             const uint4 g0 = ntld_u4(grow + o0 + n0), g1 = ntld_u4(grow + o1 + n0);
	v_lshlrev_b32_e32 v77, 16, v1
	v_pk_fma_f32 v[72:73], v[34:35], v[72:73], v[4:5]
	v_lshlrev_b32_e32 v4, 16, v139
	v_cndmask_b32_e64 v5, 0, v4, s[42:43]
	s_waitcnt vmcnt(0)
	v_lshlrev_b32_e32 v4, 16, v141
	v_cndmask_b32_e64 v7, 0, v4, s[44:45]
	v_lshlrev_b32_e32 v76, 16, v0
	v_and_b32_e32 v78, 0xffff0000, v0
	v_mov_b32_e32 v4, v77
	v_mov_b32_e32 v84, v76
	v_mov_b32_e32 v85, v78
	v_pk_mul_f32 v[4:5], v[56:57], v[4:5]
	v_and_b32_e32 v79, 0xffff0000, v1
	v_pk_fma_f32 v[4:5], v[56:57], v[84:85], v[4:5] op_sel:[0,0,1] op_sel_hi:[1,1,0]
	v_lshlrev_b32_e32 v83, 16, v2
	v_pk_fma_f32 v[84:85], v[34:35], v[78:79], v[4:5]
	v_pk_mul_f32 v[4:5], v[32:33], v[78:79]
	v_mov_b32_e32 v82, v77
	v_pk_fma_f32 v[4:5], v[30:31], v[76:77], v[4:5]
	v_and_b32_e32 v1, 0xffff0000, v3
	v_pk_fma_f32 v[86:87], v[34:35], v[82:83], v[4:5]
	v_and_b32_e32 v5, 16, v3
	v_lshlrev_b32_e32 v3, 16, v3
	v_and_b32_e32 v4, 0xffff0000, v2
	v_mov_b32_e32 v76, v83
	v_mov_b32_e32 v77, v3
	v_mov_b32_e32 v2, v4
	v_mov_b32_e32 v0, v4
	v_pk_mov_b32 v[4:5], v[78:79], v[4:5] op_sel:[1,0]
	v_pk_mul_f32 v[76:77], v[32:33], v[76:77]
	v_mov_b32_e32 v82, v1
	v_pk_fma_f32 v[4:5], v[30:31], v[4:5], v[76:77]
	s_waitcnt lgkmcnt(0)
	s_barrier
	v_mov_b32_e32 v6, v3
	v_pk_fma_f32 v[78:79], v[34:35], v[0:1], v[4:5]
	v_pk_mul_f32 v[0:1], v[56:57], v[82:83]
	v_pk_add_f32 v[74:75], v[36:37], v[74:75]
	v_pk_fma_f32 v[0:1], v[56:57], v[2:3], v[0:1] op_sel:[0,0,1] op_sel_hi:[1,1,0]
	v_pk_add_f32 v[68:69], v[36:37], v[68:69]
	v_pk_fma_f32 v[82:83], v[34:35], v[6:7], v[0:1]
	ds_read2_b64 v[0:3], v145 offset1:1
	ds_read2_b64 v[4:7], v145 offset0:2 offset1:3
	s_mov_b32 s14, 0
	s_mov_b32 s15, s14
	s_mov_b32 s0, s14
	s_waitcnt lgkmcnt(1)
	v_mov_b32_e32 v76, v0
	s_waitcnt lgkmcnt(0)
	v_mov_b32_e32 v77, v4
	v_mov_b32_e32 v4, v1
	v_pk_mul_f32 v[0:1], v[4:5], s[80:81] op_sel_hi:[1,0]
	v_mov_b32_e32 v4, v2
	v_mov_b32_e32 v5, v6
	v_pk_mul_f32 v[4:5], v[4:5], s[80:81] op_sel_hi:[1,0]
	v_pk_mul_f32 v[76:77], v[76:77], s[80:81] op_sel_hi:[1,0]
	v_pk_fma_f32 v[4:5], v[44:45], v[62:63], v[4:5]
	v_mov_b32_e32 v6, v3
	v_pk_fma_f32 v[64:65], v[44:45], v[64:65], v[76:77]
	v_pk_mul_f32 v[74:75], v[74:75], v[4:5]
	v_pk_mul_f32 v[2:3], v[6:7], s[80:81] op_sel_hi:[1,0]
	v_pk_add_f32 v[4:5], v[36:37], v[84:85]
	v_pk_fma_f32 v[0:1], v[44:45], v[66:67], v[0:1]
	v_pk_mul_f32 v[76:77], v[68:69], v[64:65]
	v_pk_add_f32 v[6:7], v[36:37], v[86:87]
	v_pk_mul_f32 v[68:69], v[4:5], v[0:1]
	v_pk_fma_f32 v[0:1], v[44:45], v[70:71], v[2:3]
	s_mov_b32 s1, s14
	v_pk_mul_f32 v[66:67], v[6:7], v[0:1]
	v_mov_b32_e32 v0, v76
	v_mov_b32_e32 v1, v68
	v_mov_b32_e32 v2, v74
	v_mov_b32_e32 v3, v66
	v_mov_b64_e32 v[88:89], s[14:15]
	v_mov_b64_e32 v[90:91], s[0:1]
	ds_write2_b64 v145, v[0:1], v[2:3] offset1:1
	v_mov_b32_e32 v0, v77
	v_mov_b32_e32 v1, v69
	v_mov_b32_e32 v2, v75
	v_mov_b32_e32 v3, v67
	ds_write2_b64 v142, v[88:89], v[90:91] offset1:1
	ds_write2_b64 v145, v[0:1], v[2:3] offset0:2 offset1:3
	ds_write2_b64 v138, v[88:89], v[90:91] offset1:1
	ds_read2_b64 v[0:3], v145 offset0:4 offset1:5
	ds_read2_b64 v[4:7], v145 offset0:6 offset1:7
	v_pk_add_f32 v[70:71], v[36:37], v[72:73]
	v_pk_add_f32 v[64:65], v[36:37], v[80:81]
	s_lshl_b32 s62, s11, 1
	s_waitcnt lgkmcnt(1)
	v_mov_b32_e32 v62, v0
	s_waitcnt lgkmcnt(0)
	v_mov_b32_e32 v63, v4
	v_mov_b32_e32 v4, v1
	v_pk_mul_f32 v[0:1], v[4:5], s[80:81] op_sel_hi:[1,0]
	v_mov_b32_e32 v4, v2
	v_mov_b32_e32 v5, v6
	v_pk_mul_f32 v[4:5], v[4:5], s[80:81] op_sel_hi:[1,0]
	v_pk_mul_f32 v[62:63], v[62:63], s[80:81] op_sel_hi:[1,0]
	v_pk_fma_f32 v[4:5], v[44:45], v[10:11], v[4:5]
	v_mov_b32_e32 v6, v3
	v_pk_fma_f32 v[8:9], v[44:45], v[8:9], v[62:63]
	v_pk_mul_f32 v[70:71], v[70:71], v[4:5]
	v_pk_mul_f32 v[2:3], v[6:7], s[80:81] op_sel_hi:[1,0]
	v_pk_add_f32 v[4:5], v[36:37], v[78:79]
	v_pk_fma_f32 v[0:1], v[44:45], v[12:13], v[0:1]
	v_pk_mul_f32 v[72:73], v[64:65], v[8:9]
	v_pk_add_f32 v[6:7], v[36:37], v[82:83]
	v_pk_mul_f32 v[64:65], v[4:5], v[0:1]
	v_pk_fma_f32 v[0:1], v[44:45], v[14:15], v[2:3]
	v_mov_b32_e32 v2, v70
	v_pk_mul_f32 v[62:63], v[6:7], v[0:1]
	v_mov_b32_e32 v0, v72
	v_mov_b32_e32 v1, v64
	v_mov_b32_e32 v3, v62
	s_add_u32 s0, s61, s62
	ds_write2_b64 v145, v[0:1], v[2:3] offset0:4 offset1:5
	v_mov_b32_e32 v0, v73
	v_mov_b32_e32 v1, v65
	v_mov_b32_e32 v2, v71
	v_mov_b32_e32 v3, v63
	s_addc_u32 s1, s52, 0
	ds_write2_b64 v140, v[88:89], v[90:91] offset1:1
	ds_write2_b64 v145, v[0:1], v[2:3] offset0:6 offset1:7
	ds_write2_b64 v137, v[88:89], v[90:91] offset1:1
	v_lshl_add_u64 v[0:1], s[0:1], 0, v[16:17]
	s_lshl_b32 s6, s10, 1
	global_load_dwordx4 v[4:7], v[0:1], off nt
	global_load_ushort v147, v146, s[0:1] offset:-2
	v_lshl_add_u64 v[0:1], s[0:1], 0, v[22:23]
	s_add_u32 s0, s61, s6
	s_addc_u32 s1, s52, 0
	global_load_ushort v148, v[0:1], off offset:16
	v_lshl_add_u64 v[0:1], s[0:1], 0, v[16:17]
	global_load_dwordx4 v[8:11], v[0:1], off nt
	global_load_ushort v149, v146, s[0:1] offset:-2
	v_lshl_add_u64 v[0:1], s[0:1], 0, v[22:23]
	s_mov_b32 s7, s63
	global_load_ushort v150, v[0:1], off offset:16
	v_lshl_add_u64 v[0:1], v[48:49], 0, s[62:63]
	global_load_dwordx4 v[12:15], v[0:1], off nt
	v_lshl_add_u64 v[0:1], v[48:49], 0, s[6:7]
	global_load_dwordx4 v[0:3], v[0:1], off nt
	s_cmp_eq_u32 s53, 3
	s_cbranch_scc1 .Lhy_nopf
	s_add_i32 s100, s53, 1
	s_lshl_b32 s100, s100, 14
	s_add_u32 s100, s47, s100
	s_addc_u32 s101, s58, 0
	v_lshl_add_u64 v[188:189], s[100:101], 0, v[16:17]
	v_lshl_add_u64 v[190:191], s[100:101], 0, v[22:23]
	global_load_ushort v184, v146, s[100:101] offset:-2
	global_load_dwordx4 v[176:179], v[188:189], off nt
	s_add_u32 s100, s100, 0x2000
	s_addc_u32 s101, s101, 0
	v_lshl_add_u64 v[188:189], s[100:101], 0, v[22:23]
	global_load_ushort v185, v146, s[100:101] offset:-2
	global_load_ushort v186, v[188:189], off offset:16
	global_load_ushort v187, v[190:191], off offset:16
	v_lshl_add_u64 v[188:189], s[100:101], 0, v[16:17]
	global_load_dwordx4 v[180:183], v[188:189], off nt

; #define LAS __attribute__((address_space(3)))
; __device__ __forceinline__ cf twc(cf ws, int k16) { if (k16 == 0) return ws; if (k16 == 4) return cf{ws.y, -ws.x}; return cmul(ws, cf{c16(k16), -s16(k16)}); }
; template <int LR> __device__ __forceinline__ void dif_reg(cf (&x)[1 << LR], cf w) {
;     constexpr int R = 1 << LR; cf ws = w;
; #pragma unroll
;     for (int s = 0; s < LR; ++s) { const int half = R >> (s + 1);
; #pragma unroll
;         for (int m0 = 0; m0 < R; m0 += 2 * half)
; #pragma unroll
;             for (int mm = 0; mm < half; ++mm) { const int ia = m0 + mm, ib = ia + half; const cf a = x[ia], b = x[ib];
;                 x[ia] = cf{a.x + b.x, a.y + b.y}; const cf d{a.x - b.x, a.y - b.y};
;                 x[ib] = cmul(d, twc(ws, (mm << s) * (16 / R))); }
;         ws = cmul(ws, ws); }
; }
; template <int LR> __device__ __forceinline__ void dit_reg(cf (&x)[1 << LR], cf w) {
;     constexpr int R = 1 << LR; cf wsv[LR]; wsv[0] = w;
; #pragma unroll
;     for (int s = 1; s < LR; ++s) wsv[s] = cmul(wsv[s - 1], wsv[s - 1]);
; #pragma unroll
;     for (int s = LR - 1; s >= 0; --s) { const int half = R >> (s + 1);
; #pragma unroll
;         for (int m0 = 0; m0 < R; m0 += 2 * half)
; #pragma unroll
;             for (int mm = 0; mm < half; ++mm) { const int ia = m0 + mm, ib = ia + half; const cf a = x[ia];
;                 const cf b = cmulc(x[ib], twc(wsv[s], (mm << s) * (16 / R)));
;                 x[ia] = cf{a.x + b.x, a.y + b.y}; x[ib] = cf{a.x - b.x, a.y - b.y}; } }
; }
; __device__ __forceinline__ void lds_barrier() { asm volatile("s_waitcnt lgkmcnt(0)\n\ts_barrier" ::: "memory"); }
; template <int LR, bool INV> __device__ __forceinline__ void fft_pass(ldsf2 buf, int base, int stride, int twi) {
;     constexpr int R = 1 << LR; cf x[R];
;     const v2f wv = ((ldsf2)((LAS unsigned char*)buf + 139264))[twi];
; #pragma unroll
;     for (int m = 0; m < R; ++m) { const v2f v = buf[base + m * stride]; x[m] = cf{v.x, v.y}; }
;     const cf w{wv.x, wv.y};
;     if (INV) dit_reg<LR>(x, w); else dif_reg<LR>(x, w);
; #pragma unroll
;     for (int m = 0; m < R; ++m) buf[base + m * stride] = mkv2(x[m].x, x[m].y);
; }
.LBB0_359:
	v_add_u32_e32 v80, s14, v78
	v_ashrrev_i32_e32 v79, 4, v80
	v_lshl_add_u32 v80, v80, 3, 0
	v_add_u32_e32 v81, 0x22000, v80
	v_lshl_add_u32 v79, v79, 3, v80
	ds_read2st64_b64 v[80:83], v79 offset1:17
	ds_read2st64_b64 v[84:87], v79 offset0:68 offset1:85
	ds_read2st64_b64 v[88:91], v79 offset0:34 offset1:51
	ds_read2st64_b64 v[92:95], v79 offset0:102 offset1:119
	s_movk_i32 s14, 0x200
	v_add_u32_e32 v120, s14, v78
	v_ashrrev_i32_e32 v122, 4, v120
	v_lshl_add_u32 v120, v120, 3, 0
	v_add_u32_e32 v124, 0x22000, v120
	v_lshl_add_u32 v122, v122, 3, v120
	ds_read2st64_b64 v[128:131], v122 offset1:17
	ds_read2st64_b64 v[132:135], v122 offset0:68 offset1:85
	ds_read2st64_b64 v[136:139], v122 offset0:34 offset1:51
	ds_read2st64_b64 v[140:143], v122 offset0:102 offset1:119
	s_waitcnt lgkmcnt(4)
	v_pk_add_f32 v[98:99], v[232:233], v[232:233] op_sel:[0,1] op_sel_hi:[1,0] neg_lo:[0,0] neg_hi:[0,1]
	s_nop 0
	v_pk_mul_f32 v[100:101], v[98:99], s[16:17] op_sel:[0,0] op_sel_hi:[1,0]
	v_pk_mul_f32 v[102:103], v[98:99], s[16:17] op_sel:[1,0] op_sel_hi:[0,0] neg_lo:[0,0] neg_hi:[1,0]
	v_pk_add_f32 v[108:109], v[80:81], v[84:85] neg_lo:[0,1] neg_hi:[0,1]
	v_pk_add_f32 v[110:111], v[82:83], v[86:87] neg_lo:[0,1] neg_hi:[0,1]
	v_pk_add_f32 v[112:113], v[88:89], v[92:93] neg_lo:[0,1] neg_hi:[0,1]
	v_pk_add_f32 v[114:115], v[90:91], v[94:95] neg_lo:[0,1] neg_hi:[0,1]
	v_pk_add_f32 v[80:81], v[80:81], v[84:85]
	v_pk_add_f32 v[82:83], v[82:83], v[86:87]
	v_pk_add_f32 v[88:89], v[88:89], v[92:93]
	v_pk_add_f32 v[90:91], v[90:91], v[94:95]
	v_pk_mul_f32 v[84:85], v[108:109], v[232:233] op_sel:[1,1] op_sel_hi:[1,0]
	v_pk_mul_f32 v[86:87], v[110:111], v[100:101] op_sel:[1,1] op_sel_hi:[1,0]
	v_pk_mul_f32 v[92:93], v[112:113], v[232:233] op_sel:[1,0] op_sel_hi:[1,1]
	v_pk_mul_f32 v[94:95], v[114:115], v[102:103] op_sel:[1,1] op_sel_hi:[1,0]
	v_pk_fma_f32 v[84:85], v[108:109], v[232:233], v[84:85] op_sel:[0,0,0] op_sel_hi:[0,1,1] neg_lo:[0,0,1] neg_hi:[0,0,0]
	v_pk_fma_f32 v[86:87], v[110:111], v[100:101], v[86:87] op_sel:[0,0,0] op_sel_hi:[0,1,1] neg_lo:[0,0,1] neg_hi:[0,0,0]
	v_pk_fma_f32 v[92:93], v[112:113], v[232:233], v[92:93] op_sel:[0,1,0] op_sel_hi:[0,0,1] neg_lo:[0,0,0] neg_hi:[0,1,0]
	v_pk_fma_f32 v[94:95], v[114:115], v[102:103], v[94:95] op_sel:[0,0,0] op_sel_hi:[0,1,1] neg_lo:[0,0,1] neg_hi:[0,0,0]
	v_pk_add_f32 v[108:109], v[80:81], v[88:89] neg_lo:[0,1] neg_hi:[0,1]
	v_pk_add_f32 v[110:111], v[82:83], v[90:91] neg_lo:[0,1] neg_hi:[0,1]
	v_pk_add_f32 v[112:113], v[84:85], v[92:93] neg_lo:[0,1] neg_hi:[0,1]
	v_pk_add_f32 v[114:115], v[86:87], v[94:95] neg_lo:[0,1] neg_hi:[0,1]
	v_pk_add_f32 v[80:81], v[80:81], v[88:89]
	v_pk_add_f32 v[82:83], v[82:83], v[90:91]
	v_pk_add_f32 v[84:85], v[84:85], v[92:93]
	v_pk_add_f32 v[86:87], v[86:87], v[94:95]
	v_pk_mul_f32 v[88:89], v[108:109], v[234:235] op_sel:[1,1] op_sel_hi:[1,0]
	v_pk_mul_f32 v[90:91], v[110:111], v[234:235] op_sel:[1,0] op_sel_hi:[1,1]
	v_pk_mul_f32 v[92:93], v[112:113], v[234:235] op_sel:[1,1] op_sel_hi:[1,0]
	v_pk_mul_f32 v[94:95], v[114:115], v[234:235] op_sel:[1,0] op_sel_hi:[1,1]
	v_pk_fma_f32 v[88:89], v[108:109], v[234:235], v[88:89] op_sel:[0,0,0] op_sel_hi:[0,1,1] neg_lo:[0,0,1] neg_hi:[0,0,0]
	v_pk_fma_f32 v[90:91], v[110:111], v[234:235], v[90:91] op_sel:[0,1,0] op_sel_hi:[0,0,1] neg_lo:[0,0,0] neg_hi:[0,1,0]
	v_pk_fma_f32 v[92:93], v[112:113], v[234:235], v[92:93] op_sel:[0,0,0] op_sel_hi:[0,1,1] neg_lo:[0,0,1] neg_hi:[0,0,0]
	v_pk_fma_f32 v[94:95], v[114:115], v[234:235], v[94:95] op_sel:[0,1,0] op_sel_hi:[0,0,1] neg_lo:[0,0,0] neg_hi:[0,1,0]
	v_pk_add_f32 v[108:109], v[80:81], v[82:83] neg_lo:[0,1] neg_hi:[0,1]
	v_pk_add_f32 v[110:111], v[88:89], v[90:91] neg_lo:[0,1] neg_hi:[0,1]
	v_pk_add_f32 v[112:113], v[84:85], v[86:87] neg_lo:[0,1] neg_hi:[0,1]
	v_pk_add_f32 v[114:115], v[92:93], v[94:95] neg_lo:[0,1] neg_hi:[0,1]
	v_pk_add_f32 v[80:81], v[80:81], v[82:83]
	v_pk_add_f32 v[88:89], v[88:89], v[90:91]
	v_pk_add_f32 v[84:85], v[84:85], v[86:87]
	v_pk_add_f32 v[92:93], v[92:93], v[94:95]
	v_pk_mul_f32 v[82:83], v[108:109], v[236:237] op_sel:[1,1] op_sel_hi:[1,0]
	v_pk_mul_f32 v[90:91], v[110:111], v[236:237] op_sel:[1,1] op_sel_hi:[1,0]
	v_pk_mul_f32 v[86:87], v[112:113], v[236:237] op_sel:[1,1] op_sel_hi:[1,0]
	v_pk_mul_f32 v[94:95], v[114:115], v[236:237] op_sel:[1,1] op_sel_hi:[1,0]
	v_pk_fma_f32 v[82:83], v[108:109], v[236:237], v[82:83] op_sel:[0,0,0] op_sel_hi:[0,1,1] neg_lo:[0,0,1] neg_hi:[0,0,0]
	v_pk_fma_f32 v[90:91], v[110:111], v[236:237], v[90:91] op_sel:[0,0,0] op_sel_hi:[0,1,1] neg_lo:[0,0,1] neg_hi:[0,0,0]
	v_pk_fma_f32 v[86:87], v[112:113], v[236:237], v[86:87] op_sel:[0,0,0] op_sel_hi:[0,1,1] neg_lo:[0,0,1] neg_hi:[0,0,0]
	v_pk_fma_f32 v[94:95], v[114:115], v[236:237], v[94:95] op_sel:[0,0,0] op_sel_hi:[0,1,1] neg_lo:[0,0,1] neg_hi:[0,0,0]
	ds_write2st64_b64 v79, v[80:81], v[82:83] offset1:17
	ds_write2st64_b64 v79, v[88:89], v[90:91] offset0:34 offset1:51
	ds_write2st64_b64 v79, v[84:85], v[86:87] offset0:68 offset1:85
	ds_write2st64_b64 v79, v[92:93], v[94:95] offset0:102 offset1:119
	s_waitcnt lgkmcnt(4)
; template <int LR> __device__ __forceinline__ void dif_reg(cf (&x)[1 << LR], cf w) {
;     constexpr int R = 1 << LR; cf ws = w;
; #pragma unroll
;     for (int s = 0; s < LR; ++s) { const int half = R >> (s + 1);
; #pragma unroll
;         for (int m0 = 0; m0 < R; m0 += 2 * half)
; #pragma unroll
;             for (int mm = 0; mm < half; ++mm) { const int ia = m0 + mm, ib = ia + half; const cf a = x[ia], b = x[ib];
;                 x[ia] = cf{a.x + b.x, a.y + b.y}; const cf d{a.x - b.x, a.y - b.y};
;                 x[ib] = cmul(d, twc(ws, (mm << s) * (16 / R))); }
;         ws = cmul(ws, ws); }
; }
; template <int LR> __device__ __forceinline__ void dit_reg(cf (&x)[1 << LR], cf w) {
;     constexpr int R = 1 << LR; cf wsv[LR]; wsv[0] = w;
; #pragma unroll
;     for (int s = 1; s < LR; ++s) wsv[s] = cmul(wsv[s - 1], wsv[s - 1]);
; #pragma unroll
;     for (int s = LR - 1; s >= 0; --s) { const int half = R >> (s + 1);
; #pragma unroll
;         for (int m0 = 0; m0 < R; m0 += 2 * half)
; #pragma unroll
;             for (int mm = 0; mm < half; ++mm) { const int ia = m0 + mm, ib = ia + half; const cf a = x[ia];
;                 const cf b = cmulc(x[ib], twc(wsv[s], (mm << s) * (16 / R)));
;                 x[ia] = cf{a.x + b.x, a.y + b.y}; x[ib] = cf{a.x - b.x, a.y - b.y}; } }
; }
; __device__ __forceinline__ void lds_barrier() { asm volatile("s_waitcnt lgkmcnt(0)\n\ts_barrier" ::: "memory"); }
; template <int LR, bool INV> __device__ __forceinline__ void fft_pass(ldsf2 buf, int base, int stride, int twi) {
;     constexpr int R = 1 << LR; cf x[R];
;     const v2f wv = ((ldsf2)((LAS unsigned char*)buf + 139264))[twi];
; #pragma unroll
;     for (int m = 0; m < R; ++m) { const v2f v = buf[base + m * stride]; x[m] = cf{v.x, v.y}; }
;     const cf w{wv.x, wv.y};
;     if (INV) dit_reg<LR>(x, w); else dif_reg<LR>(x, w);
; #pragma unroll
;     for (int m = 0; m < R; ++m) buf[base + m * stride] = mkv2(x[m].x, x[m].y);
; }
; __device__ __forceinline__ void wave_lds_fence() { asm volatile("s_waitcnt lgkmcnt(0)" ::: "memory"); }
; __device__ __forceinline__ void fft_fwd_abc(ldsf2 buf) {
;     const int tid = otid(); const int wv = tid >> 6, l = tid & 63;
; #pragma unroll 1
;     for (int u = 0; u < 2; ++u) { const int bf = tid + NT * u; fft_pass<3, false>(buf, bf + (bf >> 4), 1088, bf); }
;     lds_barrier();
; #pragma unroll 1
	v_pk_add_f32 v[152:153], v[240:241], v[240:241] op_sel:[0,1] op_sel_hi:[1,0] neg_lo:[0,0] neg_hi:[0,1]
	s_nop 0
	v_pk_mul_f32 v[154:155], v[152:153], s[16:17] op_sel:[0,0] op_sel_hi:[1,0]
	v_pk_mul_f32 v[156:157], v[152:153], s[16:17] op_sel:[1,0] op_sel_hi:[0,0] neg_lo:[0,0] neg_hi:[1,0]
	v_pk_add_f32 v[162:163], v[128:129], v[132:133] neg_lo:[0,1] neg_hi:[0,1]
	v_pk_add_f32 v[164:165], v[130:131], v[134:135] neg_lo:[0,1] neg_hi:[0,1]
	v_pk_add_f32 v[166:167], v[136:137], v[140:141] neg_lo:[0,1] neg_hi:[0,1]
	v_pk_add_f32 v[168:169], v[138:139], v[142:143] neg_lo:[0,1] neg_hi:[0,1]
	v_pk_add_f32 v[128:129], v[128:129], v[132:133]
	v_pk_add_f32 v[130:131], v[130:131], v[134:135]
	v_pk_add_f32 v[136:137], v[136:137], v[140:141]
	v_pk_add_f32 v[138:139], v[138:139], v[142:143]
	v_pk_mul_f32 v[132:133], v[162:163], v[240:241] op_sel:[1,1] op_sel_hi:[1,0]
	v_pk_mul_f32 v[134:135], v[164:165], v[154:155] op_sel:[1,1] op_sel_hi:[1,0]
	v_pk_mul_f32 v[140:141], v[166:167], v[240:241] op_sel:[1,0] op_sel_hi:[1,1]
	v_pk_mul_f32 v[142:143], v[168:169], v[156:157] op_sel:[1,1] op_sel_hi:[1,0]
	v_pk_fma_f32 v[132:133], v[162:163], v[240:241], v[132:133] op_sel:[0,0,0] op_sel_hi:[0,1,1] neg_lo:[0,0,1] neg_hi:[0,0,0]
	v_pk_fma_f32 v[134:135], v[164:165], v[154:155], v[134:135] op_sel:[0,0,0] op_sel_hi:[0,1,1] neg_lo:[0,0,1] neg_hi:[0,0,0]
	v_pk_fma_f32 v[140:141], v[166:167], v[240:241], v[140:141] op_sel:[0,1,0] op_sel_hi:[0,0,1] neg_lo:[0,0,0] neg_hi:[0,1,0]
	v_pk_fma_f32 v[142:143], v[168:169], v[156:157], v[142:143] op_sel:[0,0,0] op_sel_hi:[0,1,1] neg_lo:[0,0,1] neg_hi:[0,0,0]
	v_pk_add_f32 v[162:163], v[128:129], v[136:137] neg_lo:[0,1] neg_hi:[0,1]
	v_pk_add_f32 v[164:165], v[130:131], v[138:139] neg_lo:[0,1] neg_hi:[0,1]
	v_pk_add_f32 v[166:167], v[132:133], v[140:141] neg_lo:[0,1] neg_hi:[0,1]
	v_pk_add_f32 v[168:169], v[134:135], v[142:143] neg_lo:[0,1] neg_hi:[0,1]
	v_pk_add_f32 v[128:129], v[128:129], v[136:137]
	v_pk_add_f32 v[130:131], v[130:131], v[138:139]
	v_pk_add_f32 v[132:133], v[132:133], v[140:141]
	v_pk_add_f32 v[134:135], v[134:135], v[142:143]
	v_pk_mul_f32 v[136:137], v[162:163], v[242:243] op_sel:[1,1] op_sel_hi:[1,0]
	v_pk_mul_f32 v[138:139], v[164:165], v[242:243] op_sel:[1,0] op_sel_hi:[1,1]
	v_pk_mul_f32 v[140:141], v[166:167], v[242:243] op_sel:[1,1] op_sel_hi:[1,0]
	v_pk_mul_f32 v[142:143], v[168:169], v[242:243] op_sel:[1,0] op_sel_hi:[1,1]
	v_pk_fma_f32 v[136:137], v[162:163], v[242:243], v[136:137] op_sel:[0,0,0] op_sel_hi:[0,1,1] neg_lo:[0,0,1] neg_hi:[0,0,0]
	v_pk_fma_f32 v[138:139], v[164:165], v[242:243], v[138:139] op_sel:[0,1,0] op_sel_hi:[0,0,1] neg_lo:[0,0,0] neg_hi:[0,1,0]
	v_pk_fma_f32 v[140:141], v[166:167], v[242:243], v[140:141] op_sel:[0,0,0] op_sel_hi:[0,1,1] neg_lo:[0,0,1] neg_hi:[0,0,0]
	v_pk_fma_f32 v[142:143], v[168:169], v[242:243], v[142:143] op_sel:[0,1,0] op_sel_hi:[0,0,1] neg_lo:[0,0,0] neg_hi:[0,1,0]
	v_pk_add_f32 v[162:163], v[128:129], v[130:131] neg_lo:[0,1] neg_hi:[0,1]
	v_pk_add_f32 v[164:165], v[136:137], v[138:139] neg_lo:[0,1] neg_hi:[0,1]
	v_pk_add_f32 v[166:167], v[132:133], v[134:135] neg_lo:[0,1] neg_hi:[0,1]
	v_pk_add_f32 v[168:169], v[140:141], v[142:143] neg_lo:[0,1] neg_hi:[0,1]
	v_pk_add_f32 v[128:129], v[128:129], v[130:131]
	v_pk_add_f32 v[136:137], v[136:137], v[138:139]
	v_pk_add_f32 v[132:133], v[132:133], v[134:135]
	v_pk_add_f32 v[140:141], v[140:141], v[142:143]
	v_pk_mul_f32 v[130:131], v[162:163], v[244:245] op_sel:[1,1] op_sel_hi:[1,0]
	v_pk_mul_f32 v[138:139], v[164:165], v[244:245] op_sel:[1,1] op_sel_hi:[1,0]
	v_pk_mul_f32 v[134:135], v[166:167], v[244:245] op_sel:[1,1] op_sel_hi:[1,0]
	v_pk_mul_f32 v[142:143], v[168:169], v[244:245] op_sel:[1,1] op_sel_hi:[1,0]
	v_pk_fma_f32 v[130:131], v[162:163], v[244:245], v[130:131] op_sel:[0,0,0] op_sel_hi:[0,1,1] neg_lo:[0,0,1] neg_hi:[0,0,0]
	v_pk_fma_f32 v[138:139], v[164:165], v[244:245], v[138:139] op_sel:[0,0,0] op_sel_hi:[0,1,1] neg_lo:[0,0,1] neg_hi:[0,0,0]
	v_pk_fma_f32 v[134:135], v[166:167], v[244:245], v[134:135] op_sel:[0,0,0] op_sel_hi:[0,1,1] neg_lo:[0,0,1] neg_hi:[0,0,0]
	v_pk_fma_f32 v[142:143], v[168:169], v[244:245], v[142:143] op_sel:[0,0,0] op_sel_hi:[0,1,1] neg_lo:[0,0,1] neg_hi:[0,0,0]
	ds_write2st64_b64 v122, v[128:129], v[130:131] offset1:17
	ds_write2st64_b64 v122, v[136:137], v[138:139] offset0:34 offset1:51
	ds_write2st64_b64 v122, v[132:133], v[134:135] offset0:68 offset1:85
	ds_write2st64_b64 v122, v[140:141], v[142:143] offset0:102 offset1:119
	s_mov_b64 s[10:11], 0
	s_waitcnt lgkmcnt(0)
	s_barrier
	v_lshlrev_b32_e32 v80, 4, v78
	v_and_b32_e32 v79, 63, v78
	v_and_b32_e32 v80, 0xfffffc00, v80
	s_mov_b32 s0, 0
	s_mov_b64 s[10:11], -1
; #define LAS __attribute__((address_space(3)))
; __device__ __forceinline__ cf twc(cf ws, int k16) { if (k16 == 0) return ws; if (k16 == 4) return cf{ws.y, -ws.x}; return cmul(ws, cf{c16(k16), -s16(k16)}); }
; template <int LR> __device__ __forceinline__ void dif_reg(cf (&x)[1 << LR], cf w) {
;     constexpr int R = 1 << LR; cf ws = w;
; #pragma unroll
;     for (int s = 0; s < LR; ++s) { const int half = R >> (s + 1);
; #pragma unroll
;         for (int m0 = 0; m0 < R; m0 += 2 * half)
; #pragma unroll
;             for (int mm = 0; mm < half; ++mm) { const int ia = m0 + mm, ib = ia + half; const cf a = x[ia], b = x[ib];
;                 x[ia] = cf{a.x + b.x, a.y + b.y}; const cf d{a.x - b.x, a.y - b.y};
;                 x[ib] = cmul(d, twc(ws, (mm << s) * (16 / R))); }
;         ws = cmul(ws, ws); }
; }
; template <int LR> __device__ __forceinline__ void dit_reg(cf (&x)[1 << LR], cf w) {
;     constexpr int R = 1 << LR; cf wsv[LR]; wsv[0] = w;
; #pragma unroll
;     for (int s = 1; s < LR; ++s) wsv[s] = cmul(wsv[s - 1], wsv[s - 1]);
; #pragma unroll
;     for (int s = LR - 1; s >= 0; --s) { const int half = R >> (s + 1);
; #pragma unroll
;         for (int m0 = 0; m0 < R; m0 += 2 * half)
; #pragma unroll
;             for (int mm = 0; mm < half; ++mm) { const int ia = m0 + mm, ib = ia + half; const cf a = x[ia];
;                 const cf b = cmulc(x[ib], twc(wsv[s], (mm << s) * (16 / R)));
;                 x[ia] = cf{a.x + b.x, a.y + b.y}; x[ib] = cf{a.x - b.x, a.y - b.y}; } }
; }
; __device__ __forceinline__ void lds_barrier() { asm volatile("s_waitcnt lgkmcnt(0)\n\ts_barrier" ::: "memory"); }
; template <int LR, bool INV> __device__ __forceinline__ void fft_pass(ldsf2 buf, int base, int stride, int twi) {
;     constexpr int R = 1 << LR; cf x[R];
;     const v2f wv = ((ldsf2)((LAS unsigned char*)buf + 139264))[twi];
; #pragma unroll
;     for (int m = 0; m < R; ++m) { const v2f v = buf[base + m * stride]; x[m] = cf{v.x, v.y}; }
;     const cf w{wv.x, wv.y};
;     if (INV) dit_reg<LR>(x, w); else dif_reg<LR>(x, w);
; #pragma unroll
;     for (int m = 0; m < R; ++m) buf[base + m * stride] = mkv2(x[m].x, x[m].y);
; }
; __device__ __forceinline__ void fft_fwd_abc(ldsf2 buf) {
;     ...
;     for (int u = 0; u < 2; ++u) { const int o = l + 64 * u, e0 = wv * 1024 + o; fft_pass<3, false>(buf, e0 + (e0 >> 4), 136, o * 8); }
.LBB0_361:
	v_or_b32_e32 v82, s0, v79
	v_or_b32_e32 v81, v82, v80
	v_lshl_add_u32 v82, v82, 6, 0
	v_ashrrev_i32_e32 v83, 4, v81
	v_add_u32_e32 v82, 0x22000, v82
	v_lshlrev_b32_e32 v81, 3, v81
	v_lshlrev_b32_e32 v82, 3, v83
	v_add3_u32 v81, 0, v81, v82
	v_add_u32_e32 v121, 0x800, v81
	ds_read2_b64 v[82:85], v81 offset1:136
	v_add_u32_e32 v126, 0x1000, v81
	v_add_u32_e32 v127, 0x1800, v81
	ds_read2_b64 v[86:89], v121 offset0:16 offset1:152
	ds_read2_b64 v[90:93], v126 offset0:32 offset1:168
	ds_read2_b64 v[94:97], v127 offset0:48 offset1:184
	s_mov_b32 s0, 64
	v_or_b32_e32 v128, s0, v79
	v_or_b32_e32 v130, v128, v80
	v_lshl_add_u32 v128, v128, 6, 0
	v_ashrrev_i32_e32 v132, 4, v130
	v_add_u32_e32 v128, 0x22000, v128
	v_lshlrev_b32_e32 v130, 3, v130
	v_lshlrev_b32_e32 v128, 3, v132
	v_add3_u32 v130, 0, v130, v128
	v_add_u32_e32 v136, 0x800, v130
	ds_read2_b64 v[138:141], v130 offset1:136
	v_add_u32_e32 v142, 0x1000, v130
	v_add_u32_e32 v152, 0x1800, v130
	ds_read2_b64 v[154:157], v136 offset0:16 offset1:152
	ds_read2_b64 v[158:161], v142 offset0:32 offset1:168
	ds_read2_b64 v[162:165], v152 offset0:48 offset1:184
	s_waitcnt lgkmcnt(4)
	v_pk_add_f32 v[100:101], v[214:215], v[214:215] op_sel:[0,1] op_sel_hi:[1,0] neg_lo:[0,0] neg_hi:[0,1]
	s_nop 0
	v_pk_mul_f32 v[102:103], v[100:101], s[16:17] op_sel:[0,0] op_sel_hi:[1,0]
	v_pk_mul_f32 v[104:105], v[100:101], s[16:17] op_sel:[1,0] op_sel_hi:[0,0] neg_lo:[0,0] neg_hi:[1,0]
	v_pk_add_f32 v[110:111], v[82:83], v[90:91] neg_lo:[0,1] neg_hi:[0,1]
	v_pk_add_f32 v[112:113], v[84:85], v[92:93] neg_lo:[0,1] neg_hi:[0,1]
	v_pk_add_f32 v[114:115], v[86:87], v[94:95] neg_lo:[0,1] neg_hi:[0,1]
	v_pk_add_f32 v[116:117], v[88:89], v[96:97] neg_lo:[0,1] neg_hi:[0,1]
	v_pk_add_f32 v[82:83], v[82:83], v[90:91]
	v_pk_add_f32 v[84:85], v[84:85], v[92:93]
	v_pk_add_f32 v[86:87], v[86:87], v[94:95]
	v_pk_add_f32 v[88:89], v[88:89], v[96:97]
	v_pk_mul_f32 v[90:91], v[110:111], v[214:215] op_sel:[1,1] op_sel_hi:[1,0]
	v_pk_mul_f32 v[92:93], v[112:113], v[102:103] op_sel:[1,1] op_sel_hi:[1,0]
	v_pk_mul_f32 v[94:95], v[114:115], v[214:215] op_sel:[1,0] op_sel_hi:[1,1]
	v_pk_mul_f32 v[96:97], v[116:117], v[104:105] op_sel:[1,1] op_sel_hi:[1,0]
	v_pk_fma_f32 v[90:91], v[110:111], v[214:215], v[90:91] op_sel:[0,0,0] op_sel_hi:[0,1,1] neg_lo:[0,0,1] neg_hi:[0,0,0]
	v_pk_fma_f32 v[92:93], v[112:113], v[102:103], v[92:93] op_sel:[0,0,0] op_sel_hi:[0,1,1] neg_lo:[0,0,1] neg_hi:[0,0,0]
	v_pk_fma_f32 v[94:95], v[114:115], v[214:215], v[94:95] op_sel:[0,1,0] op_sel_hi:[0,0,1] neg_lo:[0,0,0] neg_hi:[0,1,0]
	v_pk_fma_f32 v[96:97], v[116:117], v[104:105], v[96:97] op_sel:[0,0,0] op_sel_hi:[0,1,1] neg_lo:[0,0,1] neg_hi:[0,0,0]
	v_pk_add_f32 v[110:111], v[82:83], v[86:87] neg_lo:[0,1] neg_hi:[0,1]
	v_pk_add_f32 v[112:113], v[84:85], v[88:89] neg_lo:[0,1] neg_hi:[0,1]
	v_pk_add_f32 v[114:115], v[90:91], v[94:95] neg_lo:[0,1] neg_hi:[0,1]
	v_pk_add_f32 v[116:117], v[92:93], v[96:97] neg_lo:[0,1] neg_hi:[0,1]
	v_pk_add_f32 v[82:83], v[82:83], v[86:87]
	v_pk_add_f32 v[84:85], v[84:85], v[88:89]
	v_pk_add_f32 v[90:91], v[90:91], v[94:95]
	v_pk_add_f32 v[92:93], v[92:93], v[96:97]
	v_pk_mul_f32 v[86:87], v[110:111], v[216:217] op_sel:[1,1] op_sel_hi:[1,0]
	v_pk_mul_f32 v[88:89], v[112:113], v[216:217] op_sel:[1,0] op_sel_hi:[1,1]
	v_pk_mul_f32 v[94:95], v[114:115], v[216:217] op_sel:[1,1] op_sel_hi:[1,0]
	v_pk_mul_f32 v[96:97], v[116:117], v[216:217] op_sel:[1,0] op_sel_hi:[1,1]
	v_pk_fma_f32 v[86:87], v[110:111], v[216:217], v[86:87] op_sel:[0,0,0] op_sel_hi:[0,1,1] neg_lo:[0,0,1] neg_hi:[0,0,0]
	v_pk_fma_f32 v[88:89], v[112:113], v[216:217], v[88:89] op_sel:[0,1,0] op_sel_hi:[0,0,1] neg_lo:[0,0,0] neg_hi:[0,1,0]
	v_pk_fma_f32 v[94:95], v[114:115], v[216:217], v[94:95] op_sel:[0,0,0] op_sel_hi:[0,1,1] neg_lo:[0,0,1] neg_hi:[0,0,0]
	v_pk_fma_f32 v[96:97], v[116:117], v[216:217], v[96:97] op_sel:[0,1,0] op_sel_hi:[0,0,1] neg_lo:[0,0,0] neg_hi:[0,1,0]
	v_pk_add_f32 v[110:111], v[82:83], v[84:85] neg_lo:[0,1] neg_hi:[0,1]
	v_pk_add_f32 v[112:113], v[86:87], v[88:89] neg_lo:[0,1] neg_hi:[0,1]
	v_pk_add_f32 v[114:115], v[90:91], v[92:93] neg_lo:[0,1] neg_hi:[0,1]
	v_pk_add_f32 v[116:117], v[94:95], v[96:97] neg_lo:[0,1] neg_hi:[0,1]
	v_pk_add_f32 v[82:83], v[82:83], v[84:85]
	v_pk_add_f32 v[86:87], v[86:87], v[88:89]
	v_pk_add_f32 v[90:91], v[90:91], v[92:93]
	v_pk_add_f32 v[94:95], v[94:95], v[96:97]
	v_pk_mul_f32 v[84:85], v[110:111], v[218:219] op_sel:[1,1] op_sel_hi:[1,0]
	v_pk_mul_f32 v[88:89], v[112:113], v[218:219] op_sel:[1,1] op_sel_hi:[1,0]
	v_pk_mul_f32 v[92:93], v[114:115], v[218:219] op_sel:[1,1] op_sel_hi:[1,0]
	v_pk_mul_f32 v[96:97], v[116:117], v[218:219] op_sel:[1,1] op_sel_hi:[1,0]
	v_pk_fma_f32 v[84:85], v[110:111], v[218:219], v[84:85] op_sel:[0,0,0] op_sel_hi:[0,1,1] neg_lo:[0,0,1] neg_hi:[0,0,0]
	v_pk_fma_f32 v[88:89], v[112:113], v[218:219], v[88:89] op_sel:[0,0,0] op_sel_hi:[0,1,1] neg_lo:[0,0,1] neg_hi:[0,0,0]
	v_pk_fma_f32 v[92:93], v[114:115], v[218:219], v[92:93] op_sel:[0,0,0] op_sel_hi:[0,1,1] neg_lo:[0,0,1] neg_hi:[0,0,0]
	v_pk_fma_f32 v[96:97], v[116:117], v[218:219], v[96:97] op_sel:[0,0,0] op_sel_hi:[0,1,1] neg_lo:[0,0,1] neg_hi:[0,0,0]
	ds_write2_b64 v81, v[82:83], v[84:85] offset1:136
	ds_write2_b64 v121, v[86:87], v[88:89] offset0:16 offset1:152
	ds_write2_b64 v126, v[90:91], v[92:93] offset0:32 offset1:168
	ds_write2_b64 v127, v[94:95], v[96:97] offset0:48 offset1:184
	s_waitcnt lgkmcnt(4)
; template <int LR> __device__ __forceinline__ void dif_reg(cf (&x)[1 << LR], cf w) {
;     constexpr int R = 1 << LR; cf ws = w;
; #pragma unroll
;     for (int s = 0; s < LR; ++s) { const int half = R >> (s + 1);
; #pragma unroll
;         for (int m0 = 0; m0 < R; m0 += 2 * half)
; #pragma unroll
;             for (int mm = 0; mm < half; ++mm) { const int ia = m0 + mm, ib = ia + half; const cf a = x[ia], b = x[ib];
;                 x[ia] = cf{a.x + b.x, a.y + b.y}; const cf d{a.x - b.x, a.y - b.y};
;                 x[ib] = cmul(d, twc(ws, (mm << s) * (16 / R))); }
;         ws = cmul(ws, ws); }
; }
; template <int LR> __device__ __forceinline__ void dit_reg(cf (&x)[1 << LR], cf w) {
;     constexpr int R = 1 << LR; cf wsv[LR]; wsv[0] = w;
; #pragma unroll
;     for (int s = 1; s < LR; ++s) wsv[s] = cmul(wsv[s - 1], wsv[s - 1]);
; #pragma unroll
;     for (int s = LR - 1; s >= 0; --s) { const int half = R >> (s + 1);
; #pragma unroll
;         for (int m0 = 0; m0 < R; m0 += 2 * half)
; #pragma unroll
;             for (int mm = 0; mm < half; ++mm) { const int ia = m0 + mm, ib = ia + half; const cf a = x[ia];
;                 const cf b = cmulc(x[ib], twc(wsv[s], (mm << s) * (16 / R)));
;                 x[ia] = cf{a.x + b.x, a.y + b.y}; x[ib] = cf{a.x - b.x, a.y - b.y}; } }
; }
; __device__ __forceinline__ void lds_barrier() { asm volatile("s_waitcnt lgkmcnt(0)\n\ts_barrier" ::: "memory"); }
; template <int LR, bool INV> __device__ __forceinline__ void fft_pass(ldsf2 buf, int base, int stride, int twi) {
;     constexpr int R = 1 << LR; cf x[R];
;     const v2f wv = ((ldsf2)((LAS unsigned char*)buf + 139264))[twi];
; #pragma unroll
;     for (int m = 0; m < R; ++m) { const v2f v = buf[base + m * stride]; x[m] = cf{v.x, v.y}; }
;     const cf w{wv.x, wv.y};
;     if (INV) dit_reg<LR>(x, w); else dif_reg<LR>(x, w);
; #pragma unroll
;     for (int m = 0; m < R; ++m) buf[base + m * stride] = mkv2(x[m].x, x[m].y);
; }
; __device__ __forceinline__ void fft_fwd_abc(ldsf2 buf) {
;     ...
;     for (int u = 0; u < 2; ++u) { const int o = l + 64 * u, e0 = wv * 1024 + o; fft_pass<3, false>(buf, e0 + (e0 >> 4), 136, o * 8); }
;     wave_lds_fence();
; #pragma unroll 1
;     for (int u = 0; u < 2; ++u) { const int j = l + 64 * u, o = j & 15, e0 = wv * 1024 + (j >> 4) * 128 + o; fft_pass<3, false>(buf, e0 + (e0 >> 4), 17, o * 64); }
	v_pk_add_f32 v[166:167], v[220:221], v[220:221] op_sel:[0,1] op_sel_hi:[1,0] neg_lo:[0,0] neg_hi:[0,1]
	s_nop 0
	v_pk_mul_f32 v[168:169], v[166:167], s[16:17] op_sel:[0,0] op_sel_hi:[1,0]
	v_pk_mul_f32 v[170:171], v[166:167], s[16:17] op_sel:[1,0] op_sel_hi:[0,0] neg_lo:[0,0] neg_hi:[1,0]
	v_pk_add_f32 v[188:189], v[138:139], v[158:159] neg_lo:[0,1] neg_hi:[0,1]
	v_pk_add_f32 v[190:191], v[140:141], v[160:161] neg_lo:[0,1] neg_hi:[0,1]
	v_pk_add_f32 v[196:197], v[154:155], v[162:163] neg_lo:[0,1] neg_hi:[0,1]
	v_pk_add_f32 v[198:199], v[156:157], v[164:165] neg_lo:[0,1] neg_hi:[0,1]
	v_pk_add_f32 v[138:139], v[138:139], v[158:159]
	v_pk_add_f32 v[140:141], v[140:141], v[160:161]
	v_pk_add_f32 v[154:155], v[154:155], v[162:163]
	v_pk_add_f32 v[156:157], v[156:157], v[164:165]
	v_pk_mul_f32 v[158:159], v[188:189], v[220:221] op_sel:[1,1] op_sel_hi:[1,0]
	v_pk_mul_f32 v[160:161], v[190:191], v[168:169] op_sel:[1,1] op_sel_hi:[1,0]
	v_pk_mul_f32 v[162:163], v[196:197], v[220:221] op_sel:[1,0] op_sel_hi:[1,1]
	v_pk_mul_f32 v[164:165], v[198:199], v[170:171] op_sel:[1,1] op_sel_hi:[1,0]
	v_pk_fma_f32 v[158:159], v[188:189], v[220:221], v[158:159] op_sel:[0,0,0] op_sel_hi:[0,1,1] neg_lo:[0,0,1] neg_hi:[0,0,0]
	v_pk_fma_f32 v[160:161], v[190:191], v[168:169], v[160:161] op_sel:[0,0,0] op_sel_hi:[0,1,1] neg_lo:[0,0,1] neg_hi:[0,0,0]
	v_pk_fma_f32 v[162:163], v[196:197], v[220:221], v[162:163] op_sel:[0,1,0] op_sel_hi:[0,0,1] neg_lo:[0,0,0] neg_hi:[0,1,0]
	v_pk_fma_f32 v[164:165], v[198:199], v[170:171], v[164:165] op_sel:[0,0,0] op_sel_hi:[0,1,1] neg_lo:[0,0,1] neg_hi:[0,0,0]
	v_pk_add_f32 v[188:189], v[138:139], v[154:155] neg_lo:[0,1] neg_hi:[0,1]
	v_pk_add_f32 v[190:191], v[140:141], v[156:157] neg_lo:[0,1] neg_hi:[0,1]
	v_pk_add_f32 v[196:197], v[158:159], v[162:163] neg_lo:[0,1] neg_hi:[0,1]
	v_pk_add_f32 v[198:199], v[160:161], v[164:165] neg_lo:[0,1] neg_hi:[0,1]
	v_pk_add_f32 v[138:139], v[138:139], v[154:155]
	v_pk_add_f32 v[140:141], v[140:141], v[156:157]
	v_pk_add_f32 v[158:159], v[158:159], v[162:163]
	v_pk_add_f32 v[160:161], v[160:161], v[164:165]
	v_pk_mul_f32 v[154:155], v[188:189], v[222:223] op_sel:[1,1] op_sel_hi:[1,0]
	v_pk_mul_f32 v[156:157], v[190:191], v[222:223] op_sel:[1,0] op_sel_hi:[1,1]
	v_pk_mul_f32 v[162:163], v[196:197], v[222:223] op_sel:[1,1] op_sel_hi:[1,0]
	v_pk_mul_f32 v[164:165], v[198:199], v[222:223] op_sel:[1,0] op_sel_hi:[1,1]
	v_pk_fma_f32 v[154:155], v[188:189], v[222:223], v[154:155] op_sel:[0,0,0] op_sel_hi:[0,1,1] neg_lo:[0,0,1] neg_hi:[0,0,0]
	v_pk_fma_f32 v[156:157], v[190:191], v[222:223], v[156:157] op_sel:[0,1,0] op_sel_hi:[0,0,1] neg_lo:[0,0,0] neg_hi:[0,1,0]
	v_pk_fma_f32 v[162:163], v[196:197], v[222:223], v[162:163] op_sel:[0,0,0] op_sel_hi:[0,1,1] neg_lo:[0,0,1] neg_hi:[0,0,0]
	v_pk_fma_f32 v[164:165], v[198:199], v[222:223], v[164:165] op_sel:[0,1,0] op_sel_hi:[0,0,1] neg_lo:[0,0,0] neg_hi:[0,1,0]
	v_pk_add_f32 v[188:189], v[138:139], v[140:141] neg_lo:[0,1] neg_hi:[0,1]
	v_pk_add_f32 v[190:191], v[154:155], v[156:157] neg_lo:[0,1] neg_hi:[0,1]
	v_pk_add_f32 v[196:197], v[158:159], v[160:161] neg_lo:[0,1] neg_hi:[0,1]
	v_pk_add_f32 v[198:199], v[162:163], v[164:165] neg_lo:[0,1] neg_hi:[0,1]
	v_pk_add_f32 v[138:139], v[138:139], v[140:141]
	v_pk_add_f32 v[154:155], v[154:155], v[156:157]
	v_pk_add_f32 v[158:159], v[158:159], v[160:161]
	v_pk_add_f32 v[162:163], v[162:163], v[164:165]
	v_pk_mul_f32 v[140:141], v[188:189], v[224:225] op_sel:[1,1] op_sel_hi:[1,0]
	v_pk_mul_f32 v[156:157], v[190:191], v[224:225] op_sel:[1,1] op_sel_hi:[1,0]
	v_pk_mul_f32 v[160:161], v[196:197], v[224:225] op_sel:[1,1] op_sel_hi:[1,0]
	v_pk_mul_f32 v[164:165], v[198:199], v[224:225] op_sel:[1,1] op_sel_hi:[1,0]
	v_pk_fma_f32 v[140:141], v[188:189], v[224:225], v[140:141] op_sel:[0,0,0] op_sel_hi:[0,1,1] neg_lo:[0,0,1] neg_hi:[0,0,0]
	v_pk_fma_f32 v[156:157], v[190:191], v[224:225], v[156:157] op_sel:[0,0,0] op_sel_hi:[0,1,1] neg_lo:[0,0,1] neg_hi:[0,0,0]
	v_pk_fma_f32 v[160:161], v[196:197], v[224:225], v[160:161] op_sel:[0,0,0] op_sel_hi:[0,1,1] neg_lo:[0,0,1] neg_hi:[0,0,0]
	v_pk_fma_f32 v[164:165], v[198:199], v[224:225], v[164:165] op_sel:[0,0,0] op_sel_hi:[0,1,1] neg_lo:[0,0,1] neg_hi:[0,0,0]
	ds_write2_b64 v130, v[138:139], v[140:141] offset1:136
	ds_write2_b64 v136, v[154:155], v[156:157] offset0:16 offset1:152
	ds_write2_b64 v142, v[158:159], v[160:161] offset0:32 offset1:168
	ds_write2_b64 v152, v[162:163], v[164:165] offset0:48 offset1:184
	s_mov_b64 s[10:11], 0
	v_and_b32_e32 v78, 15, v78
	s_waitcnt lgkmcnt(0)
	v_lshlrev_b32_e32 v79, 3, v79
	v_lshlrev_b32_e32 v81, 9, v78
	v_and_or_b32 v79, v79, s90, v80
	v_add_u32_e32 v80, 0, v81
	v_lshl_add_u32 v78, v78, 3, 0
	s_mov_b32 s0, 0
	s_mov_b64 s[10:11], -1
	v_add_u32_e32 v80, 0x22000, v80
; #define LAS __attribute__((address_space(3)))
; __device__ __forceinline__ cf twc(cf ws, int k16) { if (k16 == 0) return ws; if (k16 == 4) return cf{ws.y, -ws.x}; return cmul(ws, cf{c16(k16), -s16(k16)}); }
; template <int LR> __device__ __forceinline__ void dif_reg(cf (&x)[1 << LR], cf w) {
;     constexpr int R = 1 << LR; cf ws = w;
; #pragma unroll
;     for (int s = 0; s < LR; ++s) { const int half = R >> (s + 1);
; #pragma unroll
;         for (int m0 = 0; m0 < R; m0 += 2 * half)
; #pragma unroll
;             for (int mm = 0; mm < half; ++mm) { const int ia = m0 + mm, ib = ia + half; const cf a = x[ia], b = x[ib];
;                 x[ia] = cf{a.x + b.x, a.y + b.y}; const cf d{a.x - b.x, a.y - b.y};
;                 x[ib] = cmul(d, twc(ws, (mm << s) * (16 / R))); }
;         ws = cmul(ws, ws); }
; }
; template <int LR> __device__ __forceinline__ void dit_reg(cf (&x)[1 << LR], cf w) {
;     constexpr int R = 1 << LR; cf wsv[LR]; wsv[0] = w;
; #pragma unroll
;     for (int s = 1; s < LR; ++s) wsv[s] = cmul(wsv[s - 1], wsv[s - 1]);
; #pragma unroll
;     for (int s = LR - 1; s >= 0; --s) { const int half = R >> (s + 1);
; #pragma unroll
;         for (int m0 = 0; m0 < R; m0 += 2 * half)
; #pragma unroll
;             for (int mm = 0; mm < half; ++mm) { const int ia = m0 + mm, ib = ia + half; const cf a = x[ia];
;                 const cf b = cmulc(x[ib], twc(wsv[s], (mm << s) * (16 / R)));
;                 x[ia] = cf{a.x + b.x, a.y + b.y}; x[ib] = cf{a.x - b.x, a.y - b.y}; } }
; }
; __device__ __forceinline__ void lds_barrier() { asm volatile("s_waitcnt lgkmcnt(0)\n\ts_barrier" ::: "memory"); }
; template <int LR, bool INV> __device__ __forceinline__ void fft_pass(ldsf2 buf, int base, int stride, int twi) {
;     constexpr int R = 1 << LR; cf x[R];
;     const v2f wv = ((ldsf2)((LAS unsigned char*)buf + 139264))[twi];
; #pragma unroll
;     for (int m = 0; m < R; ++m) { const v2f v = buf[base + m * stride]; x[m] = cf{v.x, v.y}; }
;     const cf w{wv.x, wv.y};
;     if (INV) dit_reg<LR>(x, w); else dif_reg<LR>(x, w);
; #pragma unroll
;     for (int m = 0; m < R; ++m) buf[base + m * stride] = mkv2(x[m].x, x[m].y);
; }
; __device__ __forceinline__ void fft_fwd_abc(ldsf2 buf) {
;     ...
;     for (int u = 0; u < 2; ++u) { const int j = l + 64 * u, o = j & 15, e0 = wv * 1024 + (j >> 4) * 128 + o; fft_pass<3, false>(buf, e0 + (e0 >> 4), 17, o * 64); }
.LBB0_363:
	v_or_b32_e32 v81, s0, v79
	v_lshlrev_b32_e32 v82, 3, v81
	v_ashrrev_i32_e32 v81, 1, v81
	v_add3_u32 v81, v78, v82, v81
	ds_read2_b64 v[82:85], v81 offset1:17
	ds_read2_b64 v[86:89], v81 offset0:34 offset1:51
	ds_read2_b64 v[90:93], v81 offset0:68 offset1:85
	ds_read2_b64 v[94:97], v81 offset0:102 offset1:119
	s_movk_i32 s0, 0x200
	v_or_b32_e32 v126, s0, v79
	v_lshlrev_b32_e32 v130, 3, v126
	v_ashrrev_i32_e32 v126, 1, v126
	v_add3_u32 v126, v78, v130, v126
	ds_read2_b64 v[132:135], v126 offset1:17
	ds_read2_b64 v[136:139], v126 offset0:34 offset1:51
	ds_read2_b64 v[140:143], v126 offset0:68 offset1:85
	ds_read2_b64 v[152:155], v126 offset0:102 offset1:119
	s_waitcnt lgkmcnt(4)
	v_pk_add_f32 v[110:111], v[82:83], v[90:91] neg_lo:[0,1] neg_hi:[0,1]
	v_pk_add_f32 v[112:113], v[84:85], v[92:93] neg_lo:[0,1] neg_hi:[0,1]
	v_pk_add_f32 v[114:115], v[86:87], v[94:95] neg_lo:[0,1] neg_hi:[0,1]
	v_pk_add_f32 v[116:117], v[88:89], v[96:97] neg_lo:[0,1] neg_hi:[0,1]
	v_pk_add_f32 v[82:83], v[82:83], v[90:91]
	v_pk_add_f32 v[84:85], v[84:85], v[92:93]
	v_pk_add_f32 v[86:87], v[86:87], v[94:95]
	v_pk_add_f32 v[88:89], v[88:89], v[96:97]
	v_pk_mul_f32 v[90:91], v[110:111], v[204:205] op_sel:[1,1] op_sel_hi:[1,0]
	v_pk_mul_f32 v[92:93], v[112:113], v[210:211] op_sel:[1,1] op_sel_hi:[1,0]
	v_pk_mul_f32 v[94:95], v[114:115], v[204:205] op_sel:[1,0] op_sel_hi:[1,1]
	v_pk_mul_f32 v[96:97], v[116:117], v[212:213] op_sel:[1,1] op_sel_hi:[1,0]
	v_pk_fma_f32 v[90:91], v[110:111], v[204:205], v[90:91] op_sel:[0,0,0] op_sel_hi:[0,1,1] neg_lo:[0,0,1] neg_hi:[0,0,0]
	v_pk_fma_f32 v[92:93], v[112:113], v[210:211], v[92:93] op_sel:[0,0,0] op_sel_hi:[0,1,1] neg_lo:[0,0,1] neg_hi:[0,0,0]
	v_pk_fma_f32 v[94:95], v[114:115], v[204:205], v[94:95] op_sel:[0,1,0] op_sel_hi:[0,0,1] neg_lo:[0,0,0] neg_hi:[0,1,0]
	v_pk_fma_f32 v[96:97], v[116:117], v[212:213], v[96:97] op_sel:[0,0,0] op_sel_hi:[0,1,1] neg_lo:[0,0,1] neg_hi:[0,0,0]
	v_pk_add_f32 v[110:111], v[82:83], v[86:87] neg_lo:[0,1] neg_hi:[0,1]
	v_pk_add_f32 v[112:113], v[84:85], v[88:89] neg_lo:[0,1] neg_hi:[0,1]
	v_pk_add_f32 v[114:115], v[90:91], v[94:95] neg_lo:[0,1] neg_hi:[0,1]
	v_pk_add_f32 v[116:117], v[92:93], v[96:97] neg_lo:[0,1] neg_hi:[0,1]
	v_pk_add_f32 v[82:83], v[82:83], v[86:87]
	v_pk_add_f32 v[84:85], v[84:85], v[88:89]
	v_pk_add_f32 v[90:91], v[90:91], v[94:95]
	v_pk_add_f32 v[92:93], v[92:93], v[96:97]
	v_pk_mul_f32 v[86:87], v[110:111], v[206:207] op_sel:[1,1] op_sel_hi:[1,0]
	v_pk_mul_f32 v[88:89], v[112:113], v[206:207] op_sel:[1,0] op_sel_hi:[1,1]
	v_pk_mul_f32 v[94:95], v[114:115], v[206:207] op_sel:[1,1] op_sel_hi:[1,0]
	v_pk_mul_f32 v[96:97], v[116:117], v[206:207] op_sel:[1,0] op_sel_hi:[1,1]
	v_pk_fma_f32 v[86:87], v[110:111], v[206:207], v[86:87] op_sel:[0,0,0] op_sel_hi:[0,1,1] neg_lo:[0,0,1] neg_hi:[0,0,0]
	v_pk_fma_f32 v[88:89], v[112:113], v[206:207], v[88:89] op_sel:[0,1,0] op_sel_hi:[0,0,1] neg_lo:[0,0,0] neg_hi:[0,1,0]
	v_pk_fma_f32 v[94:95], v[114:115], v[206:207], v[94:95] op_sel:[0,0,0] op_sel_hi:[0,1,1] neg_lo:[0,0,1] neg_hi:[0,0,0]
	v_pk_fma_f32 v[96:97], v[116:117], v[206:207], v[96:97] op_sel:[0,1,0] op_sel_hi:[0,0,1] neg_lo:[0,0,0] neg_hi:[0,1,0]
	v_pk_add_f32 v[110:111], v[82:83], v[84:85] neg_lo:[0,1] neg_hi:[0,1]
	v_pk_add_f32 v[112:113], v[86:87], v[88:89] neg_lo:[0,1] neg_hi:[0,1]
	v_pk_add_f32 v[114:115], v[90:91], v[92:93] neg_lo:[0,1] neg_hi:[0,1]
	v_pk_add_f32 v[116:117], v[94:95], v[96:97] neg_lo:[0,1] neg_hi:[0,1]
	v_pk_add_f32 v[82:83], v[82:83], v[84:85]
	v_pk_add_f32 v[86:87], v[86:87], v[88:89]
	v_pk_add_f32 v[90:91], v[90:91], v[92:93]
	v_pk_add_f32 v[94:95], v[94:95], v[96:97]
	v_pk_mul_f32 v[84:85], v[110:111], v[208:209] op_sel:[1,1] op_sel_hi:[1,0]
	v_pk_mul_f32 v[88:89], v[112:113], v[208:209] op_sel:[1,1] op_sel_hi:[1,0]
	v_pk_mul_f32 v[92:93], v[114:115], v[208:209] op_sel:[1,1] op_sel_hi:[1,0]
	v_pk_mul_f32 v[96:97], v[116:117], v[208:209] op_sel:[1,1] op_sel_hi:[1,0]
	v_pk_fma_f32 v[84:85], v[110:111], v[208:209], v[84:85] op_sel:[0,0,0] op_sel_hi:[0,1,1] neg_lo:[0,0,1] neg_hi:[0,0,0]
	v_pk_fma_f32 v[88:89], v[112:113], v[208:209], v[88:89] op_sel:[0,0,0] op_sel_hi:[0,1,1] neg_lo:[0,0,1] neg_hi:[0,0,0]
	v_pk_fma_f32 v[92:93], v[114:115], v[208:209], v[92:93] op_sel:[0,0,0] op_sel_hi:[0,1,1] neg_lo:[0,0,1] neg_hi:[0,0,0]
	v_pk_fma_f32 v[96:97], v[116:117], v[208:209], v[96:97] op_sel:[0,0,0] op_sel_hi:[0,1,1] neg_lo:[0,0,1] neg_hi:[0,0,0]
	ds_write2_b64 v81, v[82:83], v[84:85] offset1:17
	ds_write2_b64 v81, v[86:87], v[88:89] offset0:34 offset1:51
	ds_write2_b64 v81, v[90:91], v[92:93] offset0:68 offset1:85
	ds_write2_b64 v81, v[94:95], v[96:97] offset0:102 offset1:119
	s_waitcnt lgkmcnt(4)
; #define LAS __attribute__((address_space(3)))
; __device__ __forceinline__ int otid() { int t = threadIdx.x; asm volatile("" : "+v"(t)); return t; }
; template <int LR, bool INV> __device__ __forceinline__ void fft_pass(ldsf2 buf, int base, int stride, int twi) {
;     constexpr int R = 1 << LR; cf x[R];
;     const v2f wv = ((ldsf2)((LAS unsigned char*)buf + 139264))[twi];
; #pragma unroll
;     for (int m = 0; m < R; ++m) { const v2f v = buf[base + m * stride]; x[m] = cf{v.x, v.y}; }
;     const cf w{wv.x, wv.y};
;     if (INV) dit_reg<LR>(x, w); else dif_reg<LR>(x, w);
; #pragma unroll
;     for (int m = 0; m < R; ++m) buf[base + m * stride] = mkv2(x[m].x, x[m].y);
; }
; __device__ __forceinline__ void fft_conv(ldsf2 buf, const LAS unsigned* spec) {
;     fft_fwd_abc(buf);
;     { const int tid = otid(); cf x[16];
; #pragma unroll
;       for (int m = 0; m < 16; ++m) { const v2f v = buf[tid * 17 + m]; x[m] = cf{v.x, v.y}; }
;       dif_reg<4>(x, cf{1.0f, 0.0f});
; #pragma unroll
;       for (int m = 0; m < 16; ++m) { const h2_t hv = __builtin_bit_cast(h2_t, spec[tid * 17 + m]); x[m] = cmul(x[m], cf{(float)hv.x, (float)hv.y}); }
	v_pk_add_f32 v[166:167], v[132:133], v[140:141] neg_lo:[0,1] neg_hi:[0,1]
	v_pk_add_f32 v[168:169], v[134:135], v[142:143] neg_lo:[0,1] neg_hi:[0,1]
	v_pk_add_f32 v[170:171], v[136:137], v[152:153] neg_lo:[0,1] neg_hi:[0,1]
	v_pk_add_f32 v[172:173], v[138:139], v[154:155] neg_lo:[0,1] neg_hi:[0,1]
	v_pk_add_f32 v[132:133], v[132:133], v[140:141]
	v_pk_add_f32 v[134:135], v[134:135], v[142:143]
	v_pk_add_f32 v[136:137], v[136:137], v[152:153]
	v_pk_add_f32 v[138:139], v[138:139], v[154:155]
	v_pk_mul_f32 v[140:141], v[166:167], v[204:205] op_sel:[1,1] op_sel_hi:[1,0]
	v_pk_mul_f32 v[142:143], v[168:169], v[210:211] op_sel:[1,1] op_sel_hi:[1,0]
	v_pk_mul_f32 v[152:153], v[170:171], v[204:205] op_sel:[1,0] op_sel_hi:[1,1]
	v_pk_mul_f32 v[154:155], v[172:173], v[212:213] op_sel:[1,1] op_sel_hi:[1,0]
	v_pk_fma_f32 v[140:141], v[166:167], v[204:205], v[140:141] op_sel:[0,0,0] op_sel_hi:[0,1,1] neg_lo:[0,0,1] neg_hi:[0,0,0]
	v_pk_fma_f32 v[142:143], v[168:169], v[210:211], v[142:143] op_sel:[0,0,0] op_sel_hi:[0,1,1] neg_lo:[0,0,1] neg_hi:[0,0,0]
	v_pk_fma_f32 v[152:153], v[170:171], v[204:205], v[152:153] op_sel:[0,1,0] op_sel_hi:[0,0,1] neg_lo:[0,0,0] neg_hi:[0,1,0]
	v_pk_fma_f32 v[154:155], v[172:173], v[212:213], v[154:155] op_sel:[0,0,0] op_sel_hi:[0,1,1] neg_lo:[0,0,1] neg_hi:[0,0,0]
	v_pk_add_f32 v[166:167], v[132:133], v[136:137] neg_lo:[0,1] neg_hi:[0,1]
	v_pk_add_f32 v[168:169], v[134:135], v[138:139] neg_lo:[0,1] neg_hi:[0,1]
	v_pk_add_f32 v[170:171], v[140:141], v[152:153] neg_lo:[0,1] neg_hi:[0,1]
	v_pk_add_f32 v[172:173], v[142:143], v[154:155] neg_lo:[0,1] neg_hi:[0,1]
	v_pk_add_f32 v[132:133], v[132:133], v[136:137]
	v_pk_add_f32 v[134:135], v[134:135], v[138:139]
	v_pk_add_f32 v[140:141], v[140:141], v[152:153]
	v_pk_add_f32 v[142:143], v[142:143], v[154:155]
	v_pk_mul_f32 v[136:137], v[166:167], v[206:207] op_sel:[1,1] op_sel_hi:[1,0]
	v_pk_mul_f32 v[138:139], v[168:169], v[206:207] op_sel:[1,0] op_sel_hi:[1,1]
	v_pk_mul_f32 v[152:153], v[170:171], v[206:207] op_sel:[1,1] op_sel_hi:[1,0]
	v_pk_mul_f32 v[154:155], v[172:173], v[206:207] op_sel:[1,0] op_sel_hi:[1,1]
	v_pk_fma_f32 v[136:137], v[166:167], v[206:207], v[136:137] op_sel:[0,0,0] op_sel_hi:[0,1,1] neg_lo:[0,0,1] neg_hi:[0,0,0]
	v_pk_fma_f32 v[138:139], v[168:169], v[206:207], v[138:139] op_sel:[0,1,0] op_sel_hi:[0,0,1] neg_lo:[0,0,0] neg_hi:[0,1,0]
	v_pk_fma_f32 v[152:153], v[170:171], v[206:207], v[152:153] op_sel:[0,0,0] op_sel_hi:[0,1,1] neg_lo:[0,0,1] neg_hi:[0,0,0]
	v_pk_fma_f32 v[154:155], v[172:173], v[206:207], v[154:155] op_sel:[0,1,0] op_sel_hi:[0,0,1] neg_lo:[0,0,0] neg_hi:[0,1,0]
	v_pk_add_f32 v[166:167], v[132:133], v[134:135] neg_lo:[0,1] neg_hi:[0,1]
	v_pk_add_f32 v[168:169], v[136:137], v[138:139] neg_lo:[0,1] neg_hi:[0,1]
	v_pk_add_f32 v[170:171], v[140:141], v[142:143] neg_lo:[0,1] neg_hi:[0,1]
	v_pk_add_f32 v[172:173], v[152:153], v[154:155] neg_lo:[0,1] neg_hi:[0,1]
	v_pk_add_f32 v[132:133], v[132:133], v[134:135]
	v_pk_add_f32 v[136:137], v[136:137], v[138:139]
	v_pk_add_f32 v[140:141], v[140:141], v[142:143]
	v_pk_add_f32 v[152:153], v[152:153], v[154:155]
	v_pk_mul_f32 v[134:135], v[166:167], v[208:209] op_sel:[1,1] op_sel_hi:[1,0]
	v_pk_mul_f32 v[138:139], v[168:169], v[208:209] op_sel:[1,1] op_sel_hi:[1,0]
	v_pk_mul_f32 v[142:143], v[170:171], v[208:209] op_sel:[1,1] op_sel_hi:[1,0]
	v_pk_mul_f32 v[154:155], v[172:173], v[208:209] op_sel:[1,1] op_sel_hi:[1,0]
	v_pk_fma_f32 v[134:135], v[166:167], v[208:209], v[134:135] op_sel:[0,0,0] op_sel_hi:[0,1,1] neg_lo:[0,0,1] neg_hi:[0,0,0]
	v_pk_fma_f32 v[138:139], v[168:169], v[208:209], v[138:139] op_sel:[0,0,0] op_sel_hi:[0,1,1] neg_lo:[0,0,1] neg_hi:[0,0,0]
	v_pk_fma_f32 v[142:143], v[170:171], v[208:209], v[142:143] op_sel:[0,0,0] op_sel_hi:[0,1,1] neg_lo:[0,0,1] neg_hi:[0,0,0]
	v_pk_fma_f32 v[154:155], v[172:173], v[208:209], v[154:155] op_sel:[0,0,0] op_sel_hi:[0,1,1] neg_lo:[0,0,1] neg_hi:[0,0,0]
	ds_write2_b64 v126, v[132:133], v[134:135] offset1:17
	ds_write2_b64 v126, v[136:137], v[138:139] offset0:34 offset1:51
	ds_write2_b64 v126, v[140:141], v[142:143] offset0:68 offset1:85
	ds_write2_b64 v126, v[152:153], v[154:155] offset0:102 offset1:119
	s_mov_b64 s[10:11], 0
	v_mov_b32_e32 v162, v195
	s_movk_i32 s0, 0x88
	s_waitcnt lgkmcnt(0)
	s_mov_b32 s86, s63
	v_mul_lo_u32 v78, v162, s0
	v_add_u32_e32 v151, 0, v78
	ds_read2_b64 v[80:83], v151 offset1:1
	ds_read2_b64 v[84:87], v151 offset0:2 offset1:3
	ds_read2_b64 v[98:101], v151 offset0:4 offset1:5
	ds_read2_b64 v[102:105], v151 offset0:6 offset1:7
	ds_read2_b64 v[106:109], v151 offset0:8 offset1:9
	ds_read2_b64 v[110:113], v151 offset0:10 offset1:11
	ds_read2_b64 v[126:129], v151 offset0:12 offset1:13
	ds_read2_b64 v[134:137], v151 offset0:14 offset1:15
	s_mov_b32 s10, s63
	s_mov_b32 s11, s16
	s_mov_b32 s17, s5
	s_mov_b32 s0, s16
	s_mov_b32 s1, s4
	s_mov_b32 s0, s63
	s_mov_b32 s1, s5
	s_mov_b32 s0, s87
	s_mov_b32 s1, s4
	s_mov_b32 s1, s5
	s_mov_b32 s35, s4
	s_mov_b32 s12, s63
	s_movk_i32 s0, 0x44
	v_mul_lo_u32 v114, v162, s0
	v_add_u32_e32 v114, 0, v114
	v_add_u32_e32 v114, 0x19800, v114
	ds_read2_b32 v[160:161], v114 offset1:1
	ds_read2_b32 v[162:163], v114 offset0:2 offset1:3
	ds_read2_b32 v[164:165], v114 offset0:4 offset1:5
	ds_read2_b32 v[166:167], v114 offset0:6 offset1:7
	ds_read2_b32 v[168:169], v114 offset0:8 offset1:9
	ds_read2_b32 v[142:143], v114 offset0:10 offset1:11
	ds_read2_b32 v[138:139], v114 offset0:12 offset1:13
	ds_read2_b32 v[172:173], v114 offset0:14 offset1:15
	s_mov_b32 s0, s5
	s_mov_b64 s[14:15], -1
	s_mov_b32 s35, s13
	s_mov_b32 s0, s13
	s_waitcnt lgkmcnt(8)
; __device__ __forceinline__ cf twc(cf ws, int k16) { if (k16 == 0) return ws; if (k16 == 4) return cf{ws.y, -ws.x}; return cmul(ws, cf{c16(k16), -s16(k16)}); }
; template <int LR> __device__ __forceinline__ void dif_reg(cf (&x)[1 << LR], cf w) {
;     constexpr int R = 1 << LR; cf ws = w;
; #pragma unroll
;     for (int s = 0; s < LR; ++s) { const int half = R >> (s + 1);
; #pragma unroll
;         for (int m0 = 0; m0 < R; m0 += 2 * half)
; #pragma unroll
;             for (int mm = 0; mm < half; ++mm) { const int ia = m0 + mm, ib = ia + half; const cf a = x[ia], b = x[ib];
;                 x[ia] = cf{a.x + b.x, a.y + b.y}; const cf d{a.x - b.x, a.y - b.y};
;                 x[ib] = cmul(d, twc(ws, (mm << s) * (16 / R))); }
;         ws = cmul(ws, ws); }
; }
; __device__ __forceinline__ void fft_conv(ldsf2 buf, const LAS unsigned* spec) {
;     ...
;       for (int m = 0; m < 16; ++m) { const v2f v = buf[tid * 17 + m]; x[m] = cf{v.x, v.y}; }
;       dif_reg<4>(x, cf{1.0f, 0.0f});
	v_pk_add_f32 v[88:89], v[80:81], v[106:107]
	v_pk_add_f32 v[90:91], v[82:83], v[108:109]
	v_pk_add_f32 v[92:93], v[84:85], v[110:111]
	v_pk_add_f32 v[94:95], v[86:87], v[112:113]
	v_pk_add_f32 v[80:81], v[80:81], v[106:107] neg_lo:[0,1] neg_hi:[0,1]
	v_pk_add_f32 v[82:83], v[82:83], v[108:109] neg_lo:[0,1] neg_hi:[0,1]
	v_pk_add_f32 v[84:85], v[84:85], v[110:111] neg_lo:[0,1] neg_hi:[0,1]
	v_pk_add_f32 v[86:87], v[86:87], v[112:113] neg_lo:[0,1] neg_hi:[0,1]
	v_pk_mul_f32 v[108:109], v[82:83], s[4:5] op_sel:[1,1] op_sel_hi:[1,0] neg_lo:[0,1] neg_hi:[0,0]
	v_pk_mul_f32 v[110:111], v[84:85], s[16:17] op_sel:[1,0] op_sel_hi:[1,0] neg_lo:[0,1] neg_hi:[0,0]
	v_pk_mul_f32 v[112:113], v[86:87], s[4:5] op_sel:[1,0] op_sel_hi:[1,1] neg_lo:[0,1] neg_hi:[0,0]
	v_pk_fma_f32 v[108:109], v[82:83], s[4:5], v[108:109] op_sel:[0,0,0] op_sel_hi:[0,1,1] neg_lo:[0,0,1] neg_hi:[0,1,0]
	v_pk_fma_f32 v[110:111], v[84:85], s[16:17], v[110:111] op_sel:[0,0,0] op_sel_hi:[0,0,1] neg_lo:[0,0,1] neg_hi:[0,1,0]
	v_pk_fma_f32 v[112:113], v[86:87], s[4:5], v[112:113] op_sel:[0,1,0] op_sel_hi:[0,0,1] neg_lo:[0,0,1] neg_hi:[0,1,0]
	v_pk_add_f32 v[96:97], v[98:99], v[126:127]
	v_pk_add_f32 v[116:117], v[100:101], v[128:129]
	v_pk_add_f32 v[118:119], v[102:103], v[134:135]
	v_pk_add_f32 v[120:121], v[104:105], v[136:137]
	v_pk_add_f32 v[98:99], v[98:99], v[126:127] op_sel:[1,1] op_sel_hi:[0,0] neg_lo:[0,1] neg_hi:[1,0]
	v_pk_add_f32 v[100:101], v[100:101], v[128:129] neg_lo:[0,1] neg_hi:[0,1]
	v_pk_add_f32 v[102:103], v[102:103], v[134:135] neg_lo:[0,1] neg_hi:[0,1]
	v_pk_add_f32 v[104:105], v[104:105], v[136:137] neg_lo:[0,1] neg_hi:[0,1]
	v_pk_mul_f32 v[128:129], v[100:101], s[4:5] op_sel:[1,0] op_sel_hi:[1,1] neg_lo:[0,1] neg_hi:[0,1]
	v_pk_mul_f32 v[134:135], v[102:103], s[16:17] op_sel:[1,0] op_sel_hi:[1,0] neg_lo:[0,1] neg_hi:[0,1]
	v_pk_mul_f32 v[136:137], v[104:105], s[4:5] op_sel:[1,1] op_sel_hi:[1,0] neg_lo:[0,1] neg_hi:[0,1]
	v_pk_fma_f32 v[128:129], v[100:101], s[4:5], v[128:129] op_sel:[0,1,0] op_sel_hi:[0,0,1] neg_lo:[0,1,1] neg_hi:[0,1,0]
	v_pk_fma_f32 v[134:135], v[102:103], s[16:17], v[134:135] op_sel:[0,0,0] op_sel_hi:[0,0,1] neg_lo:[0,1,1] neg_hi:[0,1,0]
	v_pk_fma_f32 v[136:137], v[104:105], s[4:5], v[136:137] op_sel:[0,0,0] op_sel_hi:[0,1,1] neg_lo:[0,1,1] neg_hi:[0,1,0]
	v_pk_add_f32 v[122:123], v[88:89], v[96:97]
	v_pk_add_f32 v[124:125], v[90:91], v[116:117]
	v_pk_add_f32 v[130:131], v[92:93], v[118:119]
	v_pk_add_f32 v[132:133], v[94:95], v[120:121]
	v_pk_add_f32 v[88:89], v[88:89], v[96:97] neg_lo:[0,1] neg_hi:[0,1]
	v_pk_add_f32 v[90:91], v[90:91], v[116:117] neg_lo:[0,1] neg_hi:[0,1]
	v_pk_add_f32 v[92:93], v[92:93], v[118:119] op_sel:[1,1] op_sel_hi:[0,0] neg_lo:[0,1] neg_hi:[1,0]
	v_pk_add_f32 v[94:95], v[94:95], v[120:121] neg_lo:[0,1] neg_hi:[0,1]
	v_pk_mul_f32 v[116:117], v[90:91], s[16:17] op_sel:[1,0] op_sel_hi:[1,0] neg_lo:[0,1] neg_hi:[0,0]
	v_pk_mul_f32 v[120:121], v[94:95], s[16:17] op_sel:[1,0] op_sel_hi:[1,0] neg_lo:[0,1] neg_hi:[0,1]
	v_pk_fma_f32 v[116:117], v[90:91], s[16:17], v[116:117] op_sel:[0,0,0] op_sel_hi:[0,0,1] neg_lo:[0,0,1] neg_hi:[0,1,0]
	v_pk_fma_f32 v[120:121], v[94:95], s[16:17], v[120:121] op_sel:[0,0,0] op_sel_hi:[0,0,1] neg_lo:[0,1,1] neg_hi:[0,1,0]
	v_pk_add_f32 v[140:141], v[80:81], v[98:99]
	v_pk_add_f32 v[152:153], v[108:109], v[128:129]
	v_pk_add_f32 v[154:155], v[110:111], v[134:135]
	v_pk_add_f32 v[156:157], v[112:113], v[136:137]
	v_pk_add_f32 v[80:81], v[80:81], v[98:99] neg_lo:[0,1] neg_hi:[0,1]
	v_pk_add_f32 v[108:109], v[108:109], v[128:129] neg_lo:[0,1] neg_hi:[0,1]
	v_pk_add_f32 v[110:111], v[110:111], v[134:135] op_sel:[1,1] op_sel_hi:[0,0] neg_lo:[0,1] neg_hi:[1,0]
	v_pk_add_f32 v[112:113], v[112:113], v[136:137] neg_lo:[0,1] neg_hi:[0,1]
	v_pk_mul_f32 v[128:129], v[108:109], s[16:17] op_sel:[1,0] op_sel_hi:[1,0] neg_lo:[0,1] neg_hi:[0,0]
	v_pk_mul_f32 v[136:137], v[112:113], s[16:17] op_sel:[1,0] op_sel_hi:[1,0] neg_lo:[0,1] neg_hi:[0,1]
	v_pk_fma_f32 v[128:129], v[108:109], s[16:17], v[128:129] op_sel:[0,0,0] op_sel_hi:[0,0,1] neg_lo:[0,0,1] neg_hi:[0,1,0]
	v_pk_fma_f32 v[136:137], v[112:113], s[16:17], v[136:137] op_sel:[0,0,0] op_sel_hi:[0,0,1] neg_lo:[0,1,1] neg_hi:[0,1,0]
	v_pk_add_f32 v[158:159], v[122:123], v[130:131]
	v_pk_add_f32 v[170:171], v[124:125], v[132:133]
	v_pk_add_f32 v[106:107], v[88:89], v[92:93]
	v_pk_add_f32 v[82:83], v[116:117], v[120:121]
	v_pk_add_f32 v[122:123], v[122:123], v[130:131] neg_lo:[0,1] neg_hi:[0,1]
	v_pk_add_f32 v[124:125], v[124:125], v[132:133] op_sel:[1,1] op_sel_hi:[0,0] neg_lo:[0,1] neg_hi:[1,0]
	v_pk_add_f32 v[88:89], v[88:89], v[92:93] neg_lo:[0,1] neg_hi:[0,1]
	v_pk_add_f32 v[116:117], v[116:117], v[120:121] op_sel:[1,1] op_sel_hi:[0,0] neg_lo:[0,1] neg_hi:[1,0]
	v_pk_add_f32 v[84:85], v[140:141], v[154:155]
	v_pk_add_f32 v[86:87], v[152:153], v[156:157]
	v_pk_add_f32 v[126:127], v[80:81], v[110:111]
	v_pk_add_f32 v[100:101], v[128:129], v[136:137]
	v_pk_add_f32 v[140:141], v[140:141], v[154:155] neg_lo:[0,1] neg_hi:[0,1]
	v_pk_add_f32 v[152:153], v[152:153], v[156:157] op_sel:[1,1] op_sel_hi:[0,0] neg_lo:[0,1] neg_hi:[1,0]
	v_pk_add_f32 v[80:81], v[80:81], v[110:111] neg_lo:[0,1] neg_hi:[0,1]
	v_pk_add_f32 v[128:129], v[128:129], v[136:137] op_sel:[1,1] op_sel_hi:[0,0] neg_lo:[0,1] neg_hi:[1,0]
	v_pk_add_f32 v[102:103], v[158:159], v[170:171]
	v_pk_add_f32 v[104:105], v[122:123], v[124:125]
	v_pk_add_f32 v[96:97], v[106:107], v[82:83]
	v_pk_add_f32 v[90:91], v[88:89], v[116:117]
	v_pk_add_f32 v[158:159], v[158:159], v[170:171] neg_lo:[0,1] neg_hi:[0,1]
	v_pk_add_f32 v[122:123], v[122:123], v[124:125] neg_lo:[0,1] neg_hi:[0,1]
	v_pk_add_f32 v[106:107], v[106:107], v[82:83] neg_lo:[0,1] neg_hi:[0,1]
	v_pk_add_f32 v[88:89], v[88:89], v[116:117] neg_lo:[0,1] neg_hi:[0,1]
	v_pk_add_f32 v[118:119], v[84:85], v[86:87]
	v_pk_add_f32 v[94:95], v[140:141], v[152:153]
	v_pk_add_f32 v[98:99], v[126:127], v[100:101]
	v_pk_add_f32 v[108:109], v[80:81], v[128:129]
	v_pk_add_f32 v[84:85], v[84:85], v[86:87] neg_lo:[0,1] neg_hi:[0,1]
	v_pk_add_f32 v[140:141], v[140:141], v[152:153] neg_lo:[0,1] neg_hi:[0,1]
	v_pk_add_f32 v[126:127], v[126:127], v[100:101] neg_lo:[0,1] neg_hi:[0,1]
	v_pk_add_f32 v[80:81], v[80:81], v[128:129] neg_lo:[0,1] neg_hi:[0,1]
	s_waitcnt lgkmcnt(0)
; #define LAS __attribute__((address_space(3)))
; __device__ __forceinline__ int otid() { int t = threadIdx.x; asm volatile("" : "+v"(t)); return t; }
; __device__ __forceinline__ void fft_conv(ldsf2 buf, const LAS unsigned* spec) {
;     fft_fwd_abc(buf);
;     { const int tid = otid(); cf x[16];
; #pragma unroll
;       for (int m = 0; m < 16; ++m) { const v2f v = buf[tid * 17 + m]; x[m] = cf{v.x, v.y}; }
;       dif_reg<4>(x, cf{1.0f, 0.0f});
; #pragma unroll
;       for (int m = 0; m < 16; ++m) { const h2_t hv = __builtin_bit_cast(h2_t, spec[tid * 17 + m]); x[m] = cmul(x[m], cf{(float)hv.x, (float)hv.y}); }
;       dit_reg<4>(x, cf{1.0f, 0.0f});
	v_cvt_f32_f16_e32 v134, v160
	v_cvt_f32_f16_e32 v130, v161
	v_cvt_f32_f16_e32 v92, v162
	v_cvt_f32_f16_e32 v154, v163
	v_cvt_f32_f16_sdwa v135, v160 dst_sel:DWORD dst_unused:UNUSED_PAD src0_sel:WORD_1
	v_cvt_f32_f16_sdwa v131, v161 dst_sel:DWORD dst_unused:UNUSED_PAD src0_sel:WORD_1
	v_cvt_f32_f16_sdwa v93, v162 dst_sel:DWORD dst_unused:UNUSED_PAD src0_sel:WORD_1
	v_cvt_f32_f16_sdwa v155, v163 dst_sel:DWORD dst_unused:UNUSED_PAD src0_sel:WORD_1
	v_pk_mul_f32 v[112:113], v[102:103], v[134:135] op_sel:[1,1] op_sel_hi:[1,0]
	v_pk_mul_f32 v[132:133], v[158:159], v[130:131] op_sel:[1,1] op_sel_hi:[1,0]
	v_pk_mul_f32 v[120:121], v[104:105], v[92:93] op_sel:[1,1] op_sel_hi:[1,0]
	v_pk_mul_f32 v[156:157], v[122:123], v[154:155] op_sel:[1,1] op_sel_hi:[1,0]
	v_pk_fma_f32 v[134:135], v[102:103], v[134:135], v[112:113] op_sel:[0,0,0] op_sel_hi:[0,1,1] neg_lo:[0,0,1] neg_hi:[0,0,0]
	v_pk_fma_f32 v[130:131], v[158:159], v[130:131], v[132:133] op_sel:[0,0,0] op_sel_hi:[0,1,1] neg_lo:[0,0,1] neg_hi:[0,0,0]
	v_pk_fma_f32 v[92:93], v[104:105], v[92:93], v[120:121] op_sel:[0,0,0] op_sel_hi:[0,1,1] neg_lo:[0,0,1] neg_hi:[0,0,0]
	v_pk_fma_f32 v[154:155], v[122:123], v[154:155], v[156:157] op_sel:[0,0,0] op_sel_hi:[0,1,1] neg_lo:[0,0,1] neg_hi:[0,0,0]
	v_cvt_f32_f16_e32 v110, v164
	v_cvt_f32_f16_e32 v170, v165
	v_cvt_f32_f16_e32 v82, v166
	v_cvt_f32_f16_e32 v86, v167
	v_cvt_f32_f16_sdwa v111, v164 dst_sel:DWORD dst_unused:UNUSED_PAD src0_sel:WORD_1
	v_cvt_f32_f16_sdwa v171, v165 dst_sel:DWORD dst_unused:UNUSED_PAD src0_sel:WORD_1
	v_cvt_f32_f16_sdwa v83, v166 dst_sel:DWORD dst_unused:UNUSED_PAD src0_sel:WORD_1
	v_cvt_f32_f16_sdwa v87, v167 dst_sel:DWORD dst_unused:UNUSED_PAD src0_sel:WORD_1
	v_pk_mul_f32 v[136:137], v[96:97], v[110:111] op_sel:[1,1] op_sel_hi:[1,0]
	v_pk_mul_f32 v[124:125], v[106:107], v[170:171] op_sel:[1,1] op_sel_hi:[1,0]
	v_pk_mul_f32 v[116:117], v[90:91], v[82:83] op_sel:[1,1] op_sel_hi:[1,0]
	v_pk_mul_f32 v[152:153], v[88:89], v[86:87] op_sel:[1,1] op_sel_hi:[1,0]
	v_pk_fma_f32 v[110:111], v[96:97], v[110:111], v[136:137] op_sel:[0,0,0] op_sel_hi:[0,1,1] neg_lo:[0,0,1] neg_hi:[0,0,0]
	v_pk_fma_f32 v[170:171], v[106:107], v[170:171], v[124:125] op_sel:[0,0,0] op_sel_hi:[0,1,1] neg_lo:[0,0,1] neg_hi:[0,0,0]
	v_pk_fma_f32 v[82:83], v[90:91], v[82:83], v[116:117] op_sel:[0,0,0] op_sel_hi:[0,1,1] neg_lo:[0,0,1] neg_hi:[0,0,0]
	v_pk_fma_f32 v[86:87], v[88:89], v[86:87], v[152:153] op_sel:[0,0,0] op_sel_hi:[0,1,1] neg_lo:[0,0,1] neg_hi:[0,0,0]
	v_cvt_f32_f16_e32 v100, v168
	v_cvt_f32_f16_e32 v112, v169
	v_cvt_f32_f16_e32 v132, v142
	v_cvt_f32_f16_e32 v120, v143
	v_cvt_f32_f16_sdwa v101, v168 dst_sel:DWORD dst_unused:UNUSED_PAD src0_sel:WORD_1
	v_cvt_f32_f16_sdwa v113, v169 dst_sel:DWORD dst_unused:UNUSED_PAD src0_sel:WORD_1
	v_cvt_f32_f16_sdwa v133, v142 dst_sel:DWORD dst_unused:UNUSED_PAD src0_sel:WORD_1
	v_cvt_f32_f16_sdwa v121, v143 dst_sel:DWORD dst_unused:UNUSED_PAD src0_sel:WORD_1
	v_pk_mul_f32 v[128:129], v[118:119], v[100:101] op_sel:[1,1] op_sel_hi:[1,0]
	v_pk_mul_f32 v[102:103], v[84:85], v[112:113] op_sel:[1,1] op_sel_hi:[1,0]
	v_pk_mul_f32 v[158:159], v[94:95], v[132:133] op_sel:[1,1] op_sel_hi:[1,0]
	v_pk_mul_f32 v[104:105], v[140:141], v[120:121] op_sel:[1,1] op_sel_hi:[1,0]
	v_pk_fma_f32 v[100:101], v[118:119], v[100:101], v[128:129] op_sel:[0,0,0] op_sel_hi:[0,1,1] neg_lo:[0,0,1] neg_hi:[0,0,0]
	v_pk_fma_f32 v[112:113], v[84:85], v[112:113], v[102:103] op_sel:[0,0,0] op_sel_hi:[0,1,1] neg_lo:[0,0,1] neg_hi:[0,0,0]
	v_pk_fma_f32 v[132:133], v[94:95], v[132:133], v[158:159] op_sel:[0,0,0] op_sel_hi:[0,1,1] neg_lo:[0,0,1] neg_hi:[0,0,0]
	v_pk_fma_f32 v[120:121], v[140:141], v[120:121], v[104:105] op_sel:[0,0,0] op_sel_hi:[0,1,1] neg_lo:[0,0,1] neg_hi:[0,0,0]
	v_cvt_f32_f16_e32 v156, v138
	v_cvt_f32_f16_e32 v136, v139
	v_cvt_f32_f16_e32 v124, v172
	v_cvt_f32_f16_e32 v116, v173
	v_cvt_f32_f16_sdwa v157, v138 dst_sel:DWORD dst_unused:UNUSED_PAD src0_sel:WORD_1
	v_cvt_f32_f16_sdwa v137, v139 dst_sel:DWORD dst_unused:UNUSED_PAD src0_sel:WORD_1
	v_cvt_f32_f16_sdwa v125, v172 dst_sel:DWORD dst_unused:UNUSED_PAD src0_sel:WORD_1
	v_cvt_f32_f16_sdwa v117, v173 dst_sel:DWORD dst_unused:UNUSED_PAD src0_sel:WORD_1
	v_pk_mul_f32 v[122:123], v[98:99], v[156:157] op_sel:[1,1] op_sel_hi:[1,0]
	v_pk_mul_f32 v[96:97], v[126:127], v[136:137] op_sel:[1,1] op_sel_hi:[1,0]
	v_pk_mul_f32 v[106:107], v[108:109], v[124:125] op_sel:[1,1] op_sel_hi:[1,0]
	v_pk_mul_f32 v[90:91], v[80:81], v[116:117] op_sel:[1,1] op_sel_hi:[1,0]
	v_pk_fma_f32 v[156:157], v[98:99], v[156:157], v[122:123] op_sel:[0,0,0] op_sel_hi:[0,1,1] neg_lo:[0,0,1] neg_hi:[0,0,0]
	v_pk_fma_f32 v[136:137], v[126:127], v[136:137], v[96:97] op_sel:[0,0,0] op_sel_hi:[0,1,1] neg_lo:[0,0,1] neg_hi:[0,0,0]
	v_pk_fma_f32 v[124:125], v[108:109], v[124:125], v[106:107] op_sel:[0,0,0] op_sel_hi:[0,1,1] neg_lo:[0,0,1] neg_hi:[0,0,0]
	v_pk_fma_f32 v[116:117], v[80:81], v[116:117], v[90:91] op_sel:[0,0,0] op_sel_hi:[0,1,1] neg_lo:[0,0,1] neg_hi:[0,0,0]
	v_pk_add_f32 v[152:153], v[134:135], v[130:131]
	v_pk_add_f32 v[88:89], v[92:93], v[154:155]
	v_pk_add_f32 v[128:129], v[110:111], v[170:171]
	v_pk_add_f32 v[118:119], v[82:83], v[86:87]
	v_pk_add_f32 v[134:135], v[134:135], v[130:131] neg_lo:[0,1] neg_hi:[0,1]
	v_pk_add_f32 v[92:93], v[92:93], v[154:155] neg_lo:[0,1] neg_hi:[0,1]
	v_pk_add_f32 v[110:111], v[110:111], v[170:171] neg_lo:[0,1] neg_hi:[0,1]
	v_pk_add_f32 v[82:83], v[82:83], v[86:87] neg_lo:[0,1] neg_hi:[0,1]
	v_pk_add_f32 v[102:103], v[100:101], v[112:113]
	v_pk_add_f32 v[84:85], v[132:133], v[120:121]
	v_pk_add_f32 v[158:159], v[156:157], v[136:137]
	v_pk_add_f32 v[94:95], v[124:125], v[116:117]
; __device__ __forceinline__ cf twc(cf ws, int k16) { if (k16 == 0) return ws; if (k16 == 4) return cf{ws.y, -ws.x}; return cmul(ws, cf{c16(k16), -s16(k16)}); }
; template <int LR> __device__ __forceinline__ void dit_reg(cf (&x)[1 << LR], cf w) {
;     constexpr int R = 1 << LR; cf wsv[LR]; wsv[0] = w;
; #pragma unroll
;     for (int s = 1; s < LR; ++s) wsv[s] = cmul(wsv[s - 1], wsv[s - 1]);
; #pragma unroll
;     for (int s = LR - 1; s >= 0; --s) { const int half = R >> (s + 1);
; #pragma unroll
;         for (int m0 = 0; m0 < R; m0 += 2 * half)
; #pragma unroll
;             for (int mm = 0; mm < half; ++mm) { const int ia = m0 + mm, ib = ia + half; const cf a = x[ia];
;                 const cf b = cmulc(x[ib], twc(wsv[s], (mm << s) * (16 / R)));
;                 x[ia] = cf{a.x + b.x, a.y + b.y}; x[ib] = cf{a.x - b.x, a.y - b.y}; } }
; }
; __device__ __forceinline__ void fft_conv(ldsf2 buf, const LAS unsigned* spec) {
;     ...
;       dit_reg<4>(x, cf{1.0f, 0.0f});
; #pragma unroll
;       for (int m = 0; m < 16; ++m) buf[tid * 17 + m] = mkv2(x[m].x, x[m].y); }
	v_pk_add_f32 v[100:101], v[100:101], v[112:113] neg_lo:[0,1] neg_hi:[0,1]
	v_pk_add_f32 v[132:133], v[132:133], v[120:121] neg_lo:[0,1] neg_hi:[0,1]
	v_pk_add_f32 v[156:157], v[156:157], v[136:137] neg_lo:[0,1] neg_hi:[0,1]
	v_pk_add_f32 v[124:125], v[124:125], v[116:117] neg_lo:[0,1] neg_hi:[0,1]
	v_pk_add_f32 v[104:105], v[152:153], v[88:89]
	v_pk_add_f32 v[140:141], v[134:135], v[92:93] op_sel:[0,1] op_sel_hi:[1,0] neg_lo:[0,1] neg_hi:[0,0]
	v_pk_add_f32 v[122:123], v[128:129], v[118:119]
	v_pk_add_f32 v[98:99], v[110:111], v[82:83] op_sel:[0,1] op_sel_hi:[1,0] neg_lo:[0,1] neg_hi:[0,0]
	v_pk_add_f32 v[152:153], v[152:153], v[88:89] neg_lo:[0,1] neg_hi:[0,1]
	v_pk_add_f32 v[134:135], v[134:135], v[92:93] op_sel:[0,1] op_sel_hi:[1,0] neg_lo:[0,0] neg_hi:[0,1]
	v_pk_add_f32 v[128:129], v[128:129], v[118:119] neg_lo:[0,1] neg_hi:[0,1]
	v_pk_add_f32 v[110:111], v[110:111], v[82:83] op_sel:[0,1] op_sel_hi:[1,0] neg_lo:[0,0] neg_hi:[0,1]
	v_pk_add_f32 v[96:97], v[102:103], v[84:85]
	v_pk_add_f32 v[126:127], v[100:101], v[132:133] op_sel:[0,1] op_sel_hi:[1,0] neg_lo:[0,1] neg_hi:[0,0]
	v_pk_add_f32 v[106:107], v[158:159], v[94:95]
	v_pk_add_f32 v[108:109], v[156:157], v[124:125] op_sel:[0,1] op_sel_hi:[1,0] neg_lo:[0,1] neg_hi:[0,0]
	v_pk_add_f32 v[102:103], v[102:103], v[84:85] neg_lo:[0,1] neg_hi:[0,1]
	v_pk_add_f32 v[100:101], v[100:101], v[132:133] op_sel:[0,1] op_sel_hi:[1,0] neg_lo:[0,0] neg_hi:[0,1]
	v_pk_add_f32 v[158:159], v[158:159], v[94:95] neg_lo:[0,1] neg_hi:[0,1]
	v_pk_add_f32 v[156:157], v[156:157], v[124:125] op_sel:[0,1] op_sel_hi:[1,0] neg_lo:[0,0] neg_hi:[0,1]
	v_pk_add_f32 v[90:91], v[104:105], v[122:123]
	v_pk_mul_f32 v[80:81], v[98:99], s[16:17] op_sel:[1,0] op_sel_hi:[1,0] neg_lo:[0,1] neg_hi:[0,0]
	v_pk_add_f32 v[130:131], v[152:153], v[128:129] op_sel:[0,1] op_sel_hi:[1,0] neg_lo:[0,1] neg_hi:[0,0]
	v_pk_mul_f32 v[154:155], v[110:111], s[16:17] op_sel:[1,0] op_sel_hi:[1,0] neg_lo:[0,1] neg_hi:[0,1]
	v_pk_add_f32 v[104:105], v[104:105], v[122:123] neg_lo:[0,1] neg_hi:[0,1]
	v_pk_fma_f32 v[80:81], v[98:99], s[16:17], v[80:81] op_sel:[0,0,0] op_sel_hi:[0,0,1] neg_lo:[0,0,0] neg_hi:[0,0,0]
	v_pk_add_f32 v[152:153], v[152:153], v[128:129] op_sel:[0,1] op_sel_hi:[1,0] neg_lo:[0,0] neg_hi:[0,1]
	v_pk_fma_f32 v[154:155], v[110:111], s[16:17], v[154:155] op_sel:[0,0,0] op_sel_hi:[0,0,1] neg_lo:[0,1,0] neg_hi:[0,0,0]
	v_pk_add_f32 v[98:99], v[140:141], v[80:81] neg_lo:[0,1] neg_hi:[0,1]
	v_pk_add_f32 v[110:111], v[134:135], v[154:155] neg_lo:[0,1] neg_hi:[0,1]
	v_pk_add_f32 v[140:141], v[140:141], v[80:81]
	v_pk_add_f32 v[134:135], v[134:135], v[154:155]
	v_pk_add_f32 v[170:171], v[96:97], v[106:107]
	v_pk_mul_f32 v[86:87], v[108:109], s[16:17] op_sel:[1,0] op_sel_hi:[1,0] neg_lo:[0,1] neg_hi:[0,0]
	v_pk_add_f32 v[112:113], v[102:103], v[158:159] op_sel:[0,1] op_sel_hi:[1,0] neg_lo:[0,1] neg_hi:[0,0]
	v_pk_mul_f32 v[120:121], v[156:157], s[16:17] op_sel:[1,0] op_sel_hi:[1,0] neg_lo:[0,1] neg_hi:[0,1]
	v_pk_add_f32 v[96:97], v[96:97], v[106:107] neg_lo:[0,1] neg_hi:[0,1]
	v_pk_fma_f32 v[86:87], v[108:109], s[16:17], v[86:87] op_sel:[0,0,0] op_sel_hi:[0,0,1] neg_lo:[0,0,0] neg_hi:[0,0,0]
	v_pk_add_f32 v[102:103], v[102:103], v[158:159] op_sel:[0,1] op_sel_hi:[1,0] neg_lo:[0,0] neg_hi:[0,1]
	v_pk_fma_f32 v[120:121], v[156:157], s[16:17], v[120:121] op_sel:[0,0,0] op_sel_hi:[0,0,1] neg_lo:[0,1,0] neg_hi:[0,0,0]
	v_pk_add_f32 v[108:109], v[126:127], v[86:87] neg_lo:[0,1] neg_hi:[0,1]
	v_pk_add_f32 v[156:157], v[100:101], v[120:121] neg_lo:[0,1] neg_hi:[0,1]
	v_pk_add_f32 v[126:127], v[126:127], v[86:87]
	v_pk_add_f32 v[100:101], v[100:101], v[120:121]
	v_pk_add_f32 v[136:137], v[90:91], v[170:171]
	v_pk_mul_f32 v[116:117], v[126:127], s[4:5] op_sel:[1,1] op_sel_hi:[1,0] neg_lo:[0,1] neg_hi:[0,0]
	v_pk_mul_f32 v[88:89], v[112:113], s[16:17] op_sel:[1,0] op_sel_hi:[1,0] neg_lo:[0,1] neg_hi:[0,0]
	v_pk_mul_f32 v[92:93], v[100:101], s[4:5] op_sel:[1,0] op_sel_hi:[1,1] neg_lo:[0,1] neg_hi:[0,0]
	v_pk_add_f32 v[90:91], v[90:91], v[170:171] neg_lo:[0,1] neg_hi:[0,1]
	v_pk_fma_f32 v[116:117], v[126:127], s[4:5], v[116:117] op_sel:[0,0,0] op_sel_hi:[0,1,1] neg_lo:[0,0,0] neg_hi:[0,0,0]
	v_pk_fma_f32 v[88:89], v[112:113], s[16:17], v[88:89] op_sel:[0,0,0] op_sel_hi:[0,0,1] neg_lo:[0,0,0] neg_hi:[0,0,0]
	v_pk_fma_f32 v[92:93], v[100:101], s[4:5], v[92:93] op_sel:[0,1,0] op_sel_hi:[0,0,1] neg_lo:[0,0,0] neg_hi:[0,0,0]
	v_pk_add_f32 v[126:127], v[140:141], v[116:117] neg_lo:[0,1] neg_hi:[0,1]
	v_pk_add_f32 v[112:113], v[130:131], v[88:89] neg_lo:[0,1] neg_hi:[0,1]
	v_pk_add_f32 v[100:101], v[134:135], v[92:93] neg_lo:[0,1] neg_hi:[0,1]
	v_pk_add_f32 v[140:141], v[140:141], v[116:117]
	v_pk_add_f32 v[130:131], v[130:131], v[88:89]
	v_pk_add_f32 v[134:135], v[134:135], v[92:93]
	v_pk_add_f32 v[118:119], v[104:105], v[96:97] op_sel:[0,1] op_sel_hi:[1,0] neg_lo:[0,1] neg_hi:[0,0]
	v_pk_mul_f32 v[82:83], v[108:109], s[4:5] op_sel:[1,0] op_sel_hi:[1,1] neg_lo:[0,1] neg_hi:[0,1]
	v_pk_mul_f32 v[84:85], v[102:103], s[16:17] op_sel:[1,0] op_sel_hi:[1,0] neg_lo:[0,1] neg_hi:[0,1]
	v_pk_mul_f32 v[132:133], v[156:157], s[4:5] op_sel:[1,1] op_sel_hi:[1,0] neg_lo:[0,1] neg_hi:[0,1]
	v_pk_add_f32 v[104:105], v[104:105], v[96:97] op_sel:[0,1] op_sel_hi:[1,0] neg_lo:[0,0] neg_hi:[0,1]
	v_pk_fma_f32 v[82:83], v[108:109], s[4:5], v[82:83] op_sel:[0,1,0] op_sel_hi:[0,0,1] neg_lo:[0,1,0] neg_hi:[0,0,0]
	v_pk_fma_f32 v[84:85], v[102:103], s[16:17], v[84:85] op_sel:[0,0,0] op_sel_hi:[0,0,1] neg_lo:[0,1,0] neg_hi:[0,0,0]
	v_pk_fma_f32 v[132:133], v[156:157], s[4:5], v[132:133] op_sel:[0,0,0] op_sel_hi:[0,1,1] neg_lo:[0,1,0] neg_hi:[0,0,0]
	v_pk_add_f32 v[108:109], v[98:99], v[82:83] neg_lo:[0,1] neg_hi:[0,1]
	v_pk_add_f32 v[102:103], v[152:153], v[84:85] neg_lo:[0,1] neg_hi:[0,1]
	v_pk_add_f32 v[156:157], v[110:111], v[132:133] neg_lo:[0,1] neg_hi:[0,1]
	v_pk_add_f32 v[98:99], v[98:99], v[82:83]
	v_pk_add_f32 v[152:153], v[152:153], v[84:85]
	v_pk_add_f32 v[110:111], v[110:111], v[132:133]
	ds_write2_b64 v151, v[136:137], v[140:141] offset1:1
	ds_write2_b64 v151, v[130:131], v[134:135] offset0:2 offset1:3
	ds_write2_b64 v151, v[118:119], v[98:99] offset0:4 offset1:5
	ds_write2_b64 v151, v[152:153], v[110:111] offset0:6 offset1:7
	ds_write2_b64 v151, v[90:91], v[126:127] offset0:8 offset1:9
	ds_write2_b64 v151, v[112:113], v[100:101] offset0:10 offset1:11
	ds_write2_b64 v151, v[104:105], v[108:109] offset0:12 offset1:13
	ds_write2_b64 v151, v[102:103], v[156:157] offset0:14 offset1:15
	v_mov_b32_e32 v78, v195
	s_waitcnt lgkmcnt(0)
	s_mov_b32 s0, 0
	v_and_b32_e32 v81, 15, v78
	v_lshlrev_b32_e32 v80, 4, v78
	v_lshlrev_b32_e32 v83, 9, v81
	v_and_b32_e32 v80, 0xfffffc00, v80
	v_lshlrev_b32_e32 v82, 3, v78
	v_add_u32_e32 v83, 0, v83
	v_and_b32_e32 v79, 63, v78
	v_lshl_add_u32 v81, v81, 3, 0
	v_and_or_b32 v82, v82, s90, v80
	v_add_u32_e32 v83, 0x22000, v83
; #define LAS __attribute__((address_space(3)))
; __device__ __forceinline__ cf twc(cf ws, int k16) { if (k16 == 0) return ws; if (k16 == 4) return cf{ws.y, -ws.x}; return cmul(ws, cf{c16(k16), -s16(k16)}); }
; template <int LR> __device__ __forceinline__ void dit_reg(cf (&x)[1 << LR], cf w) {
;     constexpr int R = 1 << LR; cf wsv[LR]; wsv[0] = w;
; #pragma unroll
;     for (int s = 1; s < LR; ++s) wsv[s] = cmul(wsv[s - 1], wsv[s - 1]);
; #pragma unroll
;     for (int s = LR - 1; s >= 0; --s) { const int half = R >> (s + 1);
; #pragma unroll
;         for (int m0 = 0; m0 < R; m0 += 2 * half)
; #pragma unroll
;             for (int mm = 0; mm < half; ++mm) { const int ia = m0 + mm, ib = ia + half; const cf a = x[ia];
;                 const cf b = cmulc(x[ib], twc(wsv[s], (mm << s) * (16 / R)));
;                 x[ia] = cf{a.x + b.x, a.y + b.y}; x[ib] = cf{a.x - b.x, a.y - b.y}; } }
; }
; __device__ __forceinline__ void lds_barrier() { asm volatile("s_waitcnt lgkmcnt(0)\n\ts_barrier" ::: "memory"); }
; template <int LR, bool INV> __device__ __forceinline__ void fft_pass(ldsf2 buf, int base, int stride, int twi) {
;     constexpr int R = 1 << LR; cf x[R];
;     const v2f wv = ((ldsf2)((LAS unsigned char*)buf + 139264))[twi];
; #pragma unroll
;     for (int m = 0; m < R; ++m) { const v2f v = buf[base + m * stride]; x[m] = cf{v.x, v.y}; }
;     const cf w{wv.x, wv.y};
;     if (INV) dit_reg<LR>(x, w); else dif_reg<LR>(x, w);
; #pragma unroll
;     for (int m = 0; m < R; ++m) buf[base + m * stride] = mkv2(x[m].x, x[m].y);
; }
; __device__ __forceinline__ void fft_inv_cba(ldsf2 buf) {
;     ...
;     for (int u = 0; u < 2; ++u) { const int j = l + 64 * u, o = j & 15, e0 = wv * 1024 + (j >> 4) * 128 + o; fft_pass<3, true>(buf, e0 + (e0 >> 4), 17, o * 64); }
.LBB0_365:
	v_or_b32_e32 v84, s0, v82
	v_lshlrev_b32_e32 v85, 3, v84
	v_ashrrev_i32_e32 v84, 1, v84
	v_add3_u32 v130, v81, v85, v84
	ds_read2_b64 v[84:87], v130 offset1:17
	ds_read2_b64 v[88:91], v130 offset0:34 offset1:51
	ds_read2_b64 v[92:95], v130 offset0:68 offset1:85
	ds_read2_b64 v[96:99], v130 offset0:102 offset1:119
	s_movk_i32 s0, 0x200
	v_or_b32_e32 v134, s0, v82
	v_lshlrev_b32_e32 v136, 3, v134
	v_ashrrev_i32_e32 v134, 1, v134
	v_add3_u32 v138, v81, v136, v134
	ds_read2_b64 v[140:143], v138 offset1:17
	ds_read2_b64 v[152:155], v138 offset0:34 offset1:51
	ds_read2_b64 v[156:159], v138 offset0:68 offset1:85
	ds_read2_b64 v[160:163], v138 offset0:102 offset1:119
	s_waitcnt lgkmcnt(4)
	v_pk_mul_f32 v[112:113], v[86:87], v[208:209] op_sel:[1,1] op_sel_hi:[1,0]
	v_pk_mul_f32 v[114:115], v[90:91], v[208:209] op_sel:[1,1] op_sel_hi:[1,0]
	v_pk_mul_f32 v[116:117], v[94:95], v[208:209] op_sel:[1,1] op_sel_hi:[1,0]
	v_pk_mul_f32 v[118:119], v[98:99], v[208:209] op_sel:[1,1] op_sel_hi:[1,0]
	v_pk_fma_f32 v[112:113], v[86:87], v[208:209], v[112:113] op_sel:[0,0,0] op_sel_hi:[0,1,1] neg_lo:[0,0,0] neg_hi:[0,1,0]
	v_pk_fma_f32 v[114:115], v[90:91], v[208:209], v[114:115] op_sel:[0,0,0] op_sel_hi:[0,1,1] neg_lo:[0,0,0] neg_hi:[0,1,0]
	v_pk_fma_f32 v[116:117], v[94:95], v[208:209], v[116:117] op_sel:[0,0,0] op_sel_hi:[0,1,1] neg_lo:[0,0,0] neg_hi:[0,1,0]
	v_pk_fma_f32 v[118:119], v[98:99], v[208:209], v[118:119] op_sel:[0,0,0] op_sel_hi:[0,1,1] neg_lo:[0,0,0] neg_hi:[0,1,0]
	v_pk_add_f32 v[86:87], v[84:85], v[112:113] neg_lo:[0,1] neg_hi:[0,1]
	v_pk_add_f32 v[90:91], v[88:89], v[114:115] neg_lo:[0,1] neg_hi:[0,1]
	v_pk_add_f32 v[94:95], v[92:93], v[116:117] neg_lo:[0,1] neg_hi:[0,1]
	v_pk_add_f32 v[98:99], v[96:97], v[118:119] neg_lo:[0,1] neg_hi:[0,1]
	v_pk_add_f32 v[84:85], v[84:85], v[112:113]
	v_pk_add_f32 v[88:89], v[88:89], v[114:115]
	v_pk_add_f32 v[92:93], v[92:93], v[116:117]
	v_pk_add_f32 v[96:97], v[96:97], v[118:119]
	v_pk_mul_f32 v[112:113], v[88:89], v[206:207] op_sel:[1,1] op_sel_hi:[1,0]
	v_pk_mul_f32 v[114:115], v[90:91], v[206:207] op_sel:[1,0] op_sel_hi:[1,1]
	v_pk_mul_f32 v[116:117], v[96:97], v[206:207] op_sel:[1,1] op_sel_hi:[1,0]
	v_pk_mul_f32 v[118:119], v[98:99], v[206:207] op_sel:[1,0] op_sel_hi:[1,1]
	v_pk_fma_f32 v[112:113], v[88:89], v[206:207], v[112:113] op_sel:[0,0,0] op_sel_hi:[0,1,1] neg_lo:[0,0,0] neg_hi:[0,1,0]
	v_pk_fma_f32 v[114:115], v[90:91], v[206:207], v[114:115] op_sel:[0,1,0] op_sel_hi:[0,0,1] neg_lo:[0,0,1] neg_hi:[0,0,0]
	v_pk_fma_f32 v[116:117], v[96:97], v[206:207], v[116:117] op_sel:[0,0,0] op_sel_hi:[0,1,1] neg_lo:[0,0,0] neg_hi:[0,1,0]
	v_pk_fma_f32 v[118:119], v[98:99], v[206:207], v[118:119] op_sel:[0,1,0] op_sel_hi:[0,0,1] neg_lo:[0,0,1] neg_hi:[0,0,0]
	v_pk_add_f32 v[88:89], v[84:85], v[112:113] neg_lo:[0,1] neg_hi:[0,1]
	v_pk_add_f32 v[90:91], v[86:87], v[114:115] neg_lo:[0,1] neg_hi:[0,1]
	v_pk_add_f32 v[96:97], v[92:93], v[116:117] neg_lo:[0,1] neg_hi:[0,1]
	v_pk_add_f32 v[98:99], v[94:95], v[118:119] neg_lo:[0,1] neg_hi:[0,1]
	v_pk_add_f32 v[84:85], v[84:85], v[112:113]
	v_pk_add_f32 v[86:87], v[86:87], v[114:115]
	v_pk_add_f32 v[92:93], v[92:93], v[116:117]
	v_pk_add_f32 v[94:95], v[94:95], v[118:119]
	v_pk_mul_f32 v[112:113], v[92:93], v[204:205] op_sel:[1,1] op_sel_hi:[1,0]
	v_pk_mul_f32 v[114:115], v[94:95], v[210:211] op_sel:[1,1] op_sel_hi:[1,0]
	v_pk_mul_f32 v[116:117], v[96:97], v[204:205] op_sel:[1,0] op_sel_hi:[1,1]
	v_pk_mul_f32 v[118:119], v[98:99], v[212:213] op_sel:[1,1] op_sel_hi:[1,0]
	v_pk_fma_f32 v[112:113], v[92:93], v[204:205], v[112:113] op_sel:[0,0,0] op_sel_hi:[0,1,1] neg_lo:[0,0,0] neg_hi:[0,1,0]
	v_pk_fma_f32 v[114:115], v[94:95], v[210:211], v[114:115] op_sel:[0,0,0] op_sel_hi:[0,1,1] neg_lo:[0,0,0] neg_hi:[0,1,0]
	v_pk_fma_f32 v[116:117], v[96:97], v[204:205], v[116:117] op_sel:[0,1,0] op_sel_hi:[0,0,1] neg_lo:[0,0,1] neg_hi:[0,0,0]
	v_pk_fma_f32 v[118:119], v[98:99], v[212:213], v[118:119] op_sel:[0,0,0] op_sel_hi:[0,1,1] neg_lo:[0,0,0] neg_hi:[0,1,0]
	v_pk_add_f32 v[92:93], v[84:85], v[112:113] neg_lo:[0,1] neg_hi:[0,1]
	v_pk_add_f32 v[94:95], v[86:87], v[114:115] neg_lo:[0,1] neg_hi:[0,1]
	v_pk_add_f32 v[96:97], v[88:89], v[116:117] neg_lo:[0,1] neg_hi:[0,1]
	v_pk_add_f32 v[98:99], v[90:91], v[118:119] neg_lo:[0,1] neg_hi:[0,1]
	v_pk_add_f32 v[84:85], v[84:85], v[112:113]
	v_pk_add_f32 v[86:87], v[86:87], v[114:115]
	v_pk_add_f32 v[88:89], v[88:89], v[116:117]
	v_pk_add_f32 v[90:91], v[90:91], v[118:119]
	ds_write2_b64 v130, v[84:85], v[86:87] offset1:17
	ds_write2_b64 v130, v[88:89], v[90:91] offset0:34 offset1:51
	ds_write2_b64 v130, v[92:93], v[94:95] offset0:68 offset1:85
	ds_write2_b64 v130, v[96:97], v[98:99] offset0:102 offset1:119
	s_waitcnt lgkmcnt(4)
; #define LAS __attribute__((address_space(3)))
; __device__ __forceinline__ cf twc(cf ws, int k16) { if (k16 == 0) return ws; if (k16 == 4) return cf{ws.y, -ws.x}; return cmul(ws, cf{c16(k16), -s16(k16)}); }
; __device__ __forceinline__ void wave_lds_fence() { asm volatile("s_waitcnt lgkmcnt(0)" ::: "memory"); }
; template <int LR> __device__ __forceinline__ void dit_reg(cf (&x)[1 << LR], cf w) {
;     constexpr int R = 1 << LR; cf wsv[LR]; wsv[0] = w;
; #pragma unroll
;     for (int s = 1; s < LR; ++s) wsv[s] = cmul(wsv[s - 1], wsv[s - 1]);
; #pragma unroll
;     for (int s = LR - 1; s >= 0; --s) { const int half = R >> (s + 1);
; #pragma unroll
;         for (int m0 = 0; m0 < R; m0 += 2 * half)
; #pragma unroll
;             for (int mm = 0; mm < half; ++mm) { const int ia = m0 + mm, ib = ia + half; const cf a = x[ia];
;                 const cf b = cmulc(x[ib], twc(wsv[s], (mm << s) * (16 / R)));
;                 x[ia] = cf{a.x + b.x, a.y + b.y}; x[ib] = cf{a.x - b.x, a.y - b.y}; } }
; }
; __device__ __forceinline__ void lds_barrier() { asm volatile("s_waitcnt lgkmcnt(0)\n\ts_barrier" ::: "memory"); }
; template <int LR, bool INV> __device__ __forceinline__ void fft_pass(ldsf2 buf, int base, int stride, int twi) {
;     constexpr int R = 1 << LR; cf x[R];
;     const v2f wv = ((ldsf2)((LAS unsigned char*)buf + 139264))[twi];
; #pragma unroll
;     for (int m = 0; m < R; ++m) { const v2f v = buf[base + m * stride]; x[m] = cf{v.x, v.y}; }
;     const cf w{wv.x, wv.y};
;     if (INV) dit_reg<LR>(x, w); else dif_reg<LR>(x, w);
; #pragma unroll
;     for (int m = 0; m < R; ++m) buf[base + m * stride] = mkv2(x[m].x, x[m].y);
; }
; __device__ __forceinline__ void fft_inv_cba(ldsf2 buf) {
;     ...
;     for (int u = 0; u < 2; ++u) { const int j = l + 64 * u, o = j & 15, e0 = wv * 1024 + (j >> 4) * 128 + o; fft_pass<3, true>(buf, e0 + (e0 >> 4), 17, o * 64); }
;     wave_lds_fence();
	v_pk_mul_f32 v[174:175], v[142:143], v[208:209] op_sel:[1,1] op_sel_hi:[1,0]
	v_pk_mul_f32 v[188:189], v[154:155], v[208:209] op_sel:[1,1] op_sel_hi:[1,0]
	v_pk_mul_f32 v[190:191], v[158:159], v[208:209] op_sel:[1,1] op_sel_hi:[1,0]
	v_pk_mul_f32 v[196:197], v[162:163], v[208:209] op_sel:[1,1] op_sel_hi:[1,0]
	v_pk_fma_f32 v[174:175], v[142:143], v[208:209], v[174:175] op_sel:[0,0,0] op_sel_hi:[0,1,1] neg_lo:[0,0,0] neg_hi:[0,1,0]
	v_pk_fma_f32 v[188:189], v[154:155], v[208:209], v[188:189] op_sel:[0,0,0] op_sel_hi:[0,1,1] neg_lo:[0,0,0] neg_hi:[0,1,0]
	v_pk_fma_f32 v[190:191], v[158:159], v[208:209], v[190:191] op_sel:[0,0,0] op_sel_hi:[0,1,1] neg_lo:[0,0,0] neg_hi:[0,1,0]
	v_pk_fma_f32 v[196:197], v[162:163], v[208:209], v[196:197] op_sel:[0,0,0] op_sel_hi:[0,1,1] neg_lo:[0,0,0] neg_hi:[0,1,0]
	v_pk_add_f32 v[142:143], v[140:141], v[174:175] neg_lo:[0,1] neg_hi:[0,1]
	v_pk_add_f32 v[154:155], v[152:153], v[188:189] neg_lo:[0,1] neg_hi:[0,1]
	v_pk_add_f32 v[158:159], v[156:157], v[190:191] neg_lo:[0,1] neg_hi:[0,1]
	v_pk_add_f32 v[162:163], v[160:161], v[196:197] neg_lo:[0,1] neg_hi:[0,1]
	v_pk_add_f32 v[140:141], v[140:141], v[174:175]
	v_pk_add_f32 v[152:153], v[152:153], v[188:189]
	v_pk_add_f32 v[156:157], v[156:157], v[190:191]
	v_pk_add_f32 v[160:161], v[160:161], v[196:197]
	v_pk_mul_f32 v[174:175], v[152:153], v[206:207] op_sel:[1,1] op_sel_hi:[1,0]
	v_pk_mul_f32 v[188:189], v[154:155], v[206:207] op_sel:[1,0] op_sel_hi:[1,1]
	v_pk_mul_f32 v[190:191], v[160:161], v[206:207] op_sel:[1,1] op_sel_hi:[1,0]
	v_pk_mul_f32 v[196:197], v[162:163], v[206:207] op_sel:[1,0] op_sel_hi:[1,1]
	v_pk_fma_f32 v[174:175], v[152:153], v[206:207], v[174:175] op_sel:[0,0,0] op_sel_hi:[0,1,1] neg_lo:[0,0,0] neg_hi:[0,1,0]
	v_pk_fma_f32 v[188:189], v[154:155], v[206:207], v[188:189] op_sel:[0,1,0] op_sel_hi:[0,0,1] neg_lo:[0,0,1] neg_hi:[0,0,0]
	v_pk_fma_f32 v[190:191], v[160:161], v[206:207], v[190:191] op_sel:[0,0,0] op_sel_hi:[0,1,1] neg_lo:[0,0,0] neg_hi:[0,1,0]
	v_pk_fma_f32 v[196:197], v[162:163], v[206:207], v[196:197] op_sel:[0,1,0] op_sel_hi:[0,0,1] neg_lo:[0,0,1] neg_hi:[0,0,0]
	v_pk_add_f32 v[152:153], v[140:141], v[174:175] neg_lo:[0,1] neg_hi:[0,1]
	v_pk_add_f32 v[154:155], v[142:143], v[188:189] neg_lo:[0,1] neg_hi:[0,1]
	v_pk_add_f32 v[160:161], v[156:157], v[190:191] neg_lo:[0,1] neg_hi:[0,1]
	v_pk_add_f32 v[162:163], v[158:159], v[196:197] neg_lo:[0,1] neg_hi:[0,1]
	v_pk_add_f32 v[140:141], v[140:141], v[174:175]
	v_pk_add_f32 v[142:143], v[142:143], v[188:189]
	v_pk_add_f32 v[156:157], v[156:157], v[190:191]
	v_pk_add_f32 v[158:159], v[158:159], v[196:197]
	v_pk_mul_f32 v[174:175], v[156:157], v[204:205] op_sel:[1,1] op_sel_hi:[1,0]
	v_pk_mul_f32 v[188:189], v[158:159], v[210:211] op_sel:[1,1] op_sel_hi:[1,0]
	v_pk_mul_f32 v[190:191], v[160:161], v[204:205] op_sel:[1,0] op_sel_hi:[1,1]
	v_pk_mul_f32 v[196:197], v[162:163], v[212:213] op_sel:[1,1] op_sel_hi:[1,0]
	v_pk_fma_f32 v[174:175], v[156:157], v[204:205], v[174:175] op_sel:[0,0,0] op_sel_hi:[0,1,1] neg_lo:[0,0,0] neg_hi:[0,1,0]
	v_pk_fma_f32 v[188:189], v[158:159], v[210:211], v[188:189] op_sel:[0,0,0] op_sel_hi:[0,1,1] neg_lo:[0,0,0] neg_hi:[0,1,0]
	v_pk_fma_f32 v[190:191], v[160:161], v[204:205], v[190:191] op_sel:[0,1,0] op_sel_hi:[0,0,1] neg_lo:[0,0,1] neg_hi:[0,0,0]
	v_pk_fma_f32 v[196:197], v[162:163], v[212:213], v[196:197] op_sel:[0,0,0] op_sel_hi:[0,1,1] neg_lo:[0,0,0] neg_hi:[0,1,0]
	v_pk_add_f32 v[156:157], v[140:141], v[174:175] neg_lo:[0,1] neg_hi:[0,1]
	v_pk_add_f32 v[158:159], v[142:143], v[188:189] neg_lo:[0,1] neg_hi:[0,1]
	v_pk_add_f32 v[160:161], v[152:153], v[190:191] neg_lo:[0,1] neg_hi:[0,1]
	v_pk_add_f32 v[162:163], v[154:155], v[196:197] neg_lo:[0,1] neg_hi:[0,1]
	v_pk_add_f32 v[140:141], v[140:141], v[174:175]
	v_pk_add_f32 v[142:143], v[142:143], v[188:189]
	v_pk_add_f32 v[152:153], v[152:153], v[190:191]
	v_pk_add_f32 v[154:155], v[154:155], v[196:197]
	ds_write2_b64 v138, v[140:141], v[142:143] offset1:17
	ds_write2_b64 v138, v[152:153], v[154:155] offset0:34 offset1:51
	ds_write2_b64 v138, v[156:157], v[158:159] offset0:68 offset1:85
	ds_write2_b64 v138, v[160:161], v[162:163] offset0:102 offset1:119
	s_mov_b64 s[14:15], 0
	s_waitcnt lgkmcnt(0)
	s_mov_b32 s0, 0
	s_mov_b64 s[14:15], -1
; #define LAS __attribute__((address_space(3)))
; __device__ __forceinline__ cf twc(cf ws, int k16) { if (k16 == 0) return ws; if (k16 == 4) return cf{ws.y, -ws.x}; return cmul(ws, cf{c16(k16), -s16(k16)}); }
; template <int LR> __device__ __forceinline__ void dit_reg(cf (&x)[1 << LR], cf w) {
;     constexpr int R = 1 << LR; cf wsv[LR]; wsv[0] = w;
; #pragma unroll
;     for (int s = 1; s < LR; ++s) wsv[s] = cmul(wsv[s - 1], wsv[s - 1]);
; #pragma unroll
;     for (int s = LR - 1; s >= 0; --s) { const int half = R >> (s + 1);
; #pragma unroll
;         for (int m0 = 0; m0 < R; m0 += 2 * half)
; #pragma unroll
;             for (int mm = 0; mm < half; ++mm) { const int ia = m0 + mm, ib = ia + half; const cf a = x[ia];
;                 const cf b = cmulc(x[ib], twc(wsv[s], (mm << s) * (16 / R)));
;                 x[ia] = cf{a.x + b.x, a.y + b.y}; x[ib] = cf{a.x - b.x, a.y - b.y}; } }
; }
; __device__ __forceinline__ void lds_barrier() { asm volatile("s_waitcnt lgkmcnt(0)\n\ts_barrier" ::: "memory"); }
; template <int LR, bool INV> __device__ __forceinline__ void fft_pass(ldsf2 buf, int base, int stride, int twi) {
;     constexpr int R = 1 << LR; cf x[R];
;     const v2f wv = ((ldsf2)((LAS unsigned char*)buf + 139264))[twi];
; #pragma unroll
;     for (int m = 0; m < R; ++m) { const v2f v = buf[base + m * stride]; x[m] = cf{v.x, v.y}; }
;     const cf w{wv.x, wv.y};
;     if (INV) dit_reg<LR>(x, w); else dif_reg<LR>(x, w);
; #pragma unroll
;     for (int m = 0; m < R; ++m) buf[base + m * stride] = mkv2(x[m].x, x[m].y);
; }
; __device__ __forceinline__ void fft_inv_cba(ldsf2 buf) {
;     ...
;     for (int u = 0; u < 2; ++u) { const int o = l + 64 * u, e0 = wv * 1024 + o; fft_pass<3, true>(buf, e0 + (e0 >> 4), 136, o * 8); }
.LBB0_367:
	v_or_b32_e32 v81, s0, v79
	v_or_b32_e32 v82, v81, v80
	v_lshl_add_u32 v81, v81, 6, 0
	v_add_u32_e32 v81, 0x22000, v81
	v_ashrrev_i32_e32 v83, 4, v82
	v_lshlrev_b32_e32 v81, 3, v82
	v_lshlrev_b32_e32 v82, 3, v83
	v_add3_u32 v81, 0, v81, v82
	v_add_u32_e32 v130, 0x1800, v81
	v_add_u32_e32 v129, 0x1000, v81
	ds_read2_b64 v[94:97], v130 offset0:48 offset1:184
	ds_read2_b64 v[90:93], v129 offset0:32 offset1:168
	v_add_u32_e32 v128, 0x800, v81
	ds_read2_b64 v[82:85], v81 offset1:136
	ds_read2_b64 v[86:89], v128 offset0:16 offset1:152
	s_mov_b32 s0, 64
	v_or_b32_e32 v132, s0, v79
	v_or_b32_e32 v134, v132, v80
	v_lshl_add_u32 v132, v132, 6, 0
	v_add_u32_e32 v132, 0x22000, v132
	v_ashrrev_i32_e32 v138, 4, v134
	v_lshlrev_b32_e32 v132, 3, v134
	v_lshlrev_b32_e32 v134, 3, v138
	v_add3_u32 v132, 0, v132, v134
	v_add_u32_e32 v140, 0x1800, v132
	v_add_u32_e32 v142, 0x1000, v132
	ds_read2_b64 v[152:155], v140 offset0:48 offset1:184
	ds_read2_b64 v[156:159], v142 offset0:32 offset1:168
	v_add_u32_e32 v160, 0x800, v132
	ds_read2_b64 v[162:165], v132 offset1:136
	ds_read2_b64 v[166:169], v160 offset0:16 offset1:152
	s_waitcnt lgkmcnt(4)
	v_pk_add_f32 v[100:101], v[214:215], v[214:215] op_sel:[0,1] op_sel_hi:[1,0] neg_lo:[0,0] neg_hi:[0,1]
	s_nop 0
	v_pk_mul_f32 v[102:103], v[100:101], s[16:17] op_sel:[0,0] op_sel_hi:[1,0]
	v_pk_mul_f32 v[104:105], v[100:101], s[16:17] op_sel:[1,0] op_sel_hi:[0,0] neg_lo:[0,0] neg_hi:[1,0]
	v_pk_mul_f32 v[110:111], v[84:85], v[218:219] op_sel:[1,1] op_sel_hi:[1,0]
	v_pk_mul_f32 v[112:113], v[88:89], v[218:219] op_sel:[1,1] op_sel_hi:[1,0]
	v_pk_mul_f32 v[114:115], v[92:93], v[218:219] op_sel:[1,1] op_sel_hi:[1,0]
	v_pk_mul_f32 v[116:117], v[96:97], v[218:219] op_sel:[1,1] op_sel_hi:[1,0]
	v_pk_fma_f32 v[110:111], v[84:85], v[218:219], v[110:111] op_sel:[0,0,0] op_sel_hi:[0,1,1] neg_lo:[0,0,0] neg_hi:[0,1,0]
	v_pk_fma_f32 v[112:113], v[88:89], v[218:219], v[112:113] op_sel:[0,0,0] op_sel_hi:[0,1,1] neg_lo:[0,0,0] neg_hi:[0,1,0]
	v_pk_fma_f32 v[114:115], v[92:93], v[218:219], v[114:115] op_sel:[0,0,0] op_sel_hi:[0,1,1] neg_lo:[0,0,0] neg_hi:[0,1,0]
	v_pk_fma_f32 v[116:117], v[96:97], v[218:219], v[116:117] op_sel:[0,0,0] op_sel_hi:[0,1,1] neg_lo:[0,0,0] neg_hi:[0,1,0]
	v_pk_add_f32 v[84:85], v[82:83], v[110:111] neg_lo:[0,1] neg_hi:[0,1]
	v_pk_add_f32 v[88:89], v[86:87], v[112:113] neg_lo:[0,1] neg_hi:[0,1]
	v_pk_add_f32 v[92:93], v[90:91], v[114:115] neg_lo:[0,1] neg_hi:[0,1]
	v_pk_add_f32 v[96:97], v[94:95], v[116:117] neg_lo:[0,1] neg_hi:[0,1]
	v_pk_add_f32 v[82:83], v[82:83], v[110:111]
	v_pk_add_f32 v[86:87], v[86:87], v[112:113]
	v_pk_add_f32 v[90:91], v[90:91], v[114:115]
	v_pk_add_f32 v[94:95], v[94:95], v[116:117]
	v_pk_mul_f32 v[110:111], v[86:87], v[216:217] op_sel:[1,1] op_sel_hi:[1,0]
	v_pk_mul_f32 v[112:113], v[88:89], v[216:217] op_sel:[1,0] op_sel_hi:[1,1]
	v_pk_mul_f32 v[114:115], v[94:95], v[216:217] op_sel:[1,1] op_sel_hi:[1,0]
	v_pk_mul_f32 v[116:117], v[96:97], v[216:217] op_sel:[1,0] op_sel_hi:[1,1]
	v_pk_fma_f32 v[110:111], v[86:87], v[216:217], v[110:111] op_sel:[0,0,0] op_sel_hi:[0,1,1] neg_lo:[0,0,0] neg_hi:[0,1,0]
	v_pk_fma_f32 v[112:113], v[88:89], v[216:217], v[112:113] op_sel:[0,1,0] op_sel_hi:[0,0,1] neg_lo:[0,0,1] neg_hi:[0,0,0]
	v_pk_fma_f32 v[114:115], v[94:95], v[216:217], v[114:115] op_sel:[0,0,0] op_sel_hi:[0,1,1] neg_lo:[0,0,0] neg_hi:[0,1,0]
	v_pk_fma_f32 v[116:117], v[96:97], v[216:217], v[116:117] op_sel:[0,1,0] op_sel_hi:[0,0,1] neg_lo:[0,0,1] neg_hi:[0,0,0]
	v_pk_add_f32 v[86:87], v[82:83], v[110:111] neg_lo:[0,1] neg_hi:[0,1]
	v_pk_add_f32 v[88:89], v[84:85], v[112:113] neg_lo:[0,1] neg_hi:[0,1]
	v_pk_add_f32 v[94:95], v[90:91], v[114:115] neg_lo:[0,1] neg_hi:[0,1]
	v_pk_add_f32 v[96:97], v[92:93], v[116:117] neg_lo:[0,1] neg_hi:[0,1]
	v_pk_add_f32 v[82:83], v[82:83], v[110:111]
	v_pk_add_f32 v[84:85], v[84:85], v[112:113]
	v_pk_add_f32 v[90:91], v[90:91], v[114:115]
	v_pk_add_f32 v[92:93], v[92:93], v[116:117]
	v_pk_mul_f32 v[110:111], v[90:91], v[214:215] op_sel:[1,1] op_sel_hi:[1,0]
	v_pk_mul_f32 v[112:113], v[92:93], v[102:103] op_sel:[1,1] op_sel_hi:[1,0]
	v_pk_mul_f32 v[114:115], v[94:95], v[214:215] op_sel:[1,0] op_sel_hi:[1,1]
	v_pk_mul_f32 v[116:117], v[96:97], v[104:105] op_sel:[1,1] op_sel_hi:[1,0]
	v_pk_fma_f32 v[110:111], v[90:91], v[214:215], v[110:111] op_sel:[0,0,0] op_sel_hi:[0,1,1] neg_lo:[0,0,0] neg_hi:[0,1,0]
	v_pk_fma_f32 v[112:113], v[92:93], v[102:103], v[112:113] op_sel:[0,0,0] op_sel_hi:[0,1,1] neg_lo:[0,0,0] neg_hi:[0,1,0]
	v_pk_fma_f32 v[114:115], v[94:95], v[214:215], v[114:115] op_sel:[0,1,0] op_sel_hi:[0,0,1] neg_lo:[0,0,1] neg_hi:[0,0,0]
	v_pk_fma_f32 v[116:117], v[96:97], v[104:105], v[116:117] op_sel:[0,0,0] op_sel_hi:[0,1,1] neg_lo:[0,0,0] neg_hi:[0,1,0]
	v_pk_add_f32 v[90:91], v[82:83], v[110:111] neg_lo:[0,1] neg_hi:[0,1]
	v_pk_add_f32 v[92:93], v[84:85], v[112:113] neg_lo:[0,1] neg_hi:[0,1]
	v_pk_add_f32 v[94:95], v[86:87], v[114:115] neg_lo:[0,1] neg_hi:[0,1]
	v_pk_add_f32 v[96:97], v[88:89], v[116:117] neg_lo:[0,1] neg_hi:[0,1]
	v_pk_add_f32 v[82:83], v[82:83], v[110:111]
	v_pk_add_f32 v[84:85], v[84:85], v[112:113]
	v_pk_add_f32 v[86:87], v[86:87], v[114:115]
	v_pk_add_f32 v[88:89], v[88:89], v[116:117]
	ds_write2_b64 v81, v[82:83], v[84:85] offset1:136
	ds_write2_b64 v128, v[86:87], v[88:89] offset0:16 offset1:152
	ds_write2_b64 v129, v[90:91], v[92:93] offset0:32 offset1:168
	ds_write2_b64 v130, v[94:95], v[96:97] offset0:48 offset1:184
	s_waitcnt lgkmcnt(4)
; #define LAS __attribute__((address_space(3)))
; __device__ __forceinline__ cf twc(cf ws, int k16) { if (k16 == 0) return ws; if (k16 == 4) return cf{ws.y, -ws.x}; return cmul(ws, cf{c16(k16), -s16(k16)}); }
; template <int LR> __device__ __forceinline__ void dit_reg(cf (&x)[1 << LR], cf w) {
;     constexpr int R = 1 << LR; cf wsv[LR]; wsv[0] = w;
; #pragma unroll
;     for (int s = 1; s < LR; ++s) wsv[s] = cmul(wsv[s - 1], wsv[s - 1]);
; #pragma unroll
;     for (int s = LR - 1; s >= 0; --s) { const int half = R >> (s + 1);
; #pragma unroll
;         for (int m0 = 0; m0 < R; m0 += 2 * half)
; #pragma unroll
;             for (int mm = 0; mm < half; ++mm) { const int ia = m0 + mm, ib = ia + half; const cf a = x[ia];
;                 const cf b = cmulc(x[ib], twc(wsv[s], (mm << s) * (16 / R)));
;                 x[ia] = cf{a.x + b.x, a.y + b.y}; x[ib] = cf{a.x - b.x, a.y - b.y}; } }
; }
; __device__ __forceinline__ void lds_barrier() { asm volatile("s_waitcnt lgkmcnt(0)\n\ts_barrier" ::: "memory"); }
; template <int LR, bool INV> __device__ __forceinline__ void fft_pass(ldsf2 buf, int base, int stride, int twi) {
;     constexpr int R = 1 << LR; cf x[R];
;     const v2f wv = ((ldsf2)((LAS unsigned char*)buf + 139264))[twi];
; #pragma unroll
;     for (int m = 0; m < R; ++m) { const v2f v = buf[base + m * stride]; x[m] = cf{v.x, v.y}; }
;     const cf w{wv.x, wv.y};
;     if (INV) dit_reg<LR>(x, w); else dif_reg<LR>(x, w);
; #pragma unroll
;     for (int m = 0; m < R; ++m) buf[base + m * stride] = mkv2(x[m].x, x[m].y);
; }
; __device__ __forceinline__ void fft_inv_cba(ldsf2 buf) {
;     ...
;     for (int u = 0; u < 2; ++u) { const int o = l + 64 * u, e0 = wv * 1024 + o; fft_pass<3, true>(buf, e0 + (e0 >> 4), 136, o * 8); }
;     lds_barrier();
	v_pk_add_f32 v[170:171], v[220:221], v[220:221] op_sel:[0,1] op_sel_hi:[1,0] neg_lo:[0,0] neg_hi:[0,1]
	s_nop 0
	v_pk_mul_f32 v[172:173], v[170:171], s[16:17] op_sel:[0,0] op_sel_hi:[1,0]
	v_pk_mul_f32 v[174:175], v[170:171], s[16:17] op_sel:[1,0] op_sel_hi:[0,0] neg_lo:[0,0] neg_hi:[1,0]
	v_pk_mul_f32 v[196:197], v[164:165], v[224:225] op_sel:[1,1] op_sel_hi:[1,0]
	v_pk_mul_f32 v[198:199], v[168:169], v[224:225] op_sel:[1,1] op_sel_hi:[1,0]
	v_pk_mul_f32 v[200:201], v[158:159], v[224:225] op_sel:[1,1] op_sel_hi:[1,0]
	v_pk_mul_f32 v[202:203], v[154:155], v[224:225] op_sel:[1,1] op_sel_hi:[1,0]
	v_pk_fma_f32 v[196:197], v[164:165], v[224:225], v[196:197] op_sel:[0,0,0] op_sel_hi:[0,1,1] neg_lo:[0,0,0] neg_hi:[0,1,0]
	v_pk_fma_f32 v[198:199], v[168:169], v[224:225], v[198:199] op_sel:[0,0,0] op_sel_hi:[0,1,1] neg_lo:[0,0,0] neg_hi:[0,1,0]
	v_pk_fma_f32 v[200:201], v[158:159], v[224:225], v[200:201] op_sel:[0,0,0] op_sel_hi:[0,1,1] neg_lo:[0,0,0] neg_hi:[0,1,0]
	v_pk_fma_f32 v[202:203], v[154:155], v[224:225], v[202:203] op_sel:[0,0,0] op_sel_hi:[0,1,1] neg_lo:[0,0,0] neg_hi:[0,1,0]
	v_pk_add_f32 v[164:165], v[162:163], v[196:197] neg_lo:[0,1] neg_hi:[0,1]
	v_pk_add_f32 v[168:169], v[166:167], v[198:199] neg_lo:[0,1] neg_hi:[0,1]
	v_pk_add_f32 v[158:159], v[156:157], v[200:201] neg_lo:[0,1] neg_hi:[0,1]
	v_pk_add_f32 v[154:155], v[152:153], v[202:203] neg_lo:[0,1] neg_hi:[0,1]
	v_pk_add_f32 v[162:163], v[162:163], v[196:197]
	v_pk_add_f32 v[166:167], v[166:167], v[198:199]
	v_pk_add_f32 v[156:157], v[156:157], v[200:201]
	v_pk_add_f32 v[152:153], v[152:153], v[202:203]
	v_pk_mul_f32 v[196:197], v[166:167], v[222:223] op_sel:[1,1] op_sel_hi:[1,0]
	v_pk_mul_f32 v[198:199], v[168:169], v[222:223] op_sel:[1,0] op_sel_hi:[1,1]
	v_pk_mul_f32 v[200:201], v[152:153], v[222:223] op_sel:[1,1] op_sel_hi:[1,0]
	v_pk_mul_f32 v[202:203], v[154:155], v[222:223] op_sel:[1,0] op_sel_hi:[1,1]
	v_pk_fma_f32 v[196:197], v[166:167], v[222:223], v[196:197] op_sel:[0,0,0] op_sel_hi:[0,1,1] neg_lo:[0,0,0] neg_hi:[0,1,0]
	v_pk_fma_f32 v[198:199], v[168:169], v[222:223], v[198:199] op_sel:[0,1,0] op_sel_hi:[0,0,1] neg_lo:[0,0,1] neg_hi:[0,0,0]
	v_pk_fma_f32 v[200:201], v[152:153], v[222:223], v[200:201] op_sel:[0,0,0] op_sel_hi:[0,1,1] neg_lo:[0,0,0] neg_hi:[0,1,0]
	v_pk_fma_f32 v[202:203], v[154:155], v[222:223], v[202:203] op_sel:[0,1,0] op_sel_hi:[0,0,1] neg_lo:[0,0,1] neg_hi:[0,0,0]
	v_pk_add_f32 v[166:167], v[162:163], v[196:197] neg_lo:[0,1] neg_hi:[0,1]
	v_pk_add_f32 v[168:169], v[164:165], v[198:199] neg_lo:[0,1] neg_hi:[0,1]
	v_pk_add_f32 v[152:153], v[156:157], v[200:201] neg_lo:[0,1] neg_hi:[0,1]
	v_pk_add_f32 v[154:155], v[158:159], v[202:203] neg_lo:[0,1] neg_hi:[0,1]
	v_pk_add_f32 v[162:163], v[162:163], v[196:197]
	v_pk_add_f32 v[164:165], v[164:165], v[198:199]
	v_pk_add_f32 v[156:157], v[156:157], v[200:201]
	v_pk_add_f32 v[158:159], v[158:159], v[202:203]
	v_pk_mul_f32 v[196:197], v[156:157], v[220:221] op_sel:[1,1] op_sel_hi:[1,0]
	v_pk_mul_f32 v[198:199], v[158:159], v[172:173] op_sel:[1,1] op_sel_hi:[1,0]
	v_pk_mul_f32 v[200:201], v[152:153], v[220:221] op_sel:[1,0] op_sel_hi:[1,1]
	v_pk_mul_f32 v[202:203], v[154:155], v[174:175] op_sel:[1,1] op_sel_hi:[1,0]
	v_pk_fma_f32 v[196:197], v[156:157], v[220:221], v[196:197] op_sel:[0,0,0] op_sel_hi:[0,1,1] neg_lo:[0,0,0] neg_hi:[0,1,0]
	v_pk_fma_f32 v[198:199], v[158:159], v[172:173], v[198:199] op_sel:[0,0,0] op_sel_hi:[0,1,1] neg_lo:[0,0,0] neg_hi:[0,1,0]
	v_pk_fma_f32 v[200:201], v[152:153], v[220:221], v[200:201] op_sel:[0,1,0] op_sel_hi:[0,0,1] neg_lo:[0,0,1] neg_hi:[0,0,0]
	v_pk_fma_f32 v[202:203], v[154:155], v[174:175], v[202:203] op_sel:[0,0,0] op_sel_hi:[0,1,1] neg_lo:[0,0,0] neg_hi:[0,1,0]
	v_pk_add_f32 v[156:157], v[162:163], v[196:197] neg_lo:[0,1] neg_hi:[0,1]
	v_pk_add_f32 v[158:159], v[164:165], v[198:199] neg_lo:[0,1] neg_hi:[0,1]
	v_pk_add_f32 v[152:153], v[166:167], v[200:201] neg_lo:[0,1] neg_hi:[0,1]
	v_pk_add_f32 v[154:155], v[168:169], v[202:203] neg_lo:[0,1] neg_hi:[0,1]
	v_pk_add_f32 v[162:163], v[162:163], v[196:197]
	v_pk_add_f32 v[164:165], v[164:165], v[198:199]
	v_pk_add_f32 v[166:167], v[166:167], v[200:201]
	v_pk_add_f32 v[168:169], v[168:169], v[202:203]
	ds_write2_b64 v132, v[162:163], v[164:165] offset1:136
	ds_write2_b64 v160, v[166:167], v[168:169] offset0:16 offset1:152
	ds_write2_b64 v142, v[156:157], v[158:159] offset0:32 offset1:168
	ds_write2_b64 v140, v[152:153], v[154:155] offset0:48 offset1:184
	s_mov_b64 s[14:15], 0
	s_waitcnt lgkmcnt(0)
	s_barrier
	s_mov_b32 s0, 0
	s_mov_b64 s[30:31], -1
; #define LAS __attribute__((address_space(3)))
; __device__ __forceinline__ cf twc(cf ws, int k16) { if (k16 == 0) return ws; if (k16 == 4) return cf{ws.y, -ws.x}; return cmul(ws, cf{c16(k16), -s16(k16)}); }
; template <int LR> __device__ __forceinline__ void dit_reg(cf (&x)[1 << LR], cf w) {
;     constexpr int R = 1 << LR; cf wsv[LR]; wsv[0] = w;
; #pragma unroll
;     for (int s = 1; s < LR; ++s) wsv[s] = cmul(wsv[s - 1], wsv[s - 1]);
; #pragma unroll
;     for (int s = LR - 1; s >= 0; --s) { const int half = R >> (s + 1);
; #pragma unroll
;         for (int m0 = 0; m0 < R; m0 += 2 * half)
; #pragma unroll
;             for (int mm = 0; mm < half; ++mm) { const int ia = m0 + mm, ib = ia + half; const cf a = x[ia];
;                 const cf b = cmulc(x[ib], twc(wsv[s], (mm << s) * (16 / R)));
;                 x[ia] = cf{a.x + b.x, a.y + b.y}; x[ib] = cf{a.x - b.x, a.y - b.y}; } }
; }
; __device__ __forceinline__ void lds_barrier() { asm volatile("s_waitcnt lgkmcnt(0)\n\ts_barrier" ::: "memory"); }
; template <int LR, bool INV> __device__ __forceinline__ void fft_pass(ldsf2 buf, int base, int stride, int twi) {
;     constexpr int R = 1 << LR; cf x[R];
;     const v2f wv = ((ldsf2)((LAS unsigned char*)buf + 139264))[twi];
; #pragma unroll
;     for (int m = 0; m < R; ++m) { const v2f v = buf[base + m * stride]; x[m] = cf{v.x, v.y}; }
;     const cf w{wv.x, wv.y};
;     if (INV) dit_reg<LR>(x, w); else dif_reg<LR>(x, w);
; #pragma unroll
;     for (int m = 0; m < R; ++m) buf[base + m * stride] = mkv2(x[m].x, x[m].y);
; }
; __device__ __forceinline__ void fft_inv_cba(ldsf2 buf) {
;     ...
;     for (int u = 0; u < 2; ++u) { const int bf = tid + NT * u; fft_pass<3, true>(buf, bf + (bf >> 4), 1088, bf); }
.LBB0_369:
	v_add_u32_e32 v79, s0, v78
	v_ashrrev_i32_e32 v80, 4, v79
	v_lshl_add_u32 v79, v79, 3, 0
	v_add_u32_e32 v81, 0x22000, v79
	v_lshl_add_u32 v79, v80, 3, v79
	ds_read2st64_b64 v[80:83], v79 offset1:17
	ds_read2st64_b64 v[84:87], v79 offset0:34 offset1:51
	ds_read2st64_b64 v[88:91], v79 offset0:68 offset1:85
	ds_read2st64_b64 v[92:95], v79 offset0:102 offset1:119
	s_movk_i32 s0, 0x200
	v_add_u32_e32 v126, s0, v78
	v_ashrrev_i32_e32 v128, 4, v126
	v_lshl_add_u32 v126, v126, 3, 0
	v_add_u32_e32 v130, 0x22000, v126
	v_lshl_add_u32 v126, v128, 3, v126
	ds_read2st64_b64 v[134:137], v126 offset1:17
	ds_read2st64_b64 v[138:141], v126 offset0:34 offset1:51
	ds_read2st64_b64 v[152:155], v126 offset0:68 offset1:85
	ds_read2st64_b64 v[156:159], v126 offset0:102 offset1:119
	s_waitcnt lgkmcnt(4)
	v_pk_add_f32 v[98:99], v[232:233], v[232:233] op_sel:[0,1] op_sel_hi:[1,0] neg_lo:[0,0] neg_hi:[0,1]
	s_nop 0
	v_pk_mul_f32 v[100:101], v[98:99], s[16:17] op_sel:[0,0] op_sel_hi:[1,0]
	v_pk_mul_f32 v[102:103], v[98:99], s[16:17] op_sel:[1,0] op_sel_hi:[0,0] neg_lo:[0,0] neg_hi:[1,0]
	v_pk_mul_f32 v[108:109], v[82:83], v[236:237] op_sel:[1,1] op_sel_hi:[1,0]
	v_pk_mul_f32 v[110:111], v[86:87], v[236:237] op_sel:[1,1] op_sel_hi:[1,0]
	v_pk_mul_f32 v[112:113], v[90:91], v[236:237] op_sel:[1,1] op_sel_hi:[1,0]
	v_pk_mul_f32 v[114:115], v[94:95], v[236:237] op_sel:[1,1] op_sel_hi:[1,0]
	v_pk_fma_f32 v[108:109], v[82:83], v[236:237], v[108:109] op_sel:[0,0,0] op_sel_hi:[0,1,1] neg_lo:[0,0,0] neg_hi:[0,1,0]
	v_pk_fma_f32 v[110:111], v[86:87], v[236:237], v[110:111] op_sel:[0,0,0] op_sel_hi:[0,1,1] neg_lo:[0,0,0] neg_hi:[0,1,0]
	v_pk_fma_f32 v[112:113], v[90:91], v[236:237], v[112:113] op_sel:[0,0,0] op_sel_hi:[0,1,1] neg_lo:[0,0,0] neg_hi:[0,1,0]
	v_pk_fma_f32 v[114:115], v[94:95], v[236:237], v[114:115] op_sel:[0,0,0] op_sel_hi:[0,1,1] neg_lo:[0,0,0] neg_hi:[0,1,0]
	v_pk_add_f32 v[82:83], v[80:81], v[108:109] neg_lo:[0,1] neg_hi:[0,1]
	v_pk_add_f32 v[86:87], v[84:85], v[110:111] neg_lo:[0,1] neg_hi:[0,1]
	v_pk_add_f32 v[90:91], v[88:89], v[112:113] neg_lo:[0,1] neg_hi:[0,1]
	v_pk_add_f32 v[94:95], v[92:93], v[114:115] neg_lo:[0,1] neg_hi:[0,1]
	v_pk_add_f32 v[80:81], v[80:81], v[108:109]
	v_pk_add_f32 v[84:85], v[84:85], v[110:111]
	v_pk_add_f32 v[88:89], v[88:89], v[112:113]
	v_pk_add_f32 v[92:93], v[92:93], v[114:115]
	v_pk_mul_f32 v[108:109], v[84:85], v[234:235] op_sel:[1,1] op_sel_hi:[1,0]
	v_pk_mul_f32 v[110:111], v[86:87], v[234:235] op_sel:[1,0] op_sel_hi:[1,1]
	v_pk_mul_f32 v[112:113], v[92:93], v[234:235] op_sel:[1,1] op_sel_hi:[1,0]
	v_pk_mul_f32 v[114:115], v[94:95], v[234:235] op_sel:[1,0] op_sel_hi:[1,1]
	v_pk_fma_f32 v[108:109], v[84:85], v[234:235], v[108:109] op_sel:[0,0,0] op_sel_hi:[0,1,1] neg_lo:[0,0,0] neg_hi:[0,1,0]
	v_pk_fma_f32 v[110:111], v[86:87], v[234:235], v[110:111] op_sel:[0,1,0] op_sel_hi:[0,0,1] neg_lo:[0,0,1] neg_hi:[0,0,0]
	v_pk_fma_f32 v[112:113], v[92:93], v[234:235], v[112:113] op_sel:[0,0,0] op_sel_hi:[0,1,1] neg_lo:[0,0,0] neg_hi:[0,1,0]
	v_pk_fma_f32 v[114:115], v[94:95], v[234:235], v[114:115] op_sel:[0,1,0] op_sel_hi:[0,0,1] neg_lo:[0,0,1] neg_hi:[0,0,0]
	v_pk_add_f32 v[84:85], v[80:81], v[108:109] neg_lo:[0,1] neg_hi:[0,1]
	v_pk_add_f32 v[86:87], v[82:83], v[110:111] neg_lo:[0,1] neg_hi:[0,1]
	v_pk_add_f32 v[92:93], v[88:89], v[112:113] neg_lo:[0,1] neg_hi:[0,1]
	v_pk_add_f32 v[94:95], v[90:91], v[114:115] neg_lo:[0,1] neg_hi:[0,1]
	v_pk_add_f32 v[80:81], v[80:81], v[108:109]
	v_pk_add_f32 v[82:83], v[82:83], v[110:111]
	v_pk_add_f32 v[88:89], v[88:89], v[112:113]
	v_pk_add_f32 v[90:91], v[90:91], v[114:115]
	v_pk_mul_f32 v[108:109], v[88:89], v[232:233] op_sel:[1,1] op_sel_hi:[1,0]
	v_pk_mul_f32 v[110:111], v[90:91], v[100:101] op_sel:[1,1] op_sel_hi:[1,0]
	v_pk_mul_f32 v[112:113], v[92:93], v[232:233] op_sel:[1,0] op_sel_hi:[1,1]
	v_pk_mul_f32 v[114:115], v[94:95], v[102:103] op_sel:[1,1] op_sel_hi:[1,0]
	v_pk_fma_f32 v[108:109], v[88:89], v[232:233], v[108:109] op_sel:[0,0,0] op_sel_hi:[0,1,1] neg_lo:[0,0,0] neg_hi:[0,1,0]
	v_pk_fma_f32 v[110:111], v[90:91], v[100:101], v[110:111] op_sel:[0,0,0] op_sel_hi:[0,1,1] neg_lo:[0,0,0] neg_hi:[0,1,0]
	v_pk_fma_f32 v[112:113], v[92:93], v[232:233], v[112:113] op_sel:[0,1,0] op_sel_hi:[0,0,1] neg_lo:[0,0,1] neg_hi:[0,0,0]
	v_pk_fma_f32 v[114:115], v[94:95], v[102:103], v[114:115] op_sel:[0,0,0] op_sel_hi:[0,1,1] neg_lo:[0,0,0] neg_hi:[0,1,0]
	v_pk_add_f32 v[88:89], v[80:81], v[108:109] neg_lo:[0,1] neg_hi:[0,1]
	v_pk_add_f32 v[90:91], v[82:83], v[110:111] neg_lo:[0,1] neg_hi:[0,1]
	v_pk_add_f32 v[92:93], v[84:85], v[112:113] neg_lo:[0,1] neg_hi:[0,1]
	v_pk_add_f32 v[94:95], v[86:87], v[114:115] neg_lo:[0,1] neg_hi:[0,1]
	v_pk_add_f32 v[80:81], v[80:81], v[108:109]
	v_pk_add_f32 v[82:83], v[82:83], v[110:111]
	v_pk_add_f32 v[84:85], v[84:85], v[112:113]
	v_pk_add_f32 v[86:87], v[86:87], v[114:115]
	ds_write2st64_b64 v79, v[80:81], v[82:83] offset1:17
	ds_write2st64_b64 v79, v[84:85], v[86:87] offset0:34 offset1:51
	ds_write2st64_b64 v79, v[88:89], v[90:91] offset0:68 offset1:85
	ds_write2st64_b64 v79, v[92:93], v[94:95] offset0:102 offset1:119
	s_waitcnt lgkmcnt(4)
; #define LAS __attribute__((address_space(3)))
; template <int LR> __device__ __forceinline__ void dit_reg(cf (&x)[1 << LR], cf w) {
;     constexpr int R = 1 << LR; cf wsv[LR]; wsv[0] = w;
; #pragma unroll
;     for (int s = 1; s < LR; ++s) wsv[s] = cmul(wsv[s - 1], wsv[s - 1]);
; #pragma unroll
;     for (int s = LR - 1; s >= 0; --s) { const int half = R >> (s + 1);
; #pragma unroll
;         for (int m0 = 0; m0 < R; m0 += 2 * half)
; #pragma unroll
;             for (int mm = 0; mm < half; ++mm) { const int ia = m0 + mm, ib = ia + half; const cf a = x[ia];
;                 const cf b = cmulc(x[ib], twc(wsv[s], (mm << s) * (16 / R)));
;                 x[ia] = cf{a.x + b.x, a.y + b.y}; x[ib] = cf{a.x - b.x, a.y - b.y}; } }
; }
; __device__ __forceinline__ void lds_barrier() { asm volatile("s_waitcnt lgkmcnt(0)\n\ts_barrier" ::: "memory"); }
; template <int LR, bool INV> __device__ __forceinline__ void fft_pass(ldsf2 buf, int base, int stride, int twi) {
;     constexpr int R = 1 << LR; cf x[R];
;     const v2f wv = ((ldsf2)((LAS unsigned char*)buf + 139264))[twi];
; #pragma unroll
;     for (int m = 0; m < R; ++m) { const v2f v = buf[base + m * stride]; x[m] = cf{v.x, v.y}; }
;     const cf w{wv.x, wv.y};
;     if (INV) dit_reg<LR>(x, w); else dif_reg<LR>(x, w);
; #pragma unroll
;     for (int m = 0; m < R; ++m) buf[base + m * stride] = mkv2(x[m].x, x[m].y);
; __device__ void ph_hyena_fft(const Params& P, int j, const bf16_t* __restrict__ projAT, const float* __restrict__ kf, bf16_t* __restrict__ yaT, unsigned char* lds_raw) {
;     ...
;             { float xa[8], xb[8]; sconv8(xb0, n0, wb0, wb1, wb2, bb, xa); sconv8(xb1, n0, wb0, wb1, wb2, bb, xb);
;               const unsigned gw0[4] = {g0.x, g0.y, g0.z, g0.w}, gw1[4] = {g1.x, g1.y, g1.z, g1.w}; unsigned w0[4], w1[4];
; #pragma unroll
;               for (int k2 = 0; k2 < 4; ++k2) { const v2f ya = buf[ph0 + 2 * k2], yb = buf[ph0 + 2 * k2 + 1];
;                   const float ra = xa[2 * k2] * (ya.x * invN + sk1 * va[2 * k2]) * silu(__uint_as_float(gw0[k2] << 16));
;                   const float rb = xa[2 * k2 + 1] * (yb.x * invN + sk1 * va[2 * k2 + 1]) * silu(__uint_as_float(gw0[k2] & 0xffff0000u));
;                   const float rc = xb[2 * k2] * (ya.y * invN + sk1 * vb[2 * k2]) * silu(__uint_as_float(gw1[k2] << 16));
	v_pk_add_f32 v[142:143], v[240:241], v[240:241] op_sel:[0,1] op_sel_hi:[1,0] neg_lo:[0,0] neg_hi:[0,1]
	s_nop 0
	v_pk_mul_f32 v[160:161], v[142:143], s[16:17] op_sel:[0,0] op_sel_hi:[1,0]
	v_pk_mul_f32 v[162:163], v[142:143], s[16:17] op_sel:[1,0] op_sel_hi:[0,0] neg_lo:[0,0] neg_hi:[1,0]
	v_pk_mul_f32 v[168:169], v[136:137], v[244:245] op_sel:[1,1] op_sel_hi:[1,0]
	v_pk_mul_f32 v[170:171], v[140:141], v[244:245] op_sel:[1,1] op_sel_hi:[1,0]
	v_pk_mul_f32 v[172:173], v[154:155], v[244:245] op_sel:[1,1] op_sel_hi:[1,0]
	v_pk_mul_f32 v[174:175], v[158:159], v[244:245] op_sel:[1,1] op_sel_hi:[1,0]
	v_pk_fma_f32 v[168:169], v[136:137], v[244:245], v[168:169] op_sel:[0,0,0] op_sel_hi:[0,1,1] neg_lo:[0,0,0] neg_hi:[0,1,0]
	v_pk_fma_f32 v[170:171], v[140:141], v[244:245], v[170:171] op_sel:[0,0,0] op_sel_hi:[0,1,1] neg_lo:[0,0,0] neg_hi:[0,1,0]
	v_pk_fma_f32 v[172:173], v[154:155], v[244:245], v[172:173] op_sel:[0,0,0] op_sel_hi:[0,1,1] neg_lo:[0,0,0] neg_hi:[0,1,0]
	v_pk_fma_f32 v[174:175], v[158:159], v[244:245], v[174:175] op_sel:[0,0,0] op_sel_hi:[0,1,1] neg_lo:[0,0,0] neg_hi:[0,1,0]
	v_pk_add_f32 v[136:137], v[134:135], v[168:169] neg_lo:[0,1] neg_hi:[0,1]
	v_pk_add_f32 v[140:141], v[138:139], v[170:171] neg_lo:[0,1] neg_hi:[0,1]
	v_pk_add_f32 v[154:155], v[152:153], v[172:173] neg_lo:[0,1] neg_hi:[0,1]
	v_pk_add_f32 v[158:159], v[156:157], v[174:175] neg_lo:[0,1] neg_hi:[0,1]
	v_pk_add_f32 v[134:135], v[134:135], v[168:169]
	v_pk_add_f32 v[138:139], v[138:139], v[170:171]
	v_pk_add_f32 v[152:153], v[152:153], v[172:173]
	v_pk_add_f32 v[156:157], v[156:157], v[174:175]
	v_pk_mul_f32 v[168:169], v[138:139], v[242:243] op_sel:[1,1] op_sel_hi:[1,0]
	v_pk_mul_f32 v[170:171], v[140:141], v[242:243] op_sel:[1,0] op_sel_hi:[1,1]
	v_pk_mul_f32 v[172:173], v[156:157], v[242:243] op_sel:[1,1] op_sel_hi:[1,0]
	v_pk_mul_f32 v[174:175], v[158:159], v[242:243] op_sel:[1,0] op_sel_hi:[1,1]
	v_pk_fma_f32 v[168:169], v[138:139], v[242:243], v[168:169] op_sel:[0,0,0] op_sel_hi:[0,1,1] neg_lo:[0,0,0] neg_hi:[0,1,0]
	v_pk_fma_f32 v[170:171], v[140:141], v[242:243], v[170:171] op_sel:[0,1,0] op_sel_hi:[0,0,1] neg_lo:[0,0,1] neg_hi:[0,0,0]
	v_pk_fma_f32 v[172:173], v[156:157], v[242:243], v[172:173] op_sel:[0,0,0] op_sel_hi:[0,1,1] neg_lo:[0,0,0] neg_hi:[0,1,0]
	v_pk_fma_f32 v[174:175], v[158:159], v[242:243], v[174:175] op_sel:[0,1,0] op_sel_hi:[0,0,1] neg_lo:[0,0,1] neg_hi:[0,0,0]
	v_pk_add_f32 v[138:139], v[134:135], v[168:169] neg_lo:[0,1] neg_hi:[0,1]
	v_pk_add_f32 v[140:141], v[136:137], v[170:171] neg_lo:[0,1] neg_hi:[0,1]
	v_pk_add_f32 v[156:157], v[152:153], v[172:173] neg_lo:[0,1] neg_hi:[0,1]
	v_pk_add_f32 v[158:159], v[154:155], v[174:175] neg_lo:[0,1] neg_hi:[0,1]
	v_pk_add_f32 v[134:135], v[134:135], v[168:169]
	v_pk_add_f32 v[136:137], v[136:137], v[170:171]
	v_pk_add_f32 v[152:153], v[152:153], v[172:173]
	v_pk_add_f32 v[154:155], v[154:155], v[174:175]
	v_pk_mul_f32 v[168:169], v[152:153], v[240:241] op_sel:[1,1] op_sel_hi:[1,0]
	v_pk_mul_f32 v[170:171], v[154:155], v[160:161] op_sel:[1,1] op_sel_hi:[1,0]
	v_pk_mul_f32 v[172:173], v[156:157], v[240:241] op_sel:[1,0] op_sel_hi:[1,1]
	v_pk_mul_f32 v[174:175], v[158:159], v[162:163] op_sel:[1,1] op_sel_hi:[1,0]
	v_pk_fma_f32 v[168:169], v[152:153], v[240:241], v[168:169] op_sel:[0,0,0] op_sel_hi:[0,1,1] neg_lo:[0,0,0] neg_hi:[0,1,0]
	v_pk_fma_f32 v[170:171], v[154:155], v[160:161], v[170:171] op_sel:[0,0,0] op_sel_hi:[0,1,1] neg_lo:[0,0,0] neg_hi:[0,1,0]
	v_pk_fma_f32 v[172:173], v[156:157], v[240:241], v[172:173] op_sel:[0,1,0] op_sel_hi:[0,0,1] neg_lo:[0,0,1] neg_hi:[0,0,0]
	v_pk_fma_f32 v[174:175], v[158:159], v[162:163], v[174:175] op_sel:[0,0,0] op_sel_hi:[0,1,1] neg_lo:[0,0,0] neg_hi:[0,1,0]
	v_pk_add_f32 v[152:153], v[134:135], v[168:169] neg_lo:[0,1] neg_hi:[0,1]
	v_pk_add_f32 v[154:155], v[136:137], v[170:171] neg_lo:[0,1] neg_hi:[0,1]
	v_pk_add_f32 v[156:157], v[138:139], v[172:173] neg_lo:[0,1] neg_hi:[0,1]
	v_pk_add_f32 v[158:159], v[140:141], v[174:175] neg_lo:[0,1] neg_hi:[0,1]
	v_pk_add_f32 v[134:135], v[134:135], v[168:169]
	v_pk_add_f32 v[136:137], v[136:137], v[170:171]
	v_pk_add_f32 v[138:139], v[138:139], v[172:173]
	v_pk_add_f32 v[140:141], v[140:141], v[174:175]
	ds_write2st64_b64 v126, v[134:135], v[136:137] offset1:17
	ds_write2st64_b64 v126, v[138:139], v[140:141] offset0:34 offset1:51
	ds_write2st64_b64 v126, v[152:153], v[154:155] offset0:68 offset1:85
	ds_write2st64_b64 v126, v[156:157], v[158:159] offset0:102 offset1:119
	s_mov_b64 s[30:31], 0
	s_waitcnt vmcnt(6)
	v_lshlrev_b32_e32 v78, 16, v147
	v_cndmask_b32_e64 v97, 0, v78, s[42:43]
	s_waitcnt vmcnt(5)
	v_lshlrev_b32_e32 v78, 16, v148
	s_waitcnt vmcnt(1)
	v_lshlrev_b32_e32 v114, 16, v12
	v_cndmask_b32_e64 v99, 0, v78, s[44:45]
	v_and_b32_e32 v12, 0xffff0000, v12
	v_mul_f32_e32 v78, 0xbfb8aa3b, v114
	v_exp_f32_e32 v78, v78
	v_mul_f32_e32 v82, 0xbfb8aa3b, v12
	v_lshlrev_b32_e32 v104, 16, v5
	v_exp_f32_e32 v82, v82
	v_and_b32_e32 v102, 0xffff0000, v4
	v_mov_b32_e32 v96, v104
	v_lshlrev_b32_e32 v100, 16, v4
	v_and_b32_e32 v103, 0xffff0000, v5
	v_mov_b32_e32 v101, v102
	v_pk_mul_f32 v[96:97], v[38:39], v[96:97]
	v_lshlrev_b32_e32 v115, 16, v13
	v_pk_fma_f32 v[96:97], v[38:39], v[100:101], v[96:97] op_sel:[0,0,1] op_sel_hi:[1,1,0]
	v_mov_b32_e32 v101, v104
	v_pk_mul_f32 v[122:123], v[54:55], v[102:103]
	v_add_f32_e32 v78, 1.0, v78
	v_pk_fma_f32 v[100:101], v[52:53], v[100:101], v[122:123]
	v_rcp_f32_e32 v122, v78
	v_add_f32_e32 v78, 1.0, v82
	v_mul_f32_e32 v82, 0xbfb8aa3b, v115
	v_exp_f32_e32 v82, v82
	s_waitcnt lgkmcnt(0)
	s_barrier
; __device__ __forceinline__ bf16_t f2bf(float f) { unsigned u = __float_as_uint(f); u += 0x7FFFu + ((u >> 16) & 1u); return (bf16_t)(u >> 16); }
; __device__ __forceinline__ float silu(float x) { return x * __builtin_amdgcn_rcpf(1.0f + __expf(-x)); }
; __device__ void ph_hyena_fft(const Params& P, int j, const bf16_t* __restrict__ projAT, const float* __restrict__ kf, bf16_t* __restrict__ yaT, unsigned char* lds_raw) {
;     ...
;             { float xa[8], xb[8]; sconv8(xb0, n0, wb0, wb1, wb2, bb, xa); sconv8(xb1, n0, wb0, wb1, wb2, bb, xb);
;               const unsigned gw0[4] = {g0.x, g0.y, g0.z, g0.w}, gw1[4] = {g1.x, g1.y, g1.z, g1.w}; unsigned w0[4], w1[4];
; #pragma unroll
;               for (int k2 = 0; k2 < 4; ++k2) { const v2f ya = buf[ph0 + 2 * k2], yb = buf[ph0 + 2 * k2 + 1];
;                   const float ra = xa[2 * k2] * (ya.x * invN + sk1 * va[2 * k2]) * silu(__uint_as_float(gw0[k2] << 16));
;                   const float rb = xa[2 * k2 + 1] * (yb.x * invN + sk1 * va[2 * k2 + 1]) * silu(__uint_as_float(gw0[k2] & 0xffff0000u));
;                   const float rc = xb[2 * k2] * (ya.y * invN + sk1 * vb[2 * k2]) * silu(__uint_as_float(gw1[k2] << 16));
;                   const float rd = xb[2 * k2 + 1] * (yb.y * invN + sk1 * vb[2 * k2 + 1]) * silu(__uint_as_float(gw1[k2] & 0xffff0000u));
;                   w0[k2] = (unsigned)f2bf(ra) | ((unsigned)f2bf(rb) << 16); w1[k2] = (unsigned)f2bf(rc) | ((unsigned)f2bf(rd) << 16); }
	ds_read2_b64 v[88:91], v145 offset1:1
	ds_read2_b64 v[92:95], v145 offset0:2 offset1:3
	v_and_b32_e32 v13, 0xffff0000, v13
	v_rcp_f32_e32 v124, v78
	v_add_f32_e32 v78, 1.0, v82
	v_rcp_f32_e32 v123, v78
	v_mul_f32_e32 v78, 0xbfb8aa3b, v13
	v_exp_f32_e32 v78, v78
	s_waitcnt lgkmcnt(1)
	v_mov_b32_e32 v126, v88
	s_waitcnt lgkmcnt(0)
	v_mov_b32_e32 v127, v92
	v_pk_fma_f32 v[96:97], v[40:41], v[102:103], v[96:97]
	v_pk_mul_f32 v[126:127], v[126:127], s[80:81] op_sel_hi:[1,0]
	v_pk_add_f32 v[96:97], v[42:43], v[96:97]
	v_pk_fma_f32 v[76:77], v[46:47], v[76:77], v[126:127]
	v_add_f32_e32 v78, 1.0, v78
	v_pk_mul_f32 v[76:77], v[96:97], v[76:77]
	v_pk_mul_f32 v[96:97], v[122:123], v[114:115]
	v_rcp_f32_e32 v125, v78
	v_lshlrev_b32_e32 v105, 16, v6
	v_pk_mul_f32 v[76:77], v[96:97], v[76:77]
	v_mov_b32_e32 v96, v90
	v_mov_b32_e32 v97, v94
	v_pk_fma_f32 v[100:101], v[40:41], v[104:105], v[100:101]
	v_pk_mul_f32 v[96:97], v[96:97], s[80:81] op_sel_hi:[1,0]
	v_pk_add_f32 v[100:101], v[42:43], v[100:101]
	v_pk_fma_f32 v[74:75], v[46:47], v[74:75], v[96:97]
	v_pk_mul_f32 v[12:13], v[124:125], v[12:13]
	v_pk_mul_f32 v[74:75], v[100:101], v[74:75]
	v_lshlrev_b32_e32 v118, 16, v14
	v_pk_mul_f32 v[12:13], v[12:13], v[74:75]
	v_and_b32_sdwa v74, v77, v229 dst_sel:DWORD dst_unused:UNUSED_PAD src0_sel:WORD_1 src1_sel:DWORD
	v_add3_u32 v74, v77, v74, s33
	v_and_b32_sdwa v77, v12, v229 dst_sel:DWORD dst_unused:UNUSED_PAD src0_sel:WORD_1 src1_sel:DWORD
	v_and_b32_sdwa v75, v76, v229 dst_sel:DWORD dst_unused:UNUSED_PAD src0_sel:WORD_1 src1_sel:DWORD
	v_add3_u32 v12, v12, v77, s33
	v_and_b32_e32 v14, 0xffff0000, v14
	v_add3_u32 v75, v76, v75, s33
	v_and_b32_e32 v12, 0xffff0000, v12
	v_or_b32_sdwa v12, v12, v75 dst_sel:DWORD dst_unused:UNUSED_PAD src0_sel:DWORD src1_sel:WORD_1
	v_mul_f32_e32 v75, 0xbfb8aa3b, v14
	v_exp_f32_e32 v75, v75
	v_lshlrev_b32_e32 v4, 16, v149
	v_lshlrev_b32_e32 v119, 16, v15
	v_and_b32_sdwa v76, v13, v229 dst_sel:DWORD dst_unused:UNUSED_PAD src0_sel:WORD_1 src1_sel:DWORD
	v_add_f32_e32 v75, 1.0, v75
	v_cndmask_b32_e64 v111, 0, v4, s[42:43]
	v_lshlrev_b32_e32 v4, 16, v150
	v_add3_u32 v13, v13, v76, s33
	v_rcp_f32_e32 v76, v75
	v_mul_f32_e32 v75, 0xbfb8aa3b, v119
	v_and_b32_e32 v106, 0xffff0000, v6
	v_lshlrev_b32_e32 v109, 16, v7
	v_and_b32_e32 v107, 0xffff0000, v7
	v_cndmask_b32_e64 v79, 0, v4, s[44:45]
	v_lshlrev_b32_e32 v112, 16, v8
	v_and_b32_e32 v86, 0xffff0000, v8
	v_lshlrev_b32_e32 v80, 16, v9
	v_and_b32_e32 v87, 0xffff0000, v9
	v_lshlrev_b32_e32 v81, 16, v10
	v_and_b32_e32 v84, 0xffff0000, v10
	v_lshlrev_b32_e32 v83, 16, v11
	v_and_b32_e32 v85, 0xffff0000, v11
	ds_read2_b64 v[4:7], v145 offset0:4 offset1:5
	ds_read2_b64 v[8:11], v145 offset0:6 offset1:7
	v_exp_f32_e32 v75, v75
	v_and_b32_e32 v15, 0xffff0000, v15
	v_and_b32_e32 v13, 0xffff0000, v13
	s_waitcnt lgkmcnt(1)
	v_mov_b32_e32 v96, v4
	v_add_f32_e32 v4, 1.0, v75
	v_rcp_f32_e32 v75, v4
	v_mul_f32_e32 v4, 0xbfb8aa3b, v15
	v_exp_f32_e32 v4, v4
	s_waitcnt lgkmcnt(0)
	v_mov_b32_e32 v97, v8
	v_or_b32_sdwa v13, v13, v74 dst_sel:DWORD dst_unused:UNUSED_PAD src0_sel:DWORD src1_sel:WORD_1
	v_mul_f32_e32 v74, 0xbfb8aa3b, v118
	v_add_f32_e32 v4, 1.0, v4
	v_pk_mul_f32 v[96:97], v[96:97], s[80:81] op_sel_hi:[1,0]
	v_rcp_f32_e32 v77, v4
	v_exp_f32_e32 v74, v74
	v_pk_fma_f32 v[72:73], v[46:47], v[72:73], v[96:97]
	v_mov_b32_e32 v96, v6
	v_mov_b32_e32 v97, v10
	v_pk_mul_f32 v[96:97], v[96:97], s[80:81] op_sel_hi:[1,0]
	v_pk_mul_f32 v[14:15], v[76:77], v[14:15]
	v_pk_fma_f32 v[70:71], v[46:47], v[70:71], v[96:97]
	v_mov_b32_e32 v96, v105
	v_mov_b32_e32 v97, v109
	v_pk_mov_b32 v[76:77], v[102:103], v[106:107] op_sel:[1,0]
	v_pk_mul_f32 v[96:97], v[54:55], v[96:97]
	v_mov_b32_e32 v104, v107
	v_mov_b32_e32 v108, v106
	v_add_f32_e32 v74, 1.0, v74
	v_pk_fma_f32 v[76:77], v[52:53], v[76:77], v[96:97]
	v_pk_mul_f32 v[96:97], v[38:39], v[104:105]
	v_mov_b32_e32 v98, v109
	v_rcp_f32_e32 v74, v74
	v_pk_fma_f32 v[96:97], v[38:39], v[108:109], v[96:97] op_sel:[0,0,1] op_sel_hi:[1,1,0]
	v_pk_fma_f32 v[76:77], v[40:41], v[106:107], v[76:77]
	v_pk_fma_f32 v[96:97], v[40:41], v[98:99], v[96:97]
	v_pk_add_f32 v[76:77], v[42:43], v[76:77]
	v_pk_add_f32 v[96:97], v[42:43], v[96:97]
	v_pk_mul_f32 v[74:75], v[74:75], v[118:119]
	v_pk_mul_f32 v[70:71], v[96:97], v[70:71]
	v_pk_mul_f32 v[72:73], v[76:77], v[72:73]
	v_pk_mul_f32 v[14:15], v[14:15], v[70:71]
	v_pk_mul_f32 v[72:73], v[74:75], v[72:73]
	v_and_b32_sdwa v8, v15, v229 dst_sel:DWORD dst_unused:UNUSED_PAD src0_sel:WORD_1 src1_sel:DWORD
	v_and_b32_sdwa v4, v73, v229 dst_sel:DWORD dst_unused:UNUSED_PAD src0_sel:WORD_1 src1_sel:DWORD
	v_and_b32_sdwa v10, v14, v229 dst_sel:DWORD dst_unused:UNUSED_PAD src0_sel:WORD_1 src1_sel:DWORD
	v_add3_u32 v8, v15, v8, s33
	s_waitcnt vmcnt(0)
; __device__ __forceinline__ bf16_t f2bf(float f) { unsigned u = __float_as_uint(f); u += 0x7FFFu + ((u >> 16) & 1u); return (bf16_t)(u >> 16); }
; __device__ __forceinline__ float silu(float x) { return x * __builtin_amdgcn_rcpf(1.0f + __expf(-x)); }
; __device__ __forceinline__ void lds_barrier() { asm volatile("s_waitcnt lgkmcnt(0)\n\ts_barrier" ::: "memory"); }
; __device__ void ph_hyena_fft(const Params& P, int j, const bf16_t* __restrict__ projAT, const float* __restrict__ kf, bf16_t* __restrict__ yaT, unsigned char* lds_raw) {
;     ...
;             { float xa[8], xb[8]; sconv8(xb0, n0, wb0, wb1, wb2, bb, xa); sconv8(xb1, n0, wb0, wb1, wb2, bb, xb);
;               const unsigned gw0[4] = {g0.x, g0.y, g0.z, g0.w}, gw1[4] = {g1.x, g1.y, g1.z, g1.w}; unsigned w0[4], w1[4];
; #pragma unroll
;               for (int k2 = 0; k2 < 4; ++k2) { const v2f ya = buf[ph0 + 2 * k2], yb = buf[ph0 + 2 * k2 + 1];
;                   const float ra = xa[2 * k2] * (ya.x * invN + sk1 * va[2 * k2]) * silu(__uint_as_float(gw0[k2] << 16));
;                   const float rb = xa[2 * k2 + 1] * (yb.x * invN + sk1 * va[2 * k2 + 1]) * silu(__uint_as_float(gw0[k2] & 0xffff0000u));
;                   const float rc = xb[2 * k2] * (ya.y * invN + sk1 * vb[2 * k2]) * silu(__uint_as_float(gw1[k2] << 16));
;                   const float rd = xb[2 * k2 + 1] * (yb.y * invN + sk1 * vb[2 * k2 + 1]) * silu(__uint_as_float(gw1[k2] & 0xffff0000u));
;                   w0[k2] = (unsigned)f2bf(ra) | ((unsigned)f2bf(rb) << 16); w1[k2] = (unsigned)f2bf(rc) | ((unsigned)f2bf(rd) << 16); }
;               *(uint4*)(yaT + (size_t)c * T_TOK + o0 + n0) = make_uint4(w0[0], w0[1], w0[2], w0[3]);
;               *(uint4*)(yaT + (size_t)c * T_TOK + o1 + n0) = make_uint4(w1[0], w1[1], w1[2], w1[3]); }
;             lds_barrier();
;         }
	v_lshlrev_b32_e32 v116, 16, v0
	v_and_b32_sdwa v6, v72, v229 dst_sel:DWORD dst_unused:UNUSED_PAD src0_sel:WORD_1 src1_sel:DWORD
	v_add3_u32 v4, v73, v4, s33
	v_add3_u32 v10, v14, v10, s33
	v_and_b32_e32 v8, 0xffff0000, v8
	v_and_b32_e32 v0, 0xffff0000, v0
	v_add3_u32 v6, v72, v6, s33
	v_and_b32_e32 v10, 0xffff0000, v10
	v_or_b32_sdwa v15, v8, v4 dst_sel:DWORD dst_unused:UNUSED_PAD src0_sel:DWORD src1_sel:WORD_1
	v_mul_f32_e32 v4, 0xbfb8aa3b, v116
	v_or_b32_sdwa v14, v10, v6 dst_sel:DWORD dst_unused:UNUSED_PAD src0_sel:DWORD src1_sel:WORD_1
	v_exp_f32_e32 v4, v4
	v_mul_f32_e32 v6, 0xbfb8aa3b, v0
	v_exp_f32_e32 v6, v6
	v_lshlrev_b32_e32 v117, 16, v1
	v_add_f32_e32 v4, 1.0, v4
	v_rcp_f32_e32 v72, v4
	v_add_f32_e32 v4, 1.0, v6
	v_rcp_f32_e32 v74, v4
	v_mul_f32_e32 v4, 0xbfb8aa3b, v117
	v_exp_f32_e32 v4, v4
	v_and_b32_e32 v1, 0xffff0000, v1
	v_lshl_add_u64 v[120:121], v[50:51], 0, s[62:63]
	v_mov_b32_e32 v110, v80
	v_add_f32_e32 v4, 1.0, v4
	v_rcp_f32_e32 v73, v4
	v_mul_f32_e32 v4, 0xbfb8aa3b, v1
	v_exp_f32_e32 v4, v4
	global_store_dwordx4 v[120:121], v[12:15], off
	v_mov_b32_e32 v113, v86
	v_mov_b32_e32 v92, v89
	v_pk_mul_f32 v[14:15], v[38:39], v[110:111]
	v_pk_mul_f32 v[76:77], v[92:93], s[80:81] op_sel_hi:[1,0]
	v_pk_fma_f32 v[14:15], v[38:39], v[112:113], v[14:15] op_sel:[0,0,1] op_sel_hi:[1,1,0]
	v_add_f32_e32 v4, 1.0, v4
	v_pk_fma_f32 v[14:15], v[40:41], v[86:87], v[14:15]
	v_mov_b32_e32 v113, v80
	v_pk_add_f32 v[14:15], v[42:43], v[14:15]
	v_pk_mul_f32 v[70:71], v[54:55], v[86:87]
	v_pk_fma_f32 v[68:69], v[46:47], v[68:69], v[76:77]
	v_rcp_f32_e32 v75, v4
	v_pk_fma_f32 v[70:71], v[52:53], v[112:113], v[70:71]
	v_pk_mul_f32 v[14:15], v[14:15], v[68:69]
	v_pk_mul_f32 v[68:69], v[72:73], v[116:117]
	v_mov_b32_e32 v94, v91
	v_pk_fma_f32 v[70:71], v[40:41], v[80:81], v[70:71]
	v_pk_mul_f32 v[14:15], v[68:69], v[14:15]
	v_pk_mul_f32 v[68:69], v[94:95], s[80:81] op_sel_hi:[1,0]
	v_pk_add_f32 v[70:71], v[42:43], v[70:71]
	v_pk_fma_f32 v[66:67], v[46:47], v[66:67], v[68:69]
	v_pk_mul_f32 v[0:1], v[74:75], v[0:1]
	v_pk_mul_f32 v[66:67], v[70:71], v[66:67]
	v_and_b32_sdwa v6, v14, v229 dst_sel:DWORD dst_unused:UNUSED_PAD src0_sel:WORD_1 src1_sel:DWORD
	v_pk_mul_f32 v[0:1], v[0:1], v[66:67]
	v_and_b32_sdwa v4, v15, v229 dst_sel:DWORD dst_unused:UNUSED_PAD src0_sel:WORD_1 src1_sel:DWORD
	v_and_b32_sdwa v10, v0, v229 dst_sel:DWORD dst_unused:UNUSED_PAD src0_sel:WORD_1 src1_sel:DWORD
	v_and_b32_sdwa v8, v1, v229 dst_sel:DWORD dst_unused:UNUSED_PAD src0_sel:WORD_1 src1_sel:DWORD
	v_add3_u32 v0, v0, v10, s33
	v_add3_u32 v6, v14, v6, s33
	v_add3_u32 v1, v1, v8, s33
	v_and_b32_e32 v0, 0xffff0000, v0
	v_lshlrev_b32_e32 v14, 16, v2
	v_and_b32_e32 v2, 0xffff0000, v2
	v_add3_u32 v4, v15, v4, s33
	v_and_b32_e32 v1, 0xffff0000, v1
	v_or_b32_sdwa v0, v0, v6 dst_sel:DWORD dst_unused:UNUSED_PAD src0_sel:DWORD src1_sel:WORD_1
	v_lshlrev_b32_e32 v15, 16, v3
	v_mul_f32_e32 v6, 0xbfb8aa3b, v2
	v_or_b32_sdwa v1, v1, v4 dst_sel:DWORD dst_unused:UNUSED_PAD src0_sel:DWORD src1_sel:WORD_1
	v_mul_f32_e32 v4, 0xbfb8aa3b, v14
	v_exp_f32_e32 v6, v6
	v_mul_f32_e32 v8, 0xbfb8aa3b, v15
	v_exp_f32_e32 v4, v4
	v_exp_f32_e32 v10, v8
	v_and_b32_e32 v3, 0xffff0000, v3
	v_add_f32_e32 v6, 1.0, v6
	v_add_f32_e32 v4, 1.0, v4
	v_rcp_f32_e32 v66, v6
	v_mov_b32_e32 v8, v5
	v_add_f32_e32 v5, 1.0, v10
	v_mul_f32_e32 v6, 0xbfb8aa3b, v3
	v_rcp_f32_e32 v4, v4
	v_rcp_f32_e32 v5, v5
	v_exp_f32_e32 v6, v6
	v_mov_b32_e32 v10, v7
	v_mov_b32_e32 v80, v85
	v_pk_mul_f32 v[4:5], v[4:5], v[14:15]
	v_add_f32_e32 v6, 1.0, v6
	v_mov_b32_e32 v14, v81
	v_mov_b32_e32 v15, v83
	v_rcp_f32_e32 v67, v6
	v_pk_mul_f32 v[6:7], v[10:11], s[80:81] op_sel_hi:[1,0]
	v_pk_mov_b32 v[10:11], v[86:87], v[84:85] op_sel:[1,0]
	v_pk_mul_f32 v[14:15], v[54:55], v[14:15]
	v_mov_b32_e32 v82, v84
	v_pk_fma_f32 v[10:11], v[52:53], v[10:11], v[14:15]
	v_pk_mul_f32 v[14:15], v[38:39], v[80:81]
	v_mov_b32_e32 v78, v83
	v_pk_mul_f32 v[8:9], v[8:9], s[80:81] op_sel_hi:[1,0]
	v_pk_fma_f32 v[10:11], v[40:41], v[84:85], v[10:11]
	v_pk_fma_f32 v[14:15], v[38:39], v[82:83], v[14:15] op_sel:[0,0,1] op_sel_hi:[1,1,0]
	v_pk_fma_f32 v[8:9], v[46:47], v[64:65], v[8:9]
	v_pk_add_f32 v[10:11], v[42:43], v[10:11]
	v_pk_fma_f32 v[14:15], v[40:41], v[78:79], v[14:15]
	v_pk_fma_f32 v[6:7], v[46:47], v[62:63], v[6:7]
	v_pk_add_f32 v[14:15], v[42:43], v[14:15]
	v_pk_mul_f32 v[8:9], v[10:11], v[8:9]
	v_pk_mul_f32 v[2:3], v[66:67], v[2:3]
	v_pk_mul_f32 v[4:5], v[4:5], v[8:9]
	v_pk_mul_f32 v[6:7], v[14:15], v[6:7]
	s_mov_b32 s7, s63
	v_pk_mul_f32 v[2:3], v[2:3], v[6:7]
	v_and_b32_sdwa v6, v5, v229 dst_sel:DWORD dst_unused:UNUSED_PAD src0_sel:WORD_1 src1_sel:DWORD
	v_and_b32_sdwa v7, v4, v229 dst_sel:DWORD dst_unused:UNUSED_PAD src0_sel:WORD_1 src1_sel:DWORD
	v_add3_u32 v4, v4, v7, s33
	v_add3_u32 v5, v5, v6, s33
	v_and_b32_sdwa v6, v3, v229 dst_sel:DWORD dst_unused:UNUSED_PAD src0_sel:WORD_1 src1_sel:DWORD
	v_and_b32_sdwa v7, v2, v229 dst_sel:DWORD dst_unused:UNUSED_PAD src0_sel:WORD_1 src1_sel:DWORD
	v_add3_u32 v3, v3, v6, s33
	v_add3_u32 v2, v2, v7, s33
	v_and_b32_e32 v3, 0xffff0000, v3
	v_and_b32_e32 v2, 0xffff0000, v2
	v_lshl_add_u64 v[12:13], v[50:51], 0, s[6:7]
	v_or_b32_sdwa v3, v3, v5 dst_sel:DWORD dst_unused:UNUSED_PAD src0_sel:DWORD src1_sel:WORD_1
	v_or_b32_sdwa v2, v2, v4 dst_sel:DWORD dst_unused:UNUSED_PAD src0_sel:DWORD src1_sel:WORD_1
	global_store_dwordx4 v[12:13], v[0:3], off
	s_waitcnt lgkmcnt(0)
	s_barrier
	s_add_i32 s53, s53, 1
	s_cmp_eq_u32 s53, 4
	s_cbranch_scc0 .LBB0_346
	s_add_i32 s46, s46, s22
	v_readlane_b32 s60, v255, 27
	s_cmpk_gt_i32 s46, 0x3ff
	v_readlane_b32 s61, v255, 28
	s_movk_i32 s59, 0xffd0
	s_cbranch_scc0 .LBB0_333
